# v10 + sc0 sc1 write-through cache policy on all wide global stores (cheaper L2 writeback at grid barriers)
# speedup vs baseline: 1.0113x; 1.0113x over previous
; __device__ __forceinline__ void tr_item(const float* W, int K, int N, int nblk, bf16_t* WT, LAS float* scr, int item, int lane, bool qperm) {
;     ...
; #pragma unroll 8
;     for (int i = 0; i < 32; ++i) { const int kk = 2 * i + (lane >> 5); const float v = W[(size_t)(k0 + kk) * N + src]; scr[kk * 33 + (lane & 31)] = ok ? v : 0.f; }
.LBB0_18:
	s_lshl_b32 s76, s60, 1
	s_lshl_b32 s77, s61, 1
	v_or_b32_e32 v26, s77, v8
	s_add_i32 s78, s76, 4
	s_add_i32 s79, s77, 4
	s_add_i32 s80, s76, 8
	s_add_i32 s81, s77, 8
	s_add_i32 s82, s76, 12
	s_add_i32 s83, s77, 12
	s_add_i32 s84, s76, 16
	s_add_i32 s85, s77, 16
	s_add_i32 s86, s76, 20
	s_add_i32 s87, s77, 20
	s_add_i32 s88, s76, 24
	s_add_i32 s89, s77, 24
	s_add_i32 s90, s76, 28
	s_add_i32 s91, s77, 28
	v_or_b32_e32 v24, s76, v3
	v_ashrrev_i32_e32 v27, 31, v26
	v_or_b32_e32 v28, s78, v3
	v_or_b32_e32 v30, s79, v8
	v_or_b32_e32 v32, s80, v3
	v_or_b32_e32 v34, s81, v8
	v_or_b32_e32 v36, s82, v3
	v_or_b32_e32 v38, s83, v8
	v_or_b32_e32 v40, s84, v3
	v_or_b32_e32 v42, s85, v8
	v_or_b32_e32 v44, s86, v3
	v_or_b32_e32 v46, s87, v8
	v_or_b32_e32 v48, s88, v3
	v_or_b32_e32 v50, s89, v8
	v_or_b32_e32 v52, s90, v3
	v_or_b32_e32 v54, s91, v8
	v_ashrrev_i32_e32 v25, 31, v24
	v_lshlrev_b64 v[26:27], 12, v[26:27]
	v_ashrrev_i32_e32 v31, 31, v30
	v_ashrrev_i32_e32 v29, 31, v28
	v_ashrrev_i32_e32 v35, 31, v34
	v_ashrrev_i32_e32 v33, 31, v32
	v_ashrrev_i32_e32 v39, 31, v38
	v_ashrrev_i32_e32 v37, 31, v36
	v_ashrrev_i32_e32 v43, 31, v42
	v_ashrrev_i32_e32 v41, 31, v40
	v_ashrrev_i32_e32 v47, 31, v46
	v_ashrrev_i32_e32 v45, 31, v44
	v_ashrrev_i32_e32 v51, 31, v50
	v_ashrrev_i32_e32 v49, 31, v48
	v_ashrrev_i32_e32 v55, 31, v54
	v_ashrrev_i32_e32 v53, 31, v52
	v_lshlrev_b64 v[24:25], 12, v[24:25]
	v_lshl_add_u64 v[26:27], v[14:15], 0, v[26:27]
	v_lshlrev_b64 v[28:29], 12, v[28:29]
	v_lshlrev_b64 v[30:31], 12, v[30:31]
	v_lshlrev_b64 v[32:33], 12, v[32:33]
	v_lshlrev_b64 v[34:35], 12, v[34:35]
	v_lshlrev_b64 v[36:37], 12, v[36:37]
	v_lshlrev_b64 v[38:39], 12, v[38:39]
	v_lshlrev_b64 v[40:41], 12, v[40:41]
	v_lshlrev_b64 v[42:43], 12, v[42:43]
	v_lshlrev_b64 v[44:45], 12, v[44:45]
	v_lshlrev_b64 v[46:47], 12, v[46:47]
	v_lshlrev_b64 v[48:49], 12, v[48:49]
	v_lshlrev_b64 v[50:51], 12, v[50:51]
	v_lshlrev_b64 v[52:53], 12, v[52:53]
	v_lshlrev_b64 v[54:55], 12, v[54:55]
	v_lshl_add_u64 v[24:25], v[14:15], 0, v[24:25]
	v_lshl_add_u64 v[30:31], v[14:15], 0, v[30:31]
	v_lshl_add_u64 v[28:29], v[14:15], 0, v[28:29]
	v_lshl_add_u64 v[34:35], v[14:15], 0, v[34:35]
	v_lshl_add_u64 v[32:33], v[14:15], 0, v[32:33]
	v_lshl_add_u64 v[38:39], v[14:15], 0, v[38:39]
	v_lshl_add_u64 v[36:37], v[14:15], 0, v[36:37]
	v_lshl_add_u64 v[42:43], v[14:15], 0, v[42:43]
	v_lshl_add_u64 v[40:41], v[14:15], 0, v[40:41]
	v_lshl_add_u64 v[46:47], v[14:15], 0, v[46:47]
	v_lshl_add_u64 v[44:45], v[14:15], 0, v[44:45]
	v_lshl_add_u64 v[50:51], v[14:15], 0, v[50:51]
	v_lshl_add_u64 v[48:49], v[14:15], 0, v[48:49]
	v_lshl_add_u64 v[54:55], v[14:15], 0, v[54:55]
	v_lshl_add_u64 v[52:53], v[14:15], 0, v[52:53]
	global_load_dword v11, v[26:27], off
	global_load_dword v56, v[24:25], off
	global_load_dword v57, v[30:31], off
	global_load_dword v58, v[28:29], off
	global_load_dword v59, v[34:35], off
	global_load_dword v60, v[32:33], off
	global_load_dword v61, v[38:39], off
	global_load_dword v62, v[36:37], off
	global_load_dword v63, v[42:43], off
	global_load_dword v64, v[40:41], off
	global_load_dword v65, v[46:47], off
	global_load_dword v66, v[44:45], off
	global_load_dword v67, v[50:51], off
	global_load_dword v68, v[48:49], off
	global_load_dword v69, v[54:55], off
	global_load_dword v70, v[52:53], off
	v_or_b32_e32 v26, s76, v1
	v_or_b32_e32 v24, s77, v2
	s_add_i32 s61, s61, 16
	s_add_i32 s60, s60, 16
	s_add_i32 s75, s75, -16
	v_mad_u64_u32 v[24:25], s[76:77], v24, s66, v[4:5]
	v_mad_u64_u32 v[26:27], s[76:77], v26, s66, v[4:5]
	v_or_b32_e32 v25, s78, v1
	v_or_b32_e32 v27, s79, v2
	v_or_b32_e32 v34, s80, v1
	v_or_b32_e32 v32, s81, v2
	v_or_b32_e32 v38, s82, v1
	v_or_b32_e32 v36, s83, v2
	v_or_b32_e32 v42, s84, v1
	v_or_b32_e32 v40, s85, v2
	v_or_b32_e32 v46, s86, v1
	v_or_b32_e32 v44, s87, v2
	v_or_b32_e32 v50, s88, v1
	v_or_b32_e32 v48, s89, v2
	v_or_b32_e32 v54, s90, v1
	v_or_b32_e32 v52, s91, v2
	s_cmp_lg_u32 s75, 0
	v_mad_u64_u32 v[28:29], s[76:77], v27, s66, v[4:5]
	v_mad_u64_u32 v[30:31], s[76:77], v25, s66, v[4:5]
	v_mad_u64_u32 v[32:33], s[76:77], v32, s66, v[4:5]
	v_mad_u64_u32 v[34:35], s[76:77], v34, s66, v[4:5]
	v_mad_u64_u32 v[36:37], s[76:77], v36, s66, v[4:5]
	v_mad_u64_u32 v[38:39], s[76:77], v38, s66, v[4:5]
	v_mad_u64_u32 v[40:41], s[76:77], v40, s66, v[4:5]
	v_mad_u64_u32 v[42:43], s[76:77], v42, s66, v[4:5]
	v_mad_u64_u32 v[44:45], s[76:77], v44, s66, v[4:5]
	v_mad_u64_u32 v[46:47], s[76:77], v46, s66, v[4:5]
	v_mad_u64_u32 v[48:49], s[76:77], v48, s66, v[4:5]
	v_mad_u64_u32 v[50:51], s[76:77], v50, s66, v[4:5]
	v_mad_u64_u32 v[52:53], s[76:77], v52, s66, v[4:5]
	v_mad_u64_u32 v[54:55], s[76:77], v54, s66, v[4:5]
	s_waitcnt vmcnt(0)
	ds_write_b32 v24, v11
	ds_write_b32 v26, v56
	ds_write_b32 v28, v57
	ds_write_b32 v30, v58
	ds_write_b32 v32, v59
	ds_write_b32 v34, v60
	ds_write_b32 v36, v61
	ds_write_b32 v38, v62
	ds_write_b32 v40, v63
	ds_write_b32 v42, v64
	ds_write_b32 v44, v65
	ds_write_b32 v46, v66
	ds_write_b32 v48, v67
	ds_write_b32 v50, v68
	ds_write_b32 v52, v69
	ds_write_b32 v54, v70
	s_cbranch_scc1 .LBB0_18
; #define LAS __attribute__((address_space(3)))
; __device__ __forceinline__ unsigned cvtpk(float lo, float hi) { f32x2_t v = {lo, hi}; bf16x2_t b = __builtin_convertvector(v, bf16x2_t); return __builtin_bit_cast(unsigned, b); }
; __device__ __forceinline__ void tr_item(const float* W, int K, int N, int nblk, bf16_t* WT, LAS float* scr, int item, int lane, bool qperm) {
;     ...
;     asm volatile("s_waitcnt lgkmcnt(0)" ::: "memory");
;     const int c = lane & 7;
; #pragma unroll
;     for (int j = 0; j < 4; ++j) { const int n = (lane >> 3) + 8 * j; const LAS float* s = scr + (8 * c) * 33 + n;
;         u32x4 o; o.x = cvtpk(s[0 * 33], s[1 * 33]); o.y = cvtpk(s[2 * 33], s[3 * 33]); o.z = cvtpk(s[4 * 33], s[5 * 33]); o.w = cvtpk(s[6 * 33], s[7 * 33]);
;         *(u32x4*)(WT + (size_t)(n0 + n) * K + k0 + 8 * c) = o; }
;     asm volatile("s_waitcnt lgkmcnt(0)" ::: "memory");
	s_waitcnt lgkmcnt(0)
	ds_read2_b32 v[14:15], v19 offset0:33 offset1:41
	ds_read2_b32 v[24:25], v19 offset1:8
	ds_read2_b32 v[26:27], v19 offset0:66 offset1:74
	ds_read2_b32 v[28:29], v19 offset0:99 offset1:107
	ds_read2_b32 v[30:31], v19 offset0:132 offset1:140
	ds_read2_b32 v[32:33], v19 offset0:165 offset1:173
	ds_read2_b32 v[34:35], v19 offset0:198 offset1:206
	ds_read2_b32 v[36:37], v19 offset0:231 offset1:239
	v_lshl_add_u64 v[12:13], v[12:13], 1, s[4:5]
	v_mov_b32_e32 v11, v9
	v_lshl_add_u64 v[10:11], v[10:11], 1, v[12:13]
	v_lshlrev_b32_e32 v8, 1, v6
	v_or_b32_e32 v3, v16, v18
	v_lshl_add_u64 v[38:39], v[10:11], 0, v[8:9]
	v_lshlrev_b32_e32 v8, 11, v3
	s_waitcnt lgkmcnt(0)
	v_cvt_pk_bf16_f32 v10, v24, v14
	v_cvt_pk_bf16_f32 v11, v26, v28
	v_cvt_pk_bf16_f32 v12, v30, v32
	v_cvt_pk_bf16_f32 v13, v34, v36
	v_lshl_add_u64 v[40:41], v[38:39], 0, v[8:9]
	global_store_dwordx4 v[40:41], v[10:13], off sc0 sc1
	v_or_b32_e32 v3, v16, v20
	v_lshlrev_b32_e32 v8, 11, v3
	v_cvt_pk_bf16_f32 v10, v25, v15
	v_cvt_pk_bf16_f32 v11, v27, v29
	v_cvt_pk_bf16_f32 v12, v31, v33
	v_cvt_pk_bf16_f32 v13, v35, v37
	ds_read2_b32 v[24:25], v19 offset0:49 offset1:57
	ds_read2_b32 v[26:27], v19 offset0:16 offset1:24
	ds_read2_b32 v[28:29], v19 offset0:82 offset1:90
	ds_read2_b32 v[30:31], v19 offset0:115 offset1:123
	ds_read2_b32 v[32:33], v19 offset0:148 offset1:156
	ds_read2_b32 v[34:35], v19 offset0:181 offset1:189
	ds_read2_b32 v[36:37], v19 offset0:214 offset1:222
	ds_read2_b32 v[40:41], v19 offset0:247 offset1:255
	v_or_b32_e32 v3, v16, v21
	v_lshl_add_u64 v[14:15], v[38:39], 0, v[8:9]
	v_lshlrev_b32_e32 v8, 11, v3
	v_or_b32_e32 v3, v16, v22
	global_store_dwordx4 v[14:15], v[10:13], off sc0 sc1
	v_lshl_add_u64 v[14:15], v[38:39], 0, v[8:9]
	v_lshlrev_b32_e32 v8, 11, v3
	s_waitcnt lgkmcnt(6)
	v_cvt_pk_bf16_f32 v10, v26, v24
	s_waitcnt lgkmcnt(4)
	v_cvt_pk_bf16_f32 v11, v28, v30
	s_waitcnt lgkmcnt(2)
	v_cvt_pk_bf16_f32 v12, v32, v34
	s_waitcnt lgkmcnt(0)
	v_cvt_pk_bf16_f32 v13, v36, v40
	global_store_dwordx4 v[14:15], v[10:13], off sc0 sc1
	v_lshl_add_u64 v[14:15], v[38:39], 0, v[8:9]
	v_readlane_b32 s84, v254, 7
	v_cvt_pk_bf16_f32 v10, v27, v25
	v_cvt_pk_bf16_f32 v11, v29, v31
	v_cvt_pk_bf16_f32 v12, v33, v35
	v_cvt_pk_bf16_f32 v13, v37, v41
	global_store_dwordx4 v[14:15], v[10:13], off sc0 sc1
	s_waitcnt lgkmcnt(0)
	v_readlane_b32 s75, v254, 6
	v_readlane_b32 s85, v254, 8

; __device__ __forceinline__ void tr_item(const float* W, int K, int N, int nblk, bf16_t* WT, LAS float* scr, int item, int lane, bool qperm) {
;     ...
; #pragma unroll 8
;     for (int i = 0; i < 32; ++i) { const int kk = 2 * i + (lane >> 5); const float v = W[(size_t)(k0 + kk) * N + src]; scr[kk * 33 + (lane & 31)] = ok ? v : 0.f; }
.LBB0_22:
	s_lshl_b32 s76, s60, 1
	s_lshl_b32 s77, s61, 1
	v_or_b32_e32 v8, s77, v16
	s_add_i32 s78, s76, 4
	s_add_i32 s79, s77, 4
	v_mov_b32_e32 v29, v9
	s_add_i32 s81, s77, 8
	v_lshlrev_b64 v[42:43], 13, v[8:9]
	v_or_b32_e32 v28, s78, v3
	v_or_b32_e32 v8, s79, v16
	v_mov_b32_e32 v27, v9
	v_or_b32_e32 v26, s76, v3
	s_add_i32 s83, s77, 12
	v_lshlrev_b64 v[28:29], 13, v[28:29]
	v_lshlrev_b64 v[44:45], 13, v[8:9]
	v_or_b32_e32 v8, s81, v16
	s_add_i32 s80, s76, 8
	s_add_i32 s82, s76, 12
	s_add_i32 s85, s77, 16
	v_lshlrev_b64 v[26:27], 13, v[26:27]
	v_lshl_add_u64 v[42:43], v[14:15], 0, v[42:43]
	v_lshl_add_u64 v[28:29], v[14:15], 0, v[28:29]
	v_lshlrev_b64 v[46:47], 13, v[8:9]
	v_or_b32_e32 v8, s83, v16
	v_mov_b32_e32 v31, v9
	v_mov_b32_e32 v33, v9
	s_add_i32 s87, s77, 20
	v_or_b32_e32 v30, s80, v3
	v_or_b32_e32 v32, s82, v3
	v_lshl_add_u64 v[26:27], v[14:15], 0, v[26:27]
	v_lshl_add_u64 v[44:45], v[14:15], 0, v[44:45]
	global_load_dword v13, v[42:43], off
	global_load_dword v25, v[26:27], off
	global_load_dword v58, v[44:45], off
	global_load_dword v59, v[28:29], off
	v_lshlrev_b64 v[28:29], 13, v[8:9]
	v_or_b32_e32 v8, s85, v16
	s_add_i32 s84, s76, 16
	s_add_i32 s86, s76, 20
	s_add_i32 s89, s77, 24
	v_lshlrev_b64 v[30:31], 13, v[30:31]
	v_lshlrev_b64 v[32:33], 13, v[32:33]
	v_lshl_add_u64 v[26:27], v[14:15], 0, v[46:47]
	v_lshl_add_u64 v[28:29], v[14:15], 0, v[28:29]
	v_lshlrev_b64 v[42:43], 13, v[8:9]
	v_or_b32_e32 v8, s87, v16
	v_mov_b32_e32 v35, v9
	v_mov_b32_e32 v37, v9
	s_add_i32 s88, s76, 24
	s_add_i32 s90, s76, 28
	s_add_i32 s91, s77, 28
	v_or_b32_e32 v34, s84, v3
	v_or_b32_e32 v36, s86, v3
	v_lshl_add_u64 v[30:31], v[14:15], 0, v[30:31]
	v_lshl_add_u64 v[32:33], v[14:15], 0, v[32:33]
	global_load_dword v60, v[26:27], off
	global_load_dword v61, v[30:31], off
	global_load_dword v62, v[28:29], off
	global_load_dword v63, v[32:33], off
	v_lshlrev_b64 v[28:29], 13, v[8:9]
	v_or_b32_e32 v8, s89, v16
	v_mov_b32_e32 v39, v9
	v_mov_b32_e32 v41, v9
	v_or_b32_e32 v38, s88, v3
	v_or_b32_e32 v40, s90, v3
	v_lshlrev_b64 v[34:35], 13, v[34:35]
	v_lshlrev_b64 v[36:37], 13, v[36:37]
	v_lshl_add_u64 v[26:27], v[14:15], 0, v[42:43]
	v_lshl_add_u64 v[28:29], v[14:15], 0, v[28:29]
	v_lshlrev_b64 v[30:31], 13, v[8:9]
	v_or_b32_e32 v8, s91, v16
	v_lshlrev_b64 v[38:39], 13, v[38:39]
	v_lshlrev_b64 v[40:41], 13, v[40:41]
	v_lshl_add_u64 v[34:35], v[14:15], 0, v[34:35]
	v_lshl_add_u64 v[36:37], v[14:15], 0, v[36:37]
	global_load_dword v64, v[26:27], off
	global_load_dword v65, v[34:35], off
	global_load_dword v66, v[28:29], off
	global_load_dword v67, v[36:37], off
	v_lshl_add_u64 v[26:27], v[14:15], 0, v[30:31]
	v_lshlrev_b64 v[28:29], 13, v[8:9]
	v_lshl_add_u64 v[38:39], v[14:15], 0, v[38:39]
	v_lshl_add_u64 v[40:41], v[14:15], 0, v[40:41]
	v_lshl_add_u64 v[28:29], v[14:15], 0, v[28:29]
	global_load_dword v8, v[26:27], off
	global_load_dword v68, v[38:39], off
	global_load_dword v69, v[28:29], off
	global_load_dword v70, v[40:41], off
	v_or_b32_e32 v28, s76, v1
	v_or_b32_e32 v26, s77, v2
	s_add_i32 s61, s61, 16
	s_add_i32 s60, s60, 16
	s_add_i32 s75, s75, -16
	v_mad_u64_u32 v[26:27], s[76:77], v26, s66, v[4:5]
	v_mad_u64_u32 v[28:29], s[76:77], v28, s66, v[4:5]
	v_or_b32_e32 v27, s78, v1
	v_or_b32_e32 v29, s79, v2
	v_or_b32_e32 v36, s80, v1
	v_or_b32_e32 v34, s81, v2
	v_or_b32_e32 v40, s82, v1
	v_or_b32_e32 v38, s83, v2
	v_or_b32_e32 v44, s84, v1
	v_or_b32_e32 v42, s85, v2
	v_or_b32_e32 v48, s86, v1
	v_or_b32_e32 v46, s87, v2
	v_or_b32_e32 v52, s88, v1
	v_or_b32_e32 v50, s89, v2
	v_or_b32_e32 v56, s90, v1
	v_or_b32_e32 v54, s91, v2
	s_cmp_lg_u32 s75, 0
	v_mad_u64_u32 v[30:31], s[76:77], v29, s66, v[4:5]
	v_mad_u64_u32 v[32:33], s[76:77], v27, s66, v[4:5]
	v_mad_u64_u32 v[34:35], s[76:77], v34, s66, v[4:5]
	v_mad_u64_u32 v[36:37], s[76:77], v36, s66, v[4:5]
	v_mad_u64_u32 v[38:39], s[76:77], v38, s66, v[4:5]
	v_mad_u64_u32 v[40:41], s[76:77], v40, s66, v[4:5]
	v_mad_u64_u32 v[42:43], s[76:77], v42, s66, v[4:5]
	v_mad_u64_u32 v[44:45], s[76:77], v44, s66, v[4:5]
	v_mad_u64_u32 v[46:47], s[76:77], v46, s66, v[4:5]
	v_mad_u64_u32 v[48:49], s[76:77], v48, s66, v[4:5]
	v_mad_u64_u32 v[50:51], s[76:77], v50, s66, v[4:5]
	v_mad_u64_u32 v[52:53], s[76:77], v52, s66, v[4:5]
	v_mad_u64_u32 v[54:55], s[76:77], v54, s66, v[4:5]
	v_mad_u64_u32 v[56:57], s[76:77], v56, s66, v[4:5]
	s_waitcnt vmcnt(0)
	ds_write_b32 v26, v13
	ds_write_b32 v28, v25
	ds_write_b32 v30, v58
	ds_write_b32 v32, v59
	ds_write_b32 v34, v60
	ds_write_b32 v36, v61
	ds_write_b32 v38, v62
	ds_write_b32 v40, v63
	ds_write_b32 v42, v64
	ds_write_b32 v44, v65
	ds_write_b32 v46, v66
	ds_write_b32 v48, v67
	ds_write_b32 v50, v8
	ds_write_b32 v52, v68
	ds_write_b32 v54, v69
	ds_write_b32 v56, v70
	s_cbranch_scc1 .LBB0_22
; #define LAS __attribute__((address_space(3)))
; __device__ __forceinline__ unsigned cvtpk(float lo, float hi) { f32x2_t v = {lo, hi}; bf16x2_t b = __builtin_convertvector(v, bf16x2_t); return __builtin_bit_cast(unsigned, b); }
; __device__ __forceinline__ void tr_item(const float* W, int K, int N, int nblk, bf16_t* WT, LAS float* scr, int item, int lane, bool qperm) {
;     ...
;     asm volatile("s_waitcnt lgkmcnt(0)" ::: "memory");
;     const int c = lane & 7;
; #pragma unroll
;     for (int j = 0; j < 4; ++j) { const int n = (lane >> 3) + 8 * j; const LAS float* s = scr + (8 * c) * 33 + n;
;         u32x4 o; o.x = cvtpk(s[0 * 33], s[1 * 33]); o.y = cvtpk(s[2 * 33], s[3 * 33]); o.z = cvtpk(s[4 * 33], s[5 * 33]); o.w = cvtpk(s[6 * 33], s[7 * 33]);
;         *(u32x4*)(WT + (size_t)(n0 + n) * K + k0 + 8 * c) = o; }
;     asm volatile("s_waitcnt lgkmcnt(0)" ::: "memory");
	s_waitcnt lgkmcnt(0)
	ds_read2_b32 v[14:15], v19 offset0:33 offset1:41
	ds_read2_b32 v[26:27], v19 offset1:8
	ds_read2_b32 v[28:29], v19 offset0:66 offset1:74
	ds_read2_b32 v[30:31], v19 offset0:99 offset1:107
	ds_read2_b32 v[32:33], v19 offset0:132 offset1:140
	ds_read2_b32 v[34:35], v19 offset0:165 offset1:173
	ds_read2_b32 v[36:37], v19 offset0:198 offset1:206
	ds_read2_b32 v[38:39], v19 offset0:231 offset1:239
	v_lshlrev_b64 v[10:11], 20, v[10:11]
	v_lshl_add_u64 v[10:11], s[6:7], 0, v[10:11]
	v_mov_b32_e32 v13, v9
	v_lshl_add_u64 v[10:11], v[12:13], 1, v[10:11]
	v_lshlrev_b32_e32 v8, 1, v6
	v_or_b32_e32 v3, v24, v18
	v_lshl_add_u64 v[40:41], v[10:11], 0, v[8:9]
	v_lshlrev_b32_e32 v8, 9, v3
	s_waitcnt lgkmcnt(0)
	v_cvt_pk_bf16_f32 v10, v26, v14
	v_cvt_pk_bf16_f32 v11, v28, v30
	v_cvt_pk_bf16_f32 v12, v32, v34
	v_cvt_pk_bf16_f32 v13, v36, v38
	v_lshl_add_u64 v[42:43], v[40:41], 0, v[8:9]
	global_store_dwordx4 v[42:43], v[10:13], off sc0 sc1
	v_or_b32_e32 v3, v24, v20
	v_lshlrev_b32_e32 v8, 9, v3
	v_cvt_pk_bf16_f32 v10, v27, v15
	v_cvt_pk_bf16_f32 v11, v29, v31
	v_cvt_pk_bf16_f32 v12, v33, v35
	v_cvt_pk_bf16_f32 v13, v37, v39
	ds_read2_b32 v[26:27], v19 offset0:49 offset1:57
	ds_read2_b32 v[28:29], v19 offset0:16 offset1:24
	ds_read2_b32 v[30:31], v19 offset0:82 offset1:90
	ds_read2_b32 v[32:33], v19 offset0:115 offset1:123
	ds_read2_b32 v[34:35], v19 offset0:148 offset1:156
	ds_read2_b32 v[36:37], v19 offset0:181 offset1:189
	ds_read2_b32 v[38:39], v19 offset0:214 offset1:222
	ds_read2_b32 v[42:43], v19 offset0:247 offset1:255
	v_or_b32_e32 v3, v24, v21
	v_lshl_add_u64 v[14:15], v[40:41], 0, v[8:9]
	v_lshlrev_b32_e32 v8, 9, v3
	v_or_b32_e32 v3, v24, v22
	global_store_dwordx4 v[14:15], v[10:13], off sc0 sc1
	v_lshl_add_u64 v[14:15], v[40:41], 0, v[8:9]
	v_lshlrev_b32_e32 v8, 9, v3
	s_waitcnt lgkmcnt(6)
	v_cvt_pk_bf16_f32 v10, v28, v26
	s_waitcnt lgkmcnt(4)
	v_cvt_pk_bf16_f32 v11, v30, v32
	s_waitcnt lgkmcnt(2)
	v_cvt_pk_bf16_f32 v12, v34, v36
	s_waitcnt lgkmcnt(0)
	v_cvt_pk_bf16_f32 v13, v38, v42
	global_store_dwordx4 v[14:15], v[10:13], off sc0 sc1
	v_lshl_add_u64 v[14:15], v[40:41], 0, v[8:9]
	v_readlane_b32 s84, v254, 7
	v_cvt_pk_bf16_f32 v10, v29, v27
	v_cvt_pk_bf16_f32 v11, v31, v33
	v_cvt_pk_bf16_f32 v12, v35, v37
	v_cvt_pk_bf16_f32 v13, v39, v43
	global_store_dwordx4 v[14:15], v[10:13], off sc0 sc1
	s_waitcnt lgkmcnt(0)
	v_readlane_b32 s75, v254, 6
	v_readlane_b32 s85, v254, 8

; __device__ __forceinline__ int qperm_src(int n) { const int hh = n / 96, d = n - hh * 96; if (d < 64) return n; const int j = d - 64; return hh * 96 + 64 + ((j & 1) ? 16 + (j >> 1) : (j >> 1)); }
; __device__ __forceinline__ void tr_item(const float* W, int K, int N, int nblk, bf16_t* WT, LAS float* scr, int item, int lane, bool qperm) {
;     ...
;     const int nn = n0 + (lane & 31); const bool ok = nn < N; const int src = qperm ? qperm_src(ok ? nn : 0) : (ok ? nn : 0);
; #pragma unroll 8
;     for (int i = 0; i < 32; ++i) { const int kk = 2 * i + (lane >> 5); const float v = W[(size_t)(k0 + kk) * N + src]; scr[kk * 33 + (lane & 31)] = ok ? v : 0.f; }
.LBB0_29:
	s_lshl_b32 s61, s0, 1
	s_lshl_b32 s75, s1, 1
	v_or_b32_e32 v15, s61, v3
	v_or_b32_e32 v16, s75, v8
	s_add_i32 s78, s61, 4
	s_add_i32 s79, s75, 4
	s_add_i32 s80, s61, 8
	s_add_i32 s81, s75, 8
	s_add_i32 s82, s61, 12
	s_add_i32 s83, s75, 12
	s_add_i32 s84, s61, 16
	s_add_i32 s85, s75, 16
	s_add_i32 s86, s61, 20
	s_add_i32 s87, s75, 20
	s_add_i32 s88, s61, 24
	s_add_i32 s89, s75, 24
	s_add_i32 s90, s61, 28
	s_add_i32 s91, s75, 28
	v_mad_u64_u32 v[24:25], s[76:77], v16, s67, v[12:13]
	v_mad_u64_u32 v[26:27], s[76:77], v15, s67, v[12:13]
	v_or_b32_e32 v15, s78, v3
	v_or_b32_e32 v16, s79, v8
	v_or_b32_e32 v34, s80, v3
	v_or_b32_e32 v32, s81, v8
	v_or_b32_e32 v38, s82, v3
	v_or_b32_e32 v36, s83, v8
	v_or_b32_e32 v42, s84, v3
	v_or_b32_e32 v40, s85, v8
	v_or_b32_e32 v46, s86, v3
	v_or_b32_e32 v44, s87, v8
	v_or_b32_e32 v50, s88, v3
	v_or_b32_e32 v48, s89, v8
	v_or_b32_e32 v54, s90, v3
	v_or_b32_e32 v52, s91, v8
	v_mad_u64_u32 v[28:29], s[76:77], v16, s67, v[12:13]
	v_mad_u64_u32 v[30:31], s[76:77], v15, s67, v[12:13]
	v_mad_u64_u32 v[32:33], s[76:77], v32, s67, v[12:13]
	v_mad_u64_u32 v[34:35], s[76:77], v34, s67, v[12:13]
	v_mad_u64_u32 v[36:37], s[76:77], v36, s67, v[12:13]
	v_mad_u64_u32 v[38:39], s[76:77], v38, s67, v[12:13]
	v_mad_u64_u32 v[40:41], s[76:77], v40, s67, v[12:13]
	v_mad_u64_u32 v[42:43], s[76:77], v42, s67, v[12:13]
	v_mad_u64_u32 v[44:45], s[76:77], v44, s67, v[12:13]
	v_mad_u64_u32 v[46:47], s[76:77], v46, s67, v[12:13]
	v_mad_u64_u32 v[48:49], s[76:77], v48, s67, v[12:13]
	v_mad_u64_u32 v[50:51], s[76:77], v50, s67, v[12:13]
	v_mad_u64_u32 v[52:53], s[76:77], v52, s67, v[12:13]
	v_mad_u64_u32 v[54:55], s[76:77], v54, s67, v[12:13]
	global_load_dword v15, v[26:27], off
	global_load_dword v16, v[28:29], off
	global_load_dword v56, v[38:39], off
	global_load_dword v57, v[34:35], off
	global_load_dword v58, v[30:31], off
	global_load_dword v59, v[24:25], off
	global_load_dword v60, v[36:37], off
	global_load_dword v61, v[32:33], off
	global_load_dword v62, v[42:43], off
	global_load_dword v63, v[44:45], off
	global_load_dword v64, v[54:55], off
	global_load_dword v65, v[50:51], off
	global_load_dword v66, v[46:47], off
	global_load_dword v67, v[40:41], off
	global_load_dword v68, v[48:49], off
	global_load_dword v69, v[52:53], off
	v_or_b32_e32 v26, s61, v1
	v_or_b32_e32 v24, s75, v2
	v_mad_u64_u32 v[24:25], s[76:77], v24, s66, v[4:5]
	v_mad_u64_u32 v[26:27], s[76:77], v26, s66, v[4:5]
	s_add_i32 s1, s1, 16
	s_add_i32 s0, s0, 16
	s_add_i32 s60, s60, -16
	v_or_b32_e32 v25, s78, v1
	v_or_b32_e32 v27, s79, v2
	v_or_b32_e32 v34, s80, v1
	v_or_b32_e32 v32, s81, v2
	v_or_b32_e32 v38, s82, v1
	v_or_b32_e32 v36, s83, v2
	v_or_b32_e32 v42, s84, v1
	v_or_b32_e32 v40, s85, v2
	v_or_b32_e32 v46, s86, v1
	v_or_b32_e32 v44, s87, v2
	v_or_b32_e32 v50, s88, v1
	v_or_b32_e32 v48, s89, v2
	v_or_b32_e32 v54, s90, v1
	v_or_b32_e32 v52, s91, v2
	s_cmp_lg_u32 s60, 0
	v_mad_u64_u32 v[28:29], s[76:77], v27, s66, v[4:5]
	v_mad_u64_u32 v[30:31], s[76:77], v25, s66, v[4:5]
	v_mad_u64_u32 v[32:33], s[76:77], v32, s66, v[4:5]
	v_mad_u64_u32 v[34:35], s[76:77], v34, s66, v[4:5]
	v_mad_u64_u32 v[36:37], s[76:77], v36, s66, v[4:5]
	v_mad_u64_u32 v[38:39], s[76:77], v38, s66, v[4:5]
	v_mad_u64_u32 v[40:41], s[76:77], v40, s66, v[4:5]
	v_mad_u64_u32 v[42:43], s[76:77], v42, s66, v[4:5]
	v_mad_u64_u32 v[44:45], s[76:77], v44, s66, v[4:5]
	v_mad_u64_u32 v[46:47], s[76:77], v46, s66, v[4:5]
	v_mad_u64_u32 v[48:49], s[76:77], v48, s66, v[4:5]
	v_mad_u64_u32 v[50:51], s[76:77], v50, s66, v[4:5]
	v_mad_u64_u32 v[52:53], s[76:77], v52, s66, v[4:5]
	v_mad_u64_u32 v[54:55], s[76:77], v54, s66, v[4:5]
	s_waitcnt vmcnt(15)
	v_cndmask_b32_e32 v15, 0, v15, vcc
	s_waitcnt vmcnt(14)
	v_cndmask_b32_e32 v16, 0, v16, vcc
	s_waitcnt vmcnt(13)
	v_cndmask_b32_e32 v33, 0, v56, vcc
	s_waitcnt vmcnt(12)
	v_cndmask_b32_e32 v29, 0, v57, vcc
	s_waitcnt vmcnt(11)
	v_cndmask_b32_e32 v27, 0, v58, vcc
	s_waitcnt vmcnt(10)
	v_cndmask_b32_e32 v25, 0, v59, vcc
	s_waitcnt vmcnt(9)
	v_cndmask_b32_e32 v35, 0, v60, vcc
	s_waitcnt vmcnt(8)
	v_cndmask_b32_e32 v31, 0, v61, vcc
	s_waitcnt vmcnt(7)
	v_cndmask_b32_e32 v37, 0, v62, vcc
	s_waitcnt vmcnt(6)
	v_cndmask_b32_e32 v43, 0, v63, vcc
	s_waitcnt vmcnt(5)
	v_cndmask_b32_e32 v49, 0, v64, vcc
	s_waitcnt vmcnt(4)
	v_cndmask_b32_e32 v45, 0, v65, vcc
	s_waitcnt vmcnt(3)
	v_cndmask_b32_e32 v41, 0, v66, vcc
	s_waitcnt vmcnt(2)
	v_cndmask_b32_e32 v39, 0, v67, vcc
	s_waitcnt vmcnt(1)
	v_cndmask_b32_e32 v47, 0, v68, vcc
	s_waitcnt vmcnt(0)
	v_cndmask_b32_e32 v51, 0, v69, vcc
	ds_write_b32 v24, v25
	ds_write_b32 v26, v15
	ds_write_b32 v28, v16
	ds_write_b32 v30, v27
	ds_write_b32 v32, v31
	ds_write_b32 v34, v29
	ds_write_b32 v36, v35
	ds_write_b32 v38, v33
	ds_write_b32 v40, v39
	ds_write_b32 v42, v37
	ds_write_b32 v44, v43
	ds_write_b32 v46, v41
	ds_write_b32 v48, v47
	ds_write_b32 v50, v45
	ds_write_b32 v52, v51
	ds_write_b32 v54, v49
	s_cbranch_scc1 .LBB0_29
; #define LAS __attribute__((address_space(3)))
; __device__ __forceinline__ unsigned cvtpk(float lo, float hi) { f32x2_t v = {lo, hi}; bf16x2_t b = __builtin_convertvector(v, bf16x2_t); return __builtin_bit_cast(unsigned, b); }
; __device__ __forceinline__ void tr_item(const float* W, int K, int N, int nblk, bf16_t* WT, LAS float* scr, int item, int lane, bool qperm) {
;     ...
;     asm volatile("s_waitcnt lgkmcnt(0)" ::: "memory");
;     const int c = lane & 7;
; #pragma unroll
;     for (int j = 0; j < 4; ++j) { const int n = (lane >> 3) + 8 * j; const LAS float* s = scr + (8 * c) * 33 + n;
;         u32x4 o; o.x = cvtpk(s[0 * 33], s[1 * 33]); o.y = cvtpk(s[2 * 33], s[3 * 33]); o.z = cvtpk(s[4 * 33], s[5 * 33]); o.w = cvtpk(s[6 * 33], s[7 * 33]);
;         *(u32x4*)(WT + (size_t)(n0 + n) * K + k0 + 8 * c) = o; }
;     asm volatile("s_waitcnt lgkmcnt(0)" ::: "memory");
	s_waitcnt lgkmcnt(0)
	ds_read2_b32 v[24:25], v19 offset0:33 offset1:41
	ds_read2_b32 v[26:27], v19 offset1:8
	ds_read2_b32 v[28:29], v19 offset0:66 offset1:74
	ds_read2_b32 v[30:31], v19 offset0:99 offset1:107
	ds_read2_b32 v[32:33], v19 offset0:132 offset1:140
	ds_read2_b32 v[34:35], v19 offset0:165 offset1:173
	ds_read2_b32 v[36:37], v19 offset0:198 offset1:206
	ds_read2_b32 v[38:39], v19 offset0:231 offset1:239
	v_mul_hi_i32_i24_e32 v13, 0x120000, v10
	v_mul_i32_i24_e32 v12, 0x120000, v10
	v_lshl_add_u64 v[12:13], s[24:25], 0, v[12:13]
	v_lshlrev_b32_e32 v8, 1, v14
	v_lshl_add_u64 v[12:13], v[12:13], 0, v[8:9]
	v_lshlrev_b32_e32 v8, 1, v6
	v_lshl_add_u64 v[40:41], v[12:13], 0, v[8:9]
	v_or_b32_e32 v3, v11, v18
	s_waitcnt lgkmcnt(6)
	v_cvt_pk_bf16_f32 v12, v26, v24
	s_waitcnt lgkmcnt(4)
	v_cvt_pk_bf16_f32 v13, v28, v30
	s_waitcnt lgkmcnt(2)
	v_cvt_pk_bf16_f32 v14, v32, v34
	s_waitcnt lgkmcnt(0)
	v_cvt_pk_bf16_f32 v15, v36, v38
	v_mad_i64_i32 v[42:43], s[0:1], v3, s68, v[40:41]
	global_store_dwordx4 v[42:43], v[12:15], off sc0 sc1
	v_or_b32_e32 v3, v11, v20
	v_readlane_b32 s84, v254, 7
	v_cvt_pk_bf16_f32 v12, v27, v25
	v_cvt_pk_bf16_f32 v13, v29, v31
	v_cvt_pk_bf16_f32 v14, v33, v35
	v_cvt_pk_bf16_f32 v15, v37, v39
	ds_read2_b32 v[26:27], v19 offset0:49 offset1:57
	ds_read2_b32 v[28:29], v19 offset0:16 offset1:24
	ds_read2_b32 v[30:31], v19 offset0:82 offset1:90
	ds_read2_b32 v[32:33], v19 offset0:115 offset1:123
	ds_read2_b32 v[34:35], v19 offset0:148 offset1:156
	ds_read2_b32 v[36:37], v19 offset0:181 offset1:189
	ds_read2_b32 v[38:39], v19 offset0:214 offset1:222
	ds_read2_b32 v[42:43], v19 offset0:247 offset1:255
	v_mad_i64_i32 v[24:25], s[0:1], v3, s68, v[40:41]
	v_or_b32_e32 v3, v11, v21
	global_store_dwordx4 v[24:25], v[12:15], off sc0 sc1
	v_mad_i64_i32 v[24:25], s[0:1], v3, s68, v[40:41]
	s_waitcnt lgkmcnt(6)
	v_cvt_pk_bf16_f32 v12, v28, v26
	s_waitcnt lgkmcnt(4)
	v_cvt_pk_bf16_f32 v13, v30, v32
	s_waitcnt lgkmcnt(2)
	v_cvt_pk_bf16_f32 v14, v34, v36
	s_waitcnt lgkmcnt(0)
	v_cvt_pk_bf16_f32 v15, v38, v42
	v_or_b32_e32 v3, v11, v22
	global_store_dwordx4 v[24:25], v[12:15], off sc0 sc1
	v_mad_i64_i32 v[10:11], s[0:1], v3, s68, v[40:41]
	s_nop 0
	v_cvt_pk_bf16_f32 v12, v29, v27
	v_cvt_pk_bf16_f32 v13, v31, v33
	v_cvt_pk_bf16_f32 v14, v35, v37
	v_cvt_pk_bf16_f32 v15, v39, v43
	global_store_dwordx4 v[10:11], v[12:15], off sc0 sc1
	s_waitcnt lgkmcnt(0)
	v_readlane_b32 s75, v254, 6
	v_readlane_b32 s85, v254, 8

; __device__ __forceinline__ int qperm_src(int n) { const int hh = n / 96, d = n - hh * 96; if (d < 64) return n; const int j = d - 64; return hh * 96 + 64 + ((j & 1) ? 16 + (j >> 1) : (j >> 1)); }
; __device__ __forceinline__ void tr_item(const float* W, int K, int N, int nblk, bf16_t* WT, LAS float* scr, int item, int lane, bool qperm) {
;     ...
;     const int nn = n0 + (lane & 31); const bool ok = nn < N; const int src = qperm ? qperm_src(ok ? nn : 0) : (ok ? nn : 0);
; #pragma unroll 8
;     for (int i = 0; i < 32; ++i) { const int kk = 2 * i + (lane >> 5); const float v = W[(size_t)(k0 + kk) * N + src]; scr[kk * 33 + (lane & 31)] = ok ? v : 0.f; }
.LBB0_34:
	s_lshl_b32 s59, s39, 1
	s_lshl_b32 s60, s38, 1
	v_or_b32_e32 v15, s59, v3
	v_or_b32_e32 v16, s60, v8
	s_add_i32 s75, s59, 4
	s_add_i32 s78, s60, 4
	s_add_i32 s79, s59, 8
	s_add_i32 s80, s60, 8
	s_add_i32 s81, s59, 12
	s_add_i32 s82, s60, 12
	s_add_i32 s83, s59, 16
	s_add_i32 s84, s60, 16
	s_add_i32 s85, s59, 20
	s_add_i32 s86, s60, 20
	s_add_i32 s87, s59, 24
	s_add_i32 s88, s60, 24
	s_add_i32 s89, s59, 28
	s_add_i32 s90, s60, 28
	v_mad_u64_u32 v[24:25], s[76:77], v16, s69, v[12:13]
	v_mad_u64_u32 v[26:27], s[76:77], v15, s69, v[12:13]
	v_or_b32_e32 v15, s75, v3
	v_or_b32_e32 v16, s78, v8
	v_or_b32_e32 v34, s79, v3
	v_or_b32_e32 v32, s80, v8
	v_or_b32_e32 v38, s81, v3
	v_or_b32_e32 v36, s82, v8
	v_or_b32_e32 v42, s83, v3
	v_or_b32_e32 v40, s84, v8
	v_or_b32_e32 v46, s85, v3
	v_or_b32_e32 v44, s86, v8
	v_or_b32_e32 v50, s87, v3
	v_or_b32_e32 v48, s88, v8
	v_or_b32_e32 v54, s89, v3
	v_or_b32_e32 v52, s90, v8
	v_mad_u64_u32 v[28:29], s[76:77], v16, s69, v[12:13]
	v_mad_u64_u32 v[30:31], s[76:77], v15, s69, v[12:13]
	v_mad_u64_u32 v[32:33], s[76:77], v32, s69, v[12:13]
	v_mad_u64_u32 v[34:35], s[76:77], v34, s69, v[12:13]
	v_mad_u64_u32 v[36:37], s[76:77], v36, s69, v[12:13]
	v_mad_u64_u32 v[38:39], s[76:77], v38, s69, v[12:13]
	v_mad_u64_u32 v[40:41], s[76:77], v40, s69, v[12:13]
	v_mad_u64_u32 v[42:43], s[76:77], v42, s69, v[12:13]
	v_mad_u64_u32 v[44:45], s[76:77], v44, s69, v[12:13]
	v_mad_u64_u32 v[46:47], s[76:77], v46, s69, v[12:13]
	v_mad_u64_u32 v[48:49], s[76:77], v48, s69, v[12:13]
	v_mad_u64_u32 v[50:51], s[76:77], v50, s69, v[12:13]
	v_mad_u64_u32 v[52:53], s[76:77], v52, s69, v[12:13]
	v_mad_u64_u32 v[54:55], s[76:77], v54, s69, v[12:13]
	global_load_dword v15, v[26:27], off
	global_load_dword v16, v[28:29], off
	global_load_dword v56, v[38:39], off
	global_load_dword v57, v[34:35], off
	global_load_dword v58, v[30:31], off
	global_load_dword v59, v[24:25], off
	global_load_dword v60, v[36:37], off
	global_load_dword v61, v[32:33], off
	global_load_dword v62, v[42:43], off
	global_load_dword v63, v[44:45], off
	global_load_dword v64, v[54:55], off
	global_load_dword v65, v[50:51], off
	global_load_dword v66, v[46:47], off
	global_load_dword v67, v[40:41], off
	global_load_dword v68, v[48:49], off
	global_load_dword v69, v[52:53], off
	v_or_b32_e32 v26, s59, v1
	v_or_b32_e32 v24, s60, v2
	v_mad_u64_u32 v[24:25], s[60:61], v24, s66, v[4:5]
	v_mad_u64_u32 v[26:27], s[60:61], v26, s66, v[4:5]
	s_add_i32 s38, s38, 16
	s_add_i32 s39, s39, 16
	s_add_i32 s58, s58, -16
	v_or_b32_e32 v25, s75, v1
	v_or_b32_e32 v27, s78, v2
	v_or_b32_e32 v34, s79, v1
	v_or_b32_e32 v32, s80, v2
	v_or_b32_e32 v38, s81, v1
	v_or_b32_e32 v36, s82, v2
	v_or_b32_e32 v42, s83, v1
	v_or_b32_e32 v40, s84, v2
	v_or_b32_e32 v46, s85, v1
	v_or_b32_e32 v44, s86, v2
	v_or_b32_e32 v50, s87, v1
	v_or_b32_e32 v48, s88, v2
	v_or_b32_e32 v54, s89, v1
	v_or_b32_e32 v52, s90, v2
	s_cmp_lg_u32 s58, 0
	v_mad_u64_u32 v[28:29], s[60:61], v27, s66, v[4:5]
	v_mad_u64_u32 v[30:31], s[60:61], v25, s66, v[4:5]
	v_mad_u64_u32 v[32:33], s[60:61], v32, s66, v[4:5]
	v_mad_u64_u32 v[34:35], s[60:61], v34, s66, v[4:5]
	v_mad_u64_u32 v[36:37], s[60:61], v36, s66, v[4:5]
	v_mad_u64_u32 v[38:39], s[60:61], v38, s66, v[4:5]
	v_mad_u64_u32 v[40:41], s[60:61], v40, s66, v[4:5]
	v_mad_u64_u32 v[42:43], s[60:61], v42, s66, v[4:5]
	v_mad_u64_u32 v[44:45], s[60:61], v44, s66, v[4:5]
	v_mad_u64_u32 v[46:47], s[60:61], v46, s66, v[4:5]
	v_mad_u64_u32 v[48:49], s[60:61], v48, s66, v[4:5]
	v_mad_u64_u32 v[50:51], s[60:61], v50, s66, v[4:5]
	v_mad_u64_u32 v[52:53], s[60:61], v52, s66, v[4:5]
	v_mad_u64_u32 v[54:55], s[60:61], v54, s66, v[4:5]
	s_waitcnt vmcnt(15)
	v_cndmask_b32_e32 v15, 0, v15, vcc
	s_waitcnt vmcnt(14)
	v_cndmask_b32_e32 v16, 0, v16, vcc
	s_waitcnt vmcnt(13)
	v_cndmask_b32_e32 v33, 0, v56, vcc
	s_waitcnt vmcnt(12)
	v_cndmask_b32_e32 v29, 0, v57, vcc
	s_waitcnt vmcnt(11)
	v_cndmask_b32_e32 v27, 0, v58, vcc
	s_waitcnt vmcnt(10)
	v_cndmask_b32_e32 v25, 0, v59, vcc
	s_waitcnt vmcnt(9)
	v_cndmask_b32_e32 v35, 0, v60, vcc
	s_waitcnt vmcnt(8)
	v_cndmask_b32_e32 v31, 0, v61, vcc
	s_waitcnt vmcnt(7)
	v_cndmask_b32_e32 v37, 0, v62, vcc
	s_waitcnt vmcnt(6)
	v_cndmask_b32_e32 v43, 0, v63, vcc
	s_waitcnt vmcnt(5)
	v_cndmask_b32_e32 v49, 0, v64, vcc
	s_waitcnt vmcnt(4)
	v_cndmask_b32_e32 v45, 0, v65, vcc
	s_waitcnt vmcnt(3)
	v_cndmask_b32_e32 v41, 0, v66, vcc
	s_waitcnt vmcnt(2)
	v_cndmask_b32_e32 v39, 0, v67, vcc
	s_waitcnt vmcnt(1)
	v_cndmask_b32_e32 v47, 0, v68, vcc
	s_waitcnt vmcnt(0)
	v_cndmask_b32_e32 v51, 0, v69, vcc
	ds_write_b32 v24, v25
	ds_write_b32 v26, v15
	ds_write_b32 v28, v16
	ds_write_b32 v30, v27
	ds_write_b32 v32, v31
	ds_write_b32 v34, v29
	ds_write_b32 v36, v35
	ds_write_b32 v38, v33
	ds_write_b32 v40, v39
	ds_write_b32 v42, v37
	ds_write_b32 v44, v43
	ds_write_b32 v46, v41
	ds_write_b32 v48, v47
	ds_write_b32 v50, v45
	ds_write_b32 v52, v51
	ds_write_b32 v54, v49
	s_cbranch_scc1 .LBB0_34
; #define LAS __attribute__((address_space(3)))
; __device__ __forceinline__ unsigned cvtpk(float lo, float hi) { f32x2_t v = {lo, hi}; bf16x2_t b = __builtin_convertvector(v, bf16x2_t); return __builtin_bit_cast(unsigned, b); }
; __device__ __forceinline__ void tr_item(const float* W, int K, int N, int nblk, bf16_t* WT, LAS float* scr, int item, int lane, bool qperm) {
;     ...
;     asm volatile("s_waitcnt lgkmcnt(0)" ::: "memory");
;     const int c = lane & 7;
; #pragma unroll
;     for (int j = 0; j < 4; ++j) { const int n = (lane >> 3) + 8 * j; const LAS float* s = scr + (8 * c) * 33 + n;
;         u32x4 o; o.x = cvtpk(s[0 * 33], s[1 * 33]); o.y = cvtpk(s[2 * 33], s[3 * 33]); o.z = cvtpk(s[4 * 33], s[5 * 33]); o.w = cvtpk(s[6 * 33], s[7 * 33]);
;         *(u32x4*)(WT + (size_t)(n0 + n) * K + k0 + 8 * c) = o; }
;     asm volatile("s_waitcnt lgkmcnt(0)" ::: "memory");
	s_waitcnt lgkmcnt(0)
	ds_read2_b32 v[24:25], v19 offset0:33 offset1:41
	ds_read2_b32 v[26:27], v19 offset1:8
	ds_read2_b32 v[28:29], v19 offset0:66 offset1:74
	ds_read2_b32 v[30:31], v19 offset0:99 offset1:107
	ds_read2_b32 v[32:33], v19 offset0:132 offset1:140
	ds_read2_b32 v[34:35], v19 offset0:165 offset1:173
	ds_read2_b32 v[36:37], v19 offset0:198 offset1:206
	ds_read2_b32 v[38:39], v19 offset0:231 offset1:239
	v_mul_hi_i32_i24_e32 v13, 0x380000, v10
	v_mul_i32_i24_e32 v12, 0x380000, v10
	v_lshl_add_u64 v[12:13], s[26:27], 0, v[12:13]
	v_lshlrev_b32_e32 v8, 1, v14
	v_or_b32_e32 v42, v11, v18
	v_lshl_add_u64 v[12:13], v[12:13], 0, v[8:9]
	v_lshlrev_b32_e32 v8, 1, v6
	v_ashrrev_i32_e32 v43, 31, v42
	v_lshl_add_u64 v[40:41], v[12:13], 0, v[8:9]
	v_lshlrev_b64 v[42:43], 11, v[42:43]
	s_waitcnt lgkmcnt(6)
	v_cvt_pk_bf16_f32 v12, v26, v24
	s_waitcnt lgkmcnt(4)
	v_cvt_pk_bf16_f32 v13, v28, v30
	s_waitcnt lgkmcnt(2)
	v_cvt_pk_bf16_f32 v14, v32, v34
	s_waitcnt lgkmcnt(0)
	v_cvt_pk_bf16_f32 v15, v36, v38
	v_lshl_add_u64 v[42:43], v[40:41], 0, v[42:43]
	v_or_b32_e32 v24, v11, v20
	global_store_dwordx4 v[42:43], v[12:15], off sc0 sc1
	v_or_b32_e32 v10, v11, v22
	v_readlane_b32 s84, v254, 7
	v_cvt_pk_bf16_f32 v12, v27, v25
	v_ashrrev_i32_e32 v25, 31, v24
	v_cvt_pk_bf16_f32 v13, v29, v31
	v_cvt_pk_bf16_f32 v14, v33, v35
	v_cvt_pk_bf16_f32 v15, v37, v39
	v_lshlrev_b64 v[24:25], 11, v[24:25]
	ds_read2_b32 v[26:27], v19 offset0:49 offset1:57
	ds_read2_b32 v[28:29], v19 offset0:16 offset1:24
	ds_read2_b32 v[30:31], v19 offset0:82 offset1:90
	ds_read2_b32 v[32:33], v19 offset0:115 offset1:123
	ds_read2_b32 v[34:35], v19 offset0:148 offset1:156
	ds_read2_b32 v[36:37], v19 offset0:181 offset1:189
	ds_read2_b32 v[38:39], v19 offset0:214 offset1:222
	ds_read2_b32 v[42:43], v19 offset0:247 offset1:255
	v_lshl_add_u64 v[24:25], v[40:41], 0, v[24:25]
	global_store_dwordx4 v[24:25], v[12:15], off sc0 sc1
	v_or_b32_e32 v24, v11, v21
	v_ashrrev_i32_e32 v25, 31, v24
	v_lshlrev_b64 v[24:25], 11, v[24:25]
	v_ashrrev_i32_e32 v11, 31, v10
	s_waitcnt lgkmcnt(6)
	v_cvt_pk_bf16_f32 v12, v28, v26
	s_waitcnt lgkmcnt(4)
	v_cvt_pk_bf16_f32 v13, v30, v32
	s_waitcnt lgkmcnt(2)
	v_cvt_pk_bf16_f32 v14, v34, v36
	s_waitcnt lgkmcnt(0)
	v_cvt_pk_bf16_f32 v15, v38, v42
	v_lshl_add_u64 v[24:25], v[40:41], 0, v[24:25]
	v_lshlrev_b64 v[10:11], 11, v[10:11]
	global_store_dwordx4 v[24:25], v[12:15], off sc0 sc1
	v_lshl_add_u64 v[10:11], v[40:41], 0, v[10:11]
	v_readlane_b32 s75, v254, 6
	v_cvt_pk_bf16_f32 v12, v29, v27
	v_cvt_pk_bf16_f32 v13, v31, v33
	v_cvt_pk_bf16_f32 v14, v35, v37
	v_cvt_pk_bf16_f32 v15, v39, v43
	global_store_dwordx4 v[10:11], v[12:15], off sc0 sc1
	s_waitcnt lgkmcnt(0)
	v_readlane_b32 s85, v254, 8

; __device__ __forceinline__ int qperm_src(int n) { const int hh = n / 96, d = n - hh * 96; if (d < 64) return n; const int j = d - 64; return hh * 96 + 64 + ((j & 1) ? 16 + (j >> 1) : (j >> 1)); }
; __device__ __forceinline__ void tr_item(const float* W, int K, int N, int nblk, bf16_t* WT, LAS float* scr, int item, int lane, bool qperm) {
;     ...
;     const int nn = n0 + (lane & 31); const bool ok = nn < N; const int src = qperm ? qperm_src(ok ? nn : 0) : (ok ? nn : 0);
; #pragma unroll 8
;     for (int i = 0; i < 32; ++i) { const int kk = 2 * i + (lane >> 5); const float v = W[(size_t)(k0 + kk) * N + src]; scr[kk * 33 + (lane & 31)] = ok ? v : 0.f; }
.LBB0_39:
	s_lshl_b32 s39, s37, 1
	s_lshl_b32 s58, s36, 1
	v_mov_b32_e32 v25, v9
	v_or_b32_e32 v24, s39, v3
	v_or_b32_e32 v8, s58, v14
	s_add_i32 s61, s58, 4
	s_add_i32 s60, s39, 4
	s_add_i32 s75, s39, 8
	s_add_i32 s76, s58, 8
	v_lshlrev_b64 v[24:25], 12, v[24:25]
	v_lshlrev_b64 v[40:41], 12, v[8:9]
	v_or_b32_e32 v8, s61, v14
	v_mov_b32_e32 v27, v9
	v_mov_b32_e32 v29, v9
	s_add_i32 s77, s39, 12
	s_add_i32 s78, s58, 12
	s_add_i32 s79, s39, 16
	v_or_b32_e32 v26, s60, v3
	v_or_b32_e32 v28, s75, v3
	v_lshl_add_u64 v[24:25], v[10:11], 0, v[24:25]
	v_lshlrev_b64 v[42:43], 12, v[8:9]
	v_or_b32_e32 v8, s76, v14
	v_mov_b32_e32 v31, v9
	v_mov_b32_e32 v33, v9
	s_add_i32 s80, s58, 16
	s_add_i32 s81, s39, 20
	s_add_i32 s83, s39, 24
	s_add_i32 s85, s39, 28
	v_or_b32_e32 v30, s77, v3
	v_or_b32_e32 v32, s79, v3
	v_lshlrev_b64 v[26:27], 12, v[26:27]
	v_lshlrev_b64 v[28:29], 12, v[28:29]
	global_load_dword v56, v[24:25], off
	v_lshl_add_u64 v[24:25], v[10:11], 0, v[42:43]
	v_lshlrev_b64 v[42:43], 12, v[8:9]
	v_or_b32_e32 v8, s78, v14
	v_mov_b32_e32 v35, v9
	v_mov_b32_e32 v37, v9
	v_mov_b32_e32 v39, v9
	s_add_i32 s82, s58, 20
	v_or_b32_e32 v34, s81, v3
	v_or_b32_e32 v36, s83, v3
	v_or_b32_e32 v38, s85, v3
	v_lshlrev_b64 v[30:31], 12, v[30:31]
	v_lshlrev_b64 v[32:33], 12, v[32:33]
	v_lshl_add_u64 v[26:27], v[10:11], 0, v[26:27]
	v_lshl_add_u64 v[28:29], v[10:11], 0, v[28:29]
	v_lshlrev_b64 v[44:45], 12, v[8:9]
	v_or_b32_e32 v8, s80, v14
	s_add_i32 s84, s58, 24
	v_lshlrev_b64 v[34:35], 12, v[34:35]
	v_lshlrev_b64 v[36:37], 12, v[36:37]
	v_lshlrev_b64 v[38:39], 12, v[38:39]
	v_lshl_add_u64 v[30:31], v[10:11], 0, v[30:31]
	v_lshl_add_u64 v[32:33], v[10:11], 0, v[32:33]
	global_load_dword v57, v[26:27], off
	global_load_dword v58, v[28:29], off
	global_load_dword v59, v[30:31], off
	v_lshl_add_u64 v[26:27], v[10:11], 0, v[44:45]
	v_lshlrev_b64 v[28:29], 12, v[8:9]
	v_or_b32_e32 v8, s82, v14
	s_add_i32 s86, s58, 28
	v_lshl_add_u64 v[40:41], v[10:11], 0, v[40:41]
	v_lshl_add_u64 v[34:35], v[10:11], 0, v[34:35]
	v_lshl_add_u64 v[36:37], v[10:11], 0, v[36:37]
	v_lshl_add_u64 v[38:39], v[10:11], 0, v[38:39]
	v_lshl_add_u64 v[42:43], v[10:11], 0, v[42:43]
	global_load_dword v60, v[32:33], off
	global_load_dword v61, v[34:35], off
	global_load_dword v62, v[36:37], off
	global_load_dword v63, v[38:39], off
	global_load_dword v64, v[26:27], off
	global_load_dword v65, v[42:43], off
	global_load_dword v66, v[24:25], off
	global_load_dword v67, v[40:41], off
	v_lshlrev_b64 v[26:27], 12, v[8:9]
	v_or_b32_e32 v8, s84, v14
	v_lshl_add_u64 v[24:25], v[10:11], 0, v[28:29]
	v_lshlrev_b64 v[28:29], 12, v[8:9]
	v_or_b32_e32 v8, s86, v14
	v_lshlrev_b64 v[30:31], 12, v[8:9]
	v_lshl_add_u64 v[30:31], v[10:11], 0, v[30:31]
	v_lshl_add_u64 v[26:27], v[10:11], 0, v[26:27]
	v_lshl_add_u64 v[28:29], v[10:11], 0, v[28:29]
	global_load_dword v8, v[30:31], off
	global_load_dword v68, v[28:29], off
	global_load_dword v69, v[26:27], off
	global_load_dword v70, v[24:25], off
	v_or_b32_e32 v26, s39, v1
	v_or_b32_e32 v24, s58, v2
	v_mad_u64_u32 v[24:25], s[58:59], v24, s66, v[4:5]
	v_mad_u64_u32 v[26:27], s[58:59], v26, s66, v[4:5]
	v_or_b32_e32 v40, s80, v2
	v_or_b32_e32 v25, s60, v1
	v_or_b32_e32 v27, s61, v2
	v_or_b32_e32 v42, s79, v1
	v_or_b32_e32 v46, s81, v1
	v_or_b32_e32 v44, s82, v2
	v_mad_u64_u32 v[40:41], s[58:59], v40, s66, v[4:5]
	s_add_i32 s36, s36, 16
	s_add_i32 s37, s37, 16
	s_add_i32 s38, s38, -16
	v_or_b32_e32 v34, s75, v1
	v_or_b32_e32 v32, s76, v2
	v_or_b32_e32 v38, s77, v1
	v_or_b32_e32 v36, s78, v2
	v_mad_u64_u32 v[28:29], s[58:59], v27, s66, v[4:5]
	v_mad_u64_u32 v[30:31], s[58:59], v25, s66, v[4:5]
	v_mad_u64_u32 v[42:43], s[58:59], v42, s66, v[4:5]
	v_mad_u64_u32 v[44:45], s[58:59], v44, s66, v[4:5]
	v_mad_u64_u32 v[46:47], s[58:59], v46, s66, v[4:5]
	v_or_b32_e32 v50, s83, v1
	v_or_b32_e32 v48, s84, v2
	v_or_b32_e32 v54, s85, v1
	v_or_b32_e32 v52, s86, v2
	s_cmp_lg_u32 s38, 0
	v_mad_u64_u32 v[32:33], s[58:59], v32, s66, v[4:5]
	v_mad_u64_u32 v[34:35], s[58:59], v34, s66, v[4:5]
	v_mad_u64_u32 v[36:37], s[58:59], v36, s66, v[4:5]
	v_mad_u64_u32 v[38:39], s[58:59], v38, s66, v[4:5]
	s_waitcnt vmcnt(15)
	v_cndmask_b32_e32 v25, 0, v56, vcc
	v_mad_u64_u32 v[48:49], s[58:59], v48, s66, v[4:5]
	v_mad_u64_u32 v[50:51], s[58:59], v50, s66, v[4:5]
	v_mad_u64_u32 v[52:53], s[58:59], v52, s66, v[4:5]
	v_mad_u64_u32 v[54:55], s[58:59], v54, s66, v[4:5]
	s_waitcnt vmcnt(14)
	v_cndmask_b32_e32 v27, 0, v57, vcc
	s_waitcnt vmcnt(13)
	v_cndmask_b32_e32 v29, 0, v58, vcc
	s_waitcnt vmcnt(12)
	v_cndmask_b32_e32 v31, 0, v59, vcc
	s_waitcnt vmcnt(11)
	v_cndmask_b32_e32 v33, 0, v60, vcc
	s_waitcnt vmcnt(7)
	v_cndmask_b32_e32 v47, 0, v64, vcc
	s_waitcnt vmcnt(6)
	v_cndmask_b32_e32 v45, 0, v65, vcc
	s_waitcnt vmcnt(5)
	v_cndmask_b32_e32 v43, 0, v66, vcc
	s_waitcnt vmcnt(4)
	v_cndmask_b32_e32 v41, 0, v67, vcc
	ds_write_b32 v24, v41
	ds_write_b32 v26, v25
	ds_write_b32 v28, v43
	ds_write_b32 v30, v27
	ds_write_b32 v32, v45
	ds_write_b32 v34, v29
	ds_write_b32 v36, v47
	ds_write_b32 v38, v31
	v_cndmask_b32_e32 v35, 0, v61, vcc
	v_cndmask_b32_e32 v37, 0, v62, vcc
	v_cndmask_b32_e32 v39, 0, v63, vcc
	s_waitcnt vmcnt(3)
	v_cndmask_b32_e32 v8, 0, v8, vcc
	s_waitcnt vmcnt(2)
	v_cndmask_b32_e32 v26, 0, v68, vcc
	s_waitcnt vmcnt(1)
	v_cndmask_b32_e32 v25, 0, v69, vcc
	s_waitcnt vmcnt(0)
	v_cndmask_b32_e32 v24, 0, v70, vcc
	ds_write_b32 v40, v24
	ds_write_b32 v42, v33
	ds_write_b32 v44, v25
	ds_write_b32 v46, v35
	ds_write_b32 v48, v26
	ds_write_b32 v50, v37
	ds_write_b32 v52, v8
	ds_write_b32 v54, v39
	s_cbranch_scc1 .LBB0_39
; #define LAS __attribute__((address_space(3)))
; __device__ __forceinline__ unsigned cvtpk(float lo, float hi) { f32x2_t v = {lo, hi}; bf16x2_t b = __builtin_convertvector(v, bf16x2_t); return __builtin_bit_cast(unsigned, b); }
; __device__ __forceinline__ void tr_item(const float* W, int K, int N, int nblk, bf16_t* WT, LAS float* scr, int item, int lane, bool qperm) {
;     ...
;     asm volatile("s_waitcnt lgkmcnt(0)" ::: "memory");
;     const int c = lane & 7;
; #pragma unroll
;     for (int j = 0; j < 4; ++j) { const int n = (lane >> 3) + 8 * j; const LAS float* s = scr + (8 * c) * 33 + n;
;         u32x4 o; o.x = cvtpk(s[0 * 33], s[1 * 33]); o.y = cvtpk(s[2 * 33], s[3 * 33]); o.z = cvtpk(s[4 * 33], s[5 * 33]); o.w = cvtpk(s[6 * 33], s[7 * 33]);
;         *(u32x4*)(WT + (size_t)(n0 + n) * K + k0 + 8 * c) = o; }
;     asm volatile("s_waitcnt lgkmcnt(0)" ::: "memory");
	s_waitcnt lgkmcnt(0)
	ds_read2_b32 v[24:25], v19 offset0:33 offset1:41
	ds_read2_b32 v[26:27], v19 offset1:8
	ds_read2_b32 v[28:29], v19 offset0:66 offset1:74
	ds_read2_b32 v[30:31], v19 offset0:99 offset1:107
	ds_read2_b32 v[32:33], v19 offset0:132 offset1:140
	ds_read2_b32 v[34:35], v19 offset0:165 offset1:173
	ds_read2_b32 v[36:37], v19 offset0:198 offset1:206
	ds_read2_b32 v[38:39], v19 offset0:231 offset1:239
	v_lshl_add_u64 v[10:11], v[12:13], 1, s[28:29]
	v_lshlrev_b32_e32 v8, 1, v16
	v_or_b32_e32 v42, v15, v18
	v_lshl_add_u64 v[10:11], v[10:11], 0, v[8:9]
	v_lshlrev_b32_e32 v8, 1, v6
	v_ashrrev_i32_e32 v43, 31, v42
	v_lshl_add_u64 v[40:41], v[10:11], 0, v[8:9]
	v_lshlrev_b64 v[42:43], 11, v[42:43]
	s_waitcnt lgkmcnt(6)
	v_cvt_pk_bf16_f32 v10, v26, v24
	s_waitcnt lgkmcnt(4)
	v_cvt_pk_bf16_f32 v11, v28, v30
	s_waitcnt lgkmcnt(2)
	v_cvt_pk_bf16_f32 v12, v32, v34
	s_waitcnt lgkmcnt(0)
	v_cvt_pk_bf16_f32 v13, v36, v38
	v_lshl_add_u64 v[42:43], v[40:41], 0, v[42:43]
	v_or_b32_e32 v24, v15, v20
	global_store_dwordx4 v[42:43], v[10:13], off sc0 sc1
	v_or_b32_e32 v14, v15, v22
	v_readlane_b32 s84, v254, 7
	v_cvt_pk_bf16_f32 v10, v27, v25
	v_ashrrev_i32_e32 v25, 31, v24
	v_cvt_pk_bf16_f32 v11, v29, v31
	v_cvt_pk_bf16_f32 v12, v33, v35
	v_cvt_pk_bf16_f32 v13, v37, v39
	v_lshlrev_b64 v[24:25], 11, v[24:25]
	ds_read2_b32 v[26:27], v19 offset0:49 offset1:57
	ds_read2_b32 v[28:29], v19 offset0:16 offset1:24
	ds_read2_b32 v[30:31], v19 offset0:82 offset1:90
	ds_read2_b32 v[32:33], v19 offset0:115 offset1:123
	ds_read2_b32 v[34:35], v19 offset0:148 offset1:156
	ds_read2_b32 v[36:37], v19 offset0:181 offset1:189
	ds_read2_b32 v[38:39], v19 offset0:214 offset1:222
	ds_read2_b32 v[42:43], v19 offset0:247 offset1:255
	v_lshl_add_u64 v[24:25], v[40:41], 0, v[24:25]
	global_store_dwordx4 v[24:25], v[10:13], off sc0 sc1
	v_or_b32_e32 v24, v15, v21
	v_ashrrev_i32_e32 v25, 31, v24
	v_lshlrev_b64 v[24:25], 11, v[24:25]
	v_ashrrev_i32_e32 v15, 31, v14
	s_waitcnt lgkmcnt(6)
	v_cvt_pk_bf16_f32 v10, v28, v26
	s_waitcnt lgkmcnt(4)
	v_cvt_pk_bf16_f32 v11, v30, v32
	s_waitcnt lgkmcnt(2)
	v_cvt_pk_bf16_f32 v12, v34, v36
	s_waitcnt lgkmcnt(0)
	v_cvt_pk_bf16_f32 v13, v38, v42
	v_lshl_add_u64 v[24:25], v[40:41], 0, v[24:25]
	v_lshlrev_b64 v[14:15], 11, v[14:15]
	global_store_dwordx4 v[24:25], v[10:13], off sc0 sc1
	v_lshl_add_u64 v[14:15], v[40:41], 0, v[14:15]
	v_readlane_b32 s75, v254, 6
	v_cvt_pk_bf16_f32 v10, v29, v27
	v_cvt_pk_bf16_f32 v11, v31, v33
	v_cvt_pk_bf16_f32 v12, v35, v37
	v_cvt_pk_bf16_f32 v13, v39, v43
	global_store_dwordx4 v[14:15], v[10:13], off sc0 sc1
	s_waitcnt lgkmcnt(0)
	v_readlane_b32 s85, v254, 8

; __device__ __forceinline__ int qperm_src(int n) { const int hh = n / 96, d = n - hh * 96; if (d < 64) return n; const int j = d - 64; return hh * 96 + 64 + ((j & 1) ? 16 + (j >> 1) : (j >> 1)); }
; __device__ __forceinline__ void tr_item(const float* W, int K, int N, int nblk, bf16_t* WT, LAS float* scr, int item, int lane, bool qperm) {
;     ...
;     const int nn = n0 + (lane & 31); const bool ok = nn < N; const int src = qperm ? qperm_src(ok ? nn : 0) : (ok ? nn : 0);
; #pragma unroll 8
;     for (int i = 0; i < 32; ++i) { const int kk = 2 * i + (lane >> 5); const float v = W[(size_t)(k0 + kk) * N + src]; scr[kk * 33 + (lane & 31)] = ok ? v : 0.f; }
.LBB0_44:
	s_lshl_b32 s37, s35, 1
	s_lshl_b32 s38, s34, 1
	v_or_b32_e32 v13, s37, v3
	v_or_b32_e32 v16, s38, v8
	s_add_i32 s60, s37, 4
	s_add_i32 s61, s38, 4
	s_add_i32 s75, s37, 8
	s_add_i32 s76, s38, 8
	s_add_i32 s77, s37, 12
	s_add_i32 s78, s38, 12
	s_add_i32 s79, s37, 16
	s_add_i32 s80, s38, 16
	s_add_i32 s81, s37, 20
	s_add_i32 s82, s38, 20
	s_add_i32 s83, s37, 24
	s_add_i32 s84, s38, 24
	s_add_i32 s85, s37, 28
	s_add_i32 s86, s38, 28
	v_mad_i64_i32 v[24:25], s[58:59], v16, s72, v[14:15]
	v_mad_i64_i32 v[26:27], s[58:59], v13, s72, v[14:15]
	v_or_b32_e32 v13, s60, v3
	v_or_b32_e32 v16, s61, v8
	v_or_b32_e32 v34, s75, v3
	v_or_b32_e32 v32, s76, v8
	v_or_b32_e32 v38, s77, v3
	v_or_b32_e32 v36, s78, v8
	v_or_b32_e32 v42, s79, v3
	v_or_b32_e32 v40, s80, v8
	v_or_b32_e32 v46, s81, v3
	v_or_b32_e32 v44, s82, v8
	v_or_b32_e32 v50, s83, v3
	v_or_b32_e32 v48, s84, v8
	v_or_b32_e32 v54, s85, v3
	v_or_b32_e32 v52, s86, v8
	v_mad_i64_i32 v[28:29], s[58:59], v16, s72, v[14:15]
	v_mad_i64_i32 v[30:31], s[58:59], v13, s72, v[14:15]
	v_mad_i64_i32 v[32:33], s[58:59], v32, s72, v[14:15]
	v_mad_i64_i32 v[34:35], s[58:59], v34, s72, v[14:15]
	v_mad_i64_i32 v[36:37], s[58:59], v36, s72, v[14:15]
	v_mad_i64_i32 v[38:39], s[58:59], v38, s72, v[14:15]
	v_mad_i64_i32 v[40:41], s[58:59], v40, s72, v[14:15]
	v_mad_i64_i32 v[42:43], s[58:59], v42, s72, v[14:15]
	v_mad_i64_i32 v[44:45], s[58:59], v44, s72, v[14:15]
	v_mad_i64_i32 v[46:47], s[58:59], v46, s72, v[14:15]
	v_mad_i64_i32 v[48:49], s[58:59], v48, s72, v[14:15]
	v_mad_i64_i32 v[50:51], s[58:59], v50, s72, v[14:15]
	v_mad_i64_i32 v[52:53], s[58:59], v52, s72, v[14:15]
	v_mad_i64_i32 v[54:55], s[58:59], v54, s72, v[14:15]
	global_load_dword v13, v[26:27], off
	global_load_dword v16, v[28:29], off
	global_load_dword v56, v[30:31], off
	global_load_dword v57, v[36:37], off
	global_load_dword v58, v[32:33], off
	global_load_dword v59, v[24:25], off
	global_load_dword v60, v[34:35], off
	global_load_dword v61, v[38:39], off
	global_load_dword v62, v[42:43], off
	global_load_dword v63, v[44:45], off
	global_load_dword v64, v[46:47], off
	global_load_dword v65, v[52:53], off
	global_load_dword v66, v[48:49], off
	global_load_dword v67, v[40:41], off
	global_load_dword v68, v[50:51], off
	global_load_dword v69, v[54:55], off
	v_or_b32_e32 v26, s37, v1
	v_or_b32_e32 v24, s38, v2
	v_mad_u64_u32 v[24:25], s[38:39], v24, s66, v[4:5]
	v_mad_u64_u32 v[26:27], s[38:39], v26, s66, v[4:5]
	s_add_i32 s34, s34, 16
	s_add_i32 s35, s35, 16
	s_add_i32 s36, s36, -16
	v_or_b32_e32 v25, s60, v1
	v_or_b32_e32 v27, s61, v2
	v_or_b32_e32 v34, s75, v1
	v_or_b32_e32 v32, s76, v2
	v_or_b32_e32 v38, s77, v1
	v_or_b32_e32 v36, s78, v2
	v_or_b32_e32 v42, s79, v1
	v_or_b32_e32 v40, s80, v2
	v_or_b32_e32 v46, s81, v1
	v_or_b32_e32 v44, s82, v2
	v_or_b32_e32 v50, s83, v1
	v_or_b32_e32 v48, s84, v2
	v_or_b32_e32 v54, s85, v1
	v_or_b32_e32 v52, s86, v2
	s_cmp_lg_u32 s36, 0
	v_mad_u64_u32 v[28:29], s[38:39], v27, s66, v[4:5]
	v_mad_u64_u32 v[30:31], s[38:39], v25, s66, v[4:5]
	v_mad_u64_u32 v[32:33], s[38:39], v32, s66, v[4:5]
	v_mad_u64_u32 v[34:35], s[38:39], v34, s66, v[4:5]
	v_mad_u64_u32 v[36:37], s[38:39], v36, s66, v[4:5]
	v_mad_u64_u32 v[38:39], s[38:39], v38, s66, v[4:5]
	v_mad_u64_u32 v[40:41], s[38:39], v40, s66, v[4:5]
	v_mad_u64_u32 v[42:43], s[38:39], v42, s66, v[4:5]
	v_mad_u64_u32 v[44:45], s[38:39], v44, s66, v[4:5]
	v_mad_u64_u32 v[46:47], s[38:39], v46, s66, v[4:5]
	v_mad_u64_u32 v[48:49], s[38:39], v48, s66, v[4:5]
	v_mad_u64_u32 v[50:51], s[38:39], v50, s66, v[4:5]
	v_mad_u64_u32 v[52:53], s[38:39], v52, s66, v[4:5]
	v_mad_u64_u32 v[54:55], s[38:39], v54, s66, v[4:5]
	s_waitcnt vmcnt(15)
	v_cndmask_b32_e32 v13, 0, v13, vcc
	s_waitcnt vmcnt(14)
	v_cndmask_b32_e32 v16, 0, v16, vcc
	s_waitcnt vmcnt(13)
	v_cndmask_b32_e32 v27, 0, v56, vcc
	s_waitcnt vmcnt(12)
	v_cndmask_b32_e32 v35, 0, v57, vcc
	s_waitcnt vmcnt(11)
	v_cndmask_b32_e32 v31, 0, v58, vcc
	s_waitcnt vmcnt(10)
	v_cndmask_b32_e32 v25, 0, v59, vcc
	s_waitcnt vmcnt(9)
	v_cndmask_b32_e32 v29, 0, v60, vcc
	s_waitcnt vmcnt(8)
	v_cndmask_b32_e32 v33, 0, v61, vcc
	s_waitcnt vmcnt(7)
	v_cndmask_b32_e32 v37, 0, v62, vcc
	s_waitcnt vmcnt(6)
	v_cndmask_b32_e32 v43, 0, v63, vcc
	s_waitcnt vmcnt(5)
	v_cndmask_b32_e32 v41, 0, v64, vcc
	s_waitcnt vmcnt(4)
	v_cndmask_b32_e32 v51, 0, v65, vcc
	s_waitcnt vmcnt(3)
	v_cndmask_b32_e32 v47, 0, v66, vcc
	s_waitcnt vmcnt(2)
	v_cndmask_b32_e32 v39, 0, v67, vcc
	s_waitcnt vmcnt(1)
	v_cndmask_b32_e32 v45, 0, v68, vcc
	s_waitcnt vmcnt(0)
	v_cndmask_b32_e32 v49, 0, v69, vcc
	ds_write_b32 v24, v25
	ds_write_b32 v26, v13
	ds_write_b32 v28, v16
	ds_write_b32 v30, v27
	ds_write_b32 v32, v31
	ds_write_b32 v34, v29
	ds_write_b32 v36, v35
	ds_write_b32 v38, v33
	ds_write_b32 v40, v39
	ds_write_b32 v42, v37
	ds_write_b32 v44, v43
	ds_write_b32 v46, v41
	ds_write_b32 v48, v47
	ds_write_b32 v50, v45
	ds_write_b32 v52, v51
	ds_write_b32 v54, v49
	s_cbranch_scc1 .LBB0_44
; #define LAS __attribute__((address_space(3)))
; __device__ __forceinline__ unsigned cvtpk(float lo, float hi) { f32x2_t v = {lo, hi}; bf16x2_t b = __builtin_convertvector(v, bf16x2_t); return __builtin_bit_cast(unsigned, b); }
; __device__ __forceinline__ void tr_item(const float* W, int K, int N, int nblk, bf16_t* WT, LAS float* scr, int item, int lane, bool qperm) {
;     ...
;     asm volatile("s_waitcnt lgkmcnt(0)" ::: "memory");
;     const int c = lane & 7;
; #pragma unroll
;     for (int j = 0; j < 4; ++j) { const int n = (lane >> 3) + 8 * j; const LAS float* s = scr + (8 * c) * 33 + n;
;         u32x4 o; o.x = cvtpk(s[0 * 33], s[1 * 33]); o.y = cvtpk(s[2 * 33], s[3 * 33]); o.z = cvtpk(s[4 * 33], s[5 * 33]); o.w = cvtpk(s[6 * 33], s[7 * 33]);
;         *(u32x4*)(WT + (size_t)(n0 + n) * K + k0 + 8 * c) = o; }
;     asm volatile("s_waitcnt lgkmcnt(0)" ::: "memory");
	s_waitcnt lgkmcnt(0)
	ds_read2_b32 v[24:25], v19 offset0:33 offset1:41
	ds_read2_b32 v[26:27], v19 offset1:8
	ds_read2_b32 v[28:29], v19 offset0:66 offset1:74
	ds_read2_b32 v[30:31], v19 offset0:99 offset1:107
	ds_read2_b32 v[32:33], v19 offset0:132 offset1:140
	ds_read2_b32 v[34:35], v19 offset0:165 offset1:173
	ds_read2_b32 v[36:37], v19 offset0:198 offset1:206
	ds_read2_b32 v[38:39], v19 offset0:231 offset1:239
	v_mov_b64_e32 v[14:15], s[42:43]
	v_mad_i64_i32 v[14:15], s[34:35], v10, s73, v[14:15]
	v_ashrrev_i32_e32 v13, 31, v12
	v_or_b32_e32 v42, v11, v18
	v_lshl_add_u64 v[12:13], v[12:13], 1, v[14:15]
	v_lshlrev_b32_e32 v8, 1, v6
	v_ashrrev_i32_e32 v43, 31, v42
	v_lshl_add_u64 v[40:41], v[12:13], 0, v[8:9]
	v_lshlrev_b64 v[42:43], 11, v[42:43]
	s_waitcnt lgkmcnt(6)
	v_cvt_pk_bf16_f32 v12, v26, v24
	s_waitcnt lgkmcnt(4)
	v_cvt_pk_bf16_f32 v13, v28, v30
	s_waitcnt lgkmcnt(2)
	v_cvt_pk_bf16_f32 v14, v32, v34
	s_waitcnt lgkmcnt(0)
	v_cvt_pk_bf16_f32 v15, v36, v38
	v_lshl_add_u64 v[42:43], v[40:41], 0, v[42:43]
	v_or_b32_e32 v24, v11, v20
	global_store_dwordx4 v[42:43], v[12:15], off sc0 sc1
	v_or_b32_e32 v10, v11, v22
	v_readlane_b32 s84, v254, 7
	v_cvt_pk_bf16_f32 v12, v27, v25
	v_ashrrev_i32_e32 v25, 31, v24
	v_cvt_pk_bf16_f32 v13, v29, v31
	v_cvt_pk_bf16_f32 v14, v33, v35
	v_cvt_pk_bf16_f32 v15, v37, v39
	v_lshlrev_b64 v[24:25], 11, v[24:25]
	ds_read2_b32 v[26:27], v19 offset0:49 offset1:57
	ds_read2_b32 v[28:29], v19 offset0:16 offset1:24
	ds_read2_b32 v[30:31], v19 offset0:82 offset1:90
	ds_read2_b32 v[32:33], v19 offset0:115 offset1:123
	ds_read2_b32 v[34:35], v19 offset0:148 offset1:156
	ds_read2_b32 v[36:37], v19 offset0:181 offset1:189
	ds_read2_b32 v[38:39], v19 offset0:214 offset1:222
	ds_read2_b32 v[42:43], v19 offset0:247 offset1:255
	v_lshl_add_u64 v[24:25], v[40:41], 0, v[24:25]
	global_store_dwordx4 v[24:25], v[12:15], off sc0 sc1
	v_or_b32_e32 v24, v11, v21
	v_ashrrev_i32_e32 v25, 31, v24
	v_lshlrev_b64 v[24:25], 11, v[24:25]
	v_ashrrev_i32_e32 v11, 31, v10
	s_waitcnt lgkmcnt(6)
	v_cvt_pk_bf16_f32 v12, v28, v26
	s_waitcnt lgkmcnt(4)
	v_cvt_pk_bf16_f32 v13, v30, v32
	s_waitcnt lgkmcnt(2)
	v_cvt_pk_bf16_f32 v14, v34, v36
	s_waitcnt lgkmcnt(0)
	v_cvt_pk_bf16_f32 v15, v38, v42
	v_lshl_add_u64 v[24:25], v[40:41], 0, v[24:25]
	v_lshlrev_b64 v[10:11], 11, v[10:11]
	global_store_dwordx4 v[24:25], v[12:15], off sc0 sc1
	v_lshl_add_u64 v[10:11], v[40:41], 0, v[10:11]
	v_readlane_b32 s75, v254, 6
	v_cvt_pk_bf16_f32 v12, v29, v27
	v_cvt_pk_bf16_f32 v13, v31, v33
	v_cvt_pk_bf16_f32 v14, v35, v37
	v_cvt_pk_bf16_f32 v15, v39, v43
	global_store_dwordx4 v[10:11], v[12:15], off sc0 sc1
	s_waitcnt lgkmcnt(0)
	v_readlane_b32 s85, v254, 8
	s_branch .LBB0_11

; #define GAS __attribute__((address_space(1)))
; __global__ void __launch_bounds__(512, 2) mega_fwd(Args a) {
;     ...
;         if (blockIdx.x == 0 && threadIdx.x == 0) { P* p = (P*)(a.ws + W_P); p->xp = (const GAS float*)a.xp; p->xs = (const GAS float*)a.xs; p->norm_g = (const GAS float*)a.norm_g; p->b_qn = (const GAS float*)a.b_qn; p->b_kvn = (const GAS float*)a.b_kvn; p->fin_g = (const GAS float*)a.fin_g; p->out = (GAS float*)a.out; }
.LBB0_65:
	s_or_b64 exec, exec, s[4:5]
	s_mov_b64 s[0:1], exec
	v_readlane_b32 s2, v254, 2
	v_readlane_b32 s3, v254, 3
	s_and_b64 s[2:3], s[0:1], s[2:3]
	s_mov_b64 exec, s[2:3]
	s_cbranch_execz .LBB0_67
	v_mov_b32_e32 v2, s8
	v_mov_b32_e32 v3, s9
	v_mov_b32_e32 v4, s10
	v_mov_b32_e32 v5, s11
	v_mov_b32_e32 v1, 0x3bc0000
	global_store_dwordx4 v1, v[2:5], s[42:43] sc0 sc1
	s_nop 1
	v_mov_b32_e32 v2, s12
	v_mov_b32_e32 v3, s13
	v_mov_b32_e32 v4, s20
	v_mov_b32_e32 v5, s21
	global_store_dwordx4 v1, v[2:5], s[42:43] offset:16 sc0 sc1
	s_nop 1
	v_mov_b32_e32 v2, s48
	v_mov_b32_e32 v3, s49
	v_mov_b32_e32 v4, s54
	v_mov_b32_e32 v5, s55
	global_store_dwordx4 v1, v[2:5], s[42:43] offset:32 sc0 sc1
	s_nop 1
	v_mov_b64_e32 v[2:3], s[40:41]
	global_store_dwordx2 v1, v[2:3], s[42:43] offset:48 sc0 sc1

; __device__ __forceinline__ void final_norm_phase(const _Float16* xh, float* out, const float* g, int rows) {
;     ...
;     for (int m0 = gw * 4; m0 < rows; m0 += NGW * 4) {
;         f32x4 v[4][4];
; #pragma unroll
;         for (int r = 0; r < 4; ++r) { const f16x4* xr = (const f16x4*)(xh + (size_t)(m0 + r) * DM) + lane;
; #pragma unroll
;             for (int j = 0; j < 4; ++j) v[r][j] = __builtin_convertvector(xr[64 * j], f32x4); }
; #pragma unroll
;         for (int r = 0; r < 4; ++r) { float s = 0.f;
; #pragma unroll
;             for (int j = 0; j < 4; ++j) s += (v[r][j].x * v[r][j].x + v[r][j].y * v[r][j].y) + (v[r][j].z * v[r][j].z + v[r][j].w * v[r][j].w);
;             const float rstd = 1.0f / sqrtf(wave_sum(s) * (1.0f / DM) + RMS_EPS);
.LBB0_184:
	v_add_co_u32_e32 v26, vcc, 0xfffff000, v24
	v_add_u32_e32 v20, s30, v20
	s_nop 0
	v_addc_co_u32_e32 v27, vcc, -1, v25, vcc
	global_load_dwordx2 v[16:17], v[26:27], off offset:-3584
	global_load_dwordx2 v[28:29], v[26:27], off offset:-2048
	global_load_dwordx2 v[34:35], v[24:25], off offset:-1536
	global_load_dwordx2 v[38:39], v[24:25], off offset:-1024
	global_load_dwordx2 v[46:47], v[24:25], off offset:-512
	global_load_dwordx2 v[92:93], v[24:25], off
	s_waitcnt vmcnt(5)
	v_cvt_f32_f16_e32 v82, v16
	v_cvt_f32_f16_sdwa v83, v16 dst_sel:DWORD dst_unused:UNUSED_PAD src0_sel:WORD_1
	v_cvt_f32_f16_e32 v84, v17
	v_cvt_f32_f16_sdwa v85, v17 dst_sel:DWORD dst_unused:UNUSED_PAD src0_sel:WORD_1
	global_load_dwordx2 v[16:17], v[26:27], off offset:-3072
	s_waitcnt vmcnt(5)
	v_cvt_f32_f16_sdwa v81, v28 dst_sel:DWORD dst_unused:UNUSED_PAD src0_sel:WORD_1
	v_cvt_f32_f16_e32 v80, v28
	s_waitcnt vmcnt(3)
	v_cvt_f32_f16_sdwa v37, v39 dst_sel:DWORD dst_unused:UNUSED_PAD src0_sel:WORD_1
	v_cvt_f32_f16_e32 v36, v39
	s_waitcnt vmcnt(2)
	v_cvt_f32_f16_sdwa v39, v46 dst_sel:DWORD dst_unused:UNUSED_PAD src0_sel:WORD_1
	v_cvt_f32_f16_sdwa v41, v47 dst_sel:DWORD dst_unused:UNUSED_PAD src0_sel:WORD_1
	v_cvt_f32_f16_e32 v40, v47
	v_pk_mul_f32 v[94:95], v[82:83], v[82:83]
	v_mul_f32_e32 v21, v80, v80
	s_waitcnt vmcnt(1)
	v_cvt_f32_f16_sdwa v47, v93 dst_sel:DWORD dst_unused:UNUSED_PAD src0_sel:WORD_1
	v_cvt_f32_f16_sdwa v49, v92 dst_sel:DWORD dst_unused:UNUSED_PAD src0_sel:WORD_1
	v_cvt_f32_f16_e32 v48, v92
	s_waitcnt vmcnt(0)
	v_cvt_f32_f16_e32 v74, v16
	v_cvt_f32_f16_sdwa v75, v16 dst_sel:DWORD dst_unused:UNUSED_PAD src0_sel:WORD_1
	v_cvt_f32_f16_e32 v78, v17
	v_cvt_f32_f16_sdwa v79, v17 dst_sel:DWORD dst_unused:UNUSED_PAD src0_sel:WORD_1
	global_load_dwordx2 v[16:17], v[26:27], off offset:-2560
	s_waitcnt vmcnt(0)
	v_cvt_f32_f16_e32 v18, v16
	v_cvt_f32_f16_sdwa v19, v16 dst_sel:DWORD dst_unused:UNUSED_PAD src0_sel:WORD_1
	v_cvt_f32_f16_e32 v76, v17
	v_cvt_f32_f16_sdwa v77, v17 dst_sel:DWORD dst_unused:UNUSED_PAD src0_sel:WORD_1
	v_cvt_f32_f16_sdwa v17, v29 dst_sel:DWORD dst_unused:UNUSED_PAD src0_sel:WORD_1
	v_cvt_f32_f16_e32 v16, v29
	global_load_dwordx2 v[28:29], v[26:27], off offset:-1536
	s_waitcnt vmcnt(0)
	v_cvt_f32_f16_e32 v60, v28
	v_cvt_f32_f16_sdwa v61, v28 dst_sel:DWORD dst_unused:UNUSED_PAD src0_sel:WORD_1
	v_cvt_f32_f16_e32 v68, v29
	v_cvt_f32_f16_sdwa v69, v29 dst_sel:DWORD dst_unused:UNUSED_PAD src0_sel:WORD_1
	global_load_dwordx2 v[28:29], v[26:27], off offset:-1024
	s_waitcnt vmcnt(0)
	v_cvt_f32_f16_e32 v58, v28
	global_load_dwordx2 v[26:27], v[26:27], off offset:-512
	v_cvt_f32_f16_sdwa v59, v28 dst_sel:DWORD dst_unused:UNUSED_PAD src0_sel:WORD_1
	v_cvt_f32_f16_e32 v66, v29
	v_cvt_f32_f16_sdwa v67, v29 dst_sel:DWORD dst_unused:UNUSED_PAD src0_sel:WORD_1
	v_cvt_f32_f16_sdwa v29, v35 dst_sel:DWORD dst_unused:UNUSED_PAD src0_sel:WORD_1
	v_cvt_f32_f16_e32 v28, v35
	v_cvt_f32_f16_sdwa v35, v38 dst_sel:DWORD dst_unused:UNUSED_PAD src0_sel:WORD_1
	s_waitcnt vmcnt(0)
	v_cvt_f32_f16_e32 v56, v26
	v_cvt_f32_f16_sdwa v57, v26 dst_sel:DWORD dst_unused:UNUSED_PAD src0_sel:WORD_1
	v_cvt_f32_f16_e32 v64, v27
	v_cvt_f32_f16_sdwa v65, v27 dst_sel:DWORD dst_unused:UNUSED_PAD src0_sel:WORD_1
	global_load_dwordx2 v[26:27], v[24:25], off offset:-4096
	s_waitcnt vmcnt(0)
	v_cvt_f32_f16_sdwa v55, v27 dst_sel:DWORD dst_unused:UNUSED_PAD src0_sel:WORD_1
	v_cvt_f32_f16_sdwa v63, v26 dst_sel:DWORD dst_unused:UNUSED_PAD src0_sel:WORD_1
	v_cvt_f32_f16_e32 v54, v27
	v_cvt_f32_f16_e32 v62, v26
	global_load_dwordx2 v[26:27], v[24:25], off offset:-3584
	s_waitcnt vmcnt(0)
	v_cvt_f32_f16_sdwa v71, v26 dst_sel:DWORD dst_unused:UNUSED_PAD src0_sel:WORD_1
	v_cvt_f32_f16_sdwa v73, v27 dst_sel:DWORD dst_unused:UNUSED_PAD src0_sel:WORD_1
	v_cvt_f32_f16_e32 v70, v26
	v_cvt_f32_f16_e32 v72, v27
	global_load_dwordx2 v[26:27], v[24:25], off offset:-3072
	s_waitcnt vmcnt(0)
	v_cvt_f32_f16_sdwa v31, v26 dst_sel:DWORD dst_unused:UNUSED_PAD src0_sel:WORD_1
	v_cvt_f32_f16_sdwa v33, v27 dst_sel:DWORD dst_unused:UNUSED_PAD src0_sel:WORD_1
	v_cvt_f32_f16_e32 v30, v26
	v_cvt_f32_f16_e32 v32, v27
	global_load_dwordx2 v[26:27], v[24:25], off offset:-2560
	s_waitcnt vmcnt(0)
	v_cvt_f32_f16_sdwa v43, v26 dst_sel:DWORD dst_unused:UNUSED_PAD src0_sel:WORD_1
	v_cvt_f32_f16_sdwa v45, v27 dst_sel:DWORD dst_unused:UNUSED_PAD src0_sel:WORD_1
	v_cvt_f32_f16_e32 v42, v26
	v_cvt_f32_f16_e32 v44, v27
	global_load_dwordx2 v[26:27], v[24:25], off offset:-2048
	v_lshl_add_u64 v[24:25], v[24:25], 0, s[68:69]
	s_waitcnt vmcnt(0)
	v_cvt_f32_f16_sdwa v51, v27 dst_sel:DWORD dst_unused:UNUSED_PAD src0_sel:WORD_1
	v_cvt_f32_f16_sdwa v53, v26 dst_sel:DWORD dst_unused:UNUSED_PAD src0_sel:WORD_1
	v_cvt_f32_f16_e32 v50, v27
	v_cvt_f32_f16_e32 v52, v26
	v_cvt_f32_f16_sdwa v27, v34 dst_sel:DWORD dst_unused:UNUSED_PAD src0_sel:WORD_1
	v_cvt_f32_f16_e32 v26, v34
	v_cvt_f32_f16_e32 v34, v38
	v_cvt_f32_f16_e32 v38, v46
	v_cvt_f32_f16_e32 v46, v93
	v_pk_mul_f32 v[92:93], v[84:85], v[84:85]
	s_nop 0
	v_pk_mov_b32 v[96:97], v[94:95], v[92:93] op_sel:[1,0]
	v_mov_b32_e32 v95, v93
	v_pk_add_f32 v[92:93], v[96:97], v[94:95]
	v_pk_mul_f32 v[94:95], v[78:79], v[78:79]
	v_pk_mul_f32 v[96:97], v[74:75], v[74:75]
	v_pk_add_f32 v[92:93], v[92:93], v[92:93] op_sel:[0,1] op_sel_hi:[1,0]
	v_pk_mov_b32 v[98:99], v[96:97], v[94:95] op_sel:[1,0]
	v_mov_b32_e32 v97, v95
	v_pk_add_f32 v[94:95], v[98:99], v[96:97]
	v_mul_f32_e32 v96, v81, v81
	v_pk_add_f32 v[94:95], v[94:95], v[94:95] op_sel:[0,1] op_sel_hi:[1,0]
	v_mov_b32_e32 v93, v21
	v_mov_b32_e32 v95, v96
	v_pk_add_f32 v[92:93], v[92:93], v[94:95]
	v_mul_f32_e32 v94, v19, v19
	v_mul_f32_e32 v97, v16, v16
	v_pk_fma_f32 v[94:95], v[18:19], v[18:19], v[94:95] op_sel_hi:[1,1,0]
	v_mul_f32_e32 v96, v77, v77
	v_mul_f32_e32 v98, v17, v17
	v_mov_b32_e32 v95, v97
	v_pk_fma_f32 v[96:97], v[76:77], v[76:77], v[96:97] op_sel_hi:[1,1,0]
	s_nop 0
	v_mov_b32_e32 v97, v98
	v_pk_add_f32 v[94:95], v[94:95], v[96:97]
	s_nop 0
	v_pk_add_f32 v[92:93], v[92:93], v[94:95]
	s_nop 0
	v_add_f32_e32 v21, v92, v93
	ds_bpermute_b32 v92, v86, v21
	s_waitcnt lgkmcnt(0)
; __device__ __forceinline__ void final_norm_phase(const _Float16* xh, float* out, const float* g, int rows) {
;     ...
;         for (int r = 0; r < 4; ++r) { float s = 0.f;
; #pragma unroll
;             for (int j = 0; j < 4; ++j) s += (v[r][j].x * v[r][j].x + v[r][j].y * v[r][j].y) + (v[r][j].z * v[r][j].z + v[r][j].w * v[r][j].w);
;             const float rstd = 1.0f / sqrtf(wave_sum(s) * (1.0f / DM) + RMS_EPS);
;             f32x4* orow = (f32x4*)(out + (size_t)(m0 + r) * DM) + lane;
; #pragma unroll
;             for (int j = 0; j < 4; ++j) orow[64 * j] = v[r][j] * rstd * gv[j]; }
	v_add_f32_e32 v21, v21, v92
	ds_bpermute_b32 v92, v87, v21
	s_waitcnt lgkmcnt(0)
	v_add_f32_e32 v21, v21, v92
	ds_bpermute_b32 v92, v88, v21
	s_waitcnt lgkmcnt(0)
	v_add_f32_e32 v21, v21, v92
	ds_bpermute_b32 v92, v89, v21
	s_waitcnt lgkmcnt(0)
	v_add_f32_e32 v21, v21, v92
	ds_bpermute_b32 v92, v90, v21
	s_waitcnt lgkmcnt(0)
	v_add_f32_e32 v21, v21, v92
	ds_bpermute_b32 v92, v91, v21
	s_waitcnt lgkmcnt(0)
	v_add_f32_e32 v21, v21, v92
	v_fmamk_f32 v21, v21, 0x3a800000, v195
	v_cmp_gt_f32_e32 vcc, s33, v21
	v_mul_f32_e32 v92, 0x4f800000, v21
	s_nop 0
	v_cndmask_b32_e32 v21, v21, v92, vcc
	v_sqrt_f32_e32 v92, v21
	s_nop 0
	v_add_u32_e32 v93, -1, v92
	v_fma_f32 v94, -v93, v92, v21
	v_cmp_ge_f32_e64 s[0:1], 0, v94
	v_add_u32_e32 v94, 1, v92
	s_nop 0
	v_cndmask_b32_e64 v93, v92, v93, s[0:1]
	v_fma_f32 v92, -v94, v92, v21
	v_cmp_lt_f32_e64 s[0:1], 0, v92
	s_nop 1
	v_cndmask_b32_e64 v92, v93, v94, s[0:1]
	v_mul_f32_e32 v93, 0x37800000, v92
	v_cndmask_b32_e32 v92, v92, v93, vcc
	v_cmp_class_f32_e32 vcc, v21, v197
	s_nop 1
	v_cndmask_b32_e32 v21, v92, v21, vcc
	v_div_scale_f32 v92, s[0:1], v21, v21, 1.0
	v_rcp_f32_e32 v93, v92
	s_movk_i32 s0, 0xd000
	v_fma_f32 v94, -v92, v93, 1.0
	v_fmac_f32_e32 v93, v94, v93
	v_div_scale_f32 v94, vcc, 1.0, v21, 1.0
	v_mul_f32_e32 v95, v94, v93
	v_fma_f32 v96, -v92, v95, v94
	v_fmac_f32_e32 v95, v96, v93
	v_fma_f32 v92, -v92, v95, v94
	v_div_fmas_f32 v92, v92, v93, v95
	v_div_fixup_f32 v92, v92, v21, 1.0
	v_pk_mul_f32 v[82:83], v[92:93], v[82:83] op_sel_hi:[0,1]
	v_pk_mul_f32 v[84:85], v[92:93], v[84:85] op_sel_hi:[0,1]
	v_add_co_u32_e32 v94, vcc, s0, v22
	v_pk_mul_f32 v[84:85], v[2:3], v[84:85]
	v_pk_mul_f32 v[82:83], v[0:1], v[82:83]
	v_addc_co_u32_e32 v95, vcc, -1, v23, vcc
	v_pk_mul_f32 v[74:75], v[92:93], v[74:75] op_sel_hi:[0,1]
	global_store_dwordx4 v[94:95], v[82:85], off offset:-3072 sc0 sc1
	v_pk_mul_f32 v[18:19], v[92:93], v[18:19] op_sel_hi:[0,1]
	v_pk_mul_f32 v[16:17], v[92:93], v[16:17] op_sel_hi:[0,1]
	v_pk_mul_f32 v[82:83], v[4:5], v[74:75]
	v_pk_mul_f32 v[74:75], v[92:93], v[76:77] op_sel_hi:[0,1]
	v_pk_mul_f32 v[76:77], v[10:11], v[74:75]
	v_pk_mul_f32 v[74:75], v[8:9], v[18:19]
	global_store_dwordx4 v[94:95], v[74:77], off offset:-1024 sc0 sc1
	s_movk_i32 s0, 0xe000
	v_pk_mul_f32 v[18:19], v[14:15], v[16:17]
	v_pk_mul_f32 v[74:75], v[92:93], v[80:81] op_sel_hi:[0,1]
	v_pk_mul_f32 v[16:17], v[12:13], v[74:75]
	v_add_co_u32_e32 v74, vcc, s0, v22
	v_pk_mul_f32 v[78:79], v[92:93], v[78:79] op_sel_hi:[0,1]
	s_nop 0
	v_addc_co_u32_e32 v75, vcc, -1, v23, vcc
	global_store_dwordx4 v[74:75], v[16:19], off offset:-4096 sc0 sc1
	v_pk_mul_f32 v[84:85], v[6:7], v[78:79]
	v_mul_f32_e32 v21, v62, v62
	v_pk_mul_f32 v[16:17], v[68:69], v[68:69]
	v_pk_mul_f32 v[18:19], v[60:61], v[60:61]
	global_store_dwordx4 v[94:95], v[82:85], off offset:-2048 sc0 sc1
	v_pk_mov_b32 v[76:77], v[18:19], v[16:17] op_sel:[1,0]
	v_mov_b32_e32 v19, v17
	v_pk_add_f32 v[16:17], v[76:77], v[18:19]
	v_pk_mul_f32 v[18:19], v[66:67], v[66:67]
	v_pk_mul_f32 v[76:77], v[58:59], v[58:59]
	v_pk_add_f32 v[16:17], v[16:17], v[16:17] op_sel:[0,1] op_sel_hi:[1,0]
	v_pk_mov_b32 v[78:79], v[76:77], v[18:19] op_sel:[1,0]
	v_mov_b32_e32 v77, v19
	v_pk_add_f32 v[18:19], v[78:79], v[76:77]
	v_mul_f32_e32 v76, v63, v63
	v_pk_add_f32 v[18:19], v[18:19], v[18:19] op_sel:[0,1] op_sel_hi:[1,0]
	v_mov_b32_e32 v17, v21
	v_mov_b32_e32 v19, v76
	v_pk_add_f32 v[16:17], v[16:17], v[18:19]
	v_mul_f32_e32 v18, v57, v57
	v_mul_f32_e32 v77, v54, v54
	v_pk_fma_f32 v[18:19], v[56:57], v[56:57], v[18:19] op_sel_hi:[1,1,0]
	v_mul_f32_e32 v76, v65, v65
	v_mul_f32_e32 v78, v55, v55
	v_mov_b32_e32 v19, v77
	v_pk_fma_f32 v[76:77], v[64:65], v[64:65], v[76:77] op_sel_hi:[1,1,0]
	s_nop 0
	v_mov_b32_e32 v77, v78
	v_pk_add_f32 v[18:19], v[18:19], v[76:77]
	s_nop 0
	v_pk_add_f32 v[16:17], v[16:17], v[18:19]
	s_nop 0
	v_add_f32_e32 v16, v16, v17
	ds_bpermute_b32 v17, v86, v16
	s_waitcnt lgkmcnt(0)
	v_add_f32_e32 v16, v16, v17
	ds_bpermute_b32 v17, v87, v16
	s_waitcnt lgkmcnt(0)
	v_add_f32_e32 v16, v16, v17
	ds_bpermute_b32 v17, v88, v16
	s_waitcnt lgkmcnt(0)
	v_add_f32_e32 v16, v16, v17
	ds_bpermute_b32 v17, v89, v16
	s_waitcnt lgkmcnt(0)
	v_add_f32_e32 v16, v16, v17
	ds_bpermute_b32 v17, v90, v16
	s_waitcnt lgkmcnt(0)
	v_add_f32_e32 v16, v16, v17
	ds_bpermute_b32 v17, v91, v16
	s_waitcnt lgkmcnt(0)
; __device__ __forceinline__ void final_norm_phase(const _Float16* xh, float* out, const float* g, int rows) {
;     ...
;         for (int r = 0; r < 4; ++r) { float s = 0.f;
; #pragma unroll
;             for (int j = 0; j < 4; ++j) s += (v[r][j].x * v[r][j].x + v[r][j].y * v[r][j].y) + (v[r][j].z * v[r][j].z + v[r][j].w * v[r][j].w);
;             const float rstd = 1.0f / sqrtf(wave_sum(s) * (1.0f / DM) + RMS_EPS);
;             f32x4* orow = (f32x4*)(out + (size_t)(m0 + r) * DM) + lane;
; #pragma unroll
;             for (int j = 0; j < 4; ++j) orow[64 * j] = v[r][j] * rstd * gv[j]; }
	v_add_f32_e32 v16, v16, v17
	v_fmamk_f32 v16, v16, 0x3a800000, v195
	v_cmp_gt_f32_e32 vcc, s33, v16
	v_mul_f32_e32 v17, 0x4f800000, v16
	s_nop 0
	v_cndmask_b32_e32 v16, v16, v17, vcc
	v_sqrt_f32_e32 v17, v16
	s_nop 0
	v_add_u32_e32 v18, -1, v17
	v_fma_f32 v19, -v18, v17, v16
	v_cmp_ge_f32_e64 s[0:1], 0, v19
	v_add_u32_e32 v19, 1, v17
	s_nop 0
	v_cndmask_b32_e64 v18, v17, v18, s[0:1]
	v_fma_f32 v17, -v19, v17, v16
	v_cmp_lt_f32_e64 s[0:1], 0, v17
	s_nop 1
	v_cndmask_b32_e64 v17, v18, v19, s[0:1]
	v_mul_f32_e32 v18, 0x37800000, v17
	v_cndmask_b32_e32 v17, v17, v18, vcc
	v_cmp_class_f32_e32 vcc, v16, v197
	s_nop 1
	v_cndmask_b32_e32 v16, v17, v16, vcc
	v_div_scale_f32 v17, s[0:1], v16, v16, 1.0
	v_rcp_f32_e32 v18, v17
	s_nop 0
	v_fma_f32 v19, -v17, v18, 1.0
	v_fmac_f32_e32 v18, v19, v18
	v_div_scale_f32 v19, vcc, 1.0, v16, 1.0
	v_mul_f32_e32 v21, v19, v18
	v_fma_f32 v76, -v17, v21, v19
	v_fmac_f32_e32 v21, v76, v18
	v_fma_f32 v17, -v17, v21, v19
	v_div_fmas_f32 v17, v17, v18, v21
	v_div_fixup_f32 v76, v17, v16, 1.0
	v_pk_mul_f32 v[16:17], v[76:77], v[60:61] op_sel_hi:[0,1]
	v_pk_mul_f32 v[18:19], v[76:77], v[68:69] op_sel_hi:[0,1]
	v_pk_mul_f32 v[18:19], v[2:3], v[18:19]
	v_pk_mul_f32 v[16:17], v[0:1], v[16:17]
	global_store_dwordx4 v[74:75], v[16:19], off offset:-3072 sc0 sc1
	v_mul_f32_e32 v21, v52, v52
	s_nop 0
	v_pk_mul_f32 v[16:17], v[76:77], v[58:59] op_sel_hi:[0,1]
	v_pk_mul_f32 v[18:19], v[76:77], v[66:67] op_sel_hi:[0,1]
	v_pk_mul_f32 v[18:19], v[6:7], v[18:19]
	v_pk_mul_f32 v[16:17], v[4:5], v[16:17]
	global_store_dwordx4 v[74:75], v[16:19], off offset:-2048 sc0 sc1
	s_nop 1
	v_pk_mul_f32 v[16:17], v[76:77], v[56:57] op_sel_hi:[0,1]
	v_pk_mul_f32 v[18:19], v[76:77], v[64:65] op_sel_hi:[0,1]
	v_pk_mul_f32 v[18:19], v[10:11], v[18:19]
	v_pk_mul_f32 v[16:17], v[8:9], v[16:17]
	global_store_dwordx4 v[74:75], v[16:19], off offset:-1024 sc0 sc1
	s_nop 1
	v_pk_mul_f32 v[16:17], v[76:77], v[62:63] op_sel_hi:[0,1]
	v_pk_mul_f32 v[18:19], v[76:77], v[54:55] op_sel_hi:[0,1]
	v_pk_mul_f32 v[18:19], v[14:15], v[18:19]
	v_pk_mul_f32 v[16:17], v[12:13], v[16:17]
	global_store_dwordx4 v[74:75], v[16:19], off sc0 sc1
	s_nop 1
	v_pk_mul_f32 v[16:17], v[72:73], v[72:73]
	v_pk_mul_f32 v[18:19], v[70:71], v[70:71]
	s_nop 0
	v_pk_mov_b32 v[54:55], v[18:19], v[16:17] op_sel:[1,0]
	v_mov_b32_e32 v19, v17
	v_pk_add_f32 v[16:17], v[54:55], v[18:19]
	v_pk_mul_f32 v[18:19], v[32:33], v[32:33]
	v_pk_mul_f32 v[54:55], v[30:31], v[30:31]
	v_pk_add_f32 v[16:17], v[16:17], v[16:17] op_sel:[0,1] op_sel_hi:[1,0]
	v_pk_mov_b32 v[56:57], v[54:55], v[18:19] op_sel:[1,0]
	v_mov_b32_e32 v55, v19
	v_pk_add_f32 v[18:19], v[56:57], v[54:55]
	v_mul_f32_e32 v54, v53, v53
	v_pk_add_f32 v[18:19], v[18:19], v[18:19] op_sel:[0,1] op_sel_hi:[1,0]
	v_mov_b32_e32 v17, v21
	v_mov_b32_e32 v19, v54
	v_pk_add_f32 v[16:17], v[16:17], v[18:19]
	v_mul_f32_e32 v18, v43, v43
	v_mul_f32_e32 v55, v50, v50
	v_pk_fma_f32 v[18:19], v[42:43], v[42:43], v[18:19] op_sel_hi:[1,1,0]
	v_mul_f32_e32 v54, v45, v45
	v_mul_f32_e32 v56, v51, v51
	v_mov_b32_e32 v19, v55
	v_pk_fma_f32 v[54:55], v[44:45], v[44:45], v[54:55] op_sel_hi:[1,1,0]
	s_nop 0
	v_mov_b32_e32 v55, v56
	v_pk_add_f32 v[18:19], v[18:19], v[54:55]
	s_nop 0
	v_pk_add_f32 v[16:17], v[16:17], v[18:19]
	s_nop 0
	v_add_f32_e32 v16, v16, v17
	ds_bpermute_b32 v17, v86, v16
	s_waitcnt lgkmcnt(0)
	v_add_f32_e32 v16, v16, v17
	ds_bpermute_b32 v17, v87, v16
	s_waitcnt lgkmcnt(0)
	v_add_f32_e32 v16, v16, v17
	ds_bpermute_b32 v17, v88, v16
	s_waitcnt lgkmcnt(0)
	v_add_f32_e32 v16, v16, v17
	ds_bpermute_b32 v17, v89, v16
	s_waitcnt lgkmcnt(0)
	v_add_f32_e32 v16, v16, v17
	ds_bpermute_b32 v17, v90, v16
	s_waitcnt lgkmcnt(0)
	v_add_f32_e32 v16, v16, v17
	ds_bpermute_b32 v17, v91, v16
	s_waitcnt lgkmcnt(0)
; __device__ __forceinline__ void final_norm_phase(const _Float16* xh, float* out, const float* g, int rows) {
;     ...
;         for (int r = 0; r < 4; ++r) { float s = 0.f;
; #pragma unroll
;             for (int j = 0; j < 4; ++j) s += (v[r][j].x * v[r][j].x + v[r][j].y * v[r][j].y) + (v[r][j].z * v[r][j].z + v[r][j].w * v[r][j].w);
;             const float rstd = 1.0f / sqrtf(wave_sum(s) * (1.0f / DM) + RMS_EPS);
;             f32x4* orow = (f32x4*)(out + (size_t)(m0 + r) * DM) + lane;
; #pragma unroll
;             for (int j = 0; j < 4; ++j) orow[64 * j] = v[r][j] * rstd * gv[j]; }
	v_add_f32_e32 v16, v16, v17
	v_fmamk_f32 v16, v16, 0x3a800000, v195
	v_cmp_gt_f32_e32 vcc, s33, v16
	v_mul_f32_e32 v17, 0x4f800000, v16
	s_nop 0
	v_cndmask_b32_e32 v16, v16, v17, vcc
	v_sqrt_f32_e32 v17, v16
	s_nop 0
	v_add_u32_e32 v18, -1, v17
	v_fma_f32 v19, -v18, v17, v16
	v_cmp_ge_f32_e64 s[0:1], 0, v19
	v_add_u32_e32 v19, 1, v17
	s_nop 0
	v_cndmask_b32_e64 v18, v17, v18, s[0:1]
	v_fma_f32 v17, -v19, v17, v16
	v_cmp_lt_f32_e64 s[0:1], 0, v17
	s_nop 1
	v_cndmask_b32_e64 v17, v18, v19, s[0:1]
	v_mul_f32_e32 v18, 0x37800000, v17
	v_cndmask_b32_e32 v17, v17, v18, vcc
	v_cmp_class_f32_e32 vcc, v16, v197
	s_nop 1
	v_cndmask_b32_e32 v16, v17, v16, vcc
	v_div_scale_f32 v17, s[0:1], v16, v16, 1.0
	v_rcp_f32_e32 v18, v17
	s_movk_i32 s0, 0xf000
	v_fma_f32 v19, -v17, v18, 1.0
	v_fmac_f32_e32 v18, v19, v18
	v_div_scale_f32 v19, vcc, 1.0, v16, 1.0
	v_mul_f32_e32 v21, v19, v18
	v_fma_f32 v54, -v17, v21, v19
	v_fmac_f32_e32 v21, v54, v18
	v_fma_f32 v17, -v17, v21, v19
	v_div_fmas_f32 v17, v17, v18, v21
	v_div_fixup_f32 v16, v17, v16, 1.0
	v_pk_mul_f32 v[18:19], v[16:17], v[70:71] op_sel_hi:[0,1]
	v_pk_mul_f32 v[54:55], v[16:17], v[72:73] op_sel_hi:[0,1]
	v_pk_mul_f32 v[56:57], v[2:3], v[54:55]
	v_pk_mul_f32 v[54:55], v[0:1], v[18:19]
	v_add_co_u32_e32 v18, vcc, s0, v22
	v_pk_mul_f32 v[30:31], v[16:17], v[30:31] op_sel_hi:[0,1]
	v_pk_mul_f32 v[32:33], v[16:17], v[32:33] op_sel_hi:[0,1]
	v_addc_co_u32_e32 v19, vcc, -1, v23, vcc
	v_pk_mul_f32 v[32:33], v[6:7], v[32:33]
	v_pk_mul_f32 v[30:31], v[4:5], v[30:31]
	global_store_dwordx4 v[18:19], v[30:33], off offset:-2048 sc0 sc1
	global_store_dwordx4 v[18:19], v[54:57], off offset:-3072 sc0 sc1
	v_mul_f32_e32 v21, v48, v48
	v_pk_mul_f32 v[30:31], v[16:17], v[42:43] op_sel_hi:[0,1]
	v_pk_mul_f32 v[32:33], v[16:17], v[44:45] op_sel_hi:[0,1]
	v_pk_mul_f32 v[32:33], v[10:11], v[32:33]
	v_pk_mul_f32 v[30:31], v[8:9], v[30:31]
	global_store_dwordx4 v[18:19], v[30:33], off offset:-1024 sc0 sc1
	s_nop 1
	v_pk_mul_f32 v[30:31], v[16:17], v[52:53] op_sel_hi:[0,1]
	v_pk_mul_f32 v[16:17], v[16:17], v[50:51] op_sel_hi:[0,1]
	v_pk_mul_f32 v[18:19], v[14:15], v[16:17]
	v_pk_mul_f32 v[16:17], v[12:13], v[30:31]
	global_store_dwordx4 v[22:23], v[16:19], off offset:-4096 sc0 sc1
	s_nop 1
	v_pk_mul_f32 v[16:17], v[28:29], v[28:29]
	v_pk_mul_f32 v[18:19], v[26:27], v[26:27]
	s_nop 0
	v_pk_mov_b32 v[30:31], v[18:19], v[16:17] op_sel:[1,0]
	v_mov_b32_e32 v19, v17
	v_pk_add_f32 v[16:17], v[30:31], v[18:19]
	v_pk_mul_f32 v[18:19], v[36:37], v[36:37]
	v_pk_mul_f32 v[30:31], v[34:35], v[34:35]
	v_pk_add_f32 v[16:17], v[16:17], v[16:17] op_sel:[0,1] op_sel_hi:[1,0]
	v_pk_mov_b32 v[32:33], v[30:31], v[18:19] op_sel:[1,0]
	v_mov_b32_e32 v31, v19
	v_pk_add_f32 v[18:19], v[32:33], v[30:31]
	v_mul_f32_e32 v30, v49, v49
	v_pk_add_f32 v[18:19], v[18:19], v[18:19] op_sel:[0,1] op_sel_hi:[1,0]
	v_mov_b32_e32 v17, v21
	v_mov_b32_e32 v19, v30
	v_pk_add_f32 v[16:17], v[16:17], v[18:19]
	v_mul_f32_e32 v18, v39, v39
	v_mul_f32_e32 v31, v46, v46
	v_pk_fma_f32 v[18:19], v[38:39], v[38:39], v[18:19] op_sel_hi:[1,1,0]
	v_mul_f32_e32 v30, v41, v41
	v_mul_f32_e32 v32, v47, v47
	v_mov_b32_e32 v19, v31
	v_pk_fma_f32 v[30:31], v[40:41], v[40:41], v[30:31] op_sel_hi:[1,1,0]
	s_nop 0
	v_mov_b32_e32 v31, v32
	v_pk_add_f32 v[18:19], v[18:19], v[30:31]
	s_nop 0
	v_pk_add_f32 v[16:17], v[16:17], v[18:19]
	s_nop 0
	v_add_f32_e32 v16, v16, v17
	ds_bpermute_b32 v17, v86, v16
	s_waitcnt lgkmcnt(0)
	v_add_f32_e32 v16, v16, v17
	ds_bpermute_b32 v17, v87, v16
	s_waitcnt lgkmcnt(0)
	v_add_f32_e32 v16, v16, v17
	ds_bpermute_b32 v17, v88, v16
	s_waitcnt lgkmcnt(0)
	v_add_f32_e32 v16, v16, v17
	ds_bpermute_b32 v17, v89, v16
	s_waitcnt lgkmcnt(0)
	v_add_f32_e32 v16, v16, v17
	ds_bpermute_b32 v17, v90, v16
	s_waitcnt lgkmcnt(0)
	v_add_f32_e32 v16, v16, v17
	ds_bpermute_b32 v17, v91, v16
	s_waitcnt lgkmcnt(0)
	v_add_f32_e32 v16, v16, v17
	v_fmamk_f32 v16, v16, 0x3a800000, v195
	v_cmp_gt_f32_e32 vcc, s33, v16
	v_mul_f32_e32 v17, 0x4f800000, v16
	s_nop 0
	v_cndmask_b32_e32 v16, v16, v17, vcc
	v_sqrt_f32_e32 v17, v16
	s_nop 0
	v_add_u32_e32 v18, -1, v17
	v_fma_f32 v19, -v18, v17, v16
	v_cmp_ge_f32_e64 s[0:1], 0, v19
	v_add_u32_e32 v19, 1, v17
	s_nop 0
	v_cndmask_b32_e64 v18, v17, v18, s[0:1]
	v_fma_f32 v17, -v19, v17, v16
	v_cmp_lt_f32_e64 s[0:1], 0, v17
	s_nop 1
	v_cndmask_b32_e64 v17, v18, v19, s[0:1]
	v_mul_f32_e32 v18, 0x37800000, v17
	v_cndmask_b32_e32 v17, v17, v18, vcc
	v_cmp_class_f32_e32 vcc, v16, v197
	s_nop 1
	v_cndmask_b32_e32 v16, v17, v16, vcc
	v_div_scale_f32 v17, s[0:1], v16, v16, 1.0
	v_rcp_f32_e32 v18, v17
	s_nop 0
	v_fma_f32 v19, -v17, v18, 1.0
	v_fmac_f32_e32 v18, v19, v18
	v_div_scale_f32 v19, vcc, 1.0, v16, 1.0
	v_mul_f32_e32 v21, v19, v18
	v_fma_f32 v30, -v17, v21, v19
	v_fmac_f32_e32 v21, v30, v18
	v_fma_f32 v17, -v17, v21, v19
	v_div_fmas_f32 v17, v17, v18, v21
	v_div_fixup_f32 v30, v17, v16, 1.0
	v_pk_mul_f32 v[16:17], v[30:31], v[26:27] op_sel_hi:[0,1]
	v_pk_mul_f32 v[18:19], v[30:31], v[28:29] op_sel_hi:[0,1]
	v_pk_mul_f32 v[18:19], v[2:3], v[18:19]
	v_pk_mul_f32 v[16:17], v[0:1], v[16:17]
	global_store_dwordx4 v[22:23], v[16:19], off offset:-3072 sc0 sc1
	v_cmp_le_i32_e32 vcc, s62, v20
	s_or_b64 s[6:7], vcc, s[6:7]
	v_pk_mul_f32 v[16:17], v[30:31], v[34:35] op_sel_hi:[0,1]
	v_pk_mul_f32 v[18:19], v[30:31], v[36:37] op_sel_hi:[0,1]
	v_pk_mul_f32 v[18:19], v[6:7], v[18:19]
	v_pk_mul_f32 v[16:17], v[4:5], v[16:17]
	global_store_dwordx4 v[22:23], v[16:19], off offset:-2048 sc0 sc1
	s_nop 1
	v_pk_mul_f32 v[16:17], v[30:31], v[38:39] op_sel_hi:[0,1]
	v_pk_mul_f32 v[18:19], v[30:31], v[40:41] op_sel_hi:[0,1]
	v_pk_mul_f32 v[18:19], v[10:11], v[18:19]
	v_pk_mul_f32 v[16:17], v[8:9], v[16:17]
	global_store_dwordx4 v[22:23], v[16:19], off offset:-1024 sc0 sc1
	s_nop 1
	v_pk_mul_f32 v[16:17], v[30:31], v[48:49] op_sel_hi:[0,1]
	v_pk_mul_f32 v[18:19], v[30:31], v[46:47] op_sel_hi:[0,1]
	v_pk_mul_f32 v[18:19], v[14:15], v[18:19]
	v_pk_mul_f32 v[16:17], v[12:13], v[16:17]
	global_store_dwordx4 v[22:23], v[16:19], off sc0 sc1
	v_lshl_add_u64 v[22:23], v[22:23], 0, s[70:71]
	s_andn2_b64 exec, exec, s[6:7]
	s_cbranch_execnz .LBB0_184

; __device__ __forceinline__ void mla_attn_phase(LAS unsigned char* lds, const bf16_t* q, const bf16_t* kv, const bf16_t* krope, const bf16_t* projb, bf16_t* y, int unit0, int G, int nu) {
;     ...
;     MLA_EXP(n0, n1);
;     MLA_PV(lds + sl_c + MLA_KB);
;     __syncthreads();
.LBB0_200:
	v_exp_f32_e32 v48, v48
	v_exp_f32_e32 v65, v32
	v_exp_f32_e32 v32, v49
	v_exp_f32_e32 v49, v33
	v_exp_f32_e32 v33, v50
	v_exp_f32_e32 v50, v34
	v_exp_f32_e32 v34, v51
	v_exp_f32_e32 v51, v35
	v_exp_f32_e32 v35, v52
	v_exp_f32_e32 v52, v36
	v_exp_f32_e32 v36, v53
	v_exp_f32_e32 v53, v37
	v_exp_f32_e32 v37, v54
	v_exp_f32_e32 v54, v38
	v_exp_f32_e32 v38, v55
	v_exp_f32_e32 v39, v39
	v_exp_f32_e32 v55, v56
	v_exp_f32_e32 v56, v40
	v_exp_f32_e32 v40, v57
	v_exp_f32_e32 v57, v41
	s_ashr_i32 s6, s2, 8
	s_ashr_i32 s7, s6, 31
	s_waitcnt vmcnt(2)
	ds_write_b128 v185, v[152:155]
	s_waitcnt vmcnt(1)
	ds_write_b128 v201, v[156:159]
	s_waitcnt vmcnt(0)
	ds_write_b128 v214, v[160:163]
	v_add_f32_e32 v66, v65, v48
	v_add_f32_e32 v68, v50, v33
	v_add_f32_e32 v69, v51, v34
	v_add_f32_e32 v71, v53, v36
	v_cvt_pk_bf16_f32 v33, v33, v34
	v_cvt_pk_bf16_f32 v34, v35, v36
	v_cvt_pk_bf16_f32 v36, v65, v49
	v_add_u32_e32 v65, 0x16000, v233
	s_lshl_b64 s[6:7], s[6:7], 12
	v_add_f32_e32 v67, v49, v32
	v_add_f32_e32 v70, v52, v35
	v_add_f32_e32 v72, v54, v37
	v_add_f32_e32 v73, v39, v38
	v_add_f32_e32 v74, v56, v55
	v_add_f32_e32 v75, v57, v40
	v_cvt_pk_bf16_f32 v32, v48, v32
	v_cvt_pk_bf16_f32 v35, v37, v38
	v_cvt_pk_bf16_f32 v37, v50, v51
	v_cvt_pk_bf16_f32 v38, v52, v53
	v_cvt_pk_bf16_f32 v39, v54, v39
	v_cvt_pk_bf16_f32 v40, v55, v40
	ds_read_b64_tr_b16 v[48:49], v65
	ds_read_b64_tr_b16 v[50:51], v65 offset:1536
	ds_read_b64_tr_b16 v[54:55], v65 offset:1600
	ds_read_b64_tr_b16 v[52:53], v65 offset:64
	s_add_i32 s3, s2, s56
	v_readlane_b32 s16, v254, 47
	v_exp_f32_e32 v41, v58
	v_exp_f32_e32 v58, v42
	v_exp_f32_e32 v42, v59
	v_exp_f32_e32 v59, v43
	v_exp_f32_e32 v43, v60
	v_exp_f32_e32 v60, v44
	v_exp_f32_e32 v44, v61
	v_exp_f32_e32 v61, v45
	s_cmp_lt_i32 s3, s16
	s_cselect_b32 s12, s3, s2
	s_ashr_i32 s8, s12, 8
	v_exp_f32_e32 v45, v62
	v_exp_f32_e32 v62, v46
	v_exp_f32_e32 v46, v63
	v_exp_f32_e32 v47, v47
	s_ashr_i32 s9, s8, 31
	v_add_f32_e32 v76, v58, v41
	v_add_f32_e32 v77, v59, v42
	v_add_f32_e32 v79, v61, v44
	v_cvt_pk_bf16_f32 v41, v41, v42
	v_cvt_pk_bf16_f32 v42, v43, v44
	v_cvt_pk_bf16_f32 v44, v56, v57
	v_add_f32_e32 v56, 0, v66
	s_waitcnt lgkmcnt(0)
	v_mfma_f32_32x32x16_bf16 v[16:31], v[32:35], v[52:55], v[16:31]
	s_lshl_b64 s[10:11], s[8:9], 12
	s_lshl_b32 s8, s12, 8
	v_add_f32_e32 v56, v67, v56
	s_and_b32 s8, s8, 0xf00
	v_add_f32_e32 v56, v68, v56
	s_bfe_u32 s15, s12, 0x40004
	s_or_b32 s12, s10, s8
	v_mfma_f32_32x32x16_bf16 v[0:15], v[32:35], v[48:51], v[0:15]
	s_lshl_b32 s8, s2, 8
	v_add_f32_e32 v78, v60, v43
	v_add_f32_e32 v80, v62, v45
	v_add_f32_e32 v81, v47, v46
	v_cvt_pk_bf16_f32 v43, v45, v46
	v_cvt_pk_bf16_f32 v45, v58, v59
	v_cvt_pk_bf16_f32 v46, v60, v61
	v_add_f32_e32 v60, v69, v56
	ds_read_b64_tr_b16 v[52:53], v65 offset:3072
	ds_read_b64_tr_b16 v[54:55], v65 offset:4608
	ds_read_b64_tr_b16 v[58:59], v65 offset:4672
	ds_read_b64_tr_b16 v[56:57], v65 offset:3136
	s_lshl_b32 s14, s15, 8
	s_and_b32 s8, s8, 0xf00
	s_add_u32 s8, s8, s0
	s_addc_u32 s13, 0, s1
	s_add_u32 s9, s8, s6
	s_addc_u32 s8, s13, s7
	s_mov_b32 s13, s11
	v_add_f32_e32 v60, v70, v60
	s_waitcnt lgkmcnt(0)
	v_mfma_f32_32x32x16_bf16 v[16:31], v[40:43], v[56:59], v[16:31]
	v_lshl_add_u64 v[32:33], s[12:13], 0, v[186:187]
	v_readlane_b32 s12, v254, 17
	v_add_f32_e32 v60, v71, v60
	s_lshl_b32 s2, s2, 3
	v_readlane_b32 s13, v254, 18
	v_add_f32_e32 v60, v72, v60
	s_and_b32 s6, s2, 0x780
	v_mfma_f32_32x32x16_bf16 v[0:15], v[40:43], v[52:55], v[0:15]
	v_mov_b64_e32 v[34:35], s[12:13]
	s_movk_i32 s2, 0xc00
	v_cvt_pk_bf16_f32 v47, v62, v47
	v_add_f32_e32 v66, v73, v60
	ds_read_b64_tr_b16 v[56:57], v65 offset:6144
	ds_read_b64_tr_b16 v[58:59], v65 offset:7680
	ds_read_b64_tr_b16 v[62:63], v65 offset:7744
	ds_read_b64_tr_b16 v[60:61], v65 offset:6208
	v_mad_u64_u32 v[34:35], s[12:13], v32, s2, v[34:35]
	v_mov_b32_e32 v32, v35
	v_add_f32_e32 v66, v74, v66
	v_mad_u64_u32 v[32:33], s[12:13], v33, s2, v[32:33]
	v_add_f32_e32 v66, v75, v66
	v_mov_b32_e32 v35, v32
	s_mul_i32 s76, s15, 0xc0
	v_add_f32_e32 v66, v76, v66
	v_lshl_add_u64 v[32:33], v[34:35], 0, s[76:77]
	v_mov_b32_e32 v201, v179
	v_add_f32_e32 v70, v77, v66
	s_waitcnt lgkmcnt(0)
	v_mfma_f32_32x32x16_bf16 v[16:31], v[36:39], v[60:63], v[16:31]
	v_lshl_add_u64 v[32:33], v[32:33], 0, v[200:201]
	ds_read_b64_tr_b16 v[60:61], v65 offset:9216
	ds_read_b64_tr_b16 v[62:63], v65 offset:10752
	ds_read_b64_tr_b16 v[68:69], v65 offset:10816
	ds_read_b64_tr_b16 v[66:67], v65 offset:9280
	v_add_f32_e32 v65, v78, v70
	s_waitcnt lgkmcnt(0)
	s_barrier
; #define LAS __attribute__((address_space(3)))
; __device__ __forceinline__ int crow(int r, int hi) { return (r & 3) + 8 * (r >> 2) + 4 * hi; }
; __device__ __forceinline__ void mla_attn_phase(LAS unsigned char* lds, const bf16_t* q, const bf16_t* kv, const bf16_t* krope, const bf16_t* projb, bf16_t* y, int unit0, int G, int nu) {
;     ...
;     const int unit_n = unit + G; const bool more = unit_n < nu;
;     { const int uf_ = more ? unit_n : unit; MLA_FETCH(uf_); }
;     lsum += __shfl_xor(lsum, 32);
;     const float inv = 1.0f / lsum;
;     LAS float* stg = (LAS float*)(lds + w * 8704);
; #pragma unroll
;     for (int rr = 0; rr < 16; ++rr) { const int qi = crow(rr, hi); const float a = __shfl(inv, qi); stg[qi * 68 + r32] = o0[rr] * a; stg[qi * 68 + 32 + r32] = o1[rr] * a; }
;     asm volatile("s_waitcnt lgkmcnt(0)" ::: "memory");
	global_load_dwordx4 v[148:151], v[32:33], off
	global_load_dwordx4 v[144:147], v[32:33], off offset:32
	global_load_dwordx4 v[140:143], v[32:33], off offset:64
	global_load_dwordx4 v[136:139], v[32:33], off offset:96
	global_load_dwordx4 v[132:135], v[32:33], off offset:128
	global_load_dwordx4 v[128:131], v[32:33], off offset:160
	v_mfma_f32_32x32x16_bf16 v[0:15], v[36:39], v[56:59], v[0:15]
	v_lshl_add_u64 v[32:33], s[10:11], 0, v[182:183]
	v_readlane_b32 s12, v254, 19
	v_add_f32_e32 v65, v79, v65
	v_lshlrev_b64 v[32:33], 12, v[32:33]
	v_readlane_b32 s13, v254, 20
	v_add_f32_e32 v65, v80, v65
	s_mov_b32 s15, s77
	v_lshl_add_u64 v[32:33], s[12:13], 0, v[32:33]
	v_add_f32_e32 v65, v81, v65
	v_lshl_add_u64 v[32:33], v[32:33], 0, s[14:15]
	v_mov_b32_e32 v203, v179
	v_lshl_add_u64 v[206:207], v[32:33], 0, v[202:203]
	v_add_f32_e32 v56, v64, v65
	v_add_co_u32_e32 v40, vcc, s83, v206
	ds_bpermute_b32 v57, v216, v56
	s_nop 0
	v_addc_co_u32_e32 v41, vcc, 0, v207, vcc
	s_mov_b32 s2, 0x40000
	v_mfma_f32_32x32x16_bf16 v[16:31], v[44:47], v[66:69], v[16:31]
	v_mov_b32_e32 v33, s11
	v_or_b32_e32 v32, s10, v184
	v_lshlrev_b64 v[32:33], 6, v[32:33]
	v_lshl_add_u64 v[208:209], v[188:189], 0, v[32:33]
	s_waitcnt lgkmcnt(0)
	v_add_f32_e32 v58, v56, v57
	v_div_scale_f32 v59, s[10:11], v58, v58, 1.0
	v_mfma_f32_32x32x16_bf16 v[0:15], v[44:47], v[60:63], v[0:15]
	v_add_co_u32_e32 v44, vcc, s2, v206
	s_mov_b32 s2, 0x60000
	s_nop 0
	v_addc_co_u32_e32 v45, vcc, 0, v207, vcc
	v_add_co_u32_e32 v48, vcc, s2, v206
	s_movk_i32 s2, 0x2000
	s_nop 0
	v_addc_co_u32_e32 v49, vcc, 0, v207, vcc
	v_add_co_u32_e32 v60, vcc, s2, v208
	s_mov_b32 s2, 0x80000
	s_nop 0
	v_addc_co_u32_e32 v61, vcc, 0, v209, vcc
	v_rcp_f32_e32 v62, v59
	v_add_co_u32_e32 v52, vcc, s2, v206
	s_mov_b32 s2, 0xa0000
	s_nop 0
	v_addc_co_u32_e32 v53, vcc, 0, v207, vcc
	v_add_co_u32_e32 v56, vcc, s2, v206
	v_fma_f32 v63, -v59, v62, 1.0
	s_nop 0
	v_addc_co_u32_e32 v57, vcc, 0, v207, vcc
	v_fmac_f32_e32 v62, v63, v62
	v_div_scale_f32 v63, vcc, 1.0, v58, 1.0
	v_mul_f32_e32 v64, v63, v62
	v_fma_f32 v65, -v59, v64, v63
	v_fmac_f32_e32 v64, v65, v62
	v_fma_f32 v59, -v59, v64, v63
	v_div_fmas_f32 v59, v59, v62, v64
	v_div_fixup_f32 v68, v59, v58, 1.0
	ds_bpermute_b32 v69, v217, v68
	ds_bpermute_b32 v70, v236, v68
	global_load_dwordx4 v[32:35], v[206:207], off
	global_load_dwordx4 v[36:39], v[208:209], off
	s_nop 0
	global_load_dwordx4 v[40:43], v[40:41], off
	s_nop 0
	global_load_dwordx4 v[44:47], v[44:45], off
	s_waitcnt lgkmcnt(1)
	v_mul_f32_e32 v0, v0, v69
	v_mul_f32_e32 v16, v16, v69
	global_load_dwordx4 v[48:51], v[48:49], off
	s_nop 0
	global_load_dwordx4 v[52:55], v[52:53], off
	s_nop 0
	global_load_dwordx4 v[56:59], v[56:57], off
	s_nop 0
	global_load_dwordx4 v[64:67], v[60:61], off offset:-4096
	s_nop 0
	global_load_dwordx4 v[60:63], v[60:61], off
	ds_write2_b32 v235, v0, v16 offset1:32
	ds_bpermute_b32 v0, v219, v68
	s_waitcnt lgkmcnt(2)
	v_mul_f32_e32 v1, v1, v70
	v_mul_f32_e32 v16, v17, v70
	ds_write2_b32 v237, v1, v16 offset1:32
	ds_bpermute_b32 v1, v220, v68
	s_waitcnt lgkmcnt(2)
	v_mul_f32_e32 v2, v2, v0
	v_mul_f32_e32 v0, v18, v0
	v_add_u32_e32 v16, 0x110, v237
	ds_write2_b32 v16, v2, v0 offset1:32
	ds_bpermute_b32 v0, v221, v68
	s_waitcnt lgkmcnt(2)
	v_mul_f32_e32 v2, v3, v1
	v_mul_f32_e32 v1, v19, v1
	v_add_u32_e32 v3, 0x220, v237
	ds_write2_b32 v3, v2, v1 offset1:32
	ds_bpermute_b32 v1, v222, v68
	s_waitcnt lgkmcnt(2)
	v_mul_f32_e32 v2, v4, v0
	v_mul_f32_e32 v0, v20, v0
	v_add_u32_e32 v3, 0x770, v237
	ds_write2_b32 v3, v2, v0 offset1:32
	ds_bpermute_b32 v0, v223, v68
	s_waitcnt lgkmcnt(2)
	v_mul_f32_e32 v2, v5, v1
	v_mul_f32_e32 v1, v21, v1
	v_add_u32_e32 v3, 0x880, v237
	ds_write2_b32 v3, v2, v1 offset1:32
	ds_bpermute_b32 v1, v224, v68
	s_waitcnt lgkmcnt(2)
	v_mul_f32_e32 v2, v6, v0
	v_mul_f32_e32 v0, v22, v0
	v_add_u32_e32 v3, 0x990, v237
	ds_write2_b32 v3, v2, v0 offset1:32
	ds_bpermute_b32 v0, v225, v68
	s_waitcnt lgkmcnt(2)
	v_mul_f32_e32 v2, v7, v1
	v_mul_f32_e32 v1, v23, v1
	v_add_u32_e32 v3, 0xaa0, v237
	ds_write2_b32 v3, v2, v1 offset1:32
	ds_bpermute_b32 v1, v226, v68
	s_waitcnt lgkmcnt(2)
	v_mul_f32_e32 v2, v8, v0
	v_mul_f32_e32 v0, v24, v0
	v_add_u32_e32 v3, 0xff0, v237
	ds_write2_b32 v3, v2, v0 offset1:32
	ds_bpermute_b32 v0, v227, v68
	s_waitcnt lgkmcnt(2)
	v_mul_f32_e32 v2, v9, v1
	v_mul_f32_e32 v1, v25, v1
	v_add_u32_e32 v3, 0x1100, v237
	ds_write2_b32 v3, v2, v1 offset1:32
	ds_bpermute_b32 v1, v228, v68
	s_waitcnt lgkmcnt(2)
	v_mul_f32_e32 v2, v10, v0
	v_mul_f32_e32 v0, v26, v0
	v_add_u32_e32 v3, 0x1210, v237
	ds_write2_b32 v3, v2, v0 offset1:32
	ds_bpermute_b32 v0, v229, v68
	s_waitcnt lgkmcnt(2)
	v_mul_f32_e32 v2, v11, v1
	v_mul_f32_e32 v1, v27, v1
	v_add_u32_e32 v3, 0x1320, v237
	ds_write2_b32 v3, v2, v1 offset1:32
	ds_bpermute_b32 v1, v230, v68
	s_waitcnt lgkmcnt(2)
	v_mul_f32_e32 v2, v12, v0
	v_mul_f32_e32 v0, v28, v0
	ds_write2_b32 v211, v2, v0 offset1:32
	ds_bpermute_b32 v0, v231, v68
	ds_bpermute_b32 v3, v232, v68
	s_waitcnt lgkmcnt(3)
	v_mul_f32_e32 v2, v13, v1
	v_mul_f32_e32 v1, v29, v1
	ds_write2_b32 v251, v2, v1 offset1:32
	s_waitcnt lgkmcnt(2)
	v_mul_f32_e32 v1, v14, v0
	v_mul_f32_e32 v0, v30, v0
	ds_write2_b32 v244, v1, v0 offset1:32
	s_waitcnt lgkmcnt(2)
	v_mul_f32_e32 v0, v15, v3
	v_mul_f32_e32 v1, v31, v3
	v_or_b32_e32 v16, s9, v190
	v_mov_b64_e32 v[2:3], s[54:55]
	s_movk_i32 s2, 0xe00
	ds_write2_b32 v245, v0, v1 offset1:32
	v_mad_u64_u32 v[0:1], s[10:11], v16, s2, v[2:3]
	v_mov_b32_e32 v28, 0xe00
	s_mov_b32 s7, s77
	v_mad_i32_i24 v1, s8, v28, v1
	v_lshl_add_u64 v[0:1], v[0:1], 0, s[6:7]
	v_mov_b32_e32 v205, v179
	s_waitcnt lgkmcnt(0)
; #define LAS __attribute__((address_space(3)))
; __device__ __forceinline__ unsigned cvtpk(float lo, float hi) { f32x2_t v = {lo, hi}; bf16x2_t b = __builtin_convertvector(v, bf16x2_t); return __builtin_bit_cast(unsigned, b); }
; __device__ __forceinline__ float silu_f(float x) { return x / (1.0f + __expf(-x)); }
; __device__ __forceinline__ void mla_attn_phase(LAS unsigned char* lds, const bf16_t* q, const bf16_t* kv, const bf16_t* krope, const bf16_t* projb, bf16_t* y, int unit0, int G, int nu) {
;     ...
;     for (int i = 0; i < 4; ++i) { const int row = i * 8 + (lane >> 3), c8 = lane & 7; const size_t tok = row0 + qb * 256 + w * 32 + row;
;         const f32x4 x0 = *(const LAS f32x4*)(stg + row * 68 + c8 * 8), x1 = *(const LAS f32x4*)(stg + row * 68 + c8 * 8 + 4);
;         const u32x4 g = *(const u32x4*)(projb + tok * B_INP + 672 + h * 64 + c8 * 8);
;         u32x4 yo; yo.x = cvtpk(x0[0] * silu_f(bf_lo(g.x)), x0[1] * silu_f(bf_hi(g.x))); yo.y = cvtpk(x0[2] * silu_f(bf_lo(g.y)), x0[3] * silu_f(bf_hi(g.y)));
;         yo.z = cvtpk(x1[0] * silu_f(bf_lo(g.z)), x1[1] * silu_f(bf_hi(g.z))); yo.w = cvtpk(x1[2] * silu_f(bf_lo(g.w)), x1[3] * silu_f(bf_hi(g.w)));
;         *(u32x4*)(y + tok * DM + h * 64 + c8 * 8) = yo; }
	v_lshl_add_u64 v[0:1], v[0:1], 0, v[204:205]
	v_or_b32_e32 v102, s9, v194
	v_mad_u64_u32 v[100:101], s[10:11], v102, s2, v[2:3]
	v_mad_i32_i24 v101, s8, v28, v101
	v_lshl_add_u64 v[100:101], v[100:101], 0, s[6:7]
	v_lshl_add_u64 v[100:101], v[100:101], 0, v[204:205]
	v_or_b32_e32 v106, s9, v196
	v_mad_u64_u32 v[104:105], s[10:11], v106, s2, v[2:3]
	v_mad_i32_i24 v105, s8, v28, v105
	v_lshl_add_u64 v[104:105], v[104:105], 0, s[6:7]
	v_lshl_add_u64 v[104:105], v[104:105], 0, v[204:205]
	v_or_b32_e32 v110, s9, v198
	v_mad_u64_u32 v[108:109], s[10:11], v110, s2, v[2:3]
	v_mad_i32_i24 v109, s8, v28, v109
	v_lshl_add_u64 v[108:109], v[108:109], 0, s[6:7]
	v_lshl_add_u64 v[108:109], v[108:109], 0, v[204:205]
	global_load_dwordx4 v[84:87], v[0:1], off offset:1344
	global_load_dwordx4 v[88:91], v[100:101], off offset:1344
	global_load_dwordx4 v[92:95], v[104:105], off offset:1344
	global_load_dwordx4 v[96:99], v[108:109], off offset:1344
	v_mov_b32_e32 v17, s8
	s_cmp_ge_i32 s3, s16
	s_waitcnt vmcnt(3)
	v_mov_b32_e32 v4, v84
	v_mov_b32_e32 v5, v85
	v_mov_b32_e32 v6, v86
	v_mov_b32_e32 v7, v87
	v_lshlrev_b32_e32 v22, 16, v4
	v_and_b32_e32 v4, 0xffff0000, v4
	v_mul_f32_e32 v0, 0xbfb8aa3b, v22
	v_exp_f32_e32 v8, v0
	v_mul_f32_e32 v0, 0xbfb8aa3b, v4
	v_exp_f32_e32 v9, v0
	v_and_b32_e32 v26, 0xffff0000, v5
	v_lshl_add_u64 v[0:1], v[192:193], 0, s[6:7]
	v_pk_add_f32 v[18:19], v[8:9], 1.0 op_sel_hi:[1,0]
	s_nop 0
	v_div_scale_f32 v20, s[10:11], v19, v19, v4
	v_rcp_f32_e32 v21, v20
	ds_read_b128 v[8:11], v250
	ds_read_b128 v[12:15], v250 offset:16
	v_fma_f32 v23, -v20, v21, 1.0
	v_fmac_f32_e32 v21, v23, v21
	v_div_scale_f32 v23, vcc, v4, v19, v4
	v_mul_f32_e32 v24, v23, v21
	v_fma_f32 v25, -v20, v24, v23
	v_fmac_f32_e32 v24, v25, v21
	v_fma_f32 v20, -v20, v24, v23
	v_div_scale_f32 v23, s[10:11], v18, v18, v22
	v_rcp_f32_e32 v25, v23
	v_div_fmas_f32 v20, v20, v21, v24
	v_div_fixup_f32 v19, v20, v19, v4
	v_div_scale_f32 v20, vcc, v22, v18, v22
	v_fma_f32 v4, -v23, v25, 1.0
	v_fmac_f32_e32 v25, v4, v25
	v_mul_f32_e32 v21, v20, v25
	v_fma_f32 v4, -v23, v21, v20
	v_lshlrev_b32_e32 v24, 16, v5
	v_fmac_f32_e32 v21, v4, v25
	v_mul_f32_e32 v4, 0xbfb8aa3b, v24
	v_mul_f32_e32 v5, 0xbfb8aa3b, v26
	v_exp_f32_e32 v4, v4
	v_exp_f32_e32 v5, v5
	v_fma_f32 v20, -v23, v21, v20
	v_div_fmas_f32 v23, v20, v25, v21
	v_div_fixup_f32 v18, v23, v18, v22
	v_pk_add_f32 v[20:21], v[4:5], 1.0 op_sel_hi:[1,0]
	s_waitcnt lgkmcnt(1)
	v_pk_mul_f32 v[4:5], v[8:9], v[18:19]
	v_div_scale_f32 v25, s[10:11], v21, v21, v26
	v_rcp_f32_e32 v27, v25
	v_cvt_pk_bf16_f32 v4, v4, v5
	v_div_scale_f32 v22, s[10:11], v20, v20, v24
	v_fma_f32 v5, -v25, v27, 1.0
	v_fmac_f32_e32 v27, v5, v27
	v_div_scale_f32 v5, vcc, v26, v21, v26
	v_mul_f32_e32 v8, v5, v27
	v_fma_f32 v9, -v25, v8, v5
	v_rcp_f32_e32 v23, v22
	v_fmac_f32_e32 v8, v9, v27
	v_fma_f32 v5, -v25, v8, v5
	v_div_fmas_f32 v5, v5, v27, v8
	v_div_fixup_f32 v9, v5, v21, v26
	v_fma_f32 v5, -v22, v23, 1.0
	v_fmac_f32_e32 v23, v5, v23
	v_div_scale_f32 v5, vcc, v24, v20, v24
	v_mul_f32_e32 v8, v5, v23
	v_fma_f32 v18, -v22, v8, v5
	v_lshlrev_b32_e32 v21, 16, v6
	v_and_b32_e32 v6, 0xffff0000, v6
	v_fmac_f32_e32 v8, v18, v23
	v_mul_f32_e32 v18, 0xbfb8aa3b, v21
	v_mul_f32_e32 v19, 0xbfb8aa3b, v6
	v_exp_f32_e32 v18, v18
	v_exp_f32_e32 v19, v19
	v_fma_f32 v5, -v22, v8, v5
	v_div_fmas_f32 v5, v5, v23, v8
	v_div_fixup_f32 v8, v5, v20, v24
	v_pk_add_f32 v[18:19], v[18:19], 1.0 op_sel_hi:[1,0]
	v_pk_mul_f32 v[8:9], v[10:11], v[8:9]
	v_div_scale_f32 v22, s[10:11], v19, v19, v6
	v_rcp_f32_e32 v23, v22
	v_cvt_pk_bf16_f32 v5, v8, v9
	v_lshlrev_b32_e32 v20, 16, v7
	v_fma_f32 v8, -v22, v23, 1.0
	v_fmac_f32_e32 v23, v8, v23
	v_div_scale_f32 v8, vcc, v6, v19, v6
	v_mul_f32_e32 v9, v8, v23
	v_fma_f32 v10, -v22, v9, v8
	v_fmac_f32_e32 v9, v10, v23
	v_div_scale_f32 v10, s[10:11], v18, v18, v21
	v_rcp_f32_e32 v11, v10
	v_fma_f32 v8, -v22, v9, v8
	v_div_fmas_f32 v8, v8, v23, v9
	v_div_fixup_f32 v9, v8, v19, v6
	v_fma_f32 v6, -v10, v11, 1.0
	v_fmac_f32_e32 v11, v6, v11
	v_div_scale_f32 v8, vcc, v21, v18, v21
	v_mul_f32_e32 v19, v8, v11
	v_fma_f32 v6, -v10, v19, v8
	v_and_b32_e32 v22, 0xffff0000, v7
	v_fmac_f32_e32 v19, v6, v11
	v_mul_f32_e32 v6, 0xbfb8aa3b, v20
	v_mul_f32_e32 v7, 0xbfb8aa3b, v22
	v_exp_f32_e32 v6, v6
	v_exp_f32_e32 v7, v7
	v_fma_f32 v8, -v10, v19, v8
	v_div_fmas_f32 v8, v8, v11, v19
	v_div_fixup_f32 v8, v8, v18, v21
	v_pk_add_f32 v[10:11], v[6:7], 1.0 op_sel_hi:[1,0]
	s_waitcnt lgkmcnt(0)
	v_pk_mul_f32 v[6:7], v[12:13], v[8:9]
	v_div_scale_f32 v19, s[10:11], v11, v11, v22
	v_rcp_f32_e32 v23, v19
	v_cvt_pk_bf16_f32 v6, v6, v7
	v_div_scale_f32 v12, s[10:11], v10, v10, v20
	v_fma_f32 v7, -v19, v23, 1.0
	v_fmac_f32_e32 v23, v7, v23
	v_div_scale_f32 v7, vcc, v22, v11, v22
	v_mul_f32_e32 v8, v7, v23
	v_fma_f32 v9, -v19, v8, v7
	v_rcp_f32_e32 v13, v12
	v_fmac_f32_e32 v8, v9, v23
	v_fma_f32 v7, -v19, v8, v7
	v_div_fmas_f32 v7, v7, v23, v8
	v_div_fixup_f32 v9, v7, v11, v22
	v_fma_f32 v7, -v12, v13, 1.0
	v_fmac_f32_e32 v13, v7, v13
	v_div_scale_f32 v7, vcc, v20, v10, v20
	v_mul_f32_e32 v8, v7, v13
	v_fma_f32 v11, -v12, v8, v7
	v_fmac_f32_e32 v8, v11, v13
	v_fma_f32 v7, -v12, v8, v7
	v_div_fmas_f32 v7, v7, v13, v8
	v_div_fixup_f32 v8, v7, v10, v20
	v_pk_mul_f32 v[8:9], v[14:15], v[8:9]
	s_nop 0
	v_cvt_pk_bf16_f32 v7, v8, v9
	v_lshlrev_b64 v[8:9], 11, v[16:17]
	v_lshl_add_u64 v[8:9], v[0:1], 0, v[8:9]
	v_or_b32_e32 v16, s9, v194
	global_store_dwordx4 v[8:9], v[4:7], off sc0 sc1
	s_nop 1
	v_mad_u64_u32 v[4:5], s[10:11], v16, s2, v[2:3]
	v_mad_i32_i24 v5, s8, v28, v5
	v_lshl_add_u64 v[4:5], v[4:5], 0, s[6:7]
	v_lshl_add_u64 v[4:5], v[4:5], 0, v[204:205]
	s_waitcnt vmcnt(3)
; #define LAS __attribute__((address_space(3)))
; __device__ __forceinline__ unsigned cvtpk(float lo, float hi) { f32x2_t v = {lo, hi}; bf16x2_t b = __builtin_convertvector(v, bf16x2_t); return __builtin_bit_cast(unsigned, b); }
; __device__ __forceinline__ float silu_f(float x) { return x / (1.0f + __expf(-x)); }
; __device__ __forceinline__ void mla_attn_phase(LAS unsigned char* lds, const bf16_t* q, const bf16_t* kv, const bf16_t* krope, const bf16_t* projb, bf16_t* y, int unit0, int G, int nu) {
;     ...
;     for (int i = 0; i < 4; ++i) { const int row = i * 8 + (lane >> 3), c8 = lane & 7; const size_t tok = row0 + qb * 256 + w * 32 + row;
;         const f32x4 x0 = *(const LAS f32x4*)(stg + row * 68 + c8 * 8), x1 = *(const LAS f32x4*)(stg + row * 68 + c8 * 8 + 4);
;         const u32x4 g = *(const u32x4*)(projb + tok * B_INP + 672 + h * 64 + c8 * 8);
;         u32x4 yo; yo.x = cvtpk(x0[0] * silu_f(bf_lo(g.x)), x0[1] * silu_f(bf_hi(g.x))); yo.y = cvtpk(x0[2] * silu_f(bf_lo(g.y)), x0[3] * silu_f(bf_hi(g.y)));
;         yo.z = cvtpk(x1[0] * silu_f(bf_lo(g.z)), x1[1] * silu_f(bf_hi(g.z))); yo.w = cvtpk(x1[2] * silu_f(bf_lo(g.w)), x1[3] * silu_f(bf_hi(g.w)));
;         *(u32x4*)(y + tok * DM + h * 64 + c8 * 8) = yo; }
	v_mov_b32_e32 v4, v88
	v_mov_b32_e32 v5, v89
	v_mov_b32_e32 v6, v90
	v_mov_b32_e32 v7, v91
	v_lshlrev_b32_e32 v22, 16, v4
	v_and_b32_e32 v4, 0xffff0000, v4
	v_mul_f32_e32 v8, 0xbfb8aa3b, v22
	v_mul_f32_e32 v9, 0xbfb8aa3b, v4
	v_exp_f32_e32 v8, v8
	v_exp_f32_e32 v9, v9
	v_and_b32_e32 v26, 0xffff0000, v5
	v_pk_add_f32 v[18:19], v[8:9], 1.0 op_sel_hi:[1,0]
	s_nop 0
	v_div_scale_f32 v20, s[10:11], v19, v19, v4
	v_rcp_f32_e32 v21, v20
	ds_read_b128 v[8:11], v250 offset:2176
	ds_read_b128 v[12:15], v250 offset:2192
	v_fma_f32 v23, -v20, v21, 1.0
	v_fmac_f32_e32 v21, v23, v21
	v_div_scale_f32 v23, vcc, v4, v19, v4
	v_mul_f32_e32 v24, v23, v21
	v_fma_f32 v25, -v20, v24, v23
	v_fmac_f32_e32 v24, v25, v21
	v_fma_f32 v20, -v20, v24, v23
	v_div_scale_f32 v23, s[10:11], v18, v18, v22
	v_rcp_f32_e32 v25, v23
	v_div_fmas_f32 v20, v20, v21, v24
	v_div_fixup_f32 v19, v20, v19, v4
	v_div_scale_f32 v20, vcc, v22, v18, v22
	v_fma_f32 v4, -v23, v25, 1.0
	v_fmac_f32_e32 v25, v4, v25
	v_mul_f32_e32 v21, v20, v25
	v_fma_f32 v4, -v23, v21, v20
	v_lshlrev_b32_e32 v24, 16, v5
	v_fmac_f32_e32 v21, v4, v25
	v_mul_f32_e32 v4, 0xbfb8aa3b, v24
	v_mul_f32_e32 v5, 0xbfb8aa3b, v26
	v_exp_f32_e32 v4, v4
	v_exp_f32_e32 v5, v5
	v_fma_f32 v20, -v23, v21, v20
	v_div_fmas_f32 v23, v20, v25, v21
	v_div_fixup_f32 v18, v23, v18, v22
	v_pk_add_f32 v[20:21], v[4:5], 1.0 op_sel_hi:[1,0]
	s_waitcnt lgkmcnt(1)
	v_pk_mul_f32 v[4:5], v[8:9], v[18:19]
	v_div_scale_f32 v25, s[10:11], v21, v21, v26
	v_rcp_f32_e32 v27, v25
	v_cvt_pk_bf16_f32 v4, v4, v5
	v_div_scale_f32 v22, s[10:11], v20, v20, v24
	v_fma_f32 v5, -v25, v27, 1.0
	v_fmac_f32_e32 v27, v5, v27
	v_div_scale_f32 v5, vcc, v26, v21, v26
	v_mul_f32_e32 v8, v5, v27
	v_fma_f32 v9, -v25, v8, v5
	v_rcp_f32_e32 v23, v22
	v_fmac_f32_e32 v8, v9, v27
	v_fma_f32 v5, -v25, v8, v5
	v_div_fmas_f32 v5, v5, v27, v8
	v_div_fixup_f32 v9, v5, v21, v26
	v_fma_f32 v5, -v22, v23, 1.0
	v_fmac_f32_e32 v23, v5, v23
	v_div_scale_f32 v5, vcc, v24, v20, v24
	v_mul_f32_e32 v8, v5, v23
	v_fma_f32 v18, -v22, v8, v5
	v_lshlrev_b32_e32 v21, 16, v6
	v_and_b32_e32 v6, 0xffff0000, v6
	v_fmac_f32_e32 v8, v18, v23
	v_mul_f32_e32 v18, 0xbfb8aa3b, v21
	v_mul_f32_e32 v19, 0xbfb8aa3b, v6
	v_exp_f32_e32 v18, v18
	v_exp_f32_e32 v19, v19
	v_fma_f32 v5, -v22, v8, v5
	v_div_fmas_f32 v5, v5, v23, v8
	v_div_fixup_f32 v8, v5, v20, v24
	v_pk_add_f32 v[18:19], v[18:19], 1.0 op_sel_hi:[1,0]
	v_pk_mul_f32 v[8:9], v[10:11], v[8:9]
	v_div_scale_f32 v22, s[10:11], v19, v19, v6
	v_rcp_f32_e32 v23, v22
	v_cvt_pk_bf16_f32 v5, v8, v9
	v_lshlrev_b32_e32 v20, 16, v7
	v_fma_f32 v8, -v22, v23, 1.0
	v_fmac_f32_e32 v23, v8, v23
	v_div_scale_f32 v8, vcc, v6, v19, v6
	v_mul_f32_e32 v9, v8, v23
	v_fma_f32 v10, -v22, v9, v8
	v_fmac_f32_e32 v9, v10, v23
	v_div_scale_f32 v10, s[10:11], v18, v18, v21
	v_rcp_f32_e32 v11, v10
	v_fma_f32 v8, -v22, v9, v8
	v_div_fmas_f32 v8, v8, v23, v9
	v_div_fixup_f32 v9, v8, v19, v6
	v_fma_f32 v6, -v10, v11, 1.0
	v_fmac_f32_e32 v11, v6, v11
	v_div_scale_f32 v8, vcc, v21, v18, v21
	v_mul_f32_e32 v19, v8, v11
	v_fma_f32 v6, -v10, v19, v8
	v_and_b32_e32 v22, 0xffff0000, v7
	v_fmac_f32_e32 v19, v6, v11
	v_mul_f32_e32 v6, 0xbfb8aa3b, v20
	v_mul_f32_e32 v7, 0xbfb8aa3b, v22
	v_exp_f32_e32 v6, v6
	v_exp_f32_e32 v7, v7
	v_fma_f32 v8, -v10, v19, v8
	v_div_fmas_f32 v8, v8, v11, v19
	v_div_fixup_f32 v8, v8, v18, v21
	v_pk_add_f32 v[10:11], v[6:7], 1.0 op_sel_hi:[1,0]
	s_waitcnt lgkmcnt(0)
	v_pk_mul_f32 v[6:7], v[12:13], v[8:9]
	v_div_scale_f32 v19, s[10:11], v11, v11, v22
	v_rcp_f32_e32 v23, v19
	v_cvt_pk_bf16_f32 v6, v6, v7
	v_div_scale_f32 v12, s[10:11], v10, v10, v20
	v_fma_f32 v7, -v19, v23, 1.0
	v_fmac_f32_e32 v23, v7, v23
	v_div_scale_f32 v7, vcc, v22, v11, v22
	v_mul_f32_e32 v8, v7, v23
	v_fma_f32 v9, -v19, v8, v7
	v_rcp_f32_e32 v13, v12
	v_fmac_f32_e32 v8, v9, v23
	v_fma_f32 v7, -v19, v8, v7
	v_div_fmas_f32 v7, v7, v23, v8
	v_div_fixup_f32 v9, v7, v11, v22
	v_fma_f32 v7, -v12, v13, 1.0
	v_fmac_f32_e32 v13, v7, v13
	v_div_scale_f32 v7, vcc, v20, v10, v20
	v_mul_f32_e32 v8, v7, v13
	v_fma_f32 v11, -v12, v8, v7
	v_fmac_f32_e32 v8, v11, v13
	v_fma_f32 v7, -v12, v8, v7
	v_div_fmas_f32 v7, v7, v13, v8
	v_div_fixup_f32 v8, v7, v10, v20
	v_pk_mul_f32 v[8:9], v[14:15], v[8:9]
	s_nop 0
	v_cvt_pk_bf16_f32 v7, v8, v9
	v_lshlrev_b64 v[8:9], 11, v[16:17]
	v_lshl_add_u64 v[8:9], v[0:1], 0, v[8:9]
	v_or_b32_e32 v16, s9, v196
	global_store_dwordx4 v[8:9], v[4:7], off sc0 sc1
	s_nop 1
	v_mad_u64_u32 v[4:5], s[10:11], v16, s2, v[2:3]
	v_mad_i32_i24 v5, s8, v28, v5
	v_lshl_add_u64 v[4:5], v[4:5], 0, s[6:7]
	v_lshl_add_u64 v[4:5], v[4:5], 0, v[204:205]
	s_waitcnt vmcnt(3)
	v_mov_b32_e32 v4, v92
	v_mov_b32_e32 v5, v93
	v_mov_b32_e32 v6, v94
	v_mov_b32_e32 v7, v95
	v_lshlrev_b32_e32 v22, 16, v4
	v_and_b32_e32 v4, 0xffff0000, v4
	v_mul_f32_e32 v8, 0xbfb8aa3b, v22
	v_mul_f32_e32 v9, 0xbfb8aa3b, v4
	v_exp_f32_e32 v8, v8
	v_exp_f32_e32 v9, v9
	v_and_b32_e32 v26, 0xffff0000, v5
	v_pk_add_f32 v[18:19], v[8:9], 1.0 op_sel_hi:[1,0]
	s_nop 0
	v_div_scale_f32 v20, s[10:11], v19, v19, v4
	v_rcp_f32_e32 v21, v20
	ds_read_b128 v[8:11], v250 offset:4352
	ds_read_b128 v[12:15], v250 offset:4368
	v_fma_f32 v23, -v20, v21, 1.0
	v_fmac_f32_e32 v21, v23, v21
	v_div_scale_f32 v23, vcc, v4, v19, v4
	v_mul_f32_e32 v24, v23, v21
	v_fma_f32 v25, -v20, v24, v23
	v_fmac_f32_e32 v24, v25, v21
	v_fma_f32 v20, -v20, v24, v23
	v_div_scale_f32 v23, s[10:11], v18, v18, v22
	v_rcp_f32_e32 v25, v23
	v_div_fmas_f32 v20, v20, v21, v24
	v_div_fixup_f32 v19, v20, v19, v4
	v_div_scale_f32 v20, vcc, v22, v18, v22
	v_fma_f32 v4, -v23, v25, 1.0
	v_fmac_f32_e32 v25, v4, v25
	v_mul_f32_e32 v21, v20, v25
	v_fma_f32 v4, -v23, v21, v20
	v_lshlrev_b32_e32 v24, 16, v5
	v_fmac_f32_e32 v21, v4, v25
	v_mul_f32_e32 v4, 0xbfb8aa3b, v24
	v_mul_f32_e32 v5, 0xbfb8aa3b, v26
	v_exp_f32_e32 v4, v4
	v_exp_f32_e32 v5, v5
	v_fma_f32 v20, -v23, v21, v20
	v_div_fmas_f32 v23, v20, v25, v21
	v_div_fixup_f32 v18, v23, v18, v22
	v_pk_add_f32 v[20:21], v[4:5], 1.0 op_sel_hi:[1,0]
	s_waitcnt lgkmcnt(1)
; #define LAS __attribute__((address_space(3)))
; __device__ __forceinline__ unsigned cvtpk(float lo, float hi) { f32x2_t v = {lo, hi}; bf16x2_t b = __builtin_convertvector(v, bf16x2_t); return __builtin_bit_cast(unsigned, b); }
; __device__ __forceinline__ float silu_f(float x) { return x / (1.0f + __expf(-x)); }
; __device__ __forceinline__ void mla_attn_phase(LAS unsigned char* lds, const bf16_t* q, const bf16_t* kv, const bf16_t* krope, const bf16_t* projb, bf16_t* y, int unit0, int G, int nu) {
;     ...
;     for (int i = 0; i < 4; ++i) { const int row = i * 8 + (lane >> 3), c8 = lane & 7; const size_t tok = row0 + qb * 256 + w * 32 + row;
;         const f32x4 x0 = *(const LAS f32x4*)(stg + row * 68 + c8 * 8), x1 = *(const LAS f32x4*)(stg + row * 68 + c8 * 8 + 4);
;         const u32x4 g = *(const u32x4*)(projb + tok * B_INP + 672 + h * 64 + c8 * 8);
;         u32x4 yo; yo.x = cvtpk(x0[0] * silu_f(bf_lo(g.x)), x0[1] * silu_f(bf_hi(g.x))); yo.y = cvtpk(x0[2] * silu_f(bf_lo(g.y)), x0[3] * silu_f(bf_hi(g.y)));
;         yo.z = cvtpk(x1[0] * silu_f(bf_lo(g.z)), x1[1] * silu_f(bf_hi(g.z))); yo.w = cvtpk(x1[2] * silu_f(bf_lo(g.w)), x1[3] * silu_f(bf_hi(g.w)));
;         *(u32x4*)(y + tok * DM + h * 64 + c8 * 8) = yo; }
	v_pk_mul_f32 v[4:5], v[8:9], v[18:19]
	v_div_scale_f32 v25, s[10:11], v21, v21, v26
	v_rcp_f32_e32 v27, v25
	v_cvt_pk_bf16_f32 v4, v4, v5
	v_div_scale_f32 v22, s[10:11], v20, v20, v24
	v_fma_f32 v5, -v25, v27, 1.0
	v_fmac_f32_e32 v27, v5, v27
	v_div_scale_f32 v5, vcc, v26, v21, v26
	v_mul_f32_e32 v8, v5, v27
	v_fma_f32 v9, -v25, v8, v5
	v_rcp_f32_e32 v23, v22
	v_fmac_f32_e32 v8, v9, v27
	v_fma_f32 v5, -v25, v8, v5
	v_div_fmas_f32 v5, v5, v27, v8
	v_div_fixup_f32 v9, v5, v21, v26
	v_fma_f32 v5, -v22, v23, 1.0
	v_fmac_f32_e32 v23, v5, v23
	v_div_scale_f32 v5, vcc, v24, v20, v24
	v_mul_f32_e32 v8, v5, v23
	v_fma_f32 v18, -v22, v8, v5
	v_lshlrev_b32_e32 v21, 16, v6
	v_and_b32_e32 v6, 0xffff0000, v6
	v_fmac_f32_e32 v8, v18, v23
	v_mul_f32_e32 v18, 0xbfb8aa3b, v21
	v_mul_f32_e32 v19, 0xbfb8aa3b, v6
	v_exp_f32_e32 v18, v18
	v_exp_f32_e32 v19, v19
	v_fma_f32 v5, -v22, v8, v5
	v_div_fmas_f32 v5, v5, v23, v8
	v_div_fixup_f32 v8, v5, v20, v24
	v_pk_add_f32 v[18:19], v[18:19], 1.0 op_sel_hi:[1,0]
	v_pk_mul_f32 v[8:9], v[10:11], v[8:9]
	v_div_scale_f32 v22, s[10:11], v19, v19, v6
	v_rcp_f32_e32 v23, v22
	v_cvt_pk_bf16_f32 v5, v8, v9
	v_lshlrev_b32_e32 v20, 16, v7
	v_fma_f32 v8, -v22, v23, 1.0
	v_fmac_f32_e32 v23, v8, v23
	v_div_scale_f32 v8, vcc, v6, v19, v6
	v_mul_f32_e32 v9, v8, v23
	v_fma_f32 v10, -v22, v9, v8
	v_fmac_f32_e32 v9, v10, v23
	v_div_scale_f32 v10, s[10:11], v18, v18, v21
	v_rcp_f32_e32 v11, v10
	v_fma_f32 v8, -v22, v9, v8
	v_div_fmas_f32 v8, v8, v23, v9
	v_div_fixup_f32 v9, v8, v19, v6
	v_fma_f32 v6, -v10, v11, 1.0
	v_fmac_f32_e32 v11, v6, v11
	v_div_scale_f32 v8, vcc, v21, v18, v21
	v_mul_f32_e32 v19, v8, v11
	v_fma_f32 v6, -v10, v19, v8
	v_and_b32_e32 v22, 0xffff0000, v7
	v_fmac_f32_e32 v19, v6, v11
	v_mul_f32_e32 v6, 0xbfb8aa3b, v20
	v_mul_f32_e32 v7, 0xbfb8aa3b, v22
	v_exp_f32_e32 v6, v6
	v_exp_f32_e32 v7, v7
	v_fma_f32 v8, -v10, v19, v8
	v_div_fmas_f32 v8, v8, v11, v19
	v_div_fixup_f32 v8, v8, v18, v21
	v_pk_add_f32 v[10:11], v[6:7], 1.0 op_sel_hi:[1,0]
	s_waitcnt lgkmcnt(0)
	v_pk_mul_f32 v[6:7], v[12:13], v[8:9]
	v_div_scale_f32 v19, s[10:11], v11, v11, v22
	v_rcp_f32_e32 v23, v19
	v_cvt_pk_bf16_f32 v6, v6, v7
	v_div_scale_f32 v12, s[10:11], v10, v10, v20
	v_fma_f32 v7, -v19, v23, 1.0
	v_fmac_f32_e32 v23, v7, v23
	v_div_scale_f32 v7, vcc, v22, v11, v22
	v_mul_f32_e32 v8, v7, v23
	v_fma_f32 v9, -v19, v8, v7
	v_rcp_f32_e32 v13, v12
	v_fmac_f32_e32 v8, v9, v23
	v_fma_f32 v7, -v19, v8, v7
	v_div_fmas_f32 v7, v7, v23, v8
	v_div_fixup_f32 v9, v7, v11, v22
	v_fma_f32 v7, -v12, v13, 1.0
	v_fmac_f32_e32 v13, v7, v13
	v_div_scale_f32 v7, vcc, v20, v10, v20
	v_mul_f32_e32 v8, v7, v13
	v_fma_f32 v11, -v12, v8, v7
	v_fmac_f32_e32 v8, v11, v13
	v_fma_f32 v7, -v12, v8, v7
	v_div_fmas_f32 v7, v7, v13, v8
	v_div_fixup_f32 v8, v7, v10, v20
	v_pk_mul_f32 v[8:9], v[14:15], v[8:9]
	v_or_b32_e32 v14, s9, v198
	v_mad_u64_u32 v[2:3], s[10:11], v14, s2, v[2:3]
	v_cvt_pk_bf16_f32 v7, v8, v9
	v_lshlrev_b64 v[8:9], 11, v[16:17]
	v_mad_i32_i24 v3, s8, v28, v3
	v_lshl_add_u64 v[8:9], v[0:1], 0, v[8:9]
	v_lshl_add_u64 v[2:3], v[2:3], 0, s[6:7]
	global_store_dwordx4 v[8:9], v[4:7], off sc0 sc1
	v_lshl_add_u64 v[2:3], v[2:3], 0, v[204:205]
	v_mov_b32_e32 v15, s8
	s_mov_b32 s2, s3
	s_waitcnt vmcnt(3)
; #define LAS __attribute__((address_space(3)))
; __device__ __forceinline__ unsigned cvtpk(float lo, float hi) { f32x2_t v = {lo, hi}; bf16x2_t b = __builtin_convertvector(v, bf16x2_t); return __builtin_bit_cast(unsigned, b); }
; __device__ __forceinline__ float silu_f(float x) { return x / (1.0f + __expf(-x)); }
; __device__ __forceinline__ void mla_attn_phase(LAS unsigned char* lds, const bf16_t* q, const bf16_t* kv, const bf16_t* krope, const bf16_t* projb, bf16_t* y, int unit0, int G, int nu) {
;     ...
;     for (int i = 0; i < 4; ++i) { const int row = i * 8 + (lane >> 3), c8 = lane & 7; const size_t tok = row0 + qb * 256 + w * 32 + row;
;         const f32x4 x0 = *(const LAS f32x4*)(stg + row * 68 + c8 * 8), x1 = *(const LAS f32x4*)(stg + row * 68 + c8 * 8 + 4);
;         const u32x4 g = *(const u32x4*)(projb + tok * B_INP + 672 + h * 64 + c8 * 8);
;         u32x4 yo; yo.x = cvtpk(x0[0] * silu_f(bf_lo(g.x)), x0[1] * silu_f(bf_hi(g.x))); yo.y = cvtpk(x0[2] * silu_f(bf_lo(g.y)), x0[3] * silu_f(bf_hi(g.y)));
;         yo.z = cvtpk(x1[0] * silu_f(bf_lo(g.z)), x1[1] * silu_f(bf_hi(g.z))); yo.w = cvtpk(x1[2] * silu_f(bf_lo(g.w)), x1[3] * silu_f(bf_hi(g.w)));
;         *(u32x4*)(y + tok * DM + h * 64 + c8 * 8) = yo; }
;     __syncthreads();
	v_mov_b32_e32 v2, v96
	v_mov_b32_e32 v3, v97
	v_mov_b32_e32 v4, v98
	v_mov_b32_e32 v5, v99
	v_lshlrev_b32_e32 v20, 16, v2
	v_and_b32_e32 v2, 0xffff0000, v2
	v_mul_f32_e32 v6, 0xbfb8aa3b, v20
	v_mul_f32_e32 v7, 0xbfb8aa3b, v2
	v_exp_f32_e32 v6, v6
	v_exp_f32_e32 v7, v7
	v_and_b32_e32 v24, 0xffff0000, v3
	v_pk_add_f32 v[16:17], v[6:7], 1.0 op_sel_hi:[1,0]
	s_nop 0
	v_div_scale_f32 v18, s[6:7], v17, v17, v2
	v_rcp_f32_e32 v19, v18
	ds_read_b128 v[6:9], v250 offset:6528
	ds_read_b128 v[10:13], v250 offset:6544
	v_fma_f32 v21, -v18, v19, 1.0
	v_fmac_f32_e32 v19, v21, v19
	v_div_scale_f32 v21, vcc, v2, v17, v2
	v_mul_f32_e32 v22, v21, v19
	v_fma_f32 v23, -v18, v22, v21
	v_fmac_f32_e32 v22, v23, v19
	v_fma_f32 v18, -v18, v22, v21
	v_div_scale_f32 v21, s[6:7], v16, v16, v20
	v_rcp_f32_e32 v23, v21
	v_div_fmas_f32 v18, v18, v19, v22
	v_div_fixup_f32 v17, v18, v17, v2
	v_div_scale_f32 v18, vcc, v20, v16, v20
	v_fma_f32 v2, -v21, v23, 1.0
	v_fmac_f32_e32 v23, v2, v23
	v_mul_f32_e32 v19, v18, v23
	v_fma_f32 v2, -v21, v19, v18
	v_lshlrev_b32_e32 v22, 16, v3
	v_fmac_f32_e32 v19, v2, v23
	v_mul_f32_e32 v2, 0xbfb8aa3b, v22
	v_mul_f32_e32 v3, 0xbfb8aa3b, v24
	v_exp_f32_e32 v2, v2
	v_exp_f32_e32 v3, v3
	v_fma_f32 v18, -v21, v19, v18
	v_div_fmas_f32 v21, v18, v23, v19
	v_div_fixup_f32 v16, v21, v16, v20
	v_pk_add_f32 v[18:19], v[2:3], 1.0 op_sel_hi:[1,0]
	s_waitcnt lgkmcnt(1)
	v_pk_mul_f32 v[2:3], v[6:7], v[16:17]
	v_div_scale_f32 v23, s[6:7], v19, v19, v24
	v_rcp_f32_e32 v25, v23
	v_cvt_pk_bf16_f32 v2, v2, v3
	v_div_scale_f32 v20, s[6:7], v18, v18, v22
	v_fma_f32 v3, -v23, v25, 1.0
	v_fmac_f32_e32 v25, v3, v25
	v_div_scale_f32 v3, vcc, v24, v19, v24
	v_mul_f32_e32 v6, v3, v25
	v_fma_f32 v7, -v23, v6, v3
	v_rcp_f32_e32 v21, v20
	v_fmac_f32_e32 v6, v7, v25
	v_fma_f32 v3, -v23, v6, v3
	v_div_fmas_f32 v3, v3, v25, v6
	v_div_fixup_f32 v7, v3, v19, v24
	v_fma_f32 v3, -v20, v21, 1.0
	v_fmac_f32_e32 v21, v3, v21
	v_div_scale_f32 v3, vcc, v22, v18, v22
	v_mul_f32_e32 v6, v3, v21
	v_fma_f32 v16, -v20, v6, v3
	v_lshlrev_b32_e32 v19, 16, v4
	v_and_b32_e32 v4, 0xffff0000, v4
	v_fmac_f32_e32 v6, v16, v21
	v_mul_f32_e32 v16, 0xbfb8aa3b, v19
	v_mul_f32_e32 v17, 0xbfb8aa3b, v4
	v_exp_f32_e32 v16, v16
	v_exp_f32_e32 v17, v17
	v_fma_f32 v3, -v20, v6, v3
	v_div_fmas_f32 v3, v3, v21, v6
	v_div_fixup_f32 v6, v3, v18, v22
	v_pk_add_f32 v[16:17], v[16:17], 1.0 op_sel_hi:[1,0]
	v_pk_mul_f32 v[6:7], v[8:9], v[6:7]
	v_div_scale_f32 v20, s[6:7], v17, v17, v4
	v_rcp_f32_e32 v21, v20
	v_cvt_pk_bf16_f32 v3, v6, v7
	v_lshlrev_b32_e32 v18, 16, v5
	v_fma_f32 v6, -v20, v21, 1.0
	v_fmac_f32_e32 v21, v6, v21
	v_div_scale_f32 v6, vcc, v4, v17, v4
	v_mul_f32_e32 v7, v6, v21
	v_fma_f32 v8, -v20, v7, v6
	v_fmac_f32_e32 v7, v8, v21
	v_div_scale_f32 v8, s[6:7], v16, v16, v19
	v_rcp_f32_e32 v9, v8
	v_fma_f32 v6, -v20, v7, v6
	v_div_fmas_f32 v6, v6, v21, v7
	v_div_fixup_f32 v7, v6, v17, v4
	v_fma_f32 v4, -v8, v9, 1.0
	v_fmac_f32_e32 v9, v4, v9
	v_div_scale_f32 v6, vcc, v19, v16, v19
	v_mul_f32_e32 v17, v6, v9
	v_fma_f32 v4, -v8, v17, v6
	v_and_b32_e32 v20, 0xffff0000, v5
	v_fmac_f32_e32 v17, v4, v9
	v_mul_f32_e32 v4, 0xbfb8aa3b, v18
	v_mul_f32_e32 v5, 0xbfb8aa3b, v20
	v_exp_f32_e32 v4, v4
	v_exp_f32_e32 v5, v5
	v_fma_f32 v6, -v8, v17, v6
	v_div_fmas_f32 v6, v6, v9, v17
	v_div_fixup_f32 v6, v6, v16, v19
	v_pk_add_f32 v[8:9], v[4:5], 1.0 op_sel_hi:[1,0]
	s_waitcnt lgkmcnt(0)
	v_pk_mul_f32 v[4:5], v[10:11], v[6:7]
	v_div_scale_f32 v17, s[6:7], v9, v9, v20
	v_rcp_f32_e32 v21, v17
	v_cvt_pk_bf16_f32 v4, v4, v5
	v_div_scale_f32 v10, s[6:7], v8, v8, v18
	v_fma_f32 v5, -v17, v21, 1.0
	v_fmac_f32_e32 v21, v5, v21
	v_div_scale_f32 v5, vcc, v20, v9, v20
	v_mul_f32_e32 v6, v5, v21
	v_fma_f32 v7, -v17, v6, v5
	v_rcp_f32_e32 v11, v10
	v_fmac_f32_e32 v6, v7, v21
	v_fma_f32 v5, -v17, v6, v5
	v_div_fmas_f32 v5, v5, v21, v6
	v_div_fixup_f32 v7, v5, v9, v20
	v_fma_f32 v5, -v10, v11, 1.0
	v_fmac_f32_e32 v11, v5, v11
	v_div_scale_f32 v5, vcc, v18, v8, v18
	v_mul_f32_e32 v6, v5, v11
	v_fma_f32 v9, -v10, v6, v5
	v_fmac_f32_e32 v6, v9, v11
	v_fma_f32 v5, -v10, v6, v5
	v_div_fmas_f32 v5, v5, v11, v6
	v_div_fixup_f32 v6, v5, v8, v18
	v_pk_mul_f32 v[6:7], v[12:13], v[6:7]
	s_nop 0
	v_cvt_pk_bf16_f32 v5, v6, v7
	v_lshlrev_b64 v[6:7], 11, v[14:15]
	v_lshl_add_u64 v[0:1], v[0:1], 0, v[6:7]
	global_store_dwordx4 v[0:1], v[2:5], off sc0 sc1
	s_barrier
	s_cbranch_scc1 .LBB0_211

; __device__ __forceinline__ unsigned cvtpk(float lo, float hi) { f32x2_t v = {lo, hi}; bf16x2_t b = __builtin_convertvector(v, bf16x2_t); return __builtin_bit_cast(unsigned, b); }
; __device__ __forceinline__ void mla_prep_phase(const bf16_t* projb, const float* gq, const float* gkv, const float* cs, bf16_t* cqn, bf16_t* ckvn, bf16_t* krope, int rows) {
;     ...
;             if (lane < 16) { u32x4 ob; ob.x = cvtpk(xb[0] * rkv * gB0[0], xb[1] * rkv * gB0[1]); ob.y = cvtpk(xb[2] * rkv * gB0[2], xb[3] * rkv * gB0[3]);
;                 ob.z = cvtpk(xb[4] * rkv * gB1[0], xb[5] * rkv * gB1[1]); ob.w = cvtpk(xb[6] * rkv * gB1[2], xb[7] * rkv * gB1[3]);
;                 *(u32x4*)(ckvn + (size_t)m * 256 + 8 * (16 + lane)) = ob;
;                 const float x1 = bf1(r1[r]), x2 = bf1(r2[r]);
;                 *(unsigned*)(krope + (size_t)m * 32 + 2 * lane) = cvtpk(x1 * cc[r] - x2 * sn[r], x1 * sn[r] + x2 * cc[r]); } }
.LBB0_220:
	v_pk_mul_f32 v[42:43], v[88:89], v[84:85] op_sel_hi:[0,1]
	v_pk_mul_f32 v[42:43], v[0:1], v[42:43]
	s_nop 0
	v_cvt_pk_bf16_f32 v84, v42, v43
	v_pk_mul_f32 v[42:43], v[88:89], v[82:83] op_sel_hi:[0,1]
	v_pk_mul_f32 v[42:43], v[2:3], v[42:43]
	s_nop 0
	v_cvt_pk_bf16_f32 v85, v42, v43
	v_pk_mul_f32 v[42:43], v[88:89], v[80:81] op_sel_hi:[0,1]
	v_pk_mul_f32 v[42:43], v[4:5], v[42:43]
	s_nop 0
	v_cvt_pk_bf16_f32 v86, v42, v43
	v_pk_mul_f32 v[42:43], v[88:89], v[78:79] op_sel_hi:[0,1]
	v_pk_mul_f32 v[42:43], v[6:7], v[42:43]
	s_nop 0
	v_cvt_pk_bf16_f32 v87, v42, v43
	s_waitcnt vmcnt(20)
	v_lshlrev_b32_e32 v43, 16, v77
	v_lshlrev_b32_e32 v42, 16, v75
	s_waitcnt vmcnt(18)
	v_pk_mul_f32 v[76:77], v[76:77], v[42:43] op_sel:[0,1] op_sel_hi:[0,0]
	v_pk_fma_f32 v[78:79], v[74:75], v[42:43], v[76:77] neg_lo:[0,0,1] neg_hi:[0,0,1]
	v_pk_fma_f32 v[42:43], v[74:75], v[42:43], v[76:77] op_sel_hi:[0,1,1]
	v_cvt_pk_bf16_f32 v42, v78, v43
	global_store_dwordx4 v[44:45], v[84:87], off offset:-512 sc0 sc1
	global_store_dword v[40:41], v42, off offset:-128

; __device__ __forceinline__ unsigned cvtpk(float lo, float hi) { f32x2_t v = {lo, hi}; bf16x2_t b = __builtin_convertvector(v, bf16x2_t); return __builtin_bit_cast(unsigned, b); }
; __device__ __forceinline__ void mla_prep_phase(const bf16_t* projb, const float* gq, const float* gkv, const float* cs, bf16_t* cqn, bf16_t* ckvn, bf16_t* krope, int rows) {
;     ...
;             u32x4 oa; oa.x = cvtpk(xa[0] * ra * gA0[0], xa[1] * ra * gA0[1]); oa.y = cvtpk(xa[2] * ra * gA0[2], xa[3] * ra * gA0[3]);
;             oa.z = cvtpk(xa[4] * ra * gA1[0], xa[5] * ra * gA1[1]); oa.w = cvtpk(xa[6] * ra * gA1[2], xa[7] * ra * gA1[3]);
;             if (aq) *(u32x4*)(cqn + (size_t)m * 384 + 8 * lane) = oa; else *(u32x4*)(ckvn + (size_t)m * 256 + 8 * (lane - 48)) = oa;
;             if (lane < 16) { u32x4 ob; ob.x = cvtpk(xb[0] * rkv * gB0[0], xb[1] * rkv * gB0[1]); ob.y = cvtpk(xb[2] * rkv * gB0[2], xb[3] * rkv * gB0[3]);
;                 ob.z = cvtpk(xb[4] * rkv * gB1[0], xb[5] * rkv * gB1[1]); ob.w = cvtpk(xb[6] * rkv * gB1[2], xb[7] * rkv * gB1[3]);
;                 *(u32x4*)(ckvn + (size_t)m * 256 + 8 * (16 + lane)) = ob;
;                 const float x1 = bf1(r1[r]), x2 = bf1(r2[r]);
;                 *(unsigned*)(krope + (size_t)m * 32 + 2 * lane) = cvtpk(x1 * cc[r] - x2 * sn[r], x1 * sn[r] + x2 * cc[r]); } }
.LBB0_224:
	v_pk_mul_f32 v[32:33], v[84:85], v[42:43] op_sel_hi:[0,1]
	v_pk_mul_f32 v[34:35], v[84:85], v[36:37] op_sel_hi:[0,1]
	v_pk_mul_f32 v[32:33], v[0:1], v[32:33]
	v_pk_mul_f32 v[34:35], v[2:3], v[34:35]
	v_cvt_pk_bf16_f32 v32, v32, v33
	v_cvt_pk_bf16_f32 v33, v34, v35
	v_pk_mul_f32 v[34:35], v[84:85], v[74:75] op_sel_hi:[0,1]
	v_pk_mul_f32 v[36:37], v[84:85], v[38:39] op_sel_hi:[0,1]
	v_pk_mul_f32 v[34:35], v[4:5], v[34:35]
	v_pk_mul_f32 v[36:37], v[6:7], v[36:37]
	v_cvt_pk_bf16_f32 v34, v34, v35
	v_cvt_pk_bf16_f32 v35, v36, v37
	global_store_dwordx4 v[44:45], v[32:35], off sc0 sc1
	s_waitcnt vmcnt(15)
	s_nop 0
	v_lshlrev_b32_e32 v33, 16, v95
	v_lshlrev_b32_e32 v32, 16, v71
	s_waitcnt vmcnt(13)
	v_pk_mul_f32 v[34:35], v[72:73], v[32:33] op_sel:[0,1] op_sel_hi:[0,0]
	v_pk_fma_f32 v[36:37], v[70:71], v[32:33], v[34:35] neg_lo:[0,0,1] neg_hi:[0,0,1]
	v_pk_fma_f32 v[32:33], v[70:71], v[32:33], v[34:35] op_sel_hi:[0,1,1]
	v_cvt_pk_bf16_f32 v32, v36, v33
	global_store_dword v[40:41], v32, off offset:-64

; __device__ __forceinline__ unsigned cvtpk(float lo, float hi) { f32x2_t v = {lo, hi}; bf16x2_t b = __builtin_convertvector(v, bf16x2_t); return __builtin_bit_cast(unsigned, b); }
; __device__ __forceinline__ void mla_prep_phase(const bf16_t* projb, const float* gq, const float* gkv, const float* cs, bf16_t* cqn, bf16_t* ckvn, bf16_t* krope, int rows) {
;     ...
;             u32x4 oa; oa.x = cvtpk(xa[0] * ra * gA0[0], xa[1] * ra * gA0[1]); oa.y = cvtpk(xa[2] * ra * gA0[2], xa[3] * ra * gA0[3]);
;             oa.z = cvtpk(xa[4] * ra * gA1[0], xa[5] * ra * gA1[1]); oa.w = cvtpk(xa[6] * ra * gA1[2], xa[7] * ra * gA1[3]);
;             if (aq) *(u32x4*)(cqn + (size_t)m * 384 + 8 * lane) = oa; else *(u32x4*)(ckvn + (size_t)m * 256 + 8 * (lane - 48)) = oa;
;             if (lane < 16) { u32x4 ob; ob.x = cvtpk(xb[0] * rkv * gB0[0], xb[1] * rkv * gB0[1]); ob.y = cvtpk(xb[2] * rkv * gB0[2], xb[3] * rkv * gB0[3]);
;                 ob.z = cvtpk(xb[4] * rkv * gB1[0], xb[5] * rkv * gB1[1]); ob.w = cvtpk(xb[6] * rkv * gB1[2], xb[7] * rkv * gB1[3]);
;                 *(u32x4*)(ckvn + (size_t)m * 256 + 8 * (16 + lane)) = ob;
;                 const float x1 = bf1(r1[r]), x2 = bf1(r2[r]);
;                 *(unsigned*)(krope + (size_t)m * 32 + 2 * lane) = cvtpk(x1 * cc[r] - x2 * sn[r], x1 * sn[r] + x2 * cc[r]); } }
.LBB0_228:
	v_pk_mul_f32 v[24:25], v[72:73], v[32:33] op_sel_hi:[0,1]
	v_pk_mul_f32 v[26:27], v[72:73], v[28:29] op_sel_hi:[0,1]
	v_pk_mul_f32 v[24:25], v[0:1], v[24:25]
	v_pk_mul_f32 v[26:27], v[2:3], v[26:27]
	v_cvt_pk_bf16_f32 v24, v24, v25
	v_cvt_pk_bf16_f32 v25, v26, v27
	v_pk_mul_f32 v[26:27], v[72:73], v[34:35] op_sel_hi:[0,1]
	v_pk_mul_f32 v[28:29], v[72:73], v[30:31] op_sel_hi:[0,1]
	v_pk_mul_f32 v[26:27], v[4:5], v[26:27]
	v_pk_mul_f32 v[28:29], v[6:7], v[28:29]
	v_cvt_pk_bf16_f32 v26, v26, v27
	v_cvt_pk_bf16_f32 v27, v28, v29
	global_store_dwordx4 v[44:45], v[24:27], off offset:512 sc0 sc1
	s_waitcnt vmcnt(9)
	s_nop 0
	v_lshlrev_b32_e32 v25, 16, v94
	v_lshlrev_b32_e32 v24, 16, v93
	s_waitcnt vmcnt(7)
	v_pk_mul_f32 v[26:27], v[68:69], v[24:25] op_sel:[0,1] op_sel_hi:[0,0]
	v_pk_fma_f32 v[28:29], v[66:67], v[24:25], v[26:27] neg_lo:[0,0,1] neg_hi:[0,0,1]
	v_pk_fma_f32 v[24:25], v[66:67], v[24:25], v[26:27] op_sel_hi:[0,1,1]
	v_cvt_pk_bf16_f32 v24, v28, v25
	global_store_dword v[40:41], v24, off

; __device__ __forceinline__ unsigned cvtpk(float lo, float hi) { f32x2_t v = {lo, hi}; bf16x2_t b = __builtin_convertvector(v, bf16x2_t); return __builtin_bit_cast(unsigned, b); }
; __device__ __forceinline__ void mla_prep_phase(const bf16_t* projb, const float* gq, const float* gkv, const float* cs, bf16_t* cqn, bf16_t* ckvn, bf16_t* krope, int rows) {
;     ...
;             u32x4 oa; oa.x = cvtpk(xa[0] * ra * gA0[0], xa[1] * ra * gA0[1]); oa.y = cvtpk(xa[2] * ra * gA0[2], xa[3] * ra * gA0[3]);
;             oa.z = cvtpk(xa[4] * ra * gA1[0], xa[5] * ra * gA1[1]); oa.w = cvtpk(xa[6] * ra * gA1[2], xa[7] * ra * gA1[3]);
;             if (aq) *(u32x4*)(cqn + (size_t)m * 384 + 8 * lane) = oa; else *(u32x4*)(ckvn + (size_t)m * 256 + 8 * (lane - 48)) = oa;
;             if (lane < 16) { u32x4 ob; ob.x = cvtpk(xb[0] * rkv * gB0[0], xb[1] * rkv * gB0[1]); ob.y = cvtpk(xb[2] * rkv * gB0[2], xb[3] * rkv * gB0[3]);
;                 ob.z = cvtpk(xb[4] * rkv * gB1[0], xb[5] * rkv * gB1[1]); ob.w = cvtpk(xb[6] * rkv * gB1[2], xb[7] * rkv * gB1[3]);
;                 *(u32x4*)(ckvn + (size_t)m * 256 + 8 * (16 + lane)) = ob;
;                 const float x1 = bf1(r1[r]), x2 = bf1(r2[r]);
;                 *(unsigned*)(krope + (size_t)m * 32 + 2 * lane) = cvtpk(x1 * cc[r] - x2 * sn[r], x1 * sn[r] + x2 * cc[r]); } }
.LBB0_232:
	global_store_dwordx4 v[44:45], v[40:43], off offset:-1536 sc0 sc1
	s_or_saveexec_b64 s[0:1], s[0:1]
	v_lshl_add_u64 v[46:47], s[42:43], 0, v[58:59]
	s_xor_b64 exec, exec, s[0:1]
	s_cbranch_execz .LBB0_219
.LBB0_233:
	global_store_dwordx4 v[46:47], v[40:43], off offset:-1536 sc0 sc1
	s_or_b64 exec, exec, s[0:1]
	s_nop 0
	v_lshl_add_u64 v[40:41], s[42:43], 0, v[60:61]
	s_and_saveexec_b64 s[0:1], s[8:9]
	s_cbranch_execnz .LBB0_220
	s_branch .LBB0_221
.LBB0_234:
	global_store_dwordx4 v[44:45], v[32:35], off offset:-1024 sc0 sc1
	s_andn2_saveexec_b64 s[0:1], s[0:1]
	s_cbranch_execz .LBB0_223
.LBB0_235:
	global_store_dwordx4 v[46:47], v[32:35], off offset:-768 sc0 sc1
	s_or_b64 exec, exec, s[0:1]
	s_and_saveexec_b64 s[0:1], s[8:9]
	s_cbranch_execnz .LBB0_224
	s_branch .LBB0_225
.LBB0_236:
	global_store_dwordx4 v[44:45], v[24:27], off offset:-512 sc0 sc1
	s_andn2_saveexec_b64 s[0:1], s[0:1]
	s_cbranch_execz .LBB0_227
.LBB0_237:
	global_store_dwordx4 v[46:47], v[24:27], off sc0 sc1
	s_or_b64 exec, exec, s[0:1]
	s_and_saveexec_b64 s[0:1], s[8:9]
	s_cbranch_execnz .LBB0_228
	s_branch .LBB0_229
.LBB0_238:
	global_store_dwordx4 v[44:45], v[16:19], off sc0 sc1
	s_andn2_saveexec_b64 s[0:1], s[0:1]
	s_cbranch_execz .LBB0_231
.LBB0_239:
	global_store_dwordx4 v[46:47], v[16:19], off offset:768 sc0 sc1
	s_or_b64 exec, exec, s[0:1]
	s_and_saveexec_b64 s[0:1], s[8:9]
	s_cbranch_execz .LBB0_216
.LBB0_240:
	v_pk_mul_f32 v[16:17], v[36:37], v[24:25] op_sel_hi:[0,1]
	v_pk_mul_f32 v[18:19], v[36:37], v[20:21] op_sel_hi:[0,1]
	v_pk_mul_f32 v[16:17], v[0:1], v[16:17]
	v_pk_mul_f32 v[18:19], v[2:3], v[18:19]
	v_cvt_pk_bf16_f32 v16, v16, v17
	v_cvt_pk_bf16_f32 v17, v18, v19
	v_pk_mul_f32 v[18:19], v[36:37], v[26:27] op_sel_hi:[0,1]
	v_pk_mul_f32 v[20:21], v[36:37], v[22:23] op_sel_hi:[0,1]
	v_pk_mul_f32 v[18:19], v[4:5], v[18:19]
	v_pk_mul_f32 v[20:21], v[6:7], v[20:21]
	v_cvt_pk_bf16_f32 v18, v18, v19
	v_cvt_pk_bf16_f32 v19, v20, v21
	global_store_dwordx4 v[44:45], v[16:19], off offset:1024 sc0 sc1
	s_waitcnt vmcnt(3)
	s_nop 0
	v_lshlrev_b32_e32 v17, 16, v92
	v_lshlrev_b32_e32 v16, 16, v49
	s_waitcnt vmcnt(1)
	v_pk_mul_f32 v[18:19], v[64:65], v[16:17] op_sel:[0,1] op_sel_hi:[0,0]
	v_pk_fma_f32 v[20:21], v[62:63], v[16:17], v[18:19] neg_lo:[0,0,1] neg_hi:[0,0,1]
	v_pk_fma_f32 v[16:17], v[62:63], v[16:17], v[18:19] op_sel_hi:[0,1,1]
	v_cvt_pk_bf16_f32 v16, v20, v17
	global_store_dword v[40:41], v16, off offset:64
	s_branch .LBB0_216

; #define LAS __attribute__((address_space(3)))
; __device__ __forceinline__ unsigned cvtpk(float lo, float hi) { f32x2_t v = {lo, hi}; bf16x2_t b = __builtin_convertvector(v, bf16x2_t); return __builtin_bit_cast(unsigned, b); }
; __device__ __forceinline__ float silu_f(float x) { return x / (1.0f + __expf(-x)); }
; __device__ __forceinline__ void dil_attn_unit(LAS unsigned char* lds, bf16_t* proj, float* lse, int unit, int Tc, bf16_t* ybuf) {
;     ...
;         const int tok0 = s * SEQ + U0 + 32 * w;
; #pragma unroll
;         for (int half = 0; half < 2; ++half) {
;             u32x4 o1[4], o2[4], gt[4]; float l1[4], l2[4];
; #pragma unroll
;             for (int i = 0; i < 4; ++i) { const int row = (half * 4 + i) * 4 + (lane >> 4), d8 = (lane & 15) * 8; const int tok = tok0 + row, t_ = tok & (SEQ - 1), s4_ = tok & ~(SEQ - 1);
;                 l1[i] = lse[(size_t)tok * 24 + 8 + h]; l2[i] = lse[(size_t)tok * 24 + 16 + h];
;                 o1[i] = *(const u32x4*)(proj + ((size_t)(24 + h) * Tc + s4_ + ((t_ & 3) << 10) + (t_ >> 2)) * 128 + d8);
;                 o2[i] = *(const u32x4*)(proj + ((size_t)(48 + h) * Tc + s4_ + ((t_ & 15) << 8) + (t_ >> 4)) * 128 + d8);
;                 gt[i] = *(const u32x4*)(proj + (size_t)9216 * Tc + (size_t)tok * 1024 + h * 128 + d8); }
; #pragma unroll
;             for (int i = 0; i < 4; ++i) { const int row = (half * 4 + i) * 4 + (lane >> 4), d8 = (lane & 15) * 8; const int tok = tok0 + row;
;                 const float l0 = lsr[row]; const float mxl = fmaxf(l0, fmaxf(l1[i], l2[i]));
;                 float w0 = __builtin_amdgcn_exp2f(l0 - mxl), w1 = __builtin_amdgcn_exp2f(l1[i] - mxl), w2 = __builtin_amdgcn_exp2f(l2[i] - mxl);
;                 const float iw = 1.0f / (w0 + w1 + w2); w0 *= iw; w1 *= iw; w2 *= iw;
;                 const f32x4 x0 = *(const LAS f32x4*)(stf + row * 132 + d8), x1 = *(const LAS f32x4*)(stf + row * 132 + d8 + 4);
;                 u32x4 yo;
;                 yo.x = cvtpk((w0 * x0[0] + w1 * bf_lo(o1[i].x) + w2 * bf_lo(o2[i].x)) * silu_f(bf_lo(gt[i].x)), (w0 * x0[1] + w1 * bf_hi(o1[i].x) + w2 * bf_hi(o2[i].x)) * silu_f(bf_hi(gt[i].x)));
.LBB0_248:
	s_or_b64 exec, exec, s[0:1]
	s_lshl_b32 s0, s92, 12
	s_or_b32 s1, s34, 24
	s_add_i32 s41, s41, s0
	s_mul_hi_i32 s5, s1, s62
	s_and_b32 s0, s41, 0xfffff000
	s_mul_i32 s6, s1, s62
	v_mov_b32_e32 v1, s5
	s_or_b32 s5, s34, 48
	s_ashr_i32 s1, s0, 31
	v_lshl_or_b32 v0, v75, 10, s6
	s_mul_hi_i32 s6, s5, s62
	s_mul_i32 s5, s5, s62
	v_lshl_add_u64 v[58:59], v[0:1], 0, s[0:1]
	s_add_u32 s0, s5, s0
	s_addc_u32 s1, s6, s1
	s_lshl_b32 s5, s34, 8
	v_readlane_b32 s6, v254, 57
	s_add_u32 s6, s6, s5
	v_readlane_b32 s7, v254, 59
	s_addc_u32 s7, s7, 0
	v_or_b32_e32 v0, s41, v75
	v_lshl_add_u64 v[56:57], s[6:7], 0, v[178:179]
	s_add_u32 s6, s64, s5
	s_addc_u32 s7, s65, 0
	v_lshl_add_u64 v[52:53], s[6:7], 0, v[178:179]
	v_readlane_b32 s6, v254, 11
	v_readlane_b32 s7, v254, 12
	s_lshl_b32 s76, s34, 2
	s_waitcnt lgkmcnt(0)
	v_mov_b32_e32 v1, 0xfe3
	v_mov_b64_e32 v[60:61], s[6:7]
	v_mad_i64_i32 v[2:3], s[6:7], v0, s66, v[60:61]
	v_lshl_add_u64 v[2:3], v[2:3], 0, s[76:77]
	global_load_dword v48, v[2:3], off offset:32
	global_load_dword v49, v[2:3], off offset:64
	v_bitop3_b32 v4, s41, v1, v75 bitop3:0xc8
	v_lshrrev_b32_e32 v2, 2, v4
	v_ashrrev_i32_e32 v1, 31, v0
	v_or_b32_e32 v2, v58, v2
	v_mov_b32_e32 v3, v59
	v_lshl_add_u64 v[54:55], s[54:55], 0, v[178:179]
	v_lshlrev_b64 v[2:3], 8, v[2:3]
	v_lshlrev_b64 v[64:65], 11, v[0:1]
	v_lshl_add_u64 v[2:3], v[54:55], 0, v[2:3]
	v_lshl_add_u64 v[0:1], v[56:57], 0, v[64:65]
	global_load_dwordx4 v[36:39], v[2:3], off
	global_load_dwordx4 v[44:47], v[0:1], off
	v_lshl_or_b32 v78, v75, 8, s0
	v_lshrrev_b32_e32 v2, 4, v4
	v_or_b32_e32 v62, v78, v2
	v_mov_b32_e32 v63, s1
	v_lshlrev_b64 v[2:3], 8, v[62:63]
	v_lshl_add_u64 v[2:3], v[54:55], 0, v[2:3]
	global_load_dwordx4 v[40:43], v[2:3], off
	v_or_b32_e32 v4, 4, v75
	v_or_b32_e32 v0, s41, v4
	v_mov_b32_e32 v1, 0xfe7
	v_mad_i64_i32 v[2:3], s[6:7], v0, s66, v[60:61]
	v_bitop3_b32 v5, s41, v1, v4 bitop3:0xc8
	v_lshl_add_u64 v[2:3], v[2:3], 0, s[76:77]
	global_load_dword v85, v[2:3], off offset:32
	global_load_dword v84, v[2:3], off offset:64
	v_lshrrev_b32_e32 v2, 2, v5
	v_ashrrev_i32_e32 v1, 31, v0
	v_or_b32_e32 v2, v58, v2
	v_mov_b32_e32 v3, v59
	v_lshlrev_b64 v[2:3], 8, v[2:3]
	v_lshlrev_b64 v[70:71], 11, v[0:1]
	v_lshl_add_u64 v[2:3], v[54:55], 0, v[2:3]
	v_lshl_add_u64 v[0:1], v[56:57], 0, v[70:71]
	global_load_dwordx4 v[24:27], v[2:3], off
	global_load_dwordx4 v[32:35], v[0:1], off
	v_lshlrev_b32_e32 v2, 8, v4
	v_lshrrev_b32_e32 v3, 4, v5
	v_or3_b32 v62, v3, v2, s0
	v_lshlrev_b64 v[2:3], 8, v[62:63]
	v_or_b32_e32 v4, 8, v75
	v_lshl_add_u64 v[2:3], v[54:55], 0, v[2:3]
	v_or_b32_e32 v0, s41, v4
	global_load_dwordx4 v[28:31], v[2:3], off
	v_mov_b32_e32 v1, 0xfeb
	v_mad_i64_i32 v[2:3], s[6:7], v0, s66, v[60:61]
	v_bitop3_b32 v5, s41, v1, v4 bitop3:0xc8
	v_lshl_add_u64 v[2:3], v[2:3], 0, s[76:77]
	global_load_dword v83, v[2:3], off offset:32
	global_load_dword v82, v[2:3], off offset:64
	v_lshrrev_b32_e32 v2, 2, v5
	v_ashrrev_i32_e32 v1, 31, v0
	v_or_b32_e32 v2, v58, v2
	v_mov_b32_e32 v3, v59
	v_lshlrev_b64 v[2:3], 8, v[2:3]
	v_lshlrev_b64 v[68:69], 11, v[0:1]
	v_lshl_add_u64 v[2:3], v[54:55], 0, v[2:3]
	v_lshl_add_u64 v[0:1], v[56:57], 0, v[68:69]
	global_load_dwordx4 v[12:15], v[2:3], off
	global_load_dwordx4 v[20:23], v[0:1], off
	v_lshlrev_b32_e32 v2, 8, v4
	v_lshrrev_b32_e32 v3, 4, v5
	v_or_b32_e32 v4, 12, v75
	v_or3_b32 v62, v3, v2, s0
	v_or_b32_e32 v8, s41, v4
	v_mov_b32_e32 v0, 0xfef
	v_lshlrev_b64 v[2:3], 8, v[62:63]
	v_bitop3_b32 v5, s41, v0, v4 bitop3:0xc8
	v_mad_i64_i32 v[0:1], s[6:7], v8, s66, v[60:61]
	v_lshl_add_u32 v50, v75, 2, s4
	v_lshl_add_u64 v[2:3], v[54:55], 0, v[2:3]
	v_lshl_add_u64 v[0:1], v[0:1], 0, s[76:77]
	v_add_u32_e32 v76, 0x4000, v50
	global_load_dwordx4 v[16:19], v[2:3], off
	global_load_dword v80, v[0:1], off offset:32
	global_load_dword v79, v[0:1], off offset:64
	ds_read2_b32 v[72:73], v76 offset0:128 offset1:132
	v_lshrrev_b32_e32 v0, 2, v5
	v_lshlrev_b32_e32 v4, 8, v4
	v_lshrrev_b32_e32 v5, 4, v5
	v_or3_b32 v62, v5, v4, s0
	s_waitcnt vmcnt(15) lgkmcnt(0)
	v_max3_f32 v50, v72, v48, v49
	v_sub_f32_e32 v51, v72, v50
	v_sub_f32_e32 v48, v48, v50
	v_exp_f32_e32 v51, v51
	v_exp_f32_e32 v48, v48
	v_sub_f32_e32 v49, v49, v50
	v_exp_f32_e32 v49, v49
	v_lshl_add_u32 v77, v88, 5, s4
	v_add_f32_e32 v50, v51, v48
	v_lshlrev_b64 v[4:5], 8, v[62:63]
	v_add_f32_e32 v50, v49, v50
	v_div_scale_f32 v62, s[4:5], v50, v50, 1.0
	v_rcp_f32_e32 v72, v62
	s_waitcnt vmcnt(13)
	v_lshlrev_b32_e32 v94, 16, v44
	v_and_b32_e32 v44, 0xffff0000, v44
	v_ashrrev_i32_e32 v9, 31, v8
	v_fma_f32 v74, -v62, v72, 1.0
	v_fmac_f32_e32 v72, v74, v72
	v_div_scale_f32 v74, vcc, 1.0, v50, 1.0
	v_mul_f32_e32 v81, v74, v72
	v_fma_f32 v86, -v62, v81, v74
	v_fmac_f32_e32 v81, v86, v72
	v_or_b32_e32 v0, v58, v0
	v_mov_b32_e32 v1, v59
	v_fma_f32 v62, -v62, v81, v74
	v_mul_f32_e32 v90, 0xbfb8aa3b, v94
	v_lshlrev_b32_e32 v92, 16, v36
	v_and_b32_e32 v93, 0xffff0000, v36
	v_mul_f32_e32 v36, 0xbfb8aa3b, v44
	v_lshlrev_b64 v[0:1], 8, v[0:1]
	v_lshlrev_b64 v[66:67], 11, v[8:9]
	v_div_fmas_f32 v62, v62, v72, v81
	s_movk_i32 s6, 0x210
	v_exp_f32_e32 v90, v90
	v_exp_f32_e32 v91, v36
	v_lshl_add_u64 v[0:1], v[54:55], 0, v[0:1]
	v_lshl_add_u64 v[4:5], v[54:55], 0, v[4:5]
	v_lshl_add_u64 v[8:9], v[56:57], 0, v[66:67]
	v_div_fixup_f32 v50, v62, v50, 1.0
	v_mad_u32_u24 v81, v75, s6, v77
	global_load_dwordx4 v[0:3], v[0:1], off
	v_mul_f32_e32 v72, v51, v50
	global_load_dwordx4 v[4:7], v[4:5], off
	v_mul_f32_e32 v74, v48, v50
	global_load_dwordx4 v[8:11], v[8:9], off
	v_mul_f32_e32 v62, v49, v50
	ds_read_b128 v[86:89], v81
	ds_read_b128 v[48:51], v81 offset:16
	v_pk_add_f32 v[90:91], v[90:91], 1.0 op_sel_hi:[1,0]
	v_pk_mul_f32 v[92:93], v[74:75], v[92:93] op_sel_hi:[0,1]
	v_div_scale_f32 v36, s[4:5], v91, v91, v44
	s_waitcnt lgkmcnt(1)
; #define LAS __attribute__((address_space(3)))
; __device__ __forceinline__ unsigned cvtpk(float lo, float hi) { f32x2_t v = {lo, hi}; bf16x2_t b = __builtin_convertvector(v, bf16x2_t); return __builtin_bit_cast(unsigned, b); }
; __device__ __forceinline__ float silu_f(float x) { return x / (1.0f + __expf(-x)); }
; __device__ __forceinline__ void dil_attn_unit(LAS unsigned char* lds, bf16_t* proj, float* lse, int unit, int Tc, bf16_t* ybuf) {
;     ...
;             for (int i = 0; i < 4; ++i) { const int row = (half * 4 + i) * 4 + (lane >> 4), d8 = (lane & 15) * 8; const int tok = tok0 + row;
;                 const float l0 = lsr[row]; const float mxl = fmaxf(l0, fmaxf(l1[i], l2[i]));
;                 float w0 = __builtin_amdgcn_exp2f(l0 - mxl), w1 = __builtin_amdgcn_exp2f(l1[i] - mxl), w2 = __builtin_amdgcn_exp2f(l2[i] - mxl);
;                 const float iw = 1.0f / (w0 + w1 + w2); w0 *= iw; w1 *= iw; w2 *= iw;
;                 const f32x4 x0 = *(const LAS f32x4*)(stf + row * 132 + d8), x1 = *(const LAS f32x4*)(stf + row * 132 + d8 + 4);
;                 u32x4 yo;
;                 yo.x = cvtpk((w0 * x0[0] + w1 * bf_lo(o1[i].x) + w2 * bf_lo(o2[i].x)) * silu_f(bf_lo(gt[i].x)), (w0 * x0[1] + w1 * bf_hi(o1[i].x) + w2 * bf_hi(o2[i].x)) * silu_f(bf_hi(gt[i].x)));
;                 yo.y = cvtpk((w0 * x0[2] + w1 * bf_lo(o1[i].y) + w2 * bf_lo(o2[i].y)) * silu_f(bf_lo(gt[i].y)), (w0 * x0[3] + w1 * bf_hi(o1[i].y) + w2 * bf_hi(o2[i].y)) * silu_f(bf_hi(gt[i].y)));
;                 yo.z = cvtpk((w0 * x1[0] + w1 * bf_lo(o1[i].z) + w2 * bf_lo(o2[i].z)) * silu_f(bf_lo(gt[i].z)), (w0 * x1[1] + w1 * bf_hi(o1[i].z) + w2 * bf_hi(o2[i].z)) * silu_f(bf_hi(gt[i].z)));
;                 yo.w = cvtpk((w0 * x1[2] + w1 * bf_lo(o1[i].w) + w2 * bf_lo(o2[i].w)) * silu_f(bf_lo(gt[i].w)), (w0 * x1[3] + w1 * bf_hi(o1[i].w) + w2 * bf_hi(o2[i].w)) * silu_f(bf_hi(gt[i].w)));
;                 *(u32x4*)(ybuf + (size_t)tok * DM + h * 128 + d8) = yo; }
	v_pk_fma_f32 v[86:87], v[86:87], v[72:73], v[92:93] op_sel_hi:[1,0,1]
	s_waitcnt vmcnt(15)
	v_lshlrev_b32_e32 v92, 16, v40
	v_and_b32_e32 v93, 0xffff0000, v40
	v_rcp_f32_e32 v40, v36
	v_pk_fma_f32 v[86:87], v[62:63], v[92:93], v[86:87] op_sel_hi:[0,1,1]
	v_fma_f32 v92, -v36, v40, 1.0
	v_fmac_f32_e32 v40, v92, v40
	v_div_scale_f32 v92, vcc, v44, v91, v44
	v_mul_f32_e32 v93, v92, v40
	v_fma_f32 v95, -v36, v93, v92
	v_fmac_f32_e32 v93, v95, v40
	v_fma_f32 v36, -v36, v93, v92
	v_div_fmas_f32 v36, v36, v40, v93
	v_div_fixup_f32 v91, v36, v91, v44
	v_div_scale_f32 v36, s[4:5], v90, v90, v94
	v_rcp_f32_e32 v40, v36
	s_nop 0
	v_fma_f32 v44, -v36, v40, 1.0
	v_fmac_f32_e32 v40, v44, v40
	v_div_scale_f32 v44, vcc, v94, v90, v94
	v_mul_f32_e32 v92, v44, v40
	v_fma_f32 v93, -v36, v92, v44
	v_fmac_f32_e32 v92, v93, v40
	v_fma_f32 v36, -v36, v92, v44
	v_div_fmas_f32 v36, v36, v40, v92
	v_div_fixup_f32 v90, v36, v90, v94
	v_pk_mul_f32 v[86:87], v[90:91], v[86:87]
	v_lshlrev_b32_e32 v90, 16, v45
	v_and_b32_e32 v91, 0xffff0000, v45
	v_mul_f32_e32 v40, 0xbfb8aa3b, v90
	v_lshlrev_b32_e32 v44, 16, v37
	v_and_b32_e32 v45, 0xffff0000, v37
	v_mul_f32_e32 v37, 0xbfb8aa3b, v91
	v_cvt_pk_bf16_f32 v36, v86, v87
	v_exp_f32_e32 v40, v40
	v_lshlrev_b32_e32 v86, 16, v41
	v_and_b32_e32 v87, 0xffff0000, v41
	v_exp_f32_e32 v41, v37
	v_pk_mul_f32 v[44:45], v[74:75], v[44:45] op_sel_hi:[0,1]
	v_pk_fma_f32 v[44:45], v[88:89], v[72:73], v[44:45] op_sel_hi:[1,0,1]
	v_pk_add_f32 v[40:41], v[40:41], 1.0 op_sel_hi:[1,0]
	s_nop 0
	v_div_scale_f32 v37, s[4:5], v41, v41, v91
	v_pk_fma_f32 v[44:45], v[62:63], v[86:87], v[44:45] op_sel_hi:[0,1,1]
	v_rcp_f32_e32 v86, v37
	s_nop 0
	v_fma_f32 v87, -v37, v86, 1.0
	v_fmac_f32_e32 v86, v87, v86
	v_div_scale_f32 v87, vcc, v91, v41, v91
	v_mul_f32_e32 v88, v87, v86
	v_fma_f32 v89, -v37, v88, v87
	v_fmac_f32_e32 v88, v89, v86
	v_fma_f32 v37, -v37, v88, v87
	v_div_fmas_f32 v37, v37, v86, v88
	v_div_fixup_f32 v41, v37, v41, v91
	v_div_scale_f32 v37, s[4:5], v40, v40, v90
	v_rcp_f32_e32 v86, v37
	s_nop 0
	v_fma_f32 v87, -v37, v86, 1.0
	v_fmac_f32_e32 v86, v87, v86
	v_div_scale_f32 v87, vcc, v90, v40, v90
	v_mul_f32_e32 v88, v87, v86
	v_fma_f32 v89, -v37, v88, v87
	v_fmac_f32_e32 v88, v89, v86
	v_fma_f32 v37, -v37, v88, v87
	v_div_fmas_f32 v37, v37, v86, v88
	v_div_fixup_f32 v40, v37, v40, v90
	v_pk_mul_f32 v[40:41], v[40:41], v[44:45]
	v_lshlrev_b32_e32 v86, 16, v46
	v_and_b32_e32 v46, 0xffff0000, v46
	v_cvt_pk_bf16_f32 v37, v40, v41
	v_mul_f32_e32 v40, 0xbfb8aa3b, v86
	v_lshlrev_b32_e32 v44, 16, v38
	v_and_b32_e32 v45, 0xffff0000, v38
	v_mul_f32_e32 v38, 0xbfb8aa3b, v46
	v_exp_f32_e32 v40, v40
	v_exp_f32_e32 v41, v38
	v_pk_mul_f32 v[44:45], v[74:75], v[44:45] op_sel_hi:[0,1]
	s_waitcnt lgkmcnt(0)
	v_pk_fma_f32 v[44:45], v[48:49], v[72:73], v[44:45] op_sel_hi:[1,0,1]
	v_lshlrev_b32_e32 v48, 16, v42
	v_pk_add_f32 v[40:41], v[40:41], 1.0 op_sel_hi:[1,0]
	v_and_b32_e32 v49, 0xffff0000, v42
	v_div_scale_f32 v38, s[4:5], v41, v41, v46
	v_rcp_f32_e32 v42, v38
	v_pk_fma_f32 v[44:45], v[62:63], v[48:49], v[44:45] op_sel_hi:[0,1,1]
	v_fma_f32 v48, -v38, v42, 1.0
	v_fmac_f32_e32 v42, v48, v42
	v_div_scale_f32 v48, vcc, v46, v41, v46
	v_mul_f32_e32 v49, v48, v42
	v_fma_f32 v87, -v38, v49, v48
	v_fmac_f32_e32 v49, v87, v42
	v_fma_f32 v38, -v38, v49, v48
	v_div_fmas_f32 v38, v38, v42, v49
	v_div_fixup_f32 v41, v38, v41, v46
	v_div_scale_f32 v38, s[4:5], v40, v40, v86
	v_rcp_f32_e32 v42, v38
	s_nop 0
	v_fma_f32 v46, -v38, v42, 1.0
	v_fmac_f32_e32 v42, v46, v42
	v_div_scale_f32 v46, vcc, v86, v40, v86
	v_mul_f32_e32 v48, v46, v42
	v_fma_f32 v49, -v38, v48, v46
	v_fmac_f32_e32 v48, v49, v42
	v_fma_f32 v38, -v38, v48, v46
	v_div_fmas_f32 v38, v38, v42, v48
	v_div_fixup_f32 v40, v38, v40, v86
	v_pk_mul_f32 v[40:41], v[40:41], v[44:45]
	v_lshlrev_b32_e32 v46, 16, v47
	v_and_b32_e32 v47, 0xffff0000, v47
	v_cvt_pk_bf16_f32 v38, v40, v41
	v_mul_f32_e32 v40, 0xbfb8aa3b, v46
	v_lshlrev_b32_e32 v44, 16, v39
	v_and_b32_e32 v45, 0xffff0000, v39
	v_mul_f32_e32 v39, 0xbfb8aa3b, v47
	v_exp_f32_e32 v40, v40
	v_exp_f32_e32 v41, v39
	v_pk_mul_f32 v[44:45], v[74:75], v[44:45] op_sel_hi:[0,1]
	v_pk_fma_f32 v[44:45], v[50:51], v[72:73], v[44:45] op_sel_hi:[1,0,1]
	v_lshlrev_b32_e32 v42, 16, v43
	v_pk_add_f32 v[40:41], v[40:41], 1.0 op_sel_hi:[1,0]
	v_and_b32_e32 v43, 0xffff0000, v43
	v_div_scale_f32 v39, s[4:5], v41, v41, v47
	v_pk_fma_f32 v[42:43], v[62:63], v[42:43], v[44:45] op_sel_hi:[0,1,1]
	v_rcp_f32_e32 v44, v39
	s_nop 0
	v_fma_f32 v45, -v39, v44, 1.0
	v_fmac_f32_e32 v44, v45, v44
	v_div_scale_f32 v45, vcc, v47, v41, v47
	v_mul_f32_e32 v48, v45, v44
	v_fma_f32 v49, -v39, v48, v45
	v_fmac_f32_e32 v48, v49, v44
	v_fma_f32 v39, -v39, v48, v45
	v_div_fmas_f32 v39, v39, v44, v48
	v_div_fixup_f32 v41, v39, v41, v47
	v_div_scale_f32 v39, s[4:5], v40, v40, v46
	v_rcp_f32_e32 v44, v39
	s_nop 0
	v_fma_f32 v45, -v39, v44, 1.0
	v_fmac_f32_e32 v44, v45, v44
	v_div_scale_f32 v45, vcc, v46, v40, v46
	v_mul_f32_e32 v47, v45, v44
	v_fma_f32 v48, -v39, v47, v45
	v_fmac_f32_e32 v47, v48, v44
	v_fma_f32 v39, -v39, v47, v45
	v_div_fmas_f32 v39, v39, v44, v47
	v_div_fixup_f32 v40, v39, v40, v46
	v_pk_mul_f32 v[40:41], v[40:41], v[42:43]
	s_nop 0
	v_cvt_pk_bf16_f32 v39, v40, v41
	v_lshl_add_u64 v[40:41], v[52:53], 0, v[64:65]
	global_store_dwordx4 v[40:41], v[36:39], off sc0 sc1
	ds_read2_b32 v[40:41], v76 offset0:136 offset1:140
	ds_read2_b32 v[64:65], v76 offset0:144 offset1:148
	s_waitcnt vmcnt(14)
	v_max3_f32 v36, v73, v85, v84
	v_sub_f32_e32 v37, v73, v36
	v_sub_f32_e32 v38, v85, v36
	v_exp_f32_e32 v37, v37
	v_exp_f32_e32 v38, v38
	v_sub_f32_e32 v36, v84, v36
	v_exp_f32_e32 v36, v36
	s_waitcnt vmcnt(13)
; #define LAS __attribute__((address_space(3)))
; __device__ __forceinline__ unsigned cvtpk(float lo, float hi) { f32x2_t v = {lo, hi}; bf16x2_t b = __builtin_convertvector(v, bf16x2_t); return __builtin_bit_cast(unsigned, b); }
; __device__ __forceinline__ float silu_f(float x) { return x / (1.0f + __expf(-x)); }
; __device__ __forceinline__ void dil_attn_unit(LAS unsigned char* lds, bf16_t* proj, float* lse, int unit, int Tc, bf16_t* ybuf) {
;     ...
;             for (int i = 0; i < 4; ++i) { const int row = (half * 4 + i) * 4 + (lane >> 4), d8 = (lane & 15) * 8; const int tok = tok0 + row;
;                 const float l0 = lsr[row]; const float mxl = fmaxf(l0, fmaxf(l1[i], l2[i]));
;                 float w0 = __builtin_amdgcn_exp2f(l0 - mxl), w1 = __builtin_amdgcn_exp2f(l1[i] - mxl), w2 = __builtin_amdgcn_exp2f(l2[i] - mxl);
;                 const float iw = 1.0f / (w0 + w1 + w2); w0 *= iw; w1 *= iw; w2 *= iw;
;                 const f32x4 x0 = *(const LAS f32x4*)(stf + row * 132 + d8), x1 = *(const LAS f32x4*)(stf + row * 132 + d8 + 4);
;                 u32x4 yo;
;                 yo.x = cvtpk((w0 * x0[0] + w1 * bf_lo(o1[i].x) + w2 * bf_lo(o2[i].x)) * silu_f(bf_lo(gt[i].x)), (w0 * x0[1] + w1 * bf_hi(o1[i].x) + w2 * bf_hi(o2[i].x)) * silu_f(bf_hi(gt[i].x)));
;                 yo.y = cvtpk((w0 * x0[2] + w1 * bf_lo(o1[i].y) + w2 * bf_lo(o2[i].y)) * silu_f(bf_lo(gt[i].y)), (w0 * x0[3] + w1 * bf_hi(o1[i].y) + w2 * bf_hi(o2[i].y)) * silu_f(bf_hi(gt[i].y)));
;                 yo.z = cvtpk((w0 * x1[0] + w1 * bf_lo(o1[i].z) + w2 * bf_lo(o2[i].z)) * silu_f(bf_lo(gt[i].z)), (w0 * x1[1] + w1 * bf_hi(o1[i].z) + w2 * bf_hi(o2[i].z)) * silu_f(bf_hi(gt[i].z)));
;                 yo.w = cvtpk((w0 * x1[2] + w1 * bf_lo(o1[i].w) + w2 * bf_lo(o2[i].w)) * silu_f(bf_lo(gt[i].w)), (w0 * x1[3] + w1 * bf_hi(o1[i].w) + w2 * bf_hi(o2[i].w)) * silu_f(bf_hi(gt[i].w)));
	v_lshlrev_b32_e32 v84, 16, v24
	v_add_f32_e32 v39, v37, v38
	v_and_b32_e32 v85, 0xffff0000, v24
	v_add_f32_e32 v39, v36, v39
	v_div_scale_f32 v42, s[4:5], v39, v39, 1.0
	v_rcp_f32_e32 v43, v42
	s_nop 0
	v_fma_f32 v44, -v42, v43, 1.0
	v_fmac_f32_e32 v43, v44, v43
	v_div_scale_f32 v44, vcc, 1.0, v39, 1.0
	v_mul_f32_e32 v45, v44, v43
	v_fma_f32 v46, -v42, v45, v44
	v_fmac_f32_e32 v45, v46, v43
	v_fma_f32 v42, -v42, v45, v44
	v_div_fmas_f32 v42, v42, v43, v45
	s_waitcnt vmcnt(12)
	v_lshlrev_b32_e32 v43, 16, v32
	v_and_b32_e32 v32, 0xffff0000, v32
	v_mul_f32_e32 v45, 0xbfb8aa3b, v43
	v_mul_f32_e32 v24, 0xbfb8aa3b, v32
	v_exp_f32_e32 v72, v45
	v_exp_f32_e32 v73, v24
	v_div_fixup_f32 v39, v42, v39, 1.0
	v_mul_f32_e32 v44, v37, v39
	v_mul_f32_e32 v46, v38, v39
	v_mul_f32_e32 v42, v36, v39
	ds_read_b128 v[48:51], v81 offset:2112
	ds_read_b128 v[36:39], v81 offset:2128
	v_pk_add_f32 v[72:73], v[72:73], 1.0 op_sel_hi:[1,0]
	v_pk_mul_f32 v[84:85], v[46:47], v[84:85] op_sel_hi:[0,1]
	v_div_scale_f32 v24, s[4:5], v73, v73, v32
	s_waitcnt lgkmcnt(1)
	v_pk_fma_f32 v[48:49], v[48:49], v[44:45], v[84:85] op_sel_hi:[1,0,1]
	s_waitcnt vmcnt(11)
	v_lshlrev_b32_e32 v84, 16, v28
	v_and_b32_e32 v85, 0xffff0000, v28
	v_rcp_f32_e32 v28, v24
	v_pk_fma_f32 v[48:49], v[42:43], v[84:85], v[48:49] op_sel_hi:[0,1,1]
	v_fma_f32 v45, -v24, v28, 1.0
	v_fmac_f32_e32 v28, v45, v28
	v_div_scale_f32 v45, vcc, v32, v73, v32
	v_mul_f32_e32 v47, v45, v28
	v_fma_f32 v62, -v24, v47, v45
	v_fmac_f32_e32 v47, v62, v28
	v_fma_f32 v24, -v24, v47, v45
	v_div_fmas_f32 v24, v24, v28, v47
	v_div_fixup_f32 v73, v24, v73, v32
	v_div_scale_f32 v24, s[4:5], v72, v72, v43
	v_rcp_f32_e32 v28, v24
	s_nop 0
	v_fma_f32 v32, -v24, v28, 1.0
	v_fmac_f32_e32 v28, v32, v28
	v_div_scale_f32 v32, vcc, v43, v72, v43
	v_mul_f32_e32 v45, v32, v28
	v_fma_f32 v47, -v24, v45, v32
	v_fmac_f32_e32 v45, v47, v28
	v_fma_f32 v24, -v24, v45, v32
	v_div_fmas_f32 v24, v24, v28, v45
	v_div_fixup_f32 v72, v24, v72, v43
	v_lshlrev_b32_e32 v43, 16, v33
	v_and_b32_e32 v45, 0xffff0000, v33
	v_pk_mul_f32 v[48:49], v[72:73], v[48:49]
	v_mul_f32_e32 v28, 0xbfb8aa3b, v43
	v_lshlrev_b32_e32 v32, 16, v25
	v_and_b32_e32 v33, 0xffff0000, v25
	v_mul_f32_e32 v25, 0xbfb8aa3b, v45
	v_cvt_pk_bf16_f32 v24, v48, v49
	v_exp_f32_e32 v28, v28
	v_lshlrev_b32_e32 v48, 16, v29
	v_and_b32_e32 v49, 0xffff0000, v29
	v_exp_f32_e32 v29, v25
	v_pk_mul_f32 v[32:33], v[46:47], v[32:33] op_sel_hi:[0,1]
	v_pk_fma_f32 v[32:33], v[50:51], v[44:45], v[32:33] op_sel_hi:[1,0,1]
	v_pk_add_f32 v[28:29], v[28:29], 1.0 op_sel_hi:[1,0]
	s_nop 0
	v_div_scale_f32 v25, s[4:5], v29, v29, v45
	v_rcp_f32_e32 v47, v25
	v_pk_fma_f32 v[32:33], v[42:43], v[48:49], v[32:33] op_sel_hi:[0,1,1]
	v_fma_f32 v48, -v25, v47, 1.0
	v_fmac_f32_e32 v47, v48, v47
	v_div_scale_f32 v48, vcc, v45, v29, v45
	v_mul_f32_e32 v49, v48, v47
	v_fma_f32 v50, -v25, v49, v48
	v_fmac_f32_e32 v49, v50, v47
	v_fma_f32 v25, -v25, v49, v48
	v_div_fmas_f32 v25, v25, v47, v49
	v_div_fixup_f32 v29, v25, v29, v45
	v_div_scale_f32 v25, s[4:5], v28, v28, v43
	v_rcp_f32_e32 v45, v25
	s_nop 0
	v_fma_f32 v47, -v25, v45, 1.0
	v_fmac_f32_e32 v45, v47, v45
	v_div_scale_f32 v47, vcc, v43, v28, v43
	v_mul_f32_e32 v48, v47, v45
	v_fma_f32 v49, -v25, v48, v47
	v_fmac_f32_e32 v48, v49, v45
	v_fma_f32 v25, -v25, v48, v47
	v_div_fmas_f32 v25, v25, v45, v48
	v_div_fixup_f32 v28, v25, v28, v43
	v_pk_mul_f32 v[28:29], v[28:29], v[32:33]
	v_lshlrev_b32_e32 v43, 16, v34
	v_and_b32_e32 v34, 0xffff0000, v34
	v_cvt_pk_bf16_f32 v25, v28, v29
	v_mul_f32_e32 v28, 0xbfb8aa3b, v43
	v_lshlrev_b32_e32 v32, 16, v26
	v_and_b32_e32 v33, 0xffff0000, v26
	v_mul_f32_e32 v26, 0xbfb8aa3b, v34
	v_exp_f32_e32 v28, v28
	v_exp_f32_e32 v29, v26
	v_pk_mul_f32 v[32:33], v[46:47], v[32:33] op_sel_hi:[0,1]
	s_waitcnt lgkmcnt(0)
	v_pk_fma_f32 v[32:33], v[36:37], v[44:45], v[32:33] op_sel_hi:[1,0,1]
	v_lshlrev_b32_e32 v36, 16, v30
	v_pk_add_f32 v[28:29], v[28:29], 1.0 op_sel_hi:[1,0]
	v_and_b32_e32 v37, 0xffff0000, v30
	v_div_scale_f32 v26, s[4:5], v29, v29, v34
	v_rcp_f32_e32 v30, v26
	v_pk_fma_f32 v[32:33], v[42:43], v[36:37], v[32:33] op_sel_hi:[0,1,1]
	v_or_b32_e32 v48, 16, v75
	v_fma_f32 v36, -v26, v30, 1.0
	v_fmac_f32_e32 v30, v36, v30
	v_div_scale_f32 v36, vcc, v34, v29, v34
	v_mul_f32_e32 v37, v36, v30
	v_fma_f32 v45, -v26, v37, v36
	v_fmac_f32_e32 v37, v45, v30
	v_fma_f32 v26, -v26, v37, v36
	v_div_fmas_f32 v26, v26, v30, v37
	v_div_fixup_f32 v29, v26, v29, v34
	v_div_scale_f32 v26, s[4:5], v28, v28, v43
	v_rcp_f32_e32 v30, v26
	s_nop 0
	v_fma_f32 v34, -v26, v30, 1.0
	v_fmac_f32_e32 v30, v34, v30
	v_div_scale_f32 v34, vcc, v43, v28, v43
	v_mul_f32_e32 v36, v34, v30
	v_fma_f32 v37, -v26, v36, v34
	v_fmac_f32_e32 v36, v37, v30
	v_fma_f32 v26, -v26, v36, v34
	v_div_fmas_f32 v26, v26, v30, v36
	v_div_fixup_f32 v28, v26, v28, v43
	v_pk_mul_f32 v[28:29], v[28:29], v[32:33]
	v_lshlrev_b32_e32 v34, 16, v35
	v_and_b32_e32 v35, 0xffff0000, v35
	v_cvt_pk_bf16_f32 v26, v28, v29
	v_mul_f32_e32 v28, 0xbfb8aa3b, v34
	v_lshlrev_b32_e32 v32, 16, v27
	v_and_b32_e32 v33, 0xffff0000, v27
	v_mul_f32_e32 v27, 0xbfb8aa3b, v35
	v_exp_f32_e32 v28, v28
	v_exp_f32_e32 v29, v27
	v_pk_mul_f32 v[32:33], v[46:47], v[32:33] op_sel_hi:[0,1]
	v_pk_fma_f32 v[32:33], v[38:39], v[44:45], v[32:33] op_sel_hi:[1,0,1]
	v_lshlrev_b32_e32 v30, 16, v31
	v_pk_add_f32 v[28:29], v[28:29], 1.0 op_sel_hi:[1,0]
	v_and_b32_e32 v31, 0xffff0000, v31
	v_div_scale_f32 v27, s[4:5], v29, v29, v35
	v_pk_fma_f32 v[30:31], v[42:43], v[30:31], v[32:33] op_sel_hi:[0,1,1]
	v_rcp_f32_e32 v32, v27
	s_waitcnt vmcnt(8)
; #define LAS __attribute__((address_space(3)))
; __device__ __forceinline__ unsigned cvtpk(float lo, float hi) { f32x2_t v = {lo, hi}; bf16x2_t b = __builtin_convertvector(v, bf16x2_t); return __builtin_bit_cast(unsigned, b); }
; __device__ __forceinline__ float silu_f(float x) { return x / (1.0f + __expf(-x)); }
; __device__ __forceinline__ void dil_attn_unit(LAS unsigned char* lds, bf16_t* proj, float* lse, int unit, int Tc, bf16_t* ybuf) {
;     ...
;             for (int i = 0; i < 4; ++i) { const int row = (half * 4 + i) * 4 + (lane >> 4), d8 = (lane & 15) * 8; const int tok = tok0 + row;
;                 const float l0 = lsr[row]; const float mxl = fmaxf(l0, fmaxf(l1[i], l2[i]));
;                 float w0 = __builtin_amdgcn_exp2f(l0 - mxl), w1 = __builtin_amdgcn_exp2f(l1[i] - mxl), w2 = __builtin_amdgcn_exp2f(l2[i] - mxl);
;                 const float iw = 1.0f / (w0 + w1 + w2); w0 *= iw; w1 *= iw; w2 *= iw;
;                 const f32x4 x0 = *(const LAS f32x4*)(stf + row * 132 + d8), x1 = *(const LAS f32x4*)(stf + row * 132 + d8 + 4);
;                 u32x4 yo;
;                 yo.x = cvtpk((w0 * x0[0] + w1 * bf_lo(o1[i].x) + w2 * bf_lo(o2[i].x)) * silu_f(bf_lo(gt[i].x)), (w0 * x0[1] + w1 * bf_hi(o1[i].x) + w2 * bf_hi(o2[i].x)) * silu_f(bf_hi(gt[i].x)));
;                 yo.y = cvtpk((w0 * x0[2] + w1 * bf_lo(o1[i].y) + w2 * bf_lo(o2[i].y)) * silu_f(bf_lo(gt[i].y)), (w0 * x0[3] + w1 * bf_hi(o1[i].y) + w2 * bf_hi(o2[i].y)) * silu_f(bf_hi(gt[i].y)));
;                 yo.z = cvtpk((w0 * x1[0] + w1 * bf_lo(o1[i].z) + w2 * bf_lo(o2[i].z)) * silu_f(bf_lo(gt[i].z)), (w0 * x1[1] + w1 * bf_hi(o1[i].z) + w2 * bf_hi(o2[i].z)) * silu_f(bf_hi(gt[i].z)));
;                 yo.w = cvtpk((w0 * x1[2] + w1 * bf_lo(o1[i].w) + w2 * bf_lo(o2[i].w)) * silu_f(bf_lo(gt[i].w)), (w0 * x1[3] + w1 * bf_hi(o1[i].w) + w2 * bf_hi(o2[i].w)) * silu_f(bf_hi(gt[i].w)));
;                 *(u32x4*)(ybuf + (size_t)tok * DM + h * 128 + d8) = yo; }
	v_lshlrev_b32_e32 v42, 16, v12
	v_and_b32_e32 v43, 0xffff0000, v12
	v_fma_f32 v33, -v27, v32, 1.0
	v_fmac_f32_e32 v32, v33, v32
	v_div_scale_f32 v33, vcc, v35, v29, v35
	v_mul_f32_e32 v36, v33, v32
	v_fma_f32 v37, -v27, v36, v33
	v_fmac_f32_e32 v36, v37, v32
	v_fma_f32 v27, -v27, v36, v33
	v_div_fmas_f32 v27, v27, v32, v36
	v_div_fixup_f32 v29, v27, v29, v35
	v_div_scale_f32 v27, s[4:5], v28, v28, v34
	v_rcp_f32_e32 v32, v27
	s_nop 0
	v_fma_f32 v33, -v27, v32, 1.0
	v_fmac_f32_e32 v32, v33, v32
	v_div_scale_f32 v33, vcc, v34, v28, v34
	v_mul_f32_e32 v35, v33, v32
	v_fma_f32 v36, -v27, v35, v33
	v_fmac_f32_e32 v35, v36, v32
	v_fma_f32 v27, -v27, v35, v33
	v_div_fmas_f32 v27, v27, v32, v35
	v_div_fixup_f32 v28, v27, v28, v34
	v_pk_mul_f32 v[28:29], v[28:29], v[30:31]
	s_nop 0
	v_cvt_pk_bf16_f32 v27, v28, v29
	v_lshl_add_u64 v[28:29], v[52:53], 0, v[70:71]
	global_store_dwordx4 v[28:29], v[24:27], off sc0 sc1
	s_nop 1
	v_max3_f32 v24, v40, v83, v82
	v_sub_f32_e32 v25, v40, v24
	v_sub_f32_e32 v26, v83, v24
	v_exp_f32_e32 v25, v25
	v_exp_f32_e32 v26, v26
	v_sub_f32_e32 v24, v82, v24
	v_exp_f32_e32 v24, v24
	v_add_f32_e32 v27, v25, v26
	v_add_f32_e32 v27, v24, v27
	v_div_scale_f32 v28, s[4:5], v27, v27, 1.0
	v_rcp_f32_e32 v29, v28
	s_nop 0
	v_fma_f32 v30, -v28, v29, 1.0
	v_fmac_f32_e32 v29, v30, v29
	v_div_scale_f32 v30, vcc, 1.0, v27, 1.0
	v_mul_f32_e32 v31, v30, v29
	v_fma_f32 v32, -v28, v31, v30
	v_fmac_f32_e32 v31, v32, v29
	v_fma_f32 v28, -v28, v31, v30
	v_div_fmas_f32 v28, v28, v29, v31
	s_waitcnt vmcnt(8)
	v_lshlrev_b32_e32 v29, 16, v20
	v_and_b32_e32 v20, 0xffff0000, v20
	v_mul_f32_e32 v31, 0xbfb8aa3b, v29
	v_mul_f32_e32 v12, 0xbfb8aa3b, v20
	v_exp_f32_e32 v38, v31
	v_exp_f32_e32 v39, v12
	v_div_fixup_f32 v27, v28, v27, 1.0
	v_mul_f32_e32 v30, v25, v27
	v_mul_f32_e32 v32, v26, v27
	v_mul_f32_e32 v28, v24, v27
	ds_read_b128 v[34:37], v81 offset:4224
	ds_read_b128 v[24:27], v81 offset:4240
	v_pk_add_f32 v[38:39], v[38:39], 1.0 op_sel_hi:[1,0]
	v_pk_mul_f32 v[42:43], v[32:33], v[42:43] op_sel_hi:[0,1]
	v_div_scale_f32 v12, s[4:5], v39, v39, v20
	s_waitcnt lgkmcnt(1)
	v_pk_fma_f32 v[34:35], v[34:35], v[30:31], v[42:43] op_sel_hi:[1,0,1]
	s_waitcnt vmcnt(7)
	v_lshlrev_b32_e32 v42, 16, v16
	v_and_b32_e32 v43, 0xffff0000, v16
	v_rcp_f32_e32 v16, v12
	v_pk_fma_f32 v[34:35], v[28:29], v[42:43], v[34:35] op_sel_hi:[0,1,1]
	v_fma_f32 v31, -v12, v16, 1.0
	v_fmac_f32_e32 v16, v31, v16
	v_div_scale_f32 v31, vcc, v20, v39, v20
	v_mul_f32_e32 v33, v31, v16
	v_fma_f32 v40, -v12, v33, v31
	v_fmac_f32_e32 v33, v40, v16
	v_fma_f32 v12, -v12, v33, v31
	v_div_fmas_f32 v12, v12, v16, v33
	v_div_fixup_f32 v39, v12, v39, v20
	v_div_scale_f32 v12, s[4:5], v38, v38, v29
	v_rcp_f32_e32 v16, v12
	s_nop 0
	v_fma_f32 v20, -v12, v16, 1.0
	v_fmac_f32_e32 v16, v20, v16
	v_div_scale_f32 v20, vcc, v29, v38, v29
	v_mul_f32_e32 v31, v20, v16
	v_fma_f32 v33, -v12, v31, v20
	v_fmac_f32_e32 v31, v33, v16
	v_fma_f32 v12, -v12, v31, v20
	v_div_fmas_f32 v12, v12, v16, v31
	v_div_fixup_f32 v38, v12, v38, v29
	v_lshlrev_b32_e32 v29, 16, v21
	v_and_b32_e32 v31, 0xffff0000, v21
	v_pk_mul_f32 v[34:35], v[38:39], v[34:35]
	v_mul_f32_e32 v16, 0xbfb8aa3b, v29
	v_lshlrev_b32_e32 v20, 16, v13
	v_and_b32_e32 v21, 0xffff0000, v13
	v_mul_f32_e32 v13, 0xbfb8aa3b, v31
	v_cvt_pk_bf16_f32 v12, v34, v35
	v_exp_f32_e32 v16, v16
	v_lshlrev_b32_e32 v34, 16, v17
	v_and_b32_e32 v35, 0xffff0000, v17
	v_exp_f32_e32 v17, v13
	v_pk_mul_f32 v[20:21], v[32:33], v[20:21] op_sel_hi:[0,1]
	v_pk_fma_f32 v[20:21], v[36:37], v[30:31], v[20:21] op_sel_hi:[1,0,1]
	v_pk_add_f32 v[16:17], v[16:17], 1.0 op_sel_hi:[1,0]
	s_nop 0
	v_div_scale_f32 v13, s[4:5], v17, v17, v31
	v_rcp_f32_e32 v33, v13
	v_pk_fma_f32 v[20:21], v[28:29], v[34:35], v[20:21] op_sel_hi:[0,1,1]
	v_fma_f32 v34, -v13, v33, 1.0
	v_fmac_f32_e32 v33, v34, v33
	v_div_scale_f32 v34, vcc, v31, v17, v31
	v_mul_f32_e32 v35, v34, v33
	v_fma_f32 v36, -v13, v35, v34
	v_fmac_f32_e32 v35, v36, v33
	v_fma_f32 v13, -v13, v35, v34
	v_div_fmas_f32 v13, v13, v33, v35
	v_div_fixup_f32 v17, v13, v17, v31
	v_div_scale_f32 v13, s[4:5], v16, v16, v29
	v_rcp_f32_e32 v31, v13
	s_nop 0
	v_fma_f32 v33, -v13, v31, 1.0
	v_fmac_f32_e32 v31, v33, v31
	v_div_scale_f32 v33, vcc, v29, v16, v29
	v_mul_f32_e32 v34, v33, v31
	v_fma_f32 v35, -v13, v34, v33
	v_fmac_f32_e32 v34, v35, v31
	v_fma_f32 v13, -v13, v34, v33
	v_div_fmas_f32 v13, v13, v31, v34
	v_div_fixup_f32 v16, v13, v16, v29
	v_pk_mul_f32 v[16:17], v[16:17], v[20:21]
	v_lshlrev_b32_e32 v29, 16, v22
	v_and_b32_e32 v22, 0xffff0000, v22
	v_cvt_pk_bf16_f32 v13, v16, v17
	v_mul_f32_e32 v16, 0xbfb8aa3b, v29
	v_lshlrev_b32_e32 v20, 16, v14
	v_and_b32_e32 v21, 0xffff0000, v14
	v_mul_f32_e32 v14, 0xbfb8aa3b, v22
	v_exp_f32_e32 v16, v16
	v_exp_f32_e32 v17, v14
	v_pk_mul_f32 v[20:21], v[32:33], v[20:21] op_sel_hi:[0,1]
	s_waitcnt lgkmcnt(0)
; #define LAS __attribute__((address_space(3)))
; __device__ __forceinline__ unsigned cvtpk(float lo, float hi) { f32x2_t v = {lo, hi}; bf16x2_t b = __builtin_convertvector(v, bf16x2_t); return __builtin_bit_cast(unsigned, b); }
; __device__ __forceinline__ float silu_f(float x) { return x / (1.0f + __expf(-x)); }
; __device__ __forceinline__ void dil_attn_unit(LAS unsigned char* lds, bf16_t* proj, float* lse, int unit, int Tc, bf16_t* ybuf) {
;     ...
;             for (int i = 0; i < 4; ++i) { const int row = (half * 4 + i) * 4 + (lane >> 4), d8 = (lane & 15) * 8; const int tok = tok0 + row;
;                 const float l0 = lsr[row]; const float mxl = fmaxf(l0, fmaxf(l1[i], l2[i]));
;                 float w0 = __builtin_amdgcn_exp2f(l0 - mxl), w1 = __builtin_amdgcn_exp2f(l1[i] - mxl), w2 = __builtin_amdgcn_exp2f(l2[i] - mxl);
;                 const float iw = 1.0f / (w0 + w1 + w2); w0 *= iw; w1 *= iw; w2 *= iw;
;                 const f32x4 x0 = *(const LAS f32x4*)(stf + row * 132 + d8), x1 = *(const LAS f32x4*)(stf + row * 132 + d8 + 4);
;                 u32x4 yo;
;                 yo.x = cvtpk((w0 * x0[0] + w1 * bf_lo(o1[i].x) + w2 * bf_lo(o2[i].x)) * silu_f(bf_lo(gt[i].x)), (w0 * x0[1] + w1 * bf_hi(o1[i].x) + w2 * bf_hi(o2[i].x)) * silu_f(bf_hi(gt[i].x)));
;                 yo.y = cvtpk((w0 * x0[2] + w1 * bf_lo(o1[i].y) + w2 * bf_lo(o2[i].y)) * silu_f(bf_lo(gt[i].y)), (w0 * x0[3] + w1 * bf_hi(o1[i].y) + w2 * bf_hi(o2[i].y)) * silu_f(bf_hi(gt[i].y)));
;                 yo.z = cvtpk((w0 * x1[0] + w1 * bf_lo(o1[i].z) + w2 * bf_lo(o2[i].z)) * silu_f(bf_lo(gt[i].z)), (w0 * x1[1] + w1 * bf_hi(o1[i].z) + w2 * bf_hi(o2[i].z)) * silu_f(bf_hi(gt[i].z)));
;                 yo.w = cvtpk((w0 * x1[2] + w1 * bf_lo(o1[i].w) + w2 * bf_lo(o2[i].w)) * silu_f(bf_lo(gt[i].w)), (w0 * x1[3] + w1 * bf_hi(o1[i].w) + w2 * bf_hi(o2[i].w)) * silu_f(bf_hi(gt[i].w)));
;                 *(u32x4*)(ybuf + (size_t)tok * DM + h * 128 + d8) = yo; }
	v_pk_fma_f32 v[20:21], v[24:25], v[30:31], v[20:21] op_sel_hi:[1,0,1]
	v_lshlrev_b32_e32 v24, 16, v18
	v_pk_add_f32 v[16:17], v[16:17], 1.0 op_sel_hi:[1,0]
	v_and_b32_e32 v25, 0xffff0000, v18
	v_div_scale_f32 v14, s[4:5], v17, v17, v22
	v_rcp_f32_e32 v18, v14
	v_pk_fma_f32 v[20:21], v[28:29], v[24:25], v[20:21] op_sel_hi:[0,1,1]
	v_fma_f32 v24, -v14, v18, 1.0
	v_fmac_f32_e32 v18, v24, v18
	v_div_scale_f32 v24, vcc, v22, v17, v22
	v_mul_f32_e32 v25, v24, v18
	v_fma_f32 v31, -v14, v25, v24
	v_fmac_f32_e32 v25, v31, v18
	v_fma_f32 v14, -v14, v25, v24
	v_div_fmas_f32 v14, v14, v18, v25
	v_div_fixup_f32 v17, v14, v17, v22
	v_div_scale_f32 v14, s[4:5], v16, v16, v29
	v_rcp_f32_e32 v18, v14
	s_nop 0
	v_fma_f32 v22, -v14, v18, 1.0
	v_fmac_f32_e32 v18, v22, v18
	v_div_scale_f32 v22, vcc, v29, v16, v29
	v_mul_f32_e32 v24, v22, v18
	v_fma_f32 v25, -v14, v24, v22
	v_fmac_f32_e32 v24, v25, v18
	v_fma_f32 v14, -v14, v24, v22
	v_div_fmas_f32 v14, v14, v18, v24
	v_div_fixup_f32 v16, v14, v16, v29
	v_pk_mul_f32 v[16:17], v[16:17], v[20:21]
	v_lshlrev_b32_e32 v22, 16, v23
	v_and_b32_e32 v23, 0xffff0000, v23
	v_cvt_pk_bf16_f32 v14, v16, v17
	v_mul_f32_e32 v16, 0xbfb8aa3b, v22
	v_lshlrev_b32_e32 v20, 16, v15
	v_and_b32_e32 v21, 0xffff0000, v15
	v_mul_f32_e32 v15, 0xbfb8aa3b, v23
	v_exp_f32_e32 v16, v16
	v_exp_f32_e32 v17, v15
	v_pk_mul_f32 v[20:21], v[32:33], v[20:21] op_sel_hi:[0,1]
	v_pk_fma_f32 v[20:21], v[26:27], v[30:31], v[20:21] op_sel_hi:[1,0,1]
	v_lshlrev_b32_e32 v18, 16, v19
	v_pk_add_f32 v[16:17], v[16:17], 1.0 op_sel_hi:[1,0]
	v_and_b32_e32 v19, 0xffff0000, v19
	v_div_scale_f32 v15, s[4:5], v17, v17, v23
	v_pk_fma_f32 v[18:19], v[28:29], v[18:19], v[20:21] op_sel_hi:[0,1,1]
	v_rcp_f32_e32 v20, v15
	s_waitcnt vmcnt(4)
	v_lshlrev_b32_e32 v28, 16, v0
	v_and_b32_e32 v29, 0xffff0000, v0
	v_fma_f32 v21, -v15, v20, 1.0
	v_fmac_f32_e32 v20, v21, v20
	v_div_scale_f32 v21, vcc, v23, v17, v23
	v_mul_f32_e32 v24, v21, v20
	v_fma_f32 v25, -v15, v24, v21
	v_fmac_f32_e32 v24, v25, v20
	v_fma_f32 v15, -v15, v24, v21
	v_div_fmas_f32 v15, v15, v20, v24
	v_div_fixup_f32 v17, v15, v17, v23
	v_div_scale_f32 v15, s[4:5], v16, v16, v22
	v_rcp_f32_e32 v20, v15
	s_nop 0
	v_fma_f32 v21, -v15, v20, 1.0
	v_fmac_f32_e32 v20, v21, v20
	v_div_scale_f32 v21, vcc, v22, v16, v22
	v_mul_f32_e32 v23, v21, v20
	v_fma_f32 v24, -v15, v23, v21
	v_fmac_f32_e32 v23, v24, v20
	v_fma_f32 v15, -v15, v23, v21
	v_div_fmas_f32 v15, v15, v20, v23
	v_div_fixup_f32 v16, v15, v16, v22
	v_pk_mul_f32 v[16:17], v[16:17], v[18:19]
	s_nop 0
	v_cvt_pk_bf16_f32 v15, v16, v17
	v_lshl_add_u64 v[16:17], v[52:53], 0, v[68:69]
	global_store_dwordx4 v[16:17], v[12:15], off sc0 sc1
	s_nop 1
	v_max3_f32 v12, v41, v80, v79
	v_sub_f32_e32 v13, v41, v12
	v_sub_f32_e32 v14, v80, v12
	v_exp_f32_e32 v13, v13
	v_exp_f32_e32 v14, v14
	v_sub_f32_e32 v12, v79, v12
	v_exp_f32_e32 v12, v12
	v_add_f32_e32 v15, v13, v14
	v_add_f32_e32 v15, v12, v15
	v_div_scale_f32 v16, s[4:5], v15, v15, 1.0
	v_rcp_f32_e32 v17, v16
	s_nop 0
	v_fma_f32 v18, -v16, v17, 1.0
	v_fmac_f32_e32 v17, v18, v17
	v_div_scale_f32 v18, vcc, 1.0, v15, 1.0
	v_mul_f32_e32 v19, v18, v17
	v_fma_f32 v20, -v16, v19, v18
	v_fmac_f32_e32 v19, v20, v17
	v_fma_f32 v16, -v16, v19, v18
	v_div_fmas_f32 v16, v16, v17, v19
	s_waitcnt vmcnt(3)
	v_lshlrev_b32_e32 v17, 16, v8
	v_and_b32_e32 v8, 0xffff0000, v8
	v_mul_f32_e32 v19, 0xbfb8aa3b, v17
	v_mul_f32_e32 v0, 0xbfb8aa3b, v8
	v_exp_f32_e32 v26, v19
	v_exp_f32_e32 v27, v0
	v_div_fixup_f32 v15, v16, v15, 1.0
	v_mul_f32_e32 v18, v13, v15
	v_mul_f32_e32 v20, v14, v15
	v_mul_f32_e32 v16, v12, v15
	ds_read_b128 v[22:25], v81 offset:6336
	ds_read_b128 v[12:15], v81 offset:6352
	v_pk_add_f32 v[26:27], v[26:27], 1.0 op_sel_hi:[1,0]
	v_pk_mul_f32 v[28:29], v[20:21], v[28:29] op_sel_hi:[0,1]
	v_div_scale_f32 v0, s[4:5], v27, v27, v8
	s_waitcnt lgkmcnt(1)
	v_pk_fma_f32 v[22:23], v[22:23], v[18:19], v[28:29] op_sel_hi:[1,0,1]
	v_lshlrev_b32_e32 v28, 16, v4
	v_and_b32_e32 v29, 0xffff0000, v4
	v_rcp_f32_e32 v4, v0
	v_pk_fma_f32 v[22:23], v[16:17], v[28:29], v[22:23] op_sel_hi:[0,1,1]
	v_fma_f32 v19, -v0, v4, 1.0
	v_fmac_f32_e32 v4, v19, v4
	v_div_scale_f32 v19, vcc, v8, v27, v8
	v_mul_f32_e32 v21, v19, v4
	v_fma_f32 v28, -v0, v21, v19
	v_fmac_f32_e32 v21, v28, v4
	v_fma_f32 v0, -v0, v21, v19
	v_div_fmas_f32 v0, v0, v4, v21
	v_div_fixup_f32 v27, v0, v27, v8
	v_div_scale_f32 v0, s[4:5], v26, v26, v17
	v_rcp_f32_e32 v4, v0
	s_nop 0
	v_fma_f32 v8, -v0, v4, 1.0
	v_fmac_f32_e32 v4, v8, v4
	v_div_scale_f32 v8, vcc, v17, v26, v17
	v_mul_f32_e32 v19, v8, v4
	v_fma_f32 v21, -v0, v19, v8
	v_fmac_f32_e32 v19, v21, v4
	v_fma_f32 v0, -v0, v19, v8
	v_div_fmas_f32 v0, v0, v4, v19
	v_div_fixup_f32 v26, v0, v26, v17
	v_lshlrev_b32_e32 v17, 16, v9
	v_and_b32_e32 v19, 0xffff0000, v9
	v_pk_mul_f32 v[22:23], v[26:27], v[22:23]
	v_mul_f32_e32 v4, 0xbfb8aa3b, v17
	v_lshlrev_b32_e32 v8, 16, v1
	v_and_b32_e32 v9, 0xffff0000, v1
	v_mul_f32_e32 v1, 0xbfb8aa3b, v19
	v_cvt_pk_bf16_f32 v0, v22, v23
	v_exp_f32_e32 v4, v4
	v_lshlrev_b32_e32 v22, 16, v5
	v_and_b32_e32 v23, 0xffff0000, v5
	v_exp_f32_e32 v5, v1
	v_pk_mul_f32 v[8:9], v[20:21], v[8:9] op_sel_hi:[0,1]
	v_pk_fma_f32 v[8:9], v[24:25], v[18:19], v[8:9] op_sel_hi:[1,0,1]
	v_pk_add_f32 v[4:5], v[4:5], 1.0 op_sel_hi:[1,0]
	s_nop 0
	v_div_scale_f32 v1, s[4:5], v5, v5, v19
	v_rcp_f32_e32 v21, v1
	v_pk_fma_f32 v[8:9], v[16:17], v[22:23], v[8:9] op_sel_hi:[0,1,1]
	v_fma_f32 v22, -v1, v21, 1.0
	v_fmac_f32_e32 v21, v22, v21
	v_div_scale_f32 v22, vcc, v19, v5, v19
	v_mul_f32_e32 v23, v22, v21
	v_fma_f32 v24, -v1, v23, v22
	v_fmac_f32_e32 v23, v24, v21
	v_fma_f32 v1, -v1, v23, v22
	v_div_fmas_f32 v1, v1, v21, v23
	v_div_fixup_f32 v5, v1, v5, v19
	v_div_scale_f32 v1, s[4:5], v4, v4, v17
	v_rcp_f32_e32 v19, v1
	s_nop 0
	v_fma_f32 v21, -v1, v19, 1.0
	v_fmac_f32_e32 v19, v21, v19
	v_div_scale_f32 v21, vcc, v17, v4, v17
	v_mul_f32_e32 v22, v21, v19
	v_fma_f32 v23, -v1, v22, v21
	v_fmac_f32_e32 v22, v23, v19
	v_fma_f32 v1, -v1, v22, v21
	v_div_fmas_f32 v1, v1, v19, v22
	v_div_fixup_f32 v4, v1, v4, v17
	v_pk_mul_f32 v[4:5], v[4:5], v[8:9]
	v_lshlrev_b32_e32 v17, 16, v10
	v_and_b32_e32 v10, 0xffff0000, v10
	v_cvt_pk_bf16_f32 v1, v4, v5
	v_mul_f32_e32 v4, 0xbfb8aa3b, v17
	v_lshlrev_b32_e32 v8, 16, v2
	v_and_b32_e32 v9, 0xffff0000, v2
	v_mul_f32_e32 v2, 0xbfb8aa3b, v10
	v_exp_f32_e32 v4, v4
	v_exp_f32_e32 v5, v2
	v_pk_mul_f32 v[8:9], v[20:21], v[8:9] op_sel_hi:[0,1]
	s_waitcnt lgkmcnt(0)
; __device__ __forceinline__ unsigned cvtpk(float lo, float hi) { f32x2_t v = {lo, hi}; bf16x2_t b = __builtin_convertvector(v, bf16x2_t); return __builtin_bit_cast(unsigned, b); }
; __device__ __forceinline__ float silu_f(float x) { return x / (1.0f + __expf(-x)); }
; __device__ __forceinline__ void dil_attn_unit(LAS unsigned char* lds, bf16_t* proj, float* lse, int unit, int Tc, bf16_t* ybuf) {
;     ...
;             for (int i = 0; i < 4; ++i) { const int row = (half * 4 + i) * 4 + (lane >> 4), d8 = (lane & 15) * 8; const int tok = tok0 + row, t_ = tok & (SEQ - 1), s4_ = tok & ~(SEQ - 1);
;                 l1[i] = lse[(size_t)tok * 24 + 8 + h]; l2[i] = lse[(size_t)tok * 24 + 16 + h];
;                 o1[i] = *(const u32x4*)(proj + ((size_t)(24 + h) * Tc + s4_ + ((t_ & 3) << 10) + (t_ >> 2)) * 128 + d8);
;                 o2[i] = *(const u32x4*)(proj + ((size_t)(48 + h) * Tc + s4_ + ((t_ & 15) << 8) + (t_ >> 4)) * 128 + d8);
;                 gt[i] = *(const u32x4*)(proj + (size_t)9216 * Tc + (size_t)tok * 1024 + h * 128 + d8); }
;     ...
;                 yo.x = cvtpk((w0 * x0[0] + w1 * bf_lo(o1[i].x) + w2 * bf_lo(o2[i].x)) * silu_f(bf_lo(gt[i].x)), (w0 * x0[1] + w1 * bf_hi(o1[i].x) + w2 * bf_hi(o2[i].x)) * silu_f(bf_hi(gt[i].x)));
;                 yo.y = cvtpk((w0 * x0[2] + w1 * bf_lo(o1[i].y) + w2 * bf_lo(o2[i].y)) * silu_f(bf_lo(gt[i].y)), (w0 * x0[3] + w1 * bf_hi(o1[i].y) + w2 * bf_hi(o2[i].y)) * silu_f(bf_hi(gt[i].y)));
;                 yo.z = cvtpk((w0 * x1[0] + w1 * bf_lo(o1[i].z) + w2 * bf_lo(o2[i].z)) * silu_f(bf_lo(gt[i].z)), (w0 * x1[1] + w1 * bf_hi(o1[i].z) + w2 * bf_hi(o2[i].z)) * silu_f(bf_hi(gt[i].z)));
;                 yo.w = cvtpk((w0 * x1[2] + w1 * bf_lo(o1[i].w) + w2 * bf_lo(o2[i].w)) * silu_f(bf_lo(gt[i].w)), (w0 * x1[3] + w1 * bf_hi(o1[i].w) + w2 * bf_hi(o2[i].w)) * silu_f(bf_hi(gt[i].w)));
;                 *(u32x4*)(ybuf + (size_t)tok * DM + h * 128 + d8) = yo; }
	v_pk_fma_f32 v[8:9], v[12:13], v[18:19], v[8:9] op_sel_hi:[1,0,1]
	v_lshlrev_b32_e32 v12, 16, v6
	v_pk_add_f32 v[4:5], v[4:5], 1.0 op_sel_hi:[1,0]
	v_and_b32_e32 v13, 0xffff0000, v6
	v_div_scale_f32 v2, s[4:5], v5, v5, v10
	v_rcp_f32_e32 v6, v2
	v_pk_fma_f32 v[8:9], v[16:17], v[12:13], v[8:9] op_sel_hi:[0,1,1]
	v_fma_f32 v12, -v2, v6, 1.0
	v_fmac_f32_e32 v6, v12, v6
	v_div_scale_f32 v12, vcc, v10, v5, v10
	v_mul_f32_e32 v13, v12, v6
	v_fma_f32 v19, -v2, v13, v12
	v_fmac_f32_e32 v13, v19, v6
	v_fma_f32 v2, -v2, v13, v12
	v_div_fmas_f32 v2, v2, v6, v13
	v_div_fixup_f32 v5, v2, v5, v10
	v_div_scale_f32 v2, s[4:5], v4, v4, v17
	v_rcp_f32_e32 v6, v2
	s_nop 0
	v_fma_f32 v10, -v2, v6, 1.0
	v_fmac_f32_e32 v6, v10, v6
	v_div_scale_f32 v10, vcc, v17, v4, v17
	v_mul_f32_e32 v12, v10, v6
	v_fma_f32 v13, -v2, v12, v10
	v_fmac_f32_e32 v12, v13, v6
	v_fma_f32 v2, -v2, v12, v10
	v_div_fmas_f32 v2, v2, v6, v12
	v_div_fixup_f32 v4, v2, v4, v17
	v_pk_mul_f32 v[4:5], v[4:5], v[8:9]
	v_lshlrev_b32_e32 v10, 16, v11
	v_and_b32_e32 v11, 0xffff0000, v11
	v_cvt_pk_bf16_f32 v2, v4, v5
	v_mul_f32_e32 v4, 0xbfb8aa3b, v10
	v_lshlrev_b32_e32 v8, 16, v3
	v_and_b32_e32 v9, 0xffff0000, v3
	v_mul_f32_e32 v3, 0xbfb8aa3b, v11
	v_exp_f32_e32 v4, v4
	v_exp_f32_e32 v5, v3
	v_pk_mul_f32 v[8:9], v[20:21], v[8:9] op_sel_hi:[0,1]
	v_pk_fma_f32 v[8:9], v[14:15], v[18:19], v[8:9] op_sel_hi:[1,0,1]
	v_lshlrev_b32_e32 v6, 16, v7
	v_pk_add_f32 v[4:5], v[4:5], 1.0 op_sel_hi:[1,0]
	v_and_b32_e32 v7, 0xffff0000, v7
	v_div_scale_f32 v3, s[4:5], v5, v5, v11
	v_pk_fma_f32 v[6:7], v[16:17], v[6:7], v[8:9] op_sel_hi:[0,1,1]
	v_rcp_f32_e32 v8, v3
	s_nop 0
	v_fma_f32 v9, -v3, v8, 1.0
	v_fmac_f32_e32 v8, v9, v8
	v_div_scale_f32 v9, vcc, v11, v5, v11
	v_mul_f32_e32 v12, v9, v8
	v_fma_f32 v13, -v3, v12, v9
	v_fmac_f32_e32 v12, v13, v8
	v_fma_f32 v3, -v3, v12, v9
	v_div_fmas_f32 v3, v3, v8, v12
	v_div_fixup_f32 v5, v3, v5, v11
	v_div_scale_f32 v3, s[4:5], v4, v4, v10
	v_rcp_f32_e32 v8, v3
	s_nop 0
	v_fma_f32 v9, -v3, v8, 1.0
	v_fmac_f32_e32 v8, v9, v8
	v_div_scale_f32 v9, vcc, v10, v4, v10
	v_mul_f32_e32 v11, v9, v8
	v_fma_f32 v12, -v3, v11, v9
	v_fmac_f32_e32 v11, v12, v8
	v_fma_f32 v3, -v3, v11, v9
	v_div_fmas_f32 v3, v3, v8, v11
	v_div_fixup_f32 v4, v3, v4, v10
	v_pk_mul_f32 v[4:5], v[4:5], v[6:7]
	s_nop 0
	v_cvt_pk_bf16_f32 v3, v4, v5
	v_lshl_add_u64 v[4:5], v[52:53], 0, v[66:67]
	global_store_dwordx4 v[4:5], v[0:3], off sc0 sc1
	s_nop 1
	v_or_b32_e32 v0, s41, v48
	v_mov_b32_e32 v1, 0xff3
	v_mad_i64_i32 v[2:3], s[4:5], v0, s66, v[60:61]
	v_bitop3_b32 v4, s41, v1, v48 bitop3:0xc8
	v_lshl_add_u64 v[2:3], v[2:3], 0, s[76:77]
	global_load_dword v49, v[2:3], off offset:32
	global_load_dword v50, v[2:3], off offset:64
	v_lshrrev_b32_e32 v2, 2, v4
	v_or_b32_e32 v2, v58, v2
	v_mov_b32_e32 v3, v59
	v_lshlrev_b64 v[2:3], 8, v[2:3]
	v_lshl_add_u64 v[2:3], v[54:55], 0, v[2:3]
	global_load_dwordx4 v[36:39], v[2:3], off
	v_bfe_u32 v2, v0, 4, 8
	v_ashrrev_i32_e32 v1, 31, v0
	v_or_b32_e32 v62, v78, v2
	v_lshlrev_b64 v[2:3], 8, v[62:63]
	v_lshlrev_b64 v[70:71], 11, v[0:1]
	v_lshl_add_u64 v[2:3], v[54:55], 0, v[2:3]
	v_lshl_add_u64 v[0:1], v[56:57], 0, v[70:71]
	v_or_b32_e32 v4, 20, v75
	global_load_dwordx4 v[40:43], v[2:3], off
	global_load_dwordx4 v[44:47], v[0:1], off
	v_or_b32_e32 v0, s41, v4
	v_mov_b32_e32 v1, 0xff7
	v_mad_i64_i32 v[2:3], s[4:5], v0, s66, v[60:61]
	v_bitop3_b32 v5, s41, v1, v4 bitop3:0xc8
	v_lshl_add_u64 v[2:3], v[2:3], 0, s[76:77]
	global_load_dword v79, v[2:3], off offset:32
	global_load_dword v78, v[2:3], off offset:64
	v_lshrrev_b32_e32 v2, 2, v5
	v_or_b32_e32 v2, v58, v2
	v_mov_b32_e32 v3, v59
	v_lshlrev_b64 v[2:3], 8, v[2:3]
	v_lshl_add_u64 v[2:3], v[54:55], 0, v[2:3]
	global_load_dwordx4 v[24:27], v[2:3], off
	v_lshlrev_b32_e32 v2, 8, v4
	v_and_b32_e32 v2, 0x700, v2
	v_bfe_u32 v3, v0, 4, 8
	v_ashrrev_i32_e32 v1, 31, v0
	v_or3_b32 v62, v3, v2, s0
	v_lshlrev_b64 v[2:3], 8, v[62:63]
	v_lshlrev_b64 v[68:69], 11, v[0:1]
	v_lshl_add_u64 v[2:3], v[54:55], 0, v[2:3]
	v_lshl_add_u64 v[0:1], v[56:57], 0, v[68:69]
	v_or_b32_e32 v4, 24, v75
	global_load_dwordx4 v[28:31], v[2:3], off
	global_load_dwordx4 v[32:35], v[0:1], off
	v_or_b32_e32 v0, s41, v4
	v_mov_b32_e32 v1, 0xffb
	v_mad_i64_i32 v[2:3], s[4:5], v0, s66, v[60:61]
	v_bitop3_b32 v5, s41, v1, v4 bitop3:0xc8
	v_lshl_add_u64 v[2:3], v[2:3], 0, s[76:77]
	global_load_dword v74, v[2:3], off offset:32
	global_load_dword v73, v[2:3], off offset:64
	v_lshrrev_b32_e32 v2, 2, v5
	v_or_b32_e32 v2, v58, v2
	v_mov_b32_e32 v3, v59
	v_lshlrev_b64 v[2:3], 8, v[2:3]
	v_lshl_add_u64 v[2:3], v[54:55], 0, v[2:3]
	global_load_dwordx4 v[12:15], v[2:3], off
	v_lshlrev_b32_e32 v2, 8, v4
	v_and_b32_e32 v2, 0xb00, v2
	v_bfe_u32 v3, v0, 4, 8
	v_ashrrev_i32_e32 v1, 31, v0
	v_or3_b32 v62, v3, v2, s0
	v_lshlrev_b64 v[2:3], 8, v[62:63]
	v_lshlrev_b64 v[66:67], 11, v[0:1]
	v_or_b32_e32 v4, 28, v75
	v_lshl_add_u64 v[2:3], v[54:55], 0, v[2:3]
	v_lshl_add_u64 v[0:1], v[56:57], 0, v[66:67]
	v_or_b32_e32 v8, s41, v4
	global_load_dwordx4 v[16:19], v[2:3], off
	global_load_dwordx4 v[20:23], v[0:1], off
	v_mad_i64_i32 v[0:1], s[4:5], v8, s66, v[60:61]
	v_lshl_add_u64 v[0:1], v[0:1], 0, s[76:77]
	global_load_dword v72, v[0:1], off offset:32
	global_load_dword v61, v[0:1], off offset:64
	v_lshlrev_b32_e32 v4, 8, v4
	v_bfe_u32 v0, v8, 2, 10
	v_and_b32_e32 v4, 0xf00, v4
	v_bfe_u32 v5, v8, 4, 8
	v_or_b32_e32 v58, v58, v0
	v_or3_b32 v62, v5, v4, s0
	v_ashrrev_i32_e32 v9, 31, v8
	v_lshlrev_b64 v[0:1], 8, v[58:59]
	v_lshlrev_b64 v[4:5], 8, v[62:63]
	v_lshl_add_u64 v[0:1], v[54:55], 0, v[0:1]
	v_lshl_add_u64 v[4:5], v[54:55], 0, v[4:5]
	v_lshlrev_b64 v[54:55], 11, v[8:9]
	s_waitcnt vmcnt(15)
; #define LAS __attribute__((address_space(3)))
; __device__ __forceinline__ void dil_attn_unit(LAS unsigned char* lds, bf16_t* proj, float* lse, int unit, int Tc, bf16_t* ybuf) {
;     ...
;             for (int i = 0; i < 4; ++i) { const int row = (half * 4 + i) * 4 + (lane >> 4), d8 = (lane & 15) * 8; const int tok = tok0 + row, t_ = tok & (SEQ - 1), s4_ = tok & ~(SEQ - 1);
;                 l1[i] = lse[(size_t)tok * 24 + 8 + h]; l2[i] = lse[(size_t)tok * 24 + 16 + h];
;                 o1[i] = *(const u32x4*)(proj + ((size_t)(24 + h) * Tc + s4_ + ((t_ & 3) << 10) + (t_ >> 2)) * 128 + d8);
;                 o2[i] = *(const u32x4*)(proj + ((size_t)(48 + h) * Tc + s4_ + ((t_ & 15) << 8) + (t_ >> 4)) * 128 + d8);
;                 gt[i] = *(const u32x4*)(proj + (size_t)9216 * Tc + (size_t)tok * 1024 + h * 128 + d8); }
;     ...
;             for (int i = 0; i < 4; ++i) { const int row = (half * 4 + i) * 4 + (lane >> 4), d8 = (lane & 15) * 8; const int tok = tok0 + row;
;                 const float l0 = lsr[row]; const float mxl = fmaxf(l0, fmaxf(l1[i], l2[i]));
;                 float w0 = __builtin_amdgcn_exp2f(l0 - mxl), w1 = __builtin_amdgcn_exp2f(l1[i] - mxl), w2 = __builtin_amdgcn_exp2f(l2[i] - mxl);
;                 const float iw = 1.0f / (w0 + w1 + w2); w0 *= iw; w1 *= iw; w2 *= iw;
;                 const f32x4 x0 = *(const LAS f32x4*)(stf + row * 132 + d8), x1 = *(const LAS f32x4*)(stf + row * 132 + d8 + 4);
;                 u32x4 yo;
;                 yo.x = cvtpk((w0 * x0[0] + w1 * bf_lo(o1[i].x) + w2 * bf_lo(o2[i].x)) * silu_f(bf_lo(gt[i].x)), (w0 * x0[1] + w1 * bf_hi(o1[i].x) + w2 * bf_hi(o2[i].x)) * silu_f(bf_hi(gt[i].x)));
;                 yo.y = cvtpk((w0 * x0[2] + w1 * bf_lo(o1[i].y) + w2 * bf_lo(o2[i].y)) * silu_f(bf_lo(gt[i].y)), (w0 * x0[3] + w1 * bf_hi(o1[i].y) + w2 * bf_hi(o2[i].y)) * silu_f(bf_hi(gt[i].y)));
;                 yo.z = cvtpk((w0 * x1[0] + w1 * bf_lo(o1[i].z) + w2 * bf_lo(o2[i].z)) * silu_f(bf_lo(gt[i].z)), (w0 * x1[1] + w1 * bf_hi(o1[i].z) + w2 * bf_hi(o2[i].z)) * silu_f(bf_hi(gt[i].z)));
;                 yo.w = cvtpk((w0 * x1[2] + w1 * bf_lo(o1[i].w) + w2 * bf_lo(o2[i].w)) * silu_f(bf_lo(gt[i].w)), (w0 * x1[3] + w1 * bf_hi(o1[i].w) + w2 * bf_hi(o2[i].w)) * silu_f(bf_hi(gt[i].w)));
;                 *(u32x4*)(ybuf + (size_t)tok * DM + h * 128 + d8) = yo; }
	v_max3_f32 v51, v64, v49, v50
	v_lshl_add_u64 v[8:9], v[56:57], 0, v[54:55]
	v_sub_f32_e32 v56, v64, v51
	v_sub_f32_e32 v49, v49, v51
	v_exp_f32_e32 v56, v56
	v_exp_f32_e32 v49, v49
	v_sub_f32_e32 v50, v50, v51
	v_exp_f32_e32 v50, v50
	s_waitcnt vmcnt(14)
	v_lshlrev_b32_e32 v84, 16, v36
	v_add_f32_e32 v51, v56, v49
	v_and_b32_e32 v85, 0xffff0000, v36
	v_add_f32_e32 v51, v50, v51
	v_div_scale_f32 v57, s[0:1], v51, v51, 1.0
	v_rcp_f32_e32 v58, v57
	global_load_dwordx4 v[0:3], v[0:1], off
	v_fma_f32 v59, -v57, v58, 1.0
	v_fmac_f32_e32 v58, v59, v58
	v_div_scale_f32 v59, vcc, 1.0, v51, 1.0
	v_mul_f32_e32 v60, v59, v58
	v_fma_f32 v62, -v57, v60, v59
	v_fmac_f32_e32 v60, v62, v58
	v_fma_f32 v57, -v57, v60, v59
	s_waitcnt vmcnt(13)
	v_lshlrev_b32_e32 v59, 16, v44
	v_and_b32_e32 v44, 0xffff0000, v44
	v_mul_f32_e32 v62, 0xbfb8aa3b, v59
	v_mul_f32_e32 v36, 0xbfb8aa3b, v44
	v_div_fmas_f32 v57, v57, v58, v60
	v_exp_f32_e32 v62, v62
	v_exp_f32_e32 v63, v36
	v_div_fixup_f32 v51, v57, v51, 1.0
	v_mad_u32_u24 v57, v48, s6, v77
	global_load_dwordx4 v[4:7], v[4:5], off
	v_mul_f32_e32 v58, v56, v51
	global_load_dwordx4 v[8:11], v[8:9], off
	v_mul_f32_e32 v60, v49, v51
	v_mul_f32_e32 v56, v50, v51
	ds_read_b128 v[80:83], v57
	ds_read_b128 v[48:51], v57 offset:16
	v_pk_add_f32 v[62:63], v[62:63], 1.0 op_sel_hi:[1,0]
	s_waitcnt vmcnt(3)
	v_pk_mul_f32 v[84:85], v[60:61], v[84:85] op_sel_hi:[0,1]
	v_div_scale_f32 v36, s[0:1], v63, v63, v44
	s_waitcnt lgkmcnt(1)
	v_pk_fma_f32 v[80:81], v[80:81], v[58:59], v[84:85] op_sel_hi:[1,0,1]
	v_lshlrev_b32_e32 v84, 16, v40
	v_and_b32_e32 v85, 0xffff0000, v40
	v_rcp_f32_e32 v40, v36
	v_pk_fma_f32 v[80:81], v[56:57], v[84:85], v[80:81] op_sel_hi:[0,1,1]
	v_fma_f32 v64, -v36, v40, 1.0
	v_fmac_f32_e32 v40, v64, v40
	v_div_scale_f32 v64, vcc, v44, v63, v44
	v_mul_f32_e32 v75, v64, v40
	v_fma_f32 v77, -v36, v75, v64
	v_fmac_f32_e32 v75, v77, v40
	v_fma_f32 v36, -v36, v75, v64
	v_div_fmas_f32 v36, v36, v40, v75
	v_div_fixup_f32 v63, v36, v63, v44
	v_div_scale_f32 v36, s[0:1], v62, v62, v59
	v_rcp_f32_e32 v40, v36
	s_nop 0
	v_fma_f32 v44, -v36, v40, 1.0
	v_fmac_f32_e32 v40, v44, v40
	v_div_scale_f32 v44, vcc, v59, v62, v59
	v_mul_f32_e32 v64, v44, v40
	v_fma_f32 v75, -v36, v64, v44
	v_fmac_f32_e32 v64, v75, v40
	v_fma_f32 v36, -v36, v64, v44
	v_div_fmas_f32 v36, v36, v40, v64
	v_div_fixup_f32 v62, v36, v62, v59
	v_lshlrev_b32_e32 v59, 16, v45
	v_and_b32_e32 v64, 0xffff0000, v45
	v_pk_mul_f32 v[62:63], v[62:63], v[80:81]
	v_mul_f32_e32 v40, 0xbfb8aa3b, v59
	v_lshlrev_b32_e32 v44, 16, v37
	v_and_b32_e32 v45, 0xffff0000, v37
	v_mul_f32_e32 v37, 0xbfb8aa3b, v64
	v_cvt_pk_bf16_f32 v36, v62, v63
	v_exp_f32_e32 v40, v40
	v_lshlrev_b32_e32 v62, 16, v41
	v_and_b32_e32 v63, 0xffff0000, v41
	v_exp_f32_e32 v41, v37
	v_pk_mul_f32 v[44:45], v[60:61], v[44:45] op_sel_hi:[0,1]
	v_pk_fma_f32 v[44:45], v[82:83], v[58:59], v[44:45] op_sel_hi:[1,0,1]
	v_pk_add_f32 v[40:41], v[40:41], 1.0 op_sel_hi:[1,0]
	s_nop 0
	v_div_scale_f32 v37, s[0:1], v41, v41, v64
	v_pk_fma_f32 v[44:45], v[56:57], v[62:63], v[44:45] op_sel_hi:[0,1,1]
	v_rcp_f32_e32 v62, v37
	s_nop 0
	v_fma_f32 v63, -v37, v62, 1.0
	v_fmac_f32_e32 v62, v63, v62
	v_div_scale_f32 v63, vcc, v64, v41, v64
	v_mul_f32_e32 v75, v63, v62
	v_fma_f32 v77, -v37, v75, v63
	v_fmac_f32_e32 v75, v77, v62
	v_fma_f32 v37, -v37, v75, v63
	v_div_fmas_f32 v37, v37, v62, v75
	v_div_fixup_f32 v41, v37, v41, v64
	v_div_scale_f32 v37, s[0:1], v40, v40, v59
	v_rcp_f32_e32 v62, v37
	s_nop 0
	v_fma_f32 v63, -v37, v62, 1.0
	v_fmac_f32_e32 v62, v63, v62
	v_div_scale_f32 v63, vcc, v59, v40, v59
	v_mul_f32_e32 v64, v63, v62
	v_fma_f32 v75, -v37, v64, v63
	v_fmac_f32_e32 v64, v75, v62
	v_fma_f32 v37, -v37, v64, v63
	v_div_fmas_f32 v37, v37, v62, v64
	v_div_fixup_f32 v40, v37, v40, v59
	v_pk_mul_f32 v[40:41], v[40:41], v[44:45]
	v_lshlrev_b32_e32 v59, 16, v46
	v_and_b32_e32 v46, 0xffff0000, v46
	v_cvt_pk_bf16_f32 v37, v40, v41
	v_mul_f32_e32 v40, 0xbfb8aa3b, v59
	v_lshlrev_b32_e32 v44, 16, v38
	v_and_b32_e32 v45, 0xffff0000, v38
	v_mul_f32_e32 v38, 0xbfb8aa3b, v46
	v_exp_f32_e32 v40, v40
	v_exp_f32_e32 v41, v38
	v_pk_mul_f32 v[44:45], v[60:61], v[44:45] op_sel_hi:[0,1]
	s_waitcnt lgkmcnt(0)
	v_pk_fma_f32 v[44:45], v[48:49], v[58:59], v[44:45] op_sel_hi:[1,0,1]
	v_lshlrev_b32_e32 v48, 16, v42
	v_pk_add_f32 v[40:41], v[40:41], 1.0 op_sel_hi:[1,0]
	v_and_b32_e32 v49, 0xffff0000, v42
	v_div_scale_f32 v38, s[0:1], v41, v41, v46
	v_rcp_f32_e32 v42, v38
	v_pk_fma_f32 v[44:45], v[56:57], v[48:49], v[44:45] op_sel_hi:[0,1,1]
	v_and_b32_e32 v63, 0xffff0000, v24
	v_fma_f32 v48, -v38, v42, 1.0
	v_fmac_f32_e32 v42, v48, v42
	v_div_scale_f32 v48, vcc, v46, v41, v46
	v_mul_f32_e32 v49, v48, v42
	v_fma_f32 v62, -v38, v49, v48
	v_fmac_f32_e32 v49, v62, v42
	v_fma_f32 v38, -v38, v49, v48
	v_div_fmas_f32 v38, v38, v42, v49
	v_div_fixup_f32 v41, v38, v41, v46
	v_div_scale_f32 v38, s[0:1], v40, v40, v59
	v_rcp_f32_e32 v42, v38
	v_lshlrev_b32_e32 v62, 16, v24
	v_fma_f32 v46, -v38, v42, 1.0
	v_fmac_f32_e32 v42, v46, v42
	v_div_scale_f32 v46, vcc, v59, v40, v59
	v_mul_f32_e32 v48, v46, v42
	v_fma_f32 v49, -v38, v48, v46
	v_fmac_f32_e32 v48, v49, v42
	v_fma_f32 v38, -v38, v48, v46
	v_div_fmas_f32 v38, v38, v42, v48
	v_div_fixup_f32 v40, v38, v40, v59
	v_pk_mul_f32 v[40:41], v[40:41], v[44:45]
	v_lshlrev_b32_e32 v46, 16, v47
	v_and_b32_e32 v47, 0xffff0000, v47
	v_cvt_pk_bf16_f32 v38, v40, v41
	v_mul_f32_e32 v40, 0xbfb8aa3b, v46
	v_lshlrev_b32_e32 v44, 16, v39
	v_and_b32_e32 v45, 0xffff0000, v39
	v_mul_f32_e32 v39, 0xbfb8aa3b, v47
	v_exp_f32_e32 v40, v40
	v_exp_f32_e32 v41, v39
	v_pk_mul_f32 v[44:45], v[60:61], v[44:45] op_sel_hi:[0,1]
; #define LAS __attribute__((address_space(3)))
; __device__ __forceinline__ unsigned cvtpk(float lo, float hi) { f32x2_t v = {lo, hi}; bf16x2_t b = __builtin_convertvector(v, bf16x2_t); return __builtin_bit_cast(unsigned, b); }
; __device__ __forceinline__ float silu_f(float x) { return x / (1.0f + __expf(-x)); }
; __device__ __forceinline__ void dil_attn_unit(LAS unsigned char* lds, bf16_t* proj, float* lse, int unit, int Tc, bf16_t* ybuf) {
;     ...
;             for (int i = 0; i < 4; ++i) { const int row = (half * 4 + i) * 4 + (lane >> 4), d8 = (lane & 15) * 8; const int tok = tok0 + row;
;                 const float l0 = lsr[row]; const float mxl = fmaxf(l0, fmaxf(l1[i], l2[i]));
;                 float w0 = __builtin_amdgcn_exp2f(l0 - mxl), w1 = __builtin_amdgcn_exp2f(l1[i] - mxl), w2 = __builtin_amdgcn_exp2f(l2[i] - mxl);
;                 const float iw = 1.0f / (w0 + w1 + w2); w0 *= iw; w1 *= iw; w2 *= iw;
;                 const f32x4 x0 = *(const LAS f32x4*)(stf + row * 132 + d8), x1 = *(const LAS f32x4*)(stf + row * 132 + d8 + 4);
;                 u32x4 yo;
;                 yo.x = cvtpk((w0 * x0[0] + w1 * bf_lo(o1[i].x) + w2 * bf_lo(o2[i].x)) * silu_f(bf_lo(gt[i].x)), (w0 * x0[1] + w1 * bf_hi(o1[i].x) + w2 * bf_hi(o2[i].x)) * silu_f(bf_hi(gt[i].x)));
;                 yo.y = cvtpk((w0 * x0[2] + w1 * bf_lo(o1[i].y) + w2 * bf_lo(o2[i].y)) * silu_f(bf_lo(gt[i].y)), (w0 * x0[3] + w1 * bf_hi(o1[i].y) + w2 * bf_hi(o2[i].y)) * silu_f(bf_hi(gt[i].y)));
;                 yo.z = cvtpk((w0 * x1[0] + w1 * bf_lo(o1[i].z) + w2 * bf_lo(o2[i].z)) * silu_f(bf_lo(gt[i].z)), (w0 * x1[1] + w1 * bf_hi(o1[i].z) + w2 * bf_hi(o2[i].z)) * silu_f(bf_hi(gt[i].z)));
;                 yo.w = cvtpk((w0 * x1[2] + w1 * bf_lo(o1[i].w) + w2 * bf_lo(o2[i].w)) * silu_f(bf_lo(gt[i].w)), (w0 * x1[3] + w1 * bf_hi(o1[i].w) + w2 * bf_hi(o2[i].w)) * silu_f(bf_hi(gt[i].w)));
;                 *(u32x4*)(ybuf + (size_t)tok * DM + h * 128 + d8) = yo; }
	v_pk_fma_f32 v[44:45], v[50:51], v[58:59], v[44:45] op_sel_hi:[1,0,1]
	v_lshlrev_b32_e32 v42, 16, v43
	v_pk_add_f32 v[40:41], v[40:41], 1.0 op_sel_hi:[1,0]
	v_and_b32_e32 v43, 0xffff0000, v43
	v_div_scale_f32 v39, s[0:1], v41, v41, v47
	v_pk_fma_f32 v[42:43], v[56:57], v[42:43], v[44:45] op_sel_hi:[0,1,1]
	v_rcp_f32_e32 v44, v39
	s_nop 0
	v_fma_f32 v45, -v39, v44, 1.0
	v_fmac_f32_e32 v44, v45, v44
	v_div_scale_f32 v45, vcc, v47, v41, v47
	v_mul_f32_e32 v48, v45, v44
	v_fma_f32 v49, -v39, v48, v45
	v_fmac_f32_e32 v48, v49, v44
	v_fma_f32 v39, -v39, v48, v45
	v_div_fmas_f32 v39, v39, v44, v48
	v_div_fixup_f32 v41, v39, v41, v47
	v_div_scale_f32 v39, s[0:1], v40, v40, v46
	v_rcp_f32_e32 v44, v39
	s_nop 0
	v_fma_f32 v45, -v39, v44, 1.0
	v_fmac_f32_e32 v44, v45, v44
	v_div_scale_f32 v45, vcc, v46, v40, v46
	v_mul_f32_e32 v47, v45, v44
	v_fma_f32 v48, -v39, v47, v45
	v_fmac_f32_e32 v47, v48, v44
	v_fma_f32 v39, -v39, v47, v45
	v_div_fmas_f32 v39, v39, v44, v47
	v_div_fixup_f32 v40, v39, v40, v46
	v_pk_mul_f32 v[40:41], v[40:41], v[42:43]
	s_nop 0
	v_cvt_pk_bf16_f32 v39, v40, v41
	v_lshl_add_u64 v[40:41], v[52:53], 0, v[70:71]
	global_store_dwordx4 v[40:41], v[36:39], off sc0 sc1
	ds_read2_b32 v[40:41], v76 offset0:152 offset1:156
	s_nop 0
	v_max3_f32 v36, v65, v79, v78
	v_sub_f32_e32 v37, v65, v36
	v_sub_f32_e32 v38, v79, v36
	v_exp_f32_e32 v37, v37
	v_exp_f32_e32 v38, v38
	v_sub_f32_e32 v36, v78, v36
	v_exp_f32_e32 v36, v36
	v_add_f32_e32 v39, v37, v38
	v_add_f32_e32 v39, v36, v39
	v_div_scale_f32 v42, s[0:1], v39, v39, 1.0
	v_rcp_f32_e32 v43, v42
	s_nop 0
	v_fma_f32 v44, -v42, v43, 1.0
	v_fmac_f32_e32 v43, v44, v43
	v_div_scale_f32 v44, vcc, 1.0, v39, 1.0
	v_mul_f32_e32 v45, v44, v43
	v_fma_f32 v46, -v42, v45, v44
	v_fmac_f32_e32 v45, v46, v43
	v_fma_f32 v42, -v42, v45, v44
	v_div_fmas_f32 v42, v42, v43, v45
	v_lshlrev_b32_e32 v43, 16, v32
	v_and_b32_e32 v32, 0xffff0000, v32
	v_mul_f32_e32 v45, 0xbfb8aa3b, v43
	v_mul_f32_e32 v24, 0xbfb8aa3b, v32
	v_exp_f32_e32 v58, v45
	v_exp_f32_e32 v59, v24
	v_div_fixup_f32 v39, v42, v39, 1.0
	v_mul_f32_e32 v44, v37, v39
	v_mul_f32_e32 v46, v38, v39
	v_mul_f32_e32 v42, v36, v39
	ds_read_b128 v[48:51], v57 offset:2112
	ds_read_b128 v[36:39], v57 offset:2128
	v_pk_add_f32 v[58:59], v[58:59], 1.0 op_sel_hi:[1,0]
	v_pk_mul_f32 v[62:63], v[46:47], v[62:63] op_sel_hi:[0,1]
	v_div_scale_f32 v24, s[0:1], v59, v59, v32
	s_waitcnt lgkmcnt(1)
	v_pk_fma_f32 v[48:49], v[48:49], v[44:45], v[62:63] op_sel_hi:[1,0,1]
	v_lshlrev_b32_e32 v62, 16, v28
	v_and_b32_e32 v63, 0xffff0000, v28
	v_rcp_f32_e32 v28, v24
	v_pk_fma_f32 v[48:49], v[42:43], v[62:63], v[48:49] op_sel_hi:[0,1,1]
	v_fma_f32 v45, -v24, v28, 1.0
	v_fmac_f32_e32 v28, v45, v28
	v_div_scale_f32 v45, vcc, v32, v59, v32
	v_mul_f32_e32 v47, v45, v28
	v_fma_f32 v56, -v24, v47, v45
	v_fmac_f32_e32 v47, v56, v28
	v_fma_f32 v24, -v24, v47, v45
	v_div_fmas_f32 v24, v24, v28, v47
	v_div_fixup_f32 v59, v24, v59, v32
	v_div_scale_f32 v24, s[0:1], v58, v58, v43
	v_rcp_f32_e32 v28, v24
	s_nop 0
	v_fma_f32 v32, -v24, v28, 1.0
	v_fmac_f32_e32 v28, v32, v28
	v_div_scale_f32 v32, vcc, v43, v58, v43
	v_mul_f32_e32 v45, v32, v28
	v_fma_f32 v47, -v24, v45, v32
	v_fmac_f32_e32 v45, v47, v28
	v_fma_f32 v24, -v24, v45, v32
	v_div_fmas_f32 v24, v24, v28, v45
	v_div_fixup_f32 v58, v24, v58, v43
	v_lshlrev_b32_e32 v43, 16, v33
	v_and_b32_e32 v45, 0xffff0000, v33
	v_pk_mul_f32 v[48:49], v[58:59], v[48:49]
	v_mul_f32_e32 v28, 0xbfb8aa3b, v43
	v_lshlrev_b32_e32 v32, 16, v25
	v_and_b32_e32 v33, 0xffff0000, v25
	v_mul_f32_e32 v25, 0xbfb8aa3b, v45
	v_cvt_pk_bf16_f32 v24, v48, v49
	v_exp_f32_e32 v28, v28
	v_lshlrev_b32_e32 v48, 16, v29
	v_and_b32_e32 v49, 0xffff0000, v29
	v_exp_f32_e32 v29, v25
	v_pk_mul_f32 v[32:33], v[46:47], v[32:33] op_sel_hi:[0,1]
	v_pk_fma_f32 v[32:33], v[50:51], v[44:45], v[32:33] op_sel_hi:[1,0,1]
	v_pk_add_f32 v[28:29], v[28:29], 1.0 op_sel_hi:[1,0]
	s_nop 0
	v_div_scale_f32 v25, s[0:1], v29, v29, v45
	v_rcp_f32_e32 v47, v25
	v_pk_fma_f32 v[32:33], v[42:43], v[48:49], v[32:33] op_sel_hi:[0,1,1]
	v_fma_f32 v48, -v25, v47, 1.0
	v_fmac_f32_e32 v47, v48, v47
	v_div_scale_f32 v48, vcc, v45, v29, v45
	v_mul_f32_e32 v49, v48, v47
	v_fma_f32 v50, -v25, v49, v48
	v_fmac_f32_e32 v49, v50, v47
	v_fma_f32 v25, -v25, v49, v48
	v_div_fmas_f32 v25, v25, v47, v49
	v_div_fixup_f32 v29, v25, v29, v45
	v_div_scale_f32 v25, s[0:1], v28, v28, v43
	v_rcp_f32_e32 v45, v25
	s_nop 0
	v_fma_f32 v47, -v25, v45, 1.0
	v_fmac_f32_e32 v45, v47, v45
	v_div_scale_f32 v47, vcc, v43, v28, v43
	v_mul_f32_e32 v48, v47, v45
	v_fma_f32 v49, -v25, v48, v47
	v_fmac_f32_e32 v48, v49, v45
	v_fma_f32 v25, -v25, v48, v47
	v_div_fmas_f32 v25, v25, v45, v48
	v_div_fixup_f32 v28, v25, v28, v43
	v_pk_mul_f32 v[28:29], v[28:29], v[32:33]
	v_lshlrev_b32_e32 v43, 16, v34
	v_and_b32_e32 v34, 0xffff0000, v34
	v_cvt_pk_bf16_f32 v25, v28, v29
	v_mul_f32_e32 v28, 0xbfb8aa3b, v43
	v_lshlrev_b32_e32 v32, 16, v26
	v_and_b32_e32 v33, 0xffff0000, v26
	v_mul_f32_e32 v26, 0xbfb8aa3b, v34
	v_exp_f32_e32 v28, v28
	v_exp_f32_e32 v29, v26
	v_pk_mul_f32 v[32:33], v[46:47], v[32:33] op_sel_hi:[0,1]
	s_waitcnt lgkmcnt(0)
; #define LAS __attribute__((address_space(3)))
; __device__ __forceinline__ unsigned cvtpk(float lo, float hi) { f32x2_t v = {lo, hi}; bf16x2_t b = __builtin_convertvector(v, bf16x2_t); return __builtin_bit_cast(unsigned, b); }
; __device__ __forceinline__ float silu_f(float x) { return x / (1.0f + __expf(-x)); }
; __device__ __forceinline__ void dil_attn_unit(LAS unsigned char* lds, bf16_t* proj, float* lse, int unit, int Tc, bf16_t* ybuf) {
;     ...
;             for (int i = 0; i < 4; ++i) { const int row = (half * 4 + i) * 4 + (lane >> 4), d8 = (lane & 15) * 8; const int tok = tok0 + row;
;                 const float l0 = lsr[row]; const float mxl = fmaxf(l0, fmaxf(l1[i], l2[i]));
;                 float w0 = __builtin_amdgcn_exp2f(l0 - mxl), w1 = __builtin_amdgcn_exp2f(l1[i] - mxl), w2 = __builtin_amdgcn_exp2f(l2[i] - mxl);
;                 const float iw = 1.0f / (w0 + w1 + w2); w0 *= iw; w1 *= iw; w2 *= iw;
;                 const f32x4 x0 = *(const LAS f32x4*)(stf + row * 132 + d8), x1 = *(const LAS f32x4*)(stf + row * 132 + d8 + 4);
;                 u32x4 yo;
;                 yo.x = cvtpk((w0 * x0[0] + w1 * bf_lo(o1[i].x) + w2 * bf_lo(o2[i].x)) * silu_f(bf_lo(gt[i].x)), (w0 * x0[1] + w1 * bf_hi(o1[i].x) + w2 * bf_hi(o2[i].x)) * silu_f(bf_hi(gt[i].x)));
;                 yo.y = cvtpk((w0 * x0[2] + w1 * bf_lo(o1[i].y) + w2 * bf_lo(o2[i].y)) * silu_f(bf_lo(gt[i].y)), (w0 * x0[3] + w1 * bf_hi(o1[i].y) + w2 * bf_hi(o2[i].y)) * silu_f(bf_hi(gt[i].y)));
;                 yo.z = cvtpk((w0 * x1[0] + w1 * bf_lo(o1[i].z) + w2 * bf_lo(o2[i].z)) * silu_f(bf_lo(gt[i].z)), (w0 * x1[1] + w1 * bf_hi(o1[i].z) + w2 * bf_hi(o2[i].z)) * silu_f(bf_hi(gt[i].z)));
;                 yo.w = cvtpk((w0 * x1[2] + w1 * bf_lo(o1[i].w) + w2 * bf_lo(o2[i].w)) * silu_f(bf_lo(gt[i].w)), (w0 * x1[3] + w1 * bf_hi(o1[i].w) + w2 * bf_hi(o2[i].w)) * silu_f(bf_hi(gt[i].w)));
;                 *(u32x4*)(ybuf + (size_t)tok * DM + h * 128 + d8) = yo; }
	v_pk_fma_f32 v[32:33], v[36:37], v[44:45], v[32:33] op_sel_hi:[1,0,1]
	v_lshlrev_b32_e32 v36, 16, v30
	v_pk_add_f32 v[28:29], v[28:29], 1.0 op_sel_hi:[1,0]
	v_and_b32_e32 v37, 0xffff0000, v30
	v_div_scale_f32 v26, s[0:1], v29, v29, v34
	v_rcp_f32_e32 v30, v26
	v_pk_fma_f32 v[32:33], v[42:43], v[36:37], v[32:33] op_sel_hi:[0,1,1]
	v_fma_f32 v36, -v26, v30, 1.0
	v_fmac_f32_e32 v30, v36, v30
	v_div_scale_f32 v36, vcc, v34, v29, v34
	v_mul_f32_e32 v37, v36, v30
	v_fma_f32 v45, -v26, v37, v36
	v_fmac_f32_e32 v37, v45, v30
	v_fma_f32 v26, -v26, v37, v36
	v_div_fmas_f32 v26, v26, v30, v37
	v_div_fixup_f32 v29, v26, v29, v34
	v_div_scale_f32 v26, s[0:1], v28, v28, v43
	v_rcp_f32_e32 v30, v26
	s_nop 0
	v_fma_f32 v34, -v26, v30, 1.0
	v_fmac_f32_e32 v30, v34, v30
	v_div_scale_f32 v34, vcc, v43, v28, v43
	v_mul_f32_e32 v36, v34, v30
	v_fma_f32 v37, -v26, v36, v34
	v_fmac_f32_e32 v36, v37, v30
	v_fma_f32 v26, -v26, v36, v34
	v_div_fmas_f32 v26, v26, v30, v36
	v_div_fixup_f32 v28, v26, v28, v43
	v_pk_mul_f32 v[28:29], v[28:29], v[32:33]
	v_lshlrev_b32_e32 v34, 16, v35
	v_and_b32_e32 v35, 0xffff0000, v35
	v_cvt_pk_bf16_f32 v26, v28, v29
	v_mul_f32_e32 v28, 0xbfb8aa3b, v34
	v_lshlrev_b32_e32 v32, 16, v27
	v_and_b32_e32 v33, 0xffff0000, v27
	v_mul_f32_e32 v27, 0xbfb8aa3b, v35
	v_exp_f32_e32 v28, v28
	v_exp_f32_e32 v29, v27
	v_pk_mul_f32 v[32:33], v[46:47], v[32:33] op_sel_hi:[0,1]
	v_pk_fma_f32 v[32:33], v[38:39], v[44:45], v[32:33] op_sel_hi:[1,0,1]
	v_lshlrev_b32_e32 v30, 16, v31
	v_pk_add_f32 v[28:29], v[28:29], 1.0 op_sel_hi:[1,0]
	v_and_b32_e32 v31, 0xffff0000, v31
	v_div_scale_f32 v27, s[0:1], v29, v29, v35
	v_pk_fma_f32 v[30:31], v[42:43], v[30:31], v[32:33] op_sel_hi:[0,1,1]
	v_rcp_f32_e32 v32, v27
	v_lshlrev_b32_e32 v42, 16, v12
	v_and_b32_e32 v43, 0xffff0000, v12
	v_fma_f32 v33, -v27, v32, 1.0
	v_fmac_f32_e32 v32, v33, v32
	v_div_scale_f32 v33, vcc, v35, v29, v35
	v_mul_f32_e32 v36, v33, v32
	v_fma_f32 v37, -v27, v36, v33
	v_fmac_f32_e32 v36, v37, v32
	v_fma_f32 v27, -v27, v36, v33
	v_div_fmas_f32 v27, v27, v32, v36
	v_div_fixup_f32 v29, v27, v29, v35
	v_div_scale_f32 v27, s[0:1], v28, v28, v34
	v_rcp_f32_e32 v32, v27
	s_nop 0
	v_fma_f32 v33, -v27, v32, 1.0
	v_fmac_f32_e32 v32, v33, v32
	v_div_scale_f32 v33, vcc, v34, v28, v34
	v_mul_f32_e32 v35, v33, v32
	v_fma_f32 v36, -v27, v35, v33
	v_fmac_f32_e32 v35, v36, v32
	v_fma_f32 v27, -v27, v35, v33
	v_div_fmas_f32 v27, v27, v32, v35
	v_div_fixup_f32 v28, v27, v28, v34
	v_pk_mul_f32 v[28:29], v[28:29], v[30:31]
	s_nop 0
	v_cvt_pk_bf16_f32 v27, v28, v29
	v_lshl_add_u64 v[28:29], v[52:53], 0, v[68:69]
	global_store_dwordx4 v[28:29], v[24:27], off sc0 sc1
	s_nop 1
	v_max3_f32 v24, v40, v74, v73
	v_sub_f32_e32 v25, v40, v24
	v_sub_f32_e32 v26, v74, v24
	v_exp_f32_e32 v25, v25
	v_exp_f32_e32 v26, v26
	v_sub_f32_e32 v24, v73, v24
	v_exp_f32_e32 v24, v24
	v_add_f32_e32 v27, v25, v26
	v_add_f32_e32 v27, v24, v27
	v_div_scale_f32 v28, s[0:1], v27, v27, 1.0
	v_rcp_f32_e32 v29, v28
	s_nop 0
	v_fma_f32 v30, -v28, v29, 1.0
	v_fmac_f32_e32 v29, v30, v29
	v_div_scale_f32 v30, vcc, 1.0, v27, 1.0
	v_mul_f32_e32 v31, v30, v29
	v_fma_f32 v32, -v28, v31, v30
	v_fmac_f32_e32 v31, v32, v29
	v_fma_f32 v28, -v28, v31, v30
	v_div_fmas_f32 v28, v28, v29, v31
	v_lshlrev_b32_e32 v29, 16, v20
	v_and_b32_e32 v20, 0xffff0000, v20
	v_mul_f32_e32 v31, 0xbfb8aa3b, v29
	v_mul_f32_e32 v12, 0xbfb8aa3b, v20
	v_exp_f32_e32 v38, v31
	v_exp_f32_e32 v39, v12
	v_div_fixup_f32 v27, v28, v27, 1.0
	v_mul_f32_e32 v30, v25, v27
	v_mul_f32_e32 v32, v26, v27
	v_mul_f32_e32 v28, v24, v27
	ds_read_b128 v[34:37], v57 offset:4224
	ds_read_b128 v[24:27], v57 offset:4240
	v_pk_add_f32 v[38:39], v[38:39], 1.0 op_sel_hi:[1,0]
	v_pk_mul_f32 v[42:43], v[32:33], v[42:43] op_sel_hi:[0,1]
	v_div_scale_f32 v12, s[0:1], v39, v39, v20
	s_waitcnt lgkmcnt(1)
	v_pk_fma_f32 v[34:35], v[34:35], v[30:31], v[42:43] op_sel_hi:[1,0,1]
	v_lshlrev_b32_e32 v42, 16, v16
	v_and_b32_e32 v43, 0xffff0000, v16
	v_rcp_f32_e32 v16, v12
	v_pk_fma_f32 v[34:35], v[28:29], v[42:43], v[34:35] op_sel_hi:[0,1,1]
	v_fma_f32 v31, -v12, v16, 1.0
	v_fmac_f32_e32 v16, v31, v16
	v_div_scale_f32 v31, vcc, v20, v39, v20
	v_mul_f32_e32 v33, v31, v16
	v_fma_f32 v40, -v12, v33, v31
	v_fmac_f32_e32 v33, v40, v16
	v_fma_f32 v12, -v12, v33, v31
	v_div_fmas_f32 v12, v12, v16, v33
	v_div_fixup_f32 v39, v12, v39, v20
	v_div_scale_f32 v12, s[0:1], v38, v38, v29
	v_rcp_f32_e32 v16, v12
	s_nop 0
	v_fma_f32 v20, -v12, v16, 1.0
	v_fmac_f32_e32 v16, v20, v16
	v_div_scale_f32 v20, vcc, v29, v38, v29
	v_mul_f32_e32 v31, v20, v16
	v_fma_f32 v33, -v12, v31, v20
	v_fmac_f32_e32 v31, v33, v16
	v_fma_f32 v12, -v12, v31, v20
	v_div_fmas_f32 v12, v12, v16, v31
	v_div_fixup_f32 v38, v12, v38, v29
	v_lshlrev_b32_e32 v29, 16, v21
	v_and_b32_e32 v31, 0xffff0000, v21
	v_pk_mul_f32 v[34:35], v[38:39], v[34:35]
	v_mul_f32_e32 v16, 0xbfb8aa3b, v29
	v_lshlrev_b32_e32 v20, 16, v13
	v_and_b32_e32 v21, 0xffff0000, v13
	v_mul_f32_e32 v13, 0xbfb8aa3b, v31
	v_cvt_pk_bf16_f32 v12, v34, v35
	v_exp_f32_e32 v16, v16
	v_lshlrev_b32_e32 v34, 16, v17
	v_and_b32_e32 v35, 0xffff0000, v17
	v_exp_f32_e32 v17, v13
	v_pk_mul_f32 v[20:21], v[32:33], v[20:21] op_sel_hi:[0,1]
	v_pk_fma_f32 v[20:21], v[36:37], v[30:31], v[20:21] op_sel_hi:[1,0,1]
	v_pk_add_f32 v[16:17], v[16:17], 1.0 op_sel_hi:[1,0]
	s_nop 0
	v_div_scale_f32 v13, s[0:1], v17, v17, v31
	v_rcp_f32_e32 v33, v13
	v_pk_fma_f32 v[20:21], v[28:29], v[34:35], v[20:21] op_sel_hi:[0,1,1]
	v_fma_f32 v34, -v13, v33, 1.0
	v_fmac_f32_e32 v33, v34, v33
	v_div_scale_f32 v34, vcc, v31, v17, v31
	v_mul_f32_e32 v35, v34, v33
	v_fma_f32 v36, -v13, v35, v34
	v_fmac_f32_e32 v35, v36, v33
	v_fma_f32 v13, -v13, v35, v34
	v_div_fmas_f32 v13, v13, v33, v35
	v_div_fixup_f32 v17, v13, v17, v31
	v_div_scale_f32 v13, s[0:1], v16, v16, v29
	v_rcp_f32_e32 v31, v13
	s_nop 0
	v_fma_f32 v33, -v13, v31, 1.0
	v_fmac_f32_e32 v31, v33, v31
	v_div_scale_f32 v33, vcc, v29, v16, v29
	v_mul_f32_e32 v34, v33, v31
	v_fma_f32 v35, -v13, v34, v33
	v_fmac_f32_e32 v34, v35, v31
	v_fma_f32 v13, -v13, v34, v33
	v_div_fmas_f32 v13, v13, v31, v34
	v_div_fixup_f32 v16, v13, v16, v29
	v_pk_mul_f32 v[16:17], v[16:17], v[20:21]
	v_lshlrev_b32_e32 v29, 16, v22
	v_and_b32_e32 v22, 0xffff0000, v22
	v_cvt_pk_bf16_f32 v13, v16, v17
	v_mul_f32_e32 v16, 0xbfb8aa3b, v29
	v_lshlrev_b32_e32 v20, 16, v14
	v_and_b32_e32 v21, 0xffff0000, v14
	v_mul_f32_e32 v14, 0xbfb8aa3b, v22
	v_exp_f32_e32 v16, v16
	v_exp_f32_e32 v17, v14
	v_pk_mul_f32 v[20:21], v[32:33], v[20:21] op_sel_hi:[0,1]
	s_waitcnt lgkmcnt(0)
; #define LAS __attribute__((address_space(3)))
; __device__ __forceinline__ unsigned cvtpk(float lo, float hi) { f32x2_t v = {lo, hi}; bf16x2_t b = __builtin_convertvector(v, bf16x2_t); return __builtin_bit_cast(unsigned, b); }
; __device__ __forceinline__ float silu_f(float x) { return x / (1.0f + __expf(-x)); }
; __device__ __forceinline__ void dil_attn_unit(LAS unsigned char* lds, bf16_t* proj, float* lse, int unit, int Tc, bf16_t* ybuf) {
;     ...
;             for (int i = 0; i < 4; ++i) { const int row = (half * 4 + i) * 4 + (lane >> 4), d8 = (lane & 15) * 8; const int tok = tok0 + row;
;                 const float l0 = lsr[row]; const float mxl = fmaxf(l0, fmaxf(l1[i], l2[i]));
;                 float w0 = __builtin_amdgcn_exp2f(l0 - mxl), w1 = __builtin_amdgcn_exp2f(l1[i] - mxl), w2 = __builtin_amdgcn_exp2f(l2[i] - mxl);
;                 const float iw = 1.0f / (w0 + w1 + w2); w0 *= iw; w1 *= iw; w2 *= iw;
;                 const f32x4 x0 = *(const LAS f32x4*)(stf + row * 132 + d8), x1 = *(const LAS f32x4*)(stf + row * 132 + d8 + 4);
;                 u32x4 yo;
;                 yo.x = cvtpk((w0 * x0[0] + w1 * bf_lo(o1[i].x) + w2 * bf_lo(o2[i].x)) * silu_f(bf_lo(gt[i].x)), (w0 * x0[1] + w1 * bf_hi(o1[i].x) + w2 * bf_hi(o2[i].x)) * silu_f(bf_hi(gt[i].x)));
;                 yo.y = cvtpk((w0 * x0[2] + w1 * bf_lo(o1[i].y) + w2 * bf_lo(o2[i].y)) * silu_f(bf_lo(gt[i].y)), (w0 * x0[3] + w1 * bf_hi(o1[i].y) + w2 * bf_hi(o2[i].y)) * silu_f(bf_hi(gt[i].y)));
;                 yo.z = cvtpk((w0 * x1[0] + w1 * bf_lo(o1[i].z) + w2 * bf_lo(o2[i].z)) * silu_f(bf_lo(gt[i].z)), (w0 * x1[1] + w1 * bf_hi(o1[i].z) + w2 * bf_hi(o2[i].z)) * silu_f(bf_hi(gt[i].z)));
;                 yo.w = cvtpk((w0 * x1[2] + w1 * bf_lo(o1[i].w) + w2 * bf_lo(o2[i].w)) * silu_f(bf_lo(gt[i].w)), (w0 * x1[3] + w1 * bf_hi(o1[i].w) + w2 * bf_hi(o2[i].w)) * silu_f(bf_hi(gt[i].w)));
;                 *(u32x4*)(ybuf + (size_t)tok * DM + h * 128 + d8) = yo; }
	v_pk_fma_f32 v[20:21], v[24:25], v[30:31], v[20:21] op_sel_hi:[1,0,1]
	v_lshlrev_b32_e32 v24, 16, v18
	v_pk_add_f32 v[16:17], v[16:17], 1.0 op_sel_hi:[1,0]
	v_and_b32_e32 v25, 0xffff0000, v18
	v_div_scale_f32 v14, s[0:1], v17, v17, v22
	v_rcp_f32_e32 v18, v14
	v_pk_fma_f32 v[20:21], v[28:29], v[24:25], v[20:21] op_sel_hi:[0,1,1]
	v_fma_f32 v24, -v14, v18, 1.0
	v_fmac_f32_e32 v18, v24, v18
	v_div_scale_f32 v24, vcc, v22, v17, v22
	v_mul_f32_e32 v25, v24, v18
	v_fma_f32 v31, -v14, v25, v24
	v_fmac_f32_e32 v25, v31, v18
	v_fma_f32 v14, -v14, v25, v24
	v_div_fmas_f32 v14, v14, v18, v25
	v_div_fixup_f32 v17, v14, v17, v22
	v_div_scale_f32 v14, s[0:1], v16, v16, v29
	v_rcp_f32_e32 v18, v14
	s_nop 0
	v_fma_f32 v22, -v14, v18, 1.0
	v_fmac_f32_e32 v18, v22, v18
	v_div_scale_f32 v22, vcc, v29, v16, v29
	v_mul_f32_e32 v24, v22, v18
	v_fma_f32 v25, -v14, v24, v22
	v_fmac_f32_e32 v24, v25, v18
	v_fma_f32 v14, -v14, v24, v22
	v_div_fmas_f32 v14, v14, v18, v24
	v_div_fixup_f32 v16, v14, v16, v29
	v_pk_mul_f32 v[16:17], v[16:17], v[20:21]
	v_lshlrev_b32_e32 v22, 16, v23
	v_and_b32_e32 v23, 0xffff0000, v23
	v_cvt_pk_bf16_f32 v14, v16, v17
	v_mul_f32_e32 v16, 0xbfb8aa3b, v22
	v_lshlrev_b32_e32 v20, 16, v15
	v_and_b32_e32 v21, 0xffff0000, v15
	v_mul_f32_e32 v15, 0xbfb8aa3b, v23
	v_exp_f32_e32 v16, v16
	v_exp_f32_e32 v17, v15
	v_pk_mul_f32 v[20:21], v[32:33], v[20:21] op_sel_hi:[0,1]
	v_pk_fma_f32 v[20:21], v[26:27], v[30:31], v[20:21] op_sel_hi:[1,0,1]
	v_lshlrev_b32_e32 v18, 16, v19
	v_pk_add_f32 v[16:17], v[16:17], 1.0 op_sel_hi:[1,0]
	v_and_b32_e32 v19, 0xffff0000, v19
	v_div_scale_f32 v15, s[0:1], v17, v17, v23
	v_pk_fma_f32 v[18:19], v[28:29], v[18:19], v[20:21] op_sel_hi:[0,1,1]
	v_rcp_f32_e32 v20, v15
	s_waitcnt vmcnt(4)
	v_lshlrev_b32_e32 v28, 16, v0
	v_and_b32_e32 v29, 0xffff0000, v0
	v_fma_f32 v21, -v15, v20, 1.0
	v_fmac_f32_e32 v20, v21, v20
	v_div_scale_f32 v21, vcc, v23, v17, v23
	v_mul_f32_e32 v24, v21, v20
	v_fma_f32 v25, -v15, v24, v21
	v_fmac_f32_e32 v24, v25, v20
	v_fma_f32 v15, -v15, v24, v21
	v_div_fmas_f32 v15, v15, v20, v24
	v_div_fixup_f32 v17, v15, v17, v23
	v_div_scale_f32 v15, s[0:1], v16, v16, v22
	v_rcp_f32_e32 v20, v15
	s_nop 0
	v_fma_f32 v21, -v15, v20, 1.0
	v_fmac_f32_e32 v20, v21, v20
	v_div_scale_f32 v21, vcc, v22, v16, v22
	v_mul_f32_e32 v23, v21, v20
	v_fma_f32 v24, -v15, v23, v21
	v_fmac_f32_e32 v23, v24, v20
	v_fma_f32 v15, -v15, v23, v21
	v_div_fmas_f32 v15, v15, v20, v23
	v_div_fixup_f32 v16, v15, v16, v22
	v_pk_mul_f32 v[16:17], v[16:17], v[18:19]
	s_nop 0
	v_cvt_pk_bf16_f32 v15, v16, v17
	v_lshl_add_u64 v[16:17], v[52:53], 0, v[66:67]
	global_store_dwordx4 v[16:17], v[12:15], off sc0 sc1
	s_nop 1
	v_max3_f32 v12, v41, v72, v61
	v_sub_f32_e32 v13, v41, v12
	v_sub_f32_e32 v14, v72, v12
	v_exp_f32_e32 v13, v13
	v_exp_f32_e32 v14, v14
	v_sub_f32_e32 v12, v61, v12
	v_exp_f32_e32 v12, v12
	v_add_f32_e32 v15, v13, v14
	v_add_f32_e32 v15, v12, v15
	v_div_scale_f32 v16, s[0:1], v15, v15, 1.0
	v_rcp_f32_e32 v17, v16
	s_nop 0
	v_fma_f32 v18, -v16, v17, 1.0
	v_fmac_f32_e32 v17, v18, v17
	v_div_scale_f32 v18, vcc, 1.0, v15, 1.0
	v_mul_f32_e32 v19, v18, v17
	v_fma_f32 v20, -v16, v19, v18
	v_fmac_f32_e32 v19, v20, v17
	v_fma_f32 v16, -v16, v19, v18
	v_div_fmas_f32 v16, v16, v17, v19
	s_waitcnt vmcnt(3)
	v_lshlrev_b32_e32 v17, 16, v8
	v_and_b32_e32 v8, 0xffff0000, v8
	v_mul_f32_e32 v19, 0xbfb8aa3b, v17
	v_mul_f32_e32 v0, 0xbfb8aa3b, v8
	v_exp_f32_e32 v26, v19
	v_exp_f32_e32 v27, v0
	v_div_fixup_f32 v15, v16, v15, 1.0
	v_mul_f32_e32 v18, v13, v15
	v_mul_f32_e32 v20, v14, v15
	v_mul_f32_e32 v16, v12, v15
	ds_read_b128 v[22:25], v57 offset:6336
	ds_read_b128 v[12:15], v57 offset:6352
	v_pk_add_f32 v[26:27], v[26:27], 1.0 op_sel_hi:[1,0]
	v_pk_mul_f32 v[28:29], v[20:21], v[28:29] op_sel_hi:[0,1]
	v_div_scale_f32 v0, s[0:1], v27, v27, v8
	s_waitcnt lgkmcnt(1)
; #define LAS __attribute__((address_space(3)))
; __device__ __forceinline__ unsigned cvtpk(float lo, float hi) { f32x2_t v = {lo, hi}; bf16x2_t b = __builtin_convertvector(v, bf16x2_t); return __builtin_bit_cast(unsigned, b); }
; __device__ __forceinline__ float silu_f(float x) { return x / (1.0f + __expf(-x)); }
; __device__ __forceinline__ void dil_attn_unit(LAS unsigned char* lds, bf16_t* proj, float* lse, int unit, int Tc, bf16_t* ybuf) {
;     ...
;             for (int i = 0; i < 4; ++i) { const int row = (half * 4 + i) * 4 + (lane >> 4), d8 = (lane & 15) * 8; const int tok = tok0 + row;
;                 const float l0 = lsr[row]; const float mxl = fmaxf(l0, fmaxf(l1[i], l2[i]));
;                 float w0 = __builtin_amdgcn_exp2f(l0 - mxl), w1 = __builtin_amdgcn_exp2f(l1[i] - mxl), w2 = __builtin_amdgcn_exp2f(l2[i] - mxl);
;                 const float iw = 1.0f / (w0 + w1 + w2); w0 *= iw; w1 *= iw; w2 *= iw;
;                 const f32x4 x0 = *(const LAS f32x4*)(stf + row * 132 + d8), x1 = *(const LAS f32x4*)(stf + row * 132 + d8 + 4);
;                 u32x4 yo;
;                 yo.x = cvtpk((w0 * x0[0] + w1 * bf_lo(o1[i].x) + w2 * bf_lo(o2[i].x)) * silu_f(bf_lo(gt[i].x)), (w0 * x0[1] + w1 * bf_hi(o1[i].x) + w2 * bf_hi(o2[i].x)) * silu_f(bf_hi(gt[i].x)));
;                 yo.y = cvtpk((w0 * x0[2] + w1 * bf_lo(o1[i].y) + w2 * bf_lo(o2[i].y)) * silu_f(bf_lo(gt[i].y)), (w0 * x0[3] + w1 * bf_hi(o1[i].y) + w2 * bf_hi(o2[i].y)) * silu_f(bf_hi(gt[i].y)));
;                 yo.z = cvtpk((w0 * x1[0] + w1 * bf_lo(o1[i].z) + w2 * bf_lo(o2[i].z)) * silu_f(bf_lo(gt[i].z)), (w0 * x1[1] + w1 * bf_hi(o1[i].z) + w2 * bf_hi(o2[i].z)) * silu_f(bf_hi(gt[i].z)));
;                 yo.w = cvtpk((w0 * x1[2] + w1 * bf_lo(o1[i].w) + w2 * bf_lo(o2[i].w)) * silu_f(bf_lo(gt[i].w)), (w0 * x1[3] + w1 * bf_hi(o1[i].w) + w2 * bf_hi(o2[i].w)) * silu_f(bf_hi(gt[i].w)));
;                 *(u32x4*)(ybuf + (size_t)tok * DM + h * 128 + d8) = yo; }
	v_pk_fma_f32 v[22:23], v[22:23], v[18:19], v[28:29] op_sel_hi:[1,0,1]
	v_lshlrev_b32_e32 v28, 16, v4
	v_and_b32_e32 v29, 0xffff0000, v4
	v_rcp_f32_e32 v4, v0
	v_pk_fma_f32 v[22:23], v[16:17], v[28:29], v[22:23] op_sel_hi:[0,1,1]
	v_fma_f32 v19, -v0, v4, 1.0
	v_fmac_f32_e32 v4, v19, v4
	v_div_scale_f32 v19, vcc, v8, v27, v8
	v_mul_f32_e32 v21, v19, v4
	v_fma_f32 v28, -v0, v21, v19
	v_fmac_f32_e32 v21, v28, v4
	v_fma_f32 v0, -v0, v21, v19
	v_div_fmas_f32 v0, v0, v4, v21
	v_div_fixup_f32 v27, v0, v27, v8
	v_div_scale_f32 v0, s[0:1], v26, v26, v17
	v_rcp_f32_e32 v4, v0
	s_nop 0
	v_fma_f32 v8, -v0, v4, 1.0
	v_fmac_f32_e32 v4, v8, v4
	v_div_scale_f32 v8, vcc, v17, v26, v17
	v_mul_f32_e32 v19, v8, v4
	v_fma_f32 v21, -v0, v19, v8
	v_fmac_f32_e32 v19, v21, v4
	v_fma_f32 v0, -v0, v19, v8
	v_div_fmas_f32 v0, v0, v4, v19
	v_div_fixup_f32 v26, v0, v26, v17
	v_lshlrev_b32_e32 v17, 16, v9
	v_and_b32_e32 v19, 0xffff0000, v9
	v_pk_mul_f32 v[22:23], v[26:27], v[22:23]
	v_mul_f32_e32 v4, 0xbfb8aa3b, v17
	v_lshlrev_b32_e32 v8, 16, v1
	v_and_b32_e32 v9, 0xffff0000, v1
	v_mul_f32_e32 v1, 0xbfb8aa3b, v19
	v_cvt_pk_bf16_f32 v0, v22, v23
	v_exp_f32_e32 v4, v4
	v_lshlrev_b32_e32 v22, 16, v5
	v_and_b32_e32 v23, 0xffff0000, v5
	v_exp_f32_e32 v5, v1
	v_pk_mul_f32 v[8:9], v[20:21], v[8:9] op_sel_hi:[0,1]
	v_pk_fma_f32 v[8:9], v[24:25], v[18:19], v[8:9] op_sel_hi:[1,0,1]
	v_pk_add_f32 v[4:5], v[4:5], 1.0 op_sel_hi:[1,0]
	s_nop 0
	v_div_scale_f32 v1, s[0:1], v5, v5, v19
	v_rcp_f32_e32 v21, v1
	v_pk_fma_f32 v[8:9], v[16:17], v[22:23], v[8:9] op_sel_hi:[0,1,1]
	v_fma_f32 v22, -v1, v21, 1.0
	v_fmac_f32_e32 v21, v22, v21
	v_div_scale_f32 v22, vcc, v19, v5, v19
	v_mul_f32_e32 v23, v22, v21
	v_fma_f32 v24, -v1, v23, v22
	v_fmac_f32_e32 v23, v24, v21
	v_fma_f32 v1, -v1, v23, v22
	v_div_fmas_f32 v1, v1, v21, v23
	v_div_fixup_f32 v5, v1, v5, v19
	v_div_scale_f32 v1, s[0:1], v4, v4, v17
	v_rcp_f32_e32 v19, v1
	s_nop 0
	v_fma_f32 v21, -v1, v19, 1.0
	v_fmac_f32_e32 v19, v21, v19
	v_div_scale_f32 v21, vcc, v17, v4, v17
	v_mul_f32_e32 v22, v21, v19
	v_fma_f32 v23, -v1, v22, v21
	v_fmac_f32_e32 v22, v23, v19
	v_fma_f32 v1, -v1, v22, v21
	v_div_fmas_f32 v1, v1, v19, v22
	v_div_fixup_f32 v4, v1, v4, v17
	v_pk_mul_f32 v[4:5], v[4:5], v[8:9]
	v_lshlrev_b32_e32 v17, 16, v10
	v_and_b32_e32 v10, 0xffff0000, v10
	v_cvt_pk_bf16_f32 v1, v4, v5
	v_mul_f32_e32 v4, 0xbfb8aa3b, v17
	v_lshlrev_b32_e32 v8, 16, v2
	v_and_b32_e32 v9, 0xffff0000, v2
	v_mul_f32_e32 v2, 0xbfb8aa3b, v10
	v_exp_f32_e32 v4, v4
	v_exp_f32_e32 v5, v2
	v_pk_mul_f32 v[8:9], v[20:21], v[8:9] op_sel_hi:[0,1]
	s_waitcnt lgkmcnt(0)
	v_pk_fma_f32 v[8:9], v[12:13], v[18:19], v[8:9] op_sel_hi:[1,0,1]
	v_lshlrev_b32_e32 v12, 16, v6
	v_pk_add_f32 v[4:5], v[4:5], 1.0 op_sel_hi:[1,0]
	v_and_b32_e32 v13, 0xffff0000, v6
	v_div_scale_f32 v2, s[0:1], v5, v5, v10
	v_rcp_f32_e32 v6, v2
	v_pk_fma_f32 v[8:9], v[16:17], v[12:13], v[8:9] op_sel_hi:[0,1,1]
	v_fma_f32 v12, -v2, v6, 1.0
	v_fmac_f32_e32 v6, v12, v6
	v_div_scale_f32 v12, vcc, v10, v5, v10
	v_mul_f32_e32 v13, v12, v6
	v_fma_f32 v19, -v2, v13, v12
	v_fmac_f32_e32 v13, v19, v6
	v_fma_f32 v2, -v2, v13, v12
	v_div_fmas_f32 v2, v2, v6, v13
	v_div_fixup_f32 v5, v2, v5, v10
	v_div_scale_f32 v2, s[0:1], v4, v4, v17
	v_rcp_f32_e32 v6, v2
	s_nop 0
	v_fma_f32 v10, -v2, v6, 1.0
	v_fmac_f32_e32 v6, v10, v6
	v_div_scale_f32 v10, vcc, v17, v4, v17
	v_mul_f32_e32 v12, v10, v6
	v_fma_f32 v13, -v2, v12, v10
	v_fmac_f32_e32 v12, v13, v6
	v_fma_f32 v2, -v2, v12, v10
	v_div_fmas_f32 v2, v2, v6, v12
	v_div_fixup_f32 v4, v2, v4, v17
	v_pk_mul_f32 v[4:5], v[4:5], v[8:9]
	v_lshlrev_b32_e32 v10, 16, v11
	v_and_b32_e32 v11, 0xffff0000, v11
	v_cvt_pk_bf16_f32 v2, v4, v5
	v_mul_f32_e32 v4, 0xbfb8aa3b, v10
	v_lshlrev_b32_e32 v8, 16, v3
	v_and_b32_e32 v9, 0xffff0000, v3
	v_mul_f32_e32 v3, 0xbfb8aa3b, v11
	v_exp_f32_e32 v4, v4
	v_exp_f32_e32 v5, v3
	v_pk_mul_f32 v[8:9], v[20:21], v[8:9] op_sel_hi:[0,1]
	v_pk_fma_f32 v[8:9], v[14:15], v[18:19], v[8:9] op_sel_hi:[1,0,1]
	v_lshlrev_b32_e32 v6, 16, v7
	v_pk_add_f32 v[4:5], v[4:5], 1.0 op_sel_hi:[1,0]
	v_and_b32_e32 v7, 0xffff0000, v7
	v_div_scale_f32 v3, s[0:1], v5, v5, v11
	v_pk_fma_f32 v[6:7], v[16:17], v[6:7], v[8:9] op_sel_hi:[0,1,1]
	v_rcp_f32_e32 v8, v3
	s_nop 0
	v_fma_f32 v9, -v3, v8, 1.0
	v_fmac_f32_e32 v8, v9, v8
	v_div_scale_f32 v9, vcc, v11, v5, v11
	v_mul_f32_e32 v12, v9, v8
	v_fma_f32 v13, -v3, v12, v9
	v_fmac_f32_e32 v12, v13, v8
	v_fma_f32 v3, -v3, v12, v9
	v_div_fmas_f32 v3, v3, v8, v12
	v_div_fixup_f32 v5, v3, v5, v11
	v_div_scale_f32 v3, s[0:1], v4, v4, v10
	v_rcp_f32_e32 v8, v3
	s_nop 0
	v_fma_f32 v9, -v3, v8, 1.0
	v_fmac_f32_e32 v8, v9, v8
	v_div_scale_f32 v9, vcc, v10, v4, v10
	v_mul_f32_e32 v11, v9, v8
	v_fma_f32 v12, -v3, v11, v9
	v_fmac_f32_e32 v11, v12, v8
	v_fma_f32 v3, -v3, v11, v9
	v_div_fmas_f32 v3, v3, v8, v11
	v_div_fixup_f32 v4, v3, v4, v10
	v_pk_mul_f32 v[4:5], v[4:5], v[6:7]
	s_nop 0
	v_cvt_pk_bf16_f32 v3, v4, v5
	v_lshl_add_u64 v[4:5], v[52:53], 0, v[54:55]
	global_store_dwordx4 v[4:5], v[0:3], off sc0 sc1

; #define LAS __attribute__((address_space(3)))
; __device__ __forceinline__ unsigned cvtpk(float lo, float hi) { f32x2_t v = {lo, hi}; bf16x2_t b = __builtin_convertvector(v, bf16x2_t); return __builtin_bit_cast(unsigned, b); }
; __device__ __forceinline__ void dil_attn_unit(LAS unsigned char* lds, bf16_t* proj, float* lse, int unit, int Tc, bf16_t* ybuf) {
;     ...
;     const float inv = 1.0f / ls;
;     const float lse2 = mx + __builtin_amdgcn_logf(ls);
;     if (hi == 0 && !ybuf) lse[(rowbase + ((size_t)uq << dsh)) * 24 + g * 8 + h] = lse2;
;     u32x4 pa[5][2];
; #pragma unroll
;     for (int j = 0; j < 5; ++j)
; #pragma unroll
;         for (int s2 = 0; s2 < 2; ++s2) { pa[j][s2].x = cvtpk(p[j][8 * s2 + 0], p[j][8 * s2 + 1]); pa[j][s2].y = cvtpk(p[j][8 * s2 + 2], p[j][8 * s2 + 3]);
;             pa[j][s2].z = cvtpk(p[j][8 * s2 + 4], p[j][8 * s2 + 5]); pa[j][s2].w = cvtpk(p[j][8 * s2 + 6], p[j][8 * s2 + 7]); }
;     __syncthreads();
; #pragma unroll
;     for (int it = 0; it < 12; ++it) { const int id = it * 512 + tid, row = id >> 4, ch = id & 15; const int uk = U0 - 64 + row; const bool ok = (uk >= 0) && (uk < L);
;         u32x4 z = vv[it]; if (!ok) z = (u32x4){0u, 0u, 0u, 0u}; *(LAS u32x4*)(lds + row * 320 + ch * 16) = z; }
;     __syncthreads();
;     f32x16 o[4];
; #pragma unroll
;     for (int db = 0; db < 4; ++db) o[db] = (f32x16){0.f, 0.f, 0.f, 0.f, 0.f, 0.f, 0.f, 0.f, 0.f, 0.f, 0.f, 0.f, 0.f, 0.f, 0.f, 0.f};
;     const LAS unsigned char* vbase = lds + (32 * w + 4 * hi + ((lane & 15) >> 2)) * 320 + (16 * ((lane >> 4) & 1) + 4 * (lane & 3)) * 2;
; #pragma unroll
;     for (int j = 0; j < 5; ++j)
; #pragma unroll
;         for (int s2 = 0; s2 < 2; ++s2)
; #pragma unroll
;             for (int db = 0; db < 4; ++db) {
;                 const LAS unsigned char* vp = vbase + (32 * j + 16 * s2) * 320 + db * 64;
;                 const v4i16_t lo = __builtin_amdgcn_ds_read_tr16_b64_v4i16((LAS v4i16_t*)vp);
;                 const v4i16_t hh = __builtin_amdgcn_ds_read_tr16_b64_v4i16((LAS v4i16_t*)(vp + 8 * 320));
;                 const bf16x8 vf = (bf16x8){lo[0], lo[1], lo[2], lo[3], hh[0], hh[1], hh[2], hh[3]};
;                 o[db] = __builtin_amdgcn_mfma_f32_32x32x16_bf16(__builtin_bit_cast(bf16x8, pa[j][s2]), vf, o[db], 0, 0, 0);
.LBB0_263:
	s_or_b64 exec, exec, s[0:1]
	v_div_scale_f32 v49, s[0:1], v48, v48, 1.0
	v_rcp_f32_e32 v50, v49
	v_div_scale_f32 v51, vcc, 1.0, v48, 1.0
	v_fma_f32 v128, -v49, v50, 1.0
	v_fmac_f32_e32 v50, v128, v50
	v_mul_f32_e32 v128, v51, v50
	v_fma_f32 v129, -v49, v128, v51
	v_fmac_f32_e32 v128, v129, v50
	v_fma_f32 v49, -v49, v128, v51
	v_div_fmas_f32 v49, v49, v50, v128
	v_div_fixup_f32 v142, v49, v48, 1.0
	v_cvt_pk_bf16_f32 v48, v0, v1
	v_cvt_pk_bf16_f32 v49, v2, v3
	v_cvt_pk_bf16_f32 v50, v4, v5
	s_waitcnt vmcnt(11)
	v_cndmask_b32_e64 v3, 0, v127, s[6:7]
	v_cndmask_b32_e64 v2, 0, v126, s[6:7]
	v_cndmask_b32_e64 v1, 0, v125, s[6:7]
	v_cndmask_b32_e64 v0, 0, v124, s[6:7]
	v_mad_u64_u32 v[4:5], s[0:1], v192, s59, v[156:157]
	s_barrier
	ds_write_b128 v4, v[0:3]
	s_waitcnt vmcnt(10)
	v_cndmask_b32_e64 v3, 0, v123, s[8:9]
	v_cndmask_b32_e64 v2, 0, v122, s[8:9]
	v_cndmask_b32_e64 v1, 0, v121, s[8:9]
	v_cndmask_b32_e64 v0, 0, v120, s[8:9]
	v_mad_u64_u32 v[4:5], s[0:1], v193, s59, v[156:157]
	ds_write_b128 v4, v[0:3]
	s_waitcnt vmcnt(9)
	v_cndmask_b32_e64 v3, 0, v119, s[10:11]
	v_cndmask_b32_e64 v2, 0, v118, s[10:11]
	v_cndmask_b32_e64 v1, 0, v117, s[10:11]
	v_cndmask_b32_e64 v0, 0, v116, s[10:11]
	v_mad_u64_u32 v[4:5], s[0:1], v194, s59, v[156:157]
	ds_write_b128 v4, v[0:3]
	s_waitcnt vmcnt(8)
	v_cndmask_b32_e64 v3, 0, v115, s[12:13]
	v_cndmask_b32_e64 v2, 0, v114, s[12:13]
	v_cndmask_b32_e64 v1, 0, v113, s[12:13]
	v_cndmask_b32_e64 v0, 0, v112, s[12:13]
	v_mad_u64_u32 v[4:5], s[0:1], v196, s59, v[156:157]
	ds_write_b128 v4, v[0:3]
	s_waitcnt vmcnt(7)
	v_cndmask_b32_e64 v3, 0, v111, s[14:15]
	v_cndmask_b32_e64 v2, 0, v110, s[14:15]
	v_cndmask_b32_e64 v1, 0, v109, s[14:15]
	v_cndmask_b32_e64 v0, 0, v108, s[14:15]
	v_mad_u64_u32 v[4:5], s[0:1], v198, s59, v[156:157]
	ds_write_b128 v4, v[0:3]
	s_waitcnt vmcnt(6)
	v_cndmask_b32_e64 v3, 0, v107, s[16:17]
	v_cndmask_b32_e64 v2, 0, v106, s[16:17]
	v_cndmask_b32_e64 v1, 0, v105, s[16:17]
	v_cndmask_b32_e64 v0, 0, v104, s[16:17]
	v_mad_u64_u32 v[4:5], s[0:1], v200, s59, v[156:157]
	ds_write_b128 v4, v[0:3]
	s_waitcnt vmcnt(5)
	v_cndmask_b32_e64 v3, 0, v103, s[18:19]
	v_cndmask_b32_e64 v2, 0, v102, s[18:19]
	v_cndmask_b32_e64 v1, 0, v101, s[18:19]
	v_cndmask_b32_e64 v0, 0, v100, s[18:19]
	v_mad_u64_u32 v[4:5], s[0:1], v201, s59, v[156:157]
	ds_write_b128 v4, v[0:3]
	s_waitcnt vmcnt(4)
	v_cndmask_b32_e64 v3, 0, v99, s[20:21]
	v_cndmask_b32_e64 v2, 0, v98, s[20:21]
	v_cndmask_b32_e64 v1, 0, v97, s[20:21]
	v_cndmask_b32_e64 v0, 0, v96, s[20:21]
	v_mad_u64_u32 v[4:5], s[0:1], v202, s59, v[156:157]
	ds_write_b128 v4, v[0:3]
	s_waitcnt vmcnt(3)
	v_cndmask_b32_e64 v3, 0, v95, s[22:23]
	v_cndmask_b32_e64 v2, 0, v94, s[22:23]
	v_cndmask_b32_e64 v1, 0, v93, s[22:23]
	v_cndmask_b32_e64 v0, 0, v92, s[22:23]
	v_mad_u64_u32 v[4:5], s[0:1], v203, s59, v[156:157]
	ds_write_b128 v4, v[0:3]
	s_waitcnt vmcnt(2)
	v_cndmask_b32_e64 v3, 0, v91, s[24:25]
	v_cndmask_b32_e64 v2, 0, v90, s[24:25]
	v_cndmask_b32_e64 v1, 0, v89, s[24:25]
	v_cndmask_b32_e64 v0, 0, v88, s[24:25]
	v_mad_u64_u32 v[4:5], s[0:1], v204, s59, v[156:157]
	ds_write_b128 v4, v[0:3]
	s_waitcnt vmcnt(1)
	v_cndmask_b32_e64 v3, 0, v87, s[26:27]
	v_cndmask_b32_e64 v2, 0, v86, s[26:27]
	v_cndmask_b32_e64 v1, 0, v85, s[26:27]
	v_cndmask_b32_e64 v0, 0, v84, s[26:27]
	v_mad_u64_u32 v[4:5], s[0:1], v205, s59, v[156:157]
	ds_write_b128 v4, v[0:3]
	s_waitcnt vmcnt(0)
	v_cndmask_b32_e64 v3, 0, v83, s[28:29]
	v_cndmask_b32_e64 v2, 0, v82, s[28:29]
	v_cndmask_b32_e64 v1, 0, v81, s[28:29]
	v_cndmask_b32_e64 v0, 0, v80, s[28:29]
	v_mad_u64_u32 v[4:5], s[0:1], v206, s59, v[156:157]
	ds_write_b128 v4, v[0:3]
	v_bfe_u32 v0, v189, 2, 2
	v_and_b32_e32 v1, 16, v189
	v_lshlrev_b32_e32 v2, 2, v189
	v_or3_b32 v0, v0, v190, s49
	v_and_or_b32 v1, v2, 12, v1
	v_mul_lo_u32 v0, v0, s59
	v_lshlrev_b32_e32 v1, 1, v1
	v_add3_u32 v89, 0, v0, v1
	v_cvt_pk_bf16_f32 v51, v6, v7
	v_cvt_pk_bf16_f32 v134, v64, v65
	v_cvt_pk_bf16_f32 v135, v66, v67
	s_waitcnt lgkmcnt(0)
	s_barrier
	ds_read_b64_tr_b16 v[2:3], v89 offset:2560
	ds_read_b64_tr_b16 v[0:1], v89
	ds_read_b64_tr_b16 v[64:65], v89 offset:64
	ds_read_b64_tr_b16 v[90:91], v89 offset:128
	ds_read_b64_tr_b16 v[94:95], v89 offset:192
	ds_read_b64_tr_b16 v[66:67], v89 offset:2624
	ds_read_b64_tr_b16 v[92:93], v89 offset:2688
	ds_read_b64_tr_b16 v[96:97], v89 offset:2752
	v_cvt_pk_bf16_f32 v136, v8, v9
	v_cvt_pk_bf16_f32 v137, v10, v11
	v_cvt_pk_bf16_f32 v138, v12, v13
	v_cvt_pk_bf16_f32 v139, v14, v15
	v_cvt_pk_bf16_f32 v132, v30, v31
	v_cvt_pk_bf16_f32 v133, v46, v47
	v_cvt_pk_bf16_f32 v128, v68, v69
	v_cvt_pk_bf16_f32 v129, v70, v71
	v_cvt_pk_bf16_f32 v130, v72, v73
	v_cvt_pk_bf16_f32 v72, v76, v77
	v_cvt_pk_bf16_f32 v73, v78, v79
	s_waitcnt lgkmcnt(6)
	v_mfma_f32_32x32x16_bf16 v[0:15], v[48:51], v[0:3], 0
	v_cvt_pk_bf16_f32 v84, v16, v17
	v_cvt_pk_bf16_f32 v85, v18, v19
	v_cvt_pk_bf16_f32 v86, v20, v21
	v_cvt_pk_bf16_f32 v87, v22, v23
	v_cvt_pk_bf16_f32 v80, v24, v25
	v_cvt_pk_bf16_f32 v81, v26, v27
	v_cvt_pk_bf16_f32 v82, v28, v29
	s_waitcnt lgkmcnt(2)
	v_mfma_f32_32x32x16_bf16 v[16:31], v[48:51], v[64:67], 0
	v_cvt_pk_bf16_f32 v83, v32, v33
	v_cvt_pk_bf16_f32 v76, v34, v35
	v_cvt_pk_bf16_f32 v77, v36, v37
	v_cvt_pk_bf16_f32 v78, v38, v39
	v_cvt_pk_bf16_f32 v79, v40, v41
	v_cvt_pk_bf16_f32 v68, v42, v43
	v_cvt_pk_bf16_f32 v69, v44, v45
	s_waitcnt lgkmcnt(1)
	v_mfma_f32_32x32x16_bf16 v[32:47], v[48:51], v[90:93], 0
	v_cvt_pk_bf16_f32 v70, v52, v53
	v_cvt_pk_bf16_f32 v71, v54, v55
	v_cvt_pk_bf16_f32 v64, v56, v57
	v_cvt_pk_bf16_f32 v65, v58, v59
	v_cvt_pk_bf16_f32 v66, v60, v61
	v_cvt_pk_bf16_f32 v67, v62, v63
	v_cvt_pk_bf16_f32 v131, v74, v75
	s_waitcnt lgkmcnt(0)
; #define LAS __attribute__((address_space(3)))
; __device__ __forceinline__ void dil_attn_unit(LAS unsigned char* lds, bf16_t* proj, float* lse, int unit, int Tc, bf16_t* ybuf) {
;     ...
; #pragma unroll
;     for (int j = 0; j < 5; ++j)
; #pragma unroll
;         for (int s2 = 0; s2 < 2; ++s2)
; #pragma unroll
;             for (int db = 0; db < 4; ++db) {
;                 const LAS unsigned char* vp = vbase + (32 * j + 16 * s2) * 320 + db * 64;
;                 const v4i16_t lo = __builtin_amdgcn_ds_read_tr16_b64_v4i16((LAS v4i16_t*)vp);
;                 const v4i16_t hh = __builtin_amdgcn_ds_read_tr16_b64_v4i16((LAS v4i16_t*)(vp + 8 * 320));
;                 const bf16x8 vf = (bf16x8){lo[0], lo[1], lo[2], lo[3], hh[0], hh[1], hh[2], hh[3]};
;                 o[db] = __builtin_amdgcn_mfma_f32_32x32x16_bf16(__builtin_bit_cast(bf16x8, pa[j][s2]), vf, o[db], 0, 0, 0);
;                 if (db == 3) __builtin_amdgcn_sched_barrier(0);
;             }
	v_mfma_f32_32x32x16_bf16 v[48:63], v[48:51], v[94:97], 0
	v_cvt_pk_bf16_f32 v74, v143, v144
	v_cvt_pk_bf16_f32 v75, v145, v146
	v_and_b32_e32 v88, 15, v189
	ds_read_b64_tr_b16 v[90:91], v89 offset:5120
	ds_read_b64_tr_b16 v[92:93], v89 offset:7680
	s_waitcnt lgkmcnt(0)
	v_mfma_f32_32x32x16_bf16 v[0:15], v[136:139], v[90:93], v[0:15]
	ds_read_b64_tr_b16 v[90:91], v89 offset:5184
	ds_read_b64_tr_b16 v[92:93], v89 offset:7744
	s_waitcnt lgkmcnt(0)
	v_mfma_f32_32x32x16_bf16 v[16:31], v[136:139], v[90:93], v[16:31]
	ds_read_b64_tr_b16 v[90:91], v89 offset:5248
	ds_read_b64_tr_b16 v[92:93], v89 offset:7808
	s_waitcnt lgkmcnt(0)
	v_mfma_f32_32x32x16_bf16 v[32:47], v[136:139], v[90:93], v[32:47]
	ds_read_b64_tr_b16 v[90:91], v89 offset:5312
	ds_read_b64_tr_b16 v[92:93], v89 offset:7872
	s_waitcnt lgkmcnt(0)
	v_mfma_f32_32x32x16_bf16 v[48:63], v[136:139], v[90:93], v[48:63]
	ds_read_b64_tr_b16 v[90:91], v89 offset:10240
	ds_read_b64_tr_b16 v[92:93], v89 offset:12800
	s_waitcnt lgkmcnt(0)
	v_mfma_f32_32x32x16_bf16 v[0:15], v[132:135], v[90:93], v[0:15]
	ds_read_b64_tr_b16 v[90:91], v89 offset:10304
	ds_read_b64_tr_b16 v[92:93], v89 offset:12864
	s_waitcnt lgkmcnt(0)
	v_mfma_f32_32x32x16_bf16 v[16:31], v[132:135], v[90:93], v[16:31]
	ds_read_b64_tr_b16 v[90:91], v89 offset:10368
	ds_read_b64_tr_b16 v[92:93], v89 offset:12928
	s_waitcnt lgkmcnt(0)
	v_mfma_f32_32x32x16_bf16 v[32:47], v[132:135], v[90:93], v[32:47]
	ds_read_b64_tr_b16 v[90:91], v89 offset:10432
	ds_read_b64_tr_b16 v[92:93], v89 offset:12992
	s_waitcnt lgkmcnt(0)
	v_mfma_f32_32x32x16_bf16 v[48:63], v[132:135], v[90:93], v[48:63]
	ds_read_b64_tr_b16 v[90:91], v89 offset:15360
	ds_read_b64_tr_b16 v[92:93], v89 offset:17920
	s_waitcnt lgkmcnt(0)
	v_mfma_f32_32x32x16_bf16 v[0:15], v[128:131], v[90:93], v[0:15]
	ds_read_b64_tr_b16 v[90:91], v89 offset:15424
	ds_read_b64_tr_b16 v[92:93], v89 offset:17984
	s_waitcnt lgkmcnt(0)
	v_mfma_f32_32x32x16_bf16 v[16:31], v[128:131], v[90:93], v[16:31]
	ds_read_b64_tr_b16 v[90:91], v89 offset:15488
	ds_read_b64_tr_b16 v[92:93], v89 offset:18048
	s_waitcnt lgkmcnt(0)
	v_mfma_f32_32x32x16_bf16 v[32:47], v[128:131], v[90:93], v[32:47]
	ds_read_b64_tr_b16 v[90:91], v89 offset:15552
	ds_read_b64_tr_b16 v[92:93], v89 offset:18112
	s_waitcnt lgkmcnt(0)
	v_mfma_f32_32x32x16_bf16 v[48:63], v[128:131], v[90:93], v[48:63]
	ds_read_b64_tr_b16 v[90:91], v89 offset:20480
	ds_read_b64_tr_b16 v[92:93], v89 offset:23040
	s_waitcnt lgkmcnt(0)
	v_mfma_f32_32x32x16_bf16 v[0:15], v[72:75], v[90:93], v[0:15]
	ds_read_b64_tr_b16 v[90:91], v89 offset:20544
	ds_read_b64_tr_b16 v[92:93], v89 offset:23104
	s_waitcnt lgkmcnt(0)
	v_mfma_f32_32x32x16_bf16 v[16:31], v[72:75], v[90:93], v[16:31]
	ds_read_b64_tr_b16 v[90:91], v89 offset:20608
	ds_read_b64_tr_b16 v[92:93], v89 offset:23168
	s_waitcnt lgkmcnt(0)
	v_mfma_f32_32x32x16_bf16 v[32:47], v[72:75], v[90:93], v[32:47]
	ds_read_b64_tr_b16 v[90:91], v89 offset:20672
	ds_read_b64_tr_b16 v[92:93], v89 offset:23232
	s_waitcnt lgkmcnt(0)
	v_mfma_f32_32x32x16_bf16 v[48:63], v[72:75], v[90:93], v[48:63]
	ds_read_b64_tr_b16 v[72:73], v89 offset:25600
	ds_read_b64_tr_b16 v[74:75], v89 offset:28160
	s_waitcnt lgkmcnt(0)
	v_mfma_f32_32x32x16_bf16 v[0:15], v[84:87], v[72:75], v[0:15]
	ds_read_b64_tr_b16 v[72:73], v89 offset:25664
	ds_read_b64_tr_b16 v[74:75], v89 offset:28224
	s_waitcnt lgkmcnt(0)
	v_mfma_f32_32x32x16_bf16 v[16:31], v[84:87], v[72:75], v[16:31]
	ds_read_b64_tr_b16 v[72:73], v89 offset:25728
	ds_read_b64_tr_b16 v[74:75], v89 offset:28288
	s_waitcnt lgkmcnt(0)
	v_mfma_f32_32x32x16_bf16 v[32:47], v[84:87], v[72:75], v[32:47]
	ds_read_b64_tr_b16 v[72:73], v89 offset:25792
	ds_read_b64_tr_b16 v[74:75], v89 offset:28352
	s_waitcnt lgkmcnt(0)
	v_mfma_f32_32x32x16_bf16 v[48:63], v[84:87], v[72:75], v[48:63]
	ds_read_b64_tr_b16 v[72:73], v89 offset:30720
	ds_read_b64_tr_b16 v[74:75], v89 offset:33280
	s_waitcnt lgkmcnt(0)
	v_mfma_f32_32x32x16_bf16 v[0:15], v[80:83], v[72:75], v[0:15]
	ds_read_b64_tr_b16 v[72:73], v89 offset:30784
	ds_read_b64_tr_b16 v[74:75], v89 offset:33344
	s_waitcnt lgkmcnt(0)
	v_mfma_f32_32x32x16_bf16 v[16:31], v[80:83], v[72:75], v[16:31]
	ds_read_b64_tr_b16 v[72:73], v89 offset:30848
	ds_read_b64_tr_b16 v[74:75], v89 offset:33408
	s_waitcnt lgkmcnt(0)
	v_mfma_f32_32x32x16_bf16 v[32:47], v[80:83], v[72:75], v[32:47]
	ds_read_b64_tr_b16 v[72:73], v89 offset:30912
	ds_read_b64_tr_b16 v[74:75], v89 offset:33472
	s_waitcnt lgkmcnt(0)
	v_mfma_f32_32x32x16_bf16 v[48:63], v[80:83], v[72:75], v[48:63]
	ds_read_b64_tr_b16 v[72:73], v89 offset:35840
	ds_read_b64_tr_b16 v[74:75], v89 offset:38400
	s_waitcnt lgkmcnt(0)
	v_mfma_f32_32x32x16_bf16 v[0:15], v[76:79], v[72:75], v[0:15]
	ds_read_b64_tr_b16 v[72:73], v89 offset:35904
	ds_read_b64_tr_b16 v[74:75], v89 offset:38464
	s_waitcnt lgkmcnt(0)
	v_mfma_f32_32x32x16_bf16 v[16:31], v[76:79], v[72:75], v[16:31]
	ds_read_b64_tr_b16 v[72:73], v89 offset:35968
	ds_read_b64_tr_b16 v[74:75], v89 offset:38528
	s_waitcnt lgkmcnt(0)
	v_mfma_f32_32x32x16_bf16 v[32:47], v[76:79], v[72:75], v[32:47]
	ds_read_b64_tr_b16 v[72:73], v89 offset:36032
	ds_read_b64_tr_b16 v[74:75], v89 offset:38592
	s_waitcnt lgkmcnt(0)
	v_mfma_f32_32x32x16_bf16 v[48:63], v[76:79], v[72:75], v[48:63]
	ds_read_b64_tr_b16 v[72:73], v89 offset:40960
	ds_read_b64_tr_b16 v[74:75], v89 offset:43520
	s_waitcnt lgkmcnt(0)
	v_mfma_f32_32x32x16_bf16 v[0:15], v[68:71], v[72:75], v[0:15]
	ds_read_b64_tr_b16 v[72:73], v89 offset:41024
	ds_read_b64_tr_b16 v[74:75], v89 offset:43584
	s_waitcnt lgkmcnt(0)
	v_mfma_f32_32x32x16_bf16 v[16:31], v[68:71], v[72:75], v[16:31]
	ds_read_b64_tr_b16 v[72:73], v89 offset:41088
	ds_read_b64_tr_b16 v[74:75], v89 offset:43648
	s_waitcnt lgkmcnt(0)
; #define LAS __attribute__((address_space(3)))
; __device__ __forceinline__ unsigned cvtpk(float lo, float hi) { f32x2_t v = {lo, hi}; bf16x2_t b = __builtin_convertvector(v, bf16x2_t); return __builtin_bit_cast(unsigned, b); }
; __device__ __forceinline__ int crow(int r, int hi) { return (r & 3) + 8 * (r >> 2) + 4 * hi; }
; __device__ __forceinline__ void dil_attn_unit(LAS unsigned char* lds, bf16_t* proj, float* lse, int unit, int Tc, bf16_t* ybuf) {
;     ...
; #pragma unroll
;     for (int j = 0; j < 5; ++j)
; #pragma unroll
;         for (int s2 = 0; s2 < 2; ++s2)
; #pragma unroll
;             for (int db = 0; db < 4; ++db) {
;                 const LAS unsigned char* vp = vbase + (32 * j + 16 * s2) * 320 + db * 64;
;                 const v4i16_t lo = __builtin_amdgcn_ds_read_tr16_b64_v4i16((LAS v4i16_t*)vp);
;                 const v4i16_t hh = __builtin_amdgcn_ds_read_tr16_b64_v4i16((LAS v4i16_t*)(vp + 8 * 320));
;                 const bf16x8 vf = (bf16x8){lo[0], lo[1], lo[2], lo[3], hh[0], hh[1], hh[2], hh[3]};
;                 o[db] = __builtin_amdgcn_mfma_f32_32x32x16_bf16(__builtin_bit_cast(bf16x8, pa[j][s2]), vf, o[db], 0, 0, 0);
;                 if (db == 3) __builtin_amdgcn_sched_barrier(0);
;             }
;     __syncthreads();
;     if (!ybuf) {
;         LAS bf16_t* stg = (LAS bf16_t*)(lds + w * 8704);
; #pragma unroll
;         for (int rr = 0; rr < 16; ++rr) { const int qi = crow(rr, hi); const float a = __shfl(inv, qi);
; #pragma unroll
;             for (int db = 0; db < 4; ++db) stg[qi * 136 + db * 32 + r32] = (bf16_t)(cvtpk(o[db][rr] * a, 0.f) & 0xffffu); }
	v_mfma_f32_32x32x16_bf16 v[32:47], v[68:71], v[72:75], v[32:47]
	ds_read_b64_tr_b16 v[72:73], v89 offset:41152
	ds_read_b64_tr_b16 v[74:75], v89 offset:43712
	s_waitcnt lgkmcnt(0)
	v_mfma_f32_32x32x16_bf16 v[48:63], v[68:71], v[72:75], v[48:63]
	ds_read_b64_tr_b16 v[68:69], v89 offset:46080
	ds_read_b64_tr_b16 v[70:71], v89 offset:48640
	s_waitcnt lgkmcnt(0)
	v_mfma_f32_32x32x16_bf16 v[0:15], v[64:67], v[68:71], v[0:15]
	ds_read_b64_tr_b16 v[68:69], v89 offset:46144
	ds_read_b64_tr_b16 v[70:71], v89 offset:48704
	s_waitcnt lgkmcnt(0)
	v_mfma_f32_32x32x16_bf16 v[16:31], v[64:67], v[68:71], v[16:31]
	ds_read_b64_tr_b16 v[68:69], v89 offset:46208
	ds_read_b64_tr_b16 v[70:71], v89 offset:48768
	s_waitcnt lgkmcnt(0)
	v_mfma_f32_32x32x16_bf16 v[32:47], v[64:67], v[68:71], v[32:47]
	ds_read_b64_tr_b16 v[68:69], v89 offset:46272
	ds_read_b64_tr_b16 v[70:71], v89 offset:48832
	s_waitcnt lgkmcnt(0)
	v_mfma_f32_32x32x16_bf16 v[48:63], v[64:67], v[68:71], v[48:63]
	v_or_b32_e32 v64, v210, v190
	v_lshlrev_b32_e32 v80, 2, v64
	v_lshrrev_b32_e32 v75, 4, v141
	s_mov_b64 s[0:1], -1
	s_and_b64 vcc, exec, s[4:5]
	v_lshlrev_b32_e32 v178, 4, v88
	v_or_b32_e32 v79, v210, v207
	v_or_b32_e32 v78, 8, v80
	v_or_b32_e32 v77, 12, v80
	v_or_b32_e32 v76, 32, v80
	v_or_b32_e32 v74, 36, v80
	v_or_b32_e32 v73, 40, v80
	v_or_b32_e32 v72, 44, v80
	v_or_b32_e32 v71, 64, v80
	v_or_b32_e32 v70, 0x44, v80
	v_or_b32_e32 v69, 0x48, v80
	v_or_b32_e32 v68, 0x4c, v80
	v_or_b32_e32 v67, 0x60, v80
	v_or_b32_e32 v66, 0x64, v80
	v_or_b32_e32 v65, 0x68, v80
	v_or_b32_e32 v64, 0x6c, v80
	s_barrier
	s_cbranch_vccnz .LBB0_265
	ds_bpermute_b32 v82, v80, v142
	s_mul_i32 s0, s48, 0x2200
	s_add_i32 s0, s0, 0
	v_lshl_add_u32 v81, v188, 1, s0
	s_movk_i32 s1, 0x440
	s_waitcnt lgkmcnt(0)
	v_mul_f32_e32 v84, v0, v82
	v_mad_u32_u24 v83, v157, s1, v81
	v_cvt_pk_bf16_f32 v84, v84, s0
	ds_write_b16 v83, v84
	v_mul_f32_e32 v84, v16, v82
	v_cvt_pk_bf16_f32 v84, v84, s0
	ds_write_b16 v83, v84 offset:64
	v_mul_f32_e32 v84, v32, v82
	v_mul_f32_e32 v82, v48, v82
	v_cvt_pk_bf16_f32 v82, v82, s0
	ds_write_b16 v83, v82 offset:192
	v_lshlrev_b32_e32 v82, 2, v79
	ds_bpermute_b32 v82, v82, v142
	v_cvt_pk_bf16_f32 v84, v84, s0
	ds_write_b16 v83, v84 offset:128
	v_mad_u32_u24 v81, v207, s67, v81
	s_ashr_i32 s1, s41, 31
	s_waitcnt lgkmcnt(1)
	v_mul_f32_e32 v83, v1, v82
	v_cvt_pk_bf16_f32 v83, v83, s0
	ds_write_b16 v81, v83
	v_mul_f32_e32 v83, v17, v82
	v_cvt_pk_bf16_f32 v83, v83, s0
	ds_write_b16 v81, v83 offset:64
	v_mul_f32_e32 v83, v33, v82
	v_mul_f32_e32 v82, v49, v82
	v_cvt_pk_bf16_f32 v82, v82, s0
	ds_write_b16 v81, v82 offset:192
	ds_bpermute_b32 v82, v78, v142
	v_cvt_pk_bf16_f32 v83, v83, s0
	ds_write_b16 v81, v83 offset:128
	s_add_u32 s4, s94, s41
	s_addc_u32 s5, s95, s1
	s_waitcnt lgkmcnt(1)
	v_mul_f32_e32 v83, v2, v82
	v_cvt_pk_bf16_f32 v83, v83, s0
	ds_write_b16 v81, v83 offset:272
	v_mul_f32_e32 v83, v18, v82
	v_cvt_pk_bf16_f32 v83, v83, s0
	ds_write_b16 v81, v83 offset:336
	v_mul_f32_e32 v83, v34, v82
	v_mul_f32_e32 v82, v50, v82
	v_cvt_pk_bf16_f32 v82, v82, s0
	ds_write_b16 v81, v82 offset:464
	ds_bpermute_b32 v82, v77, v142
	v_cvt_pk_bf16_f32 v83, v83, s0
	ds_write_b16 v81, v83 offset:400
	s_lshl_b64 s[4:5], s[4:5], 8
	s_add_u32 s4, s96, s4
	s_waitcnt lgkmcnt(1)
	v_mul_f32_e32 v83, v3, v82
	v_cvt_pk_bf16_f32 v83, v83, s0
	ds_write_b16 v81, v83 offset:544
	v_mul_f32_e32 v83, v19, v82
	v_cvt_pk_bf16_f32 v83, v83, s0
	ds_write_b16 v81, v83 offset:608
	v_mul_f32_e32 v83, v35, v82
	v_mul_f32_e32 v82, v51, v82
	v_cvt_pk_bf16_f32 v82, v82, s0
	ds_write_b16 v81, v82 offset:736
	ds_bpermute_b32 v82, v76, v142
	v_cvt_pk_bf16_f32 v83, v83, s0
	ds_write_b16 v81, v83 offset:672
	s_addc_u32 s5, s97, s5
	v_lshl_add_u64 v[86:87], s[4:5], 0, v[178:179]
	s_waitcnt lgkmcnt(1)
	v_mul_f32_e32 v83, v4, v82
	v_cvt_pk_bf16_f32 v83, v83, s0
	ds_write_b16 v81, v83 offset:1904
	v_mul_f32_e32 v83, v20, v82
	v_cvt_pk_bf16_f32 v83, v83, s0
	ds_write_b16 v81, v83 offset:1968
	v_mul_f32_e32 v83, v36, v82
	v_mul_f32_e32 v82, v52, v82
	v_cvt_pk_bf16_f32 v82, v82, s0
	ds_write_b16 v81, v82 offset:2096
	ds_bpermute_b32 v82, v74, v142
	v_cvt_pk_bf16_f32 v83, v83, s0
	ds_write_b16 v81, v83 offset:2032
	v_lshlrev_b32_e32 v90, 8, v75
	v_mov_b32_e32 v91, v179
	s_waitcnt lgkmcnt(1)
	v_mul_f32_e32 v83, v5, v82
	v_cvt_pk_bf16_f32 v83, v83, s0
	ds_write_b16 v81, v83 offset:2176
	v_mul_f32_e32 v83, v21, v82
	v_cvt_pk_bf16_f32 v83, v83, s0
	ds_write_b16 v81, v83 offset:2240
	v_mul_f32_e32 v83, v37, v82
	v_mul_f32_e32 v82, v53, v82
	v_cvt_pk_bf16_f32 v82, v82, s0
	ds_write_b16 v81, v82 offset:2368
	ds_bpermute_b32 v82, v73, v142
	v_cvt_pk_bf16_f32 v83, v83, s0
	ds_write_b16 v81, v83 offset:2304
	v_lshl_add_u64 v[92:93], v[86:87], 0, v[90:91]
	s_waitcnt lgkmcnt(1)
	v_mul_f32_e32 v83, v6, v82
	v_cvt_pk_bf16_f32 v83, v83, s0
	ds_write_b16 v81, v83 offset:2448
	v_mul_f32_e32 v83, v22, v82
	v_cvt_pk_bf16_f32 v83, v83, s0
	ds_write_b16 v81, v83 offset:2512
	v_mul_f32_e32 v83, v38, v82
	v_mul_f32_e32 v82, v54, v82
	v_cvt_pk_bf16_f32 v82, v82, s0
	ds_write_b16 v81, v82 offset:2640
	ds_bpermute_b32 v82, v72, v142
	v_cvt_pk_bf16_f32 v83, v83, s0
	ds_write_b16 v81, v83 offset:2576
	s_waitcnt lgkmcnt(1)
; #define LAS __attribute__((address_space(3)))
; __device__ __forceinline__ unsigned cvtpk(float lo, float hi) { f32x2_t v = {lo, hi}; bf16x2_t b = __builtin_convertvector(v, bf16x2_t); return __builtin_bit_cast(unsigned, b); }
; __device__ __forceinline__ int crow(int r, int hi) { return (r & 3) + 8 * (r >> 2) + 4 * hi; }
; __device__ __forceinline__ void dil_attn_unit(LAS unsigned char* lds, bf16_t* proj, float* lse, int unit, int Tc, bf16_t* ybuf) {
;     ...
;         for (int rr = 0; rr < 16; ++rr) { const int qi = crow(rr, hi); const float a = __shfl(inv, qi);
; #pragma unroll
;             for (int db = 0; db < 4; ++db) stg[qi * 136 + db * 32 + r32] = (bf16_t)(cvtpk(o[db][rr] * a, 0.f) & 0xffffu); }
;         asm volatile("s_waitcnt lgkmcnt(0)" ::: "memory");
;         bf16_t* obase = qblk + (pbase + (U0 + 32 * w)) * 128;
; #pragma unroll
;         for (int i = 0; i < 8; ++i) { const int row = i * 4 + (lane >> 4), c16 = lane & 15;
;             const u32x4 x = *(const LAS u32x4*)(stg + row * 136 + c16 * 8);
;             *(u32x4*)(obase + row * 128 + c16 * 8) = x; }
	v_mul_f32_e32 v83, v7, v82
	v_cvt_pk_bf16_f32 v83, v83, s0
	ds_write_b16 v81, v83 offset:2720
	v_mul_f32_e32 v83, v23, v82
	v_cvt_pk_bf16_f32 v83, v83, s0
	ds_write_b16 v81, v83 offset:2784
	v_mul_f32_e32 v83, v39, v82
	v_mul_f32_e32 v82, v55, v82
	v_cvt_pk_bf16_f32 v82, v82, s0
	ds_write_b16 v81, v82 offset:2912
	ds_bpermute_b32 v82, v71, v142
	v_cvt_pk_bf16_f32 v83, v83, s0
	ds_write_b16 v81, v83 offset:2848
	s_waitcnt lgkmcnt(1)
	v_mul_f32_e32 v83, v8, v82
	v_cvt_pk_bf16_f32 v83, v83, s0
	ds_write_b16 v81, v83 offset:4080
	v_mul_f32_e32 v83, v24, v82
	v_cvt_pk_bf16_f32 v83, v83, s0
	ds_write_b16 v81, v83 offset:4144
	v_mul_f32_e32 v83, v40, v82
	v_mul_f32_e32 v82, v56, v82
	v_cvt_pk_bf16_f32 v82, v82, s0
	ds_write_b16 v81, v82 offset:4272
	ds_bpermute_b32 v82, v70, v142
	v_cvt_pk_bf16_f32 v83, v83, s0
	ds_write_b16 v81, v83 offset:4208
	s_waitcnt lgkmcnt(1)
	v_mul_f32_e32 v83, v9, v82
	v_cvt_pk_bf16_f32 v83, v83, s0
	ds_write_b16 v81, v83 offset:4352
	v_mul_f32_e32 v83, v25, v82
	v_cvt_pk_bf16_f32 v83, v83, s0
	ds_write_b16 v81, v83 offset:4416
	v_mul_f32_e32 v83, v41, v82
	v_mul_f32_e32 v82, v57, v82
	v_cvt_pk_bf16_f32 v82, v82, s0
	ds_write_b16 v81, v82 offset:4544
	ds_bpermute_b32 v82, v69, v142
	v_cvt_pk_bf16_f32 v83, v83, s0
	ds_write_b16 v81, v83 offset:4480
	s_waitcnt lgkmcnt(1)
	v_mul_f32_e32 v83, v10, v82
	v_cvt_pk_bf16_f32 v83, v83, s0
	ds_write_b16 v81, v83 offset:4624
	v_mul_f32_e32 v83, v26, v82
	v_cvt_pk_bf16_f32 v83, v83, s0
	ds_write_b16 v81, v83 offset:4688
	v_mul_f32_e32 v83, v42, v82
	v_mul_f32_e32 v82, v58, v82
	v_cvt_pk_bf16_f32 v82, v82, s0
	ds_write_b16 v81, v82 offset:4816
	ds_bpermute_b32 v82, v68, v142
	v_cvt_pk_bf16_f32 v83, v83, s0
	ds_write_b16 v81, v83 offset:4752
	s_waitcnt lgkmcnt(1)
	v_mul_f32_e32 v83, v11, v82
	v_cvt_pk_bf16_f32 v83, v83, s0
	ds_write_b16 v81, v83 offset:4896
	v_mul_f32_e32 v83, v27, v82
	v_cvt_pk_bf16_f32 v83, v83, s0
	ds_write_b16 v81, v83 offset:4960
	v_mul_f32_e32 v83, v43, v82
	v_mul_f32_e32 v82, v59, v82
	v_cvt_pk_bf16_f32 v82, v82, s0
	ds_write_b16 v81, v82 offset:5088
	ds_bpermute_b32 v82, v67, v142
	v_cvt_pk_bf16_f32 v83, v83, s0
	ds_write_b16 v81, v83 offset:5024
	s_waitcnt lgkmcnt(1)
	v_mul_f32_e32 v83, v12, v82
	v_cvt_pk_bf16_f32 v83, v83, s0
	ds_write_b16 v81, v83 offset:6256
	v_mul_f32_e32 v83, v28, v82
	v_cvt_pk_bf16_f32 v83, v83, s0
	ds_write_b16 v81, v83 offset:6320
	v_mul_f32_e32 v83, v44, v82
	v_mul_f32_e32 v82, v60, v82
	v_cvt_pk_bf16_f32 v82, v82, s0
	ds_write_b16 v81, v82 offset:6448
	ds_bpermute_b32 v82, v66, v142
	v_cvt_pk_bf16_f32 v83, v83, s0
	ds_write_b16 v81, v83 offset:6384
	s_waitcnt lgkmcnt(1)
	v_mul_f32_e32 v83, v13, v82
	v_cvt_pk_bf16_f32 v83, v83, s0
	ds_write_b16 v81, v83 offset:6528
	v_mul_f32_e32 v83, v29, v82
	v_cvt_pk_bf16_f32 v83, v83, s0
	ds_write_b16 v81, v83 offset:6592
	v_mul_f32_e32 v83, v45, v82
	v_mul_f32_e32 v82, v61, v82
	v_cvt_pk_bf16_f32 v82, v82, s0
	ds_write_b16 v81, v82 offset:6720
	ds_bpermute_b32 v82, v65, v142
	v_cvt_pk_bf16_f32 v83, v83, s0
	ds_write_b16 v81, v83 offset:6656
	s_waitcnt lgkmcnt(1)
	v_mul_f32_e32 v83, v14, v82
	v_cvt_pk_bf16_f32 v83, v83, s0
	ds_write_b16 v81, v83 offset:6800
	v_mul_f32_e32 v83, v30, v82
	v_cvt_pk_bf16_f32 v83, v83, s0
	ds_write_b16 v81, v83 offset:6864
	v_mul_f32_e32 v83, v46, v82
	v_mul_f32_e32 v82, v62, v82
	v_cvt_pk_bf16_f32 v82, v82, s0
	ds_write_b16 v81, v82 offset:6992
	ds_bpermute_b32 v82, v64, v142
	v_cvt_pk_bf16_f32 v83, v83, s0
	ds_write_b16 v81, v83 offset:6928
	s_waitcnt lgkmcnt(1)
	v_mul_f32_e32 v83, v15, v82
	v_cvt_pk_bf16_f32 v83, v83, s0
	ds_write_b16 v81, v83 offset:7072
	v_mul_f32_e32 v83, v31, v82
	v_cvt_pk_bf16_f32 v83, v83, s0
	ds_write_b16 v81, v83 offset:7136
	v_mul_f32_e32 v83, v47, v82
	v_mul_f32_e32 v82, v63, v82
	v_cvt_pk_bf16_f32 v83, v83, s0
	v_cvt_pk_bf16_f32 v82, v82, s0
	ds_write_b16 v81, v83 offset:7200
	ds_write_b16 v81, v82 offset:7264
	v_mul_u32_u24_e32 v81, 0x110, v75
	s_waitcnt lgkmcnt(0)
	v_add3_u32 v81, s0, v178, v81
	ds_read_b128 v[82:85], v81
	s_mov_b64 s[0:1], 0
	s_waitcnt lgkmcnt(0)
	global_store_dwordx4 v[92:93], v[82:85], off sc0 sc1
	ds_read_b128 v[82:85], v81 offset:1088
	v_or_b32_e32 v92, 0x400, v90
	v_mov_b32_e32 v93, v179
	v_lshl_add_u64 v[92:93], v[86:87], 0, v[92:93]
	s_waitcnt lgkmcnt(0)
	global_store_dwordx4 v[92:93], v[82:85], off sc0 sc1
	ds_read_b128 v[82:85], v81 offset:2176
	v_or_b32_e32 v92, 0x800, v90
	v_mov_b32_e32 v93, v179
	v_lshl_add_u64 v[92:93], v[86:87], 0, v[92:93]
	s_waitcnt lgkmcnt(0)
	global_store_dwordx4 v[92:93], v[82:85], off sc0 sc1
	ds_read_b128 v[82:85], v81 offset:3264
	v_or_b32_e32 v92, 0xc00, v90
	v_mov_b32_e32 v93, v179
	v_lshl_add_u64 v[92:93], v[86:87], 0, v[92:93]
	s_waitcnt lgkmcnt(0)
	global_store_dwordx4 v[92:93], v[82:85], off sc0 sc1
	ds_read_b128 v[82:85], v81 offset:4352
	v_or_b32_e32 v92, 0x1000, v90
	v_mov_b32_e32 v93, v179
	v_lshl_add_u64 v[92:93], v[86:87], 0, v[92:93]
	s_waitcnt lgkmcnt(0)
	global_store_dwordx4 v[92:93], v[82:85], off sc0 sc1
	ds_read_b128 v[82:85], v81 offset:5440
	v_or_b32_e32 v92, 0x1400, v90
	v_mov_b32_e32 v93, v179
	v_lshl_add_u64 v[92:93], v[86:87], 0, v[92:93]
	s_waitcnt lgkmcnt(0)
	global_store_dwordx4 v[92:93], v[82:85], off sc0 sc1
	ds_read_b128 v[82:85], v81 offset:6528
	v_or_b32_e32 v92, 0x1800, v90
	v_mov_b32_e32 v93, v179
	v_lshl_add_u64 v[92:93], v[86:87], 0, v[92:93]
	v_or_b32_e32 v90, 0x1c00, v90
	s_waitcnt lgkmcnt(0)
	global_store_dwordx4 v[92:93], v[82:85], off sc0 sc1
	ds_read_b128 v[82:85], v81 offset:7616
	v_lshl_add_u64 v[86:87], v[86:87], 0, v[90:91]
	s_waitcnt lgkmcnt(0)
	global_store_dwordx4 v[86:87], v[82:85], off sc0 sc1

; __device__ __forceinline__ unsigned cvtpk(float lo, float hi) { f32x2_t v = {lo, hi}; bf16x2_t b = __builtin_convertvector(v, bf16x2_t); return __builtin_bit_cast(unsigned, b); }
;     __device__ __forceinline__ void operator()(const f32x4 (&acc)[2][2][4][2], const pg8::Unit& u, int wr, int wc, int fr, int fq) const {
;     ...
;                 for (int m = 0; m < 4; ++m) { const int row = row0 + ai * 128 + m * 16; bf16_t* rowp = O + (size_t)row * ldc + col0; const int pos = row & (SEQ - 1);
;                     const int dcol = wc * 32 + 8 * fq, sq4 = row & ~(SEQ - 1);
; #pragma unroll
;                     for (int bj = 0; bj < 2; ++bj) { f32x4 v0 = acc[ai][bj][m][0], v1 = acc[ai][bj][m][1];
;                         if (mode == 1) {
;                             const int col = col0 + bj * 128; const int d = col % 96;
;                             if (d >= 64) { const int f0 = (d - 64) >> 1;
;                                 const f32x4 c = *(const f32x4*)(cs + pos * 32 + f0), s = *(const f32x4*)(cs + pos * 32 + 16 + f0);
;                                 f32x4 a0, a1;
;                                 a0[0] = v0[0] * c[0] - v0[1] * s[0]; a0[1] = v0[0] * s[0] + v0[1] * c[0];
;                                 a0[2] = v0[2] * c[1] - v0[3] * s[1]; a0[3] = v0[2] * s[1] + v0[3] * c[1];
;                                 a1[0] = v1[0] * c[2] - v1[1] * s[2]; a1[1] = v1[0] * s[2] + v1[1] * c[2];
;                                 a1[2] = v1[2] * c[3] - v1[3] * s[3]; a1[3] = v1[2] * s[3] + v1[3] * c[3];
;                                 v0 = a0; v1 = a1; }
;                             v0 = v0 * scale; v1 = v1 * scale; }
;                         u32x4 w; w.x = cvtpk(v0[0], v0[1]); w.y = cvtpk(v0[2], v0[3]); w.z = cvtpk(v1[0], v1[1]); w.w = cvtpk(v1[2], v1[3]);
;                         if (mode == 3) { const int cb = u.pn * 2 + bj;
;                             bf16_t* dst;
;                             if (cb < 72) { const int dsh = 2 * (cb / 24); const int tp = sq4 + ((pos & ((1 << dsh) - 1)) << (12 - dsh)) + (pos >> dsh); dst = O + ((size_t)cb * ldc + tp) * 128 + dcol; }
;                             else dst = O + (size_t)9216 * ldc + (size_t)row * 1024 + (cb - 72) * 128 + dcol;
;                             *(u32x4*)dst = w; }
;                         else *(u32x4*)(rowp + bj * 128) = w; }
.LBB0_317:
	v_mad_i64_i32 v[138:139], s[10:11], v164, s40, 0
	v_ashrrev_i32_e32 v137, 31, v136
	v_lshl_add_u64 v[138:139], v[138:139], 1, s[22:23]
	v_lshl_add_u64 v[138:139], v[136:137], 1, v[138:139]
	v_cvt_pk_bf16_f32 v128, v128, v129
	v_cvt_pk_bf16_f32 v129, v130, v131
	v_cvt_pk_bf16_f32 v130, v132, v133
	v_cvt_pk_bf16_f32 v131, v134, v135
	s_mov_b64 s[10:11], -1
	s_and_b64 vcc, exec, s[28:29]
	s_cbranch_vccz .LBB0_319
	global_store_dwordx4 v[138:139], v[128:131], off sc0 sc1
	s_mov_b64 s[10:11], 0

;     __device__ __forceinline__ void operator()(const f32x4 (&acc)[2][2][4][2], const pg8::Unit& u, int wr, int wc, int fr, int fq) const {
;     ...
;                         if (mode == 3) { const int cb = u.pn * 2 + bj;
;                             bf16_t* dst;
;                             if (cb < 72) { const int dsh = 2 * (cb / 24); const int tp = sq4 + ((pos & ((1 << dsh) - 1)) << (12 - dsh)) + (pos >> dsh); dst = O + ((size_t)cb * ldc + tp) * 128 + dcol; }
;                             else dst = O + (size_t)9216 * ldc + (size_t)row * 1024 + (cb - 72) * 128 + dcol;
;                             *(u32x4*)dst = w; }
.LBB0_324:
	v_lshlrev_b32_e32 v178, 1, v158
	v_lshl_add_u64 v[132:133], v[132:133], 0, v[178:179]
	global_store_dwordx4 v[132:133], v[128:131], off sc0 sc1

; __device__ __forceinline__ unsigned cvtpk(float lo, float hi) { f32x2_t v = {lo, hi}; bf16x2_t b = __builtin_convertvector(v, bf16x2_t); return __builtin_bit_cast(unsigned, b); }
;     __device__ __forceinline__ void operator()(const f32x4 (&acc)[2][2][4][2], const pg8::Unit& u, int wr, int wc, int fr, int fq) const {
;     ...
;                         u32x4 w; w.x = cvtpk(v0[0], v0[1]); w.y = cvtpk(v0[2], v0[3]); w.z = cvtpk(v1[0], v1[1]); w.w = cvtpk(v1[2], v1[3]);
;                         if (mode == 3) { const int cb = u.pn * 2 + bj;
;                             bf16_t* dst;
;                             if (cb < 72) { const int dsh = 2 * (cb / 24); const int tp = sq4 + ((pos & ((1 << dsh) - 1)) << (12 - dsh)) + (pos >> dsh); dst = O + ((size_t)cb * ldc + tp) * 128 + dcol; }
;                             else dst = O + (size_t)9216 * ldc + (size_t)row * 1024 + (cb - 72) * 128 + dcol;
;                             *(u32x4*)dst = w; }
;                         else *(u32x4*)(rowp + bj * 128) = w; }
.LBB0_329:
	v_cvt_pk_bf16_f32 v128, v128, v129
	v_cvt_pk_bf16_f32 v129, v130, v131
	v_cvt_pk_bf16_f32 v130, v132, v133
	v_cndmask_b32_e64 v132, 0, 1, s[28:29]
	v_cvt_pk_bf16_f32 v131, v134, v135
	v_cmp_ne_u32_e64 s[10:11], 1, v132
	s_andn2_b64 vcc, exec, s[28:29]
	s_mov_b64 s[86:87], -1
	s_cbranch_vccnz .LBB0_331
	s_mov_b64 s[86:87], 0
	global_store_dwordx4 v[138:139], v[128:131], off offset:256 sc0 sc1

; __device__ __forceinline__ unsigned cvtpk(float lo, float hi) { f32x2_t v = {lo, hi}; bf16x2_t b = __builtin_convertvector(v, bf16x2_t); return __builtin_bit_cast(unsigned, b); }
;     __device__ __forceinline__ void operator()(const f32x4 (&acc)[2][2][4][2], const pg8::Unit& u, int wr, int wc, int fr, int fq) const {
;     ...
;                 for (int m = 0; m < 4; ++m) { const int row = row0 + ai * 128 + m * 16; bf16_t* rowp = O + (size_t)row * ldc + col0; const int pos = row & (SEQ - 1);
;                     const int dcol = wc * 32 + 8 * fq, sq4 = row & ~(SEQ - 1);
; #pragma unroll
;                     for (int bj = 0; bj < 2; ++bj) { f32x4 v0 = acc[ai][bj][m][0], v1 = acc[ai][bj][m][1];
;                         if (mode == 1) {
;                             const int col = col0 + bj * 128; const int d = col % 96;
;                             if (d >= 64) { const int f0 = (d - 64) >> 1;
;                                 const f32x4 c = *(const f32x4*)(cs + pos * 32 + f0), s = *(const f32x4*)(cs + pos * 32 + 16 + f0);
;                                 f32x4 a0, a1;
;                                 a0[0] = v0[0] * c[0] - v0[1] * s[0]; a0[1] = v0[0] * s[0] + v0[1] * c[0];
;                                 a0[2] = v0[2] * c[1] - v0[3] * s[1]; a0[3] = v0[2] * s[1] + v0[3] * c[1];
;                                 a1[0] = v1[0] * c[2] - v1[1] * s[2]; a1[1] = v1[0] * s[2] + v1[1] * c[2];
;                                 a1[2] = v1[2] * c[3] - v1[3] * s[3]; a1[3] = v1[2] * s[3] + v1[3] * c[3];
;                                 v0 = a0; v1 = a1; }
;                             v0 = v0 * scale; v1 = v1 * scale; }
;                         u32x4 w; w.x = cvtpk(v0[0], v0[1]); w.y = cvtpk(v0[2], v0[3]); w.z = cvtpk(v1[0], v1[1]); w.w = cvtpk(v1[2], v1[3]);
;                         if (mode == 3) { const int cb = u.pn * 2 + bj;
;                             bf16_t* dst;
;                             if (cb < 72) { const int dsh = 2 * (cb / 24); const int tp = sq4 + ((pos & ((1 << dsh) - 1)) << (12 - dsh)) + (pos >> dsh); dst = O + ((size_t)cb * ldc + tp) * 128 + dcol; }
;                             else dst = O + (size_t)9216 * ldc + (size_t)row * 1024 + (cb - 72) * 128 + dcol;
;                             *(u32x4*)dst = w; }
;                         else *(u32x4*)(rowp + bj * 128) = w; }
.LBB0_341:
	v_or_b32_e32 v138, 16, v164
	v_mad_i64_i32 v[140:141], s[74:75], v138, s40, 0
	v_lshl_add_u64 v[140:141], v[140:141], 1, s[22:23]
	v_lshl_add_u64 v[140:141], v[136:137], 1, v[140:141]
	v_cvt_pk_bf16_f32 v128, v128, v129
	v_cvt_pk_bf16_f32 v129, v130, v131
	v_cvt_pk_bf16_f32 v130, v132, v133
	v_cvt_pk_bf16_f32 v131, v134, v135
	s_and_b64 vcc, exec, s[10:11]
	s_mov_b64 s[86:87], -1
	s_cbranch_vccnz .LBB0_343
	s_mov_b64 s[86:87], 0
	global_store_dwordx4 v[140:141], v[128:131], off sc0 sc1

; __device__ __forceinline__ unsigned cvtpk(float lo, float hi) { f32x2_t v = {lo, hi}; bf16x2_t b = __builtin_convertvector(v, bf16x2_t); return __builtin_bit_cast(unsigned, b); }
;     __device__ __forceinline__ void operator()(const f32x4 (&acc)[2][2][4][2], const pg8::Unit& u, int wr, int wc, int fr, int fq) const {
;     ...
;                         u32x4 w; w.x = cvtpk(v0[0], v0[1]); w.y = cvtpk(v0[2], v0[3]); w.z = cvtpk(v1[0], v1[1]); w.w = cvtpk(v1[2], v1[3]);
;                         if (mode == 3) { const int cb = u.pn * 2 + bj;
;                             bf16_t* dst;
;                             if (cb < 72) { const int dsh = 2 * (cb / 24); const int tp = sq4 + ((pos & ((1 << dsh) - 1)) << (12 - dsh)) + (pos >> dsh); dst = O + ((size_t)cb * ldc + tp) * 128 + dcol; }
;                             else dst = O + (size_t)9216 * ldc + (size_t)row * 1024 + (cb - 72) * 128 + dcol;
;                             *(u32x4*)dst = w; }
;                         else *(u32x4*)(rowp + bj * 128) = w; }
.LBB0_353:
	v_cvt_pk_bf16_f32 v128, v128, v129
	v_cvt_pk_bf16_f32 v129, v130, v131
	v_cvt_pk_bf16_f32 v130, v132, v133
	v_cvt_pk_bf16_f32 v131, v134, v135
	s_and_b64 vcc, exec, s[10:11]
	s_mov_b64 s[86:87], -1
	s_cbranch_vccnz .LBB0_355
	s_mov_b64 s[86:87], 0
	global_store_dwordx4 v[140:141], v[128:131], off offset:256 sc0 sc1

; __device__ __forceinline__ unsigned cvtpk(float lo, float hi) { f32x2_t v = {lo, hi}; bf16x2_t b = __builtin_convertvector(v, bf16x2_t); return __builtin_bit_cast(unsigned, b); }
;     __device__ __forceinline__ void operator()(const f32x4 (&acc)[2][2][4][2], const pg8::Unit& u, int wr, int wc, int fr, int fq) const {
;     ...
;                 for (int m = 0; m < 4; ++m) { const int row = row0 + ai * 128 + m * 16; bf16_t* rowp = O + (size_t)row * ldc + col0; const int pos = row & (SEQ - 1);
;                     const int dcol = wc * 32 + 8 * fq, sq4 = row & ~(SEQ - 1);
; #pragma unroll
;                     for (int bj = 0; bj < 2; ++bj) { f32x4 v0 = acc[ai][bj][m][0], v1 = acc[ai][bj][m][1];
;                         if (mode == 1) {
;                             const int col = col0 + bj * 128; const int d = col % 96;
;                             if (d >= 64) { const int f0 = (d - 64) >> 1;
;                                 const f32x4 c = *(const f32x4*)(cs + pos * 32 + f0), s = *(const f32x4*)(cs + pos * 32 + 16 + f0);
;                                 f32x4 a0, a1;
;                                 a0[0] = v0[0] * c[0] - v0[1] * s[0]; a0[1] = v0[0] * s[0] + v0[1] * c[0];
;                                 a0[2] = v0[2] * c[1] - v0[3] * s[1]; a0[3] = v0[2] * s[1] + v0[3] * c[1];
;                                 a1[0] = v1[0] * c[2] - v1[1] * s[2]; a1[1] = v1[0] * s[2] + v1[1] * c[2];
;                                 a1[2] = v1[2] * c[3] - v1[3] * s[3]; a1[3] = v1[2] * s[3] + v1[3] * c[3];
;                                 v0 = a0; v1 = a1; }
;                             v0 = v0 * scale; v1 = v1 * scale; }
;                         u32x4 w; w.x = cvtpk(v0[0], v0[1]); w.y = cvtpk(v0[2], v0[3]); w.z = cvtpk(v1[0], v1[1]); w.w = cvtpk(v1[2], v1[3]);
;                         if (mode == 3) { const int cb = u.pn * 2 + bj;
;                             bf16_t* dst;
;                             if (cb < 72) { const int dsh = 2 * (cb / 24); const int tp = sq4 + ((pos & ((1 << dsh) - 1)) << (12 - dsh)) + (pos >> dsh); dst = O + ((size_t)cb * ldc + tp) * 128 + dcol; }
;                             else dst = O + (size_t)9216 * ldc + (size_t)row * 1024 + (cb - 72) * 128 + dcol;
;                             *(u32x4*)dst = w; }
;                         else *(u32x4*)(rowp + bj * 128) = w; }
.LBB0_365:
	v_or_b32_e32 v138, 32, v164
	v_mad_i64_i32 v[140:141], s[74:75], v138, s40, 0
	v_lshl_add_u64 v[140:141], v[140:141], 1, s[22:23]
	v_lshl_add_u64 v[140:141], v[136:137], 1, v[140:141]
	v_cvt_pk_bf16_f32 v128, v128, v129
	v_cvt_pk_bf16_f32 v129, v130, v131
	v_cvt_pk_bf16_f32 v130, v132, v133
	v_cvt_pk_bf16_f32 v131, v134, v135
	s_and_b64 vcc, exec, s[10:11]
	s_mov_b64 s[86:87], -1
	s_cbranch_vccnz .LBB0_367
	s_mov_b64 s[86:87], 0
	global_store_dwordx4 v[140:141], v[128:131], off sc0 sc1

; __device__ __forceinline__ unsigned cvtpk(float lo, float hi) { f32x2_t v = {lo, hi}; bf16x2_t b = __builtin_convertvector(v, bf16x2_t); return __builtin_bit_cast(unsigned, b); }
;     __device__ __forceinline__ void operator()(const f32x4 (&acc)[2][2][4][2], const pg8::Unit& u, int wr, int wc, int fr, int fq) const {
;     ...
;                 for (int m = 0; m < 4; ++m) { const int row = row0 + ai * 128 + m * 16; bf16_t* rowp = O + (size_t)row * ldc + col0; const int pos = row & (SEQ - 1);
;                     const int dcol = wc * 32 + 8 * fq, sq4 = row & ~(SEQ - 1);
; #pragma unroll
;                     for (int bj = 0; bj < 2; ++bj) { f32x4 v0 = acc[ai][bj][m][0], v1 = acc[ai][bj][m][1];
;                         if (mode == 1) {
;                             const int col = col0 + bj * 128; const int d = col % 96;
;                             if (d >= 64) { const int f0 = (d - 64) >> 1;
;                                 const f32x4 c = *(const f32x4*)(cs + pos * 32 + f0), s = *(const f32x4*)(cs + pos * 32 + 16 + f0);
;                                 f32x4 a0, a1;
;                                 a0[0] = v0[0] * c[0] - v0[1] * s[0]; a0[1] = v0[0] * s[0] + v0[1] * c[0];
;                                 a0[2] = v0[2] * c[1] - v0[3] * s[1]; a0[3] = v0[2] * s[1] + v0[3] * c[1];
;                                 a1[0] = v1[0] * c[2] - v1[1] * s[2]; a1[1] = v1[0] * s[2] + v1[1] * c[2];
;                                 a1[2] = v1[2] * c[3] - v1[3] * s[3]; a1[3] = v1[2] * s[3] + v1[3] * c[3];
;                                 v0 = a0; v1 = a1; }
;                             v0 = v0 * scale; v1 = v1 * scale; }
;                         u32x4 w; w.x = cvtpk(v0[0], v0[1]); w.y = cvtpk(v0[2], v0[3]); w.z = cvtpk(v1[0], v1[1]); w.w = cvtpk(v1[2], v1[3]);
;                         if (mode == 3) { const int cb = u.pn * 2 + bj;
;                             bf16_t* dst;
;                             if (cb < 72) { const int dsh = 2 * (cb / 24); const int tp = sq4 + ((pos & ((1 << dsh) - 1)) << (12 - dsh)) + (pos >> dsh); dst = O + ((size_t)cb * ldc + tp) * 128 + dcol; }
;                             else dst = O + (size_t)9216 * ldc + (size_t)row * 1024 + (cb - 72) * 128 + dcol;
;                             *(u32x4*)dst = w; }
;                         else *(u32x4*)(rowp + bj * 128) = w; }
.LBB0_389:
	v_or_b32_e32 v138, 48, v164
	v_mad_i64_i32 v[140:141], s[74:75], v138, s40, 0
	v_lshl_add_u64 v[140:141], v[140:141], 1, s[22:23]
	v_lshl_add_u64 v[140:141], v[136:137], 1, v[140:141]
	v_cvt_pk_bf16_f32 v128, v128, v129
	v_cvt_pk_bf16_f32 v129, v130, v131
	v_cvt_pk_bf16_f32 v130, v132, v133
	v_cvt_pk_bf16_f32 v131, v134, v135
	s_and_b64 vcc, exec, s[10:11]
	s_mov_b64 s[86:87], -1
	s_cbranch_vccnz .LBB0_391
	s_mov_b64 s[86:87], 0
	global_store_dwordx4 v[140:141], v[128:131], off sc0 sc1

; __device__ __forceinline__ unsigned cvtpk(float lo, float hi) { f32x2_t v = {lo, hi}; bf16x2_t b = __builtin_convertvector(v, bf16x2_t); return __builtin_bit_cast(unsigned, b); }
;     __device__ __forceinline__ void operator()(const f32x4 (&acc)[2][2][4][2], const pg8::Unit& u, int wr, int wc, int fr, int fq) const {
;     ...
;                 for (int m = 0; m < 4; ++m) { const int row = row0 + ai * 128 + m * 16; bf16_t* rowp = O + (size_t)row * ldc + col0; const int pos = row & (SEQ - 1);
;                     const int dcol = wc * 32 + 8 * fq, sq4 = row & ~(SEQ - 1);
; #pragma unroll
;                     for (int bj = 0; bj < 2; ++bj) { f32x4 v0 = acc[ai][bj][m][0], v1 = acc[ai][bj][m][1];
;                         if (mode == 1) {
;                             const int col = col0 + bj * 128; const int d = col % 96;
;                             if (d >= 64) { const int f0 = (d - 64) >> 1;
;                                 const f32x4 c = *(const f32x4*)(cs + pos * 32 + f0), s = *(const f32x4*)(cs + pos * 32 + 16 + f0);
;                                 f32x4 a0, a1;
;                                 a0[0] = v0[0] * c[0] - v0[1] * s[0]; a0[1] = v0[0] * s[0] + v0[1] * c[0];
;                                 a0[2] = v0[2] * c[1] - v0[3] * s[1]; a0[3] = v0[2] * s[1] + v0[3] * c[1];
;                                 a1[0] = v1[0] * c[2] - v1[1] * s[2]; a1[1] = v1[0] * s[2] + v1[1] * c[2];
;                                 a1[2] = v1[2] * c[3] - v1[3] * s[3]; a1[3] = v1[2] * s[3] + v1[3] * c[3];
;                                 v0 = a0; v1 = a1; }
;                             v0 = v0 * scale; v1 = v1 * scale; }
;                         u32x4 w; w.x = cvtpk(v0[0], v0[1]); w.y = cvtpk(v0[2], v0[3]); w.z = cvtpk(v1[0], v1[1]); w.w = cvtpk(v1[2], v1[3]);
;                         if (mode == 3) { const int cb = u.pn * 2 + bj;
;                             bf16_t* dst;
;                             if (cb < 72) { const int dsh = 2 * (cb / 24); const int tp = sq4 + ((pos & ((1 << dsh) - 1)) << (12 - dsh)) + (pos >> dsh); dst = O + ((size_t)cb * ldc + tp) * 128 + dcol; }
;                             else dst = O + (size_t)9216 * ldc + (size_t)row * 1024 + (cb - 72) * 128 + dcol;
;                             *(u32x4*)dst = w; }
;                         else *(u32x4*)(rowp + bj * 128) = w; }
.LBB0_413:
	v_mad_i64_i32 v[140:141], s[74:75], v138, s40, 0
	v_lshl_add_u64 v[140:141], v[140:141], 1, s[22:23]
	v_lshl_add_u64 v[140:141], v[136:137], 1, v[140:141]
	v_cvt_pk_bf16_f32 v128, v128, v129
	v_cvt_pk_bf16_f32 v129, v130, v131
	v_cvt_pk_bf16_f32 v130, v132, v133
	v_cvt_pk_bf16_f32 v131, v134, v135
	s_and_b64 vcc, exec, s[10:11]
	s_mov_b64 s[86:87], -1
	s_cbranch_vccnz .LBB0_415
	s_mov_b64 s[86:87], 0
	global_store_dwordx4 v[140:141], v[128:131], off sc0 sc1

; __device__ __forceinline__ unsigned cvtpk(float lo, float hi) { f32x2_t v = {lo, hi}; bf16x2_t b = __builtin_convertvector(v, bf16x2_t); return __builtin_bit_cast(unsigned, b); }
;     __device__ __forceinline__ void operator()(const f32x4 (&acc)[2][2][4][2], const pg8::Unit& u, int wr, int wc, int fr, int fq) const {
;     ...
;                         u32x4 w; w.x = cvtpk(v0[0], v0[1]); w.y = cvtpk(v0[2], v0[3]); w.z = cvtpk(v1[0], v1[1]); w.w = cvtpk(v1[2], v1[3]);
;                         if (mode == 3) { const int cb = u.pn * 2 + bj;
;                             bf16_t* dst;
;                             if (cb < 72) { const int dsh = 2 * (cb / 24); const int tp = sq4 + ((pos & ((1 << dsh) - 1)) << (12 - dsh)) + (pos >> dsh); dst = O + ((size_t)cb * ldc + tp) * 128 + dcol; }
;                             else dst = O + (size_t)9216 * ldc + (size_t)row * 1024 + (cb - 72) * 128 + dcol;
;                             *(u32x4*)dst = w; }
;                         else *(u32x4*)(rowp + bj * 128) = w; }
.LBB0_497:
	v_cvt_pk_bf16_f32 v128, v128, v129
	v_cvt_pk_bf16_f32 v129, v130, v131
	v_cvt_pk_bf16_f32 v130, v132, v133
	v_cvt_pk_bf16_f32 v131, v134, v135
	s_and_b64 vcc, exec, s[10:11]
	s_mov_b64 s[10:11], -1
	s_cbranch_vccnz .LBB0_499
	s_mov_b64 s[10:11], 0
	global_store_dwordx4 v[140:141], v[128:131], off offset:256 sc0 sc1

;     __device__ __forceinline__ void operator()(const f32x4 (&acc)[2][2][4][2], const pg8::Unit& u, int wr, int wc, int fr, int fq) const {
;     ...
;                 for (int ai = 0; ai < 2; ++ai) {
;                     f32x4 bv[4][2][2];
; #pragma unroll
;                     for (int m = 0; m < 4; ++m) { const size_t off = (size_t)(row0 + ai * 128 + m * 16) * DM + col0;
; #pragma unroll
;                         for (int bj = 0; bj < 2; ++bj) { bv[m][bj][0] = *(const f32x4*)(base + off + bj * 128); bv[m][bj][1] = *(const f32x4*)(base + off + bj * 128 + 4); } }
;                     asm volatile("" ::: "memory");
; #pragma unroll
;                     for (int m = 0; m < 4; ++m) { const size_t off = (size_t)(row0 + ai * 128 + m * 16) * DM + col0;
; #pragma unroll
;                         for (int bj = 0; bj < 2; ++bj) { const f32x4 x0 = bv[m][bj][0] + acc[ai][bj][m][0], x1 = bv[m][bj][1] + acc[ai][bj][m][1];
;                             const f32x8 xx = {x0[0], x0[1], x0[2], x0[3], x1[0], x1[1], x1[2], x1[3]};
;                             *(f16x8*)(xh + off + bj * 128) = __builtin_convertvector(xx, f16x8); } }
;                     asm volatile("" ::: "memory");
;                 }
.LBB0_506:
	s_and_b64 vcc, exec, s[10:11]
	s_cbranch_vccz .LBB0_510
	v_ashrrev_i32_e32 v165, 31, v164
	v_ashrrev_i32_e32 v137, 31, v136
	v_or_b32_e32 v132, 16, v164
	v_or_b32_e32 v130, 32, v164
	v_or_b32_e32 v128, 48, v164
	v_lshlrev_b64 v[134:135], 11, v[164:165]
	s_andn2_b64 vcc, exec, s[6:7]
	v_lshlrev_b64 v[166:167], 1, v[136:137]
	v_ashrrev_i32_e32 v133, 31, v132
	v_ashrrev_i32_e32 v131, 31, v130
	v_ashrrev_i32_e32 v129, 31, v128
	v_lshl_add_u64 v[174:175], s[50:51], 0, v[134:135]
	s_cbranch_vccnz .LBB0_513
	v_lshl_add_u64 v[136:137], v[136:137], 2, v[148:149]
	v_lshlrev_b64 v[138:139], 12, v[164:165]
	v_lshl_add_u64 v[146:147], v[136:137], 0, v[138:139]
	v_lshlrev_b64 v[172:173], 12, v[132:133]
	global_load_dwordx4 v[138:141], v[146:147], off
	global_load_dwordx4 v[142:145], v[146:147], off offset:16
	global_load_dwordx4 v[168:171], v[146:147], off offset:512
	global_load_dwordx4 v[186:189], v[146:147], off offset:528
	v_lshl_add_u64 v[146:147], v[136:137], 0, v[172:173]
	global_load_dwordx4 v[200:203], v[146:147], off
	global_load_dwordx4 v[204:207], v[146:147], off offset:16
	global_load_dwordx4 v[214:217], v[146:147], off offset:512
	v_lshlrev_b64 v[172:173], 12, v[130:131]
	global_load_dwordx4 v[218:221], v[146:147], off offset:528
	v_lshl_add_u64 v[146:147], v[136:137], 0, v[172:173]
	global_load_dwordx4 v[222:225], v[146:147], off
	global_load_dwordx4 v[226:229], v[146:147], off offset:16
	global_load_dwordx4 v[230:233], v[146:147], off offset:512
	global_load_dwordx4 v[234:237], v[146:147], off offset:528
	v_lshlrev_b64 v[146:147], 12, v[128:129]
	v_lshl_add_u64 v[146:147], v[136:137], 0, v[146:147]
	global_load_dwordx4 v[238:241], v[146:147], off
	global_load_dwordx4 v[242:245], v[146:147], off offset:16
	global_load_dwordx4 v[246:249], v[146:147], off offset:512
	global_load_dwordx4 v[250:253], v[146:147], off offset:528
	v_lshlrev_b64 v[172:173], 11, v[132:133]
	v_lshlrev_b64 v[182:183], 11, v[130:131]
	v_lshl_add_u64 v[146:147], v[174:175], 0, v[166:167]
	v_lshl_add_u64 v[172:173], s[50:51], 0, v[172:173]
	v_lshl_add_u64 v[182:183], s[50:51], 0, v[182:183]
	v_lshl_add_u64 v[172:173], v[172:173], 0, v[166:167]
	v_lshl_add_u64 v[182:183], v[182:183], 0, v[166:167]
	s_waitcnt vmcnt(0)
	v_pk_add_f32 v[190:191], v[126:127], v[140:141]
	v_pk_add_f32 v[192:193], v[124:125], v[138:139]
	v_pk_add_f32 v[138:139], v[122:123], v[144:145]
	v_pk_add_f32 v[142:143], v[120:121], v[142:143]
	v_pk_add_f32 v[170:171], v[110:111], v[170:171]
	v_pk_add_f32 v[168:169], v[108:109], v[168:169]
	v_pk_add_f32 v[144:145], v[106:107], v[188:189]
	v_pk_add_f32 v[186:187], v[104:105], v[186:187]
	v_pk_add_f32 v[188:189], v[118:119], v[202:203]
	v_pk_add_f32 v[200:201], v[116:117], v[200:201]
	v_pk_add_f32 v[202:203], v[114:115], v[206:207]
	v_pk_add_f32 v[204:205], v[112:113], v[204:205]
	v_pk_add_f32 v[206:207], v[102:103], v[216:217]
	v_pk_add_f32 v[208:209], v[100:101], v[214:215]
	v_pk_add_f32 v[214:215], v[98:99], v[220:221]
	v_pk_add_f32 v[216:217], v[96:97], v[218:219]
	v_pk_add_f32 v[218:219], v[94:95], v[224:225]
	v_pk_add_f32 v[220:221], v[92:93], v[222:223]
	v_pk_add_f32 v[222:223], v[90:91], v[228:229]
	v_pk_add_f32 v[224:225], v[88:89], v[226:227]
	v_cvt_pk_f16_f32 v141, v138, v139
	v_cvt_pk_f16_f32 v139, v190, v191
	v_cvt_pk_f16_f32 v140, v142, v143
	v_cvt_pk_f16_f32 v138, v192, v193
	v_cvt_pk_f16_f32 v143, v170, v171
	v_cvt_pk_f16_f32 v142, v168, v169
	v_cvt_pk_f16_f32 v145, v144, v145
	v_cvt_pk_f16_f32 v144, v186, v187
	v_cvt_pk_f16_f32 v171, v202, v203
	v_cvt_pk_f16_f32 v169, v188, v189
	v_cvt_pk_f16_f32 v170, v204, v205
	v_cvt_pk_f16_f32 v168, v200, v201
	v_cvt_pk_f16_f32 v189, v214, v215
	v_cvt_pk_f16_f32 v187, v206, v207
	v_cvt_pk_f16_f32 v188, v216, v217
	v_cvt_pk_f16_f32 v186, v208, v209
	v_cvt_pk_f16_f32 v203, v222, v223
	v_cvt_pk_f16_f32 v201, v218, v219
	v_cvt_pk_f16_f32 v202, v224, v225
	v_cvt_pk_f16_f32 v200, v220, v221
	global_store_dwordx4 v[146:147], v[138:141], off sc0 sc1
	global_store_dwordx4 v[146:147], v[142:145], off offset:256 sc0 sc1
	global_store_dwordx4 v[172:173], v[168:171], off sc0 sc1
	global_store_dwordx4 v[172:173], v[186:189], off offset:256 sc0 sc1
	global_store_dwordx4 v[182:183], v[200:203], off sc0 sc1
	v_lshlrev_b64 v[142:143], 11, v[128:129]
	v_pk_add_f32 v[138:139], v[78:79], v[240:241]
	v_pk_add_f32 v[144:145], v[76:77], v[238:239]
	v_pk_add_f32 v[140:141], v[74:75], v[244:245]
	v_pk_add_f32 v[146:147], v[72:73], v[242:243]
	v_lshl_add_u64 v[142:143], s[50:51], 0, v[142:143]
	v_cvt_pk_f16_f32 v141, v140, v141
	v_cvt_pk_f16_f32 v139, v138, v139
	v_cvt_pk_f16_f32 v140, v146, v147
	v_cvt_pk_f16_f32 v138, v144, v145
	v_lshl_add_u64 v[142:143], v[142:143], 0, v[166:167]
	global_store_dwordx4 v[142:143], v[138:141], off sc0 sc1
	v_pk_add_f32 v[146:147], v[64:65], v[250:251]
	v_pk_add_f32 v[226:227], v[86:87], v[232:233]
	v_pk_add_f32 v[140:141], v[66:67], v[252:253]
	v_pk_add_f32 v[228:229], v[84:85], v[230:231]
	v_pk_add_f32 v[230:231], v[82:83], v[236:237]
	v_pk_add_f32 v[232:233], v[80:81], v[234:235]
	v_pk_add_f32 v[138:139], v[70:71], v[248:249]
	v_pk_add_f32 v[144:145], v[68:69], v[246:247]
	v_cvt_pk_f16_f32 v141, v140, v141
	v_cvt_pk_f16_f32 v140, v146, v147
	v_add_u32_e32 v146, 0x80, v164
	v_cvt_pk_f16_f32 v207, v230, v231
	v_cvt_pk_f16_f32 v205, v226, v227
	v_cvt_pk_f16_f32 v206, v232, v233
	v_cvt_pk_f16_f32 v204, v228, v229
	v_cvt_pk_f16_f32 v139, v138, v139
	v_cvt_pk_f16_f32 v138, v144, v145
	v_ashrrev_i32_e32 v147, 31, v146
	global_store_dwordx4 v[182:183], v[204:207], off offset:256 sc0 sc1
	global_store_dwordx4 v[142:143], v[138:141], off offset:256 sc0 sc1
	s_nop 1
;     __device__ __forceinline__ void operator()(const f32x4 (&acc)[2][2][4][2], const pg8::Unit& u, int wr, int wc, int fr, int fq) const {
;     ...
;                 for (int ai = 0; ai < 2; ++ai) {
;                     f32x4 bv[4][2][2];
; #pragma unroll
;                     for (int m = 0; m < 4; ++m) { const size_t off = (size_t)(row0 + ai * 128 + m * 16) * DM + col0;
; #pragma unroll
;                         for (int bj = 0; bj < 2; ++bj) { bv[m][bj][0] = *(const f32x4*)(base + off + bj * 128); bv[m][bj][1] = *(const f32x4*)(base + off + bj * 128 + 4); } }
;                     asm volatile("" ::: "memory");
; #pragma unroll
;                     for (int m = 0; m < 4; ++m) { const size_t off = (size_t)(row0 + ai * 128 + m * 16) * DM + col0;
; #pragma unroll
;                         for (int bj = 0; bj < 2; ++bj) { const f32x4 x0 = bv[m][bj][0] + acc[ai][bj][m][0], x1 = bv[m][bj][1] + acc[ai][bj][m][1];
;                             const f32x8 xx = {x0[0], x0[1], x0[2], x0[3], x1[0], x1[1], x1[2], x1[3]};
;                             *(f16x8*)(xh + off + bj * 128) = __builtin_convertvector(xx, f16x8); } }
;                     asm volatile("" ::: "memory");
;                 }
	v_lshlrev_b64 v[138:139], 12, v[146:147]
	v_lshl_add_u64 v[172:173], v[136:137], 0, v[138:139]
	global_load_dwordx4 v[138:141], v[172:173], off
	global_load_dwordx4 v[142:145], v[172:173], off offset:16
	global_load_dwordx4 v[168:171], v[172:173], off offset:528
	global_load_dwordx4 v[186:189], v[172:173], off offset:512
	v_add_u32_e32 v172, 0x90, v164
	v_ashrrev_i32_e32 v173, 31, v172
	v_lshlrev_b64 v[182:183], 12, v[172:173]
	v_lshl_add_u64 v[182:183], v[136:137], 0, v[182:183]
	global_load_dwordx4 v[200:203], v[182:183], off
	global_load_dwordx4 v[204:207], v[182:183], off offset:16
	global_load_dwordx4 v[214:217], v[182:183], off offset:512
	global_load_dwordx4 v[218:221], v[182:183], off offset:528
	v_add_u32_e32 v182, 0xa0, v164
	v_ashrrev_i32_e32 v183, 31, v182
	v_lshlrev_b64 v[190:191], 12, v[182:183]
	v_lshl_add_u64 v[190:191], v[136:137], 0, v[190:191]
	global_load_dwordx4 v[222:225], v[190:191], off
	global_load_dwordx4 v[226:229], v[190:191], off offset:16
	global_load_dwordx4 v[230:233], v[190:191], off offset:512
	global_load_dwordx4 v[234:237], v[190:191], off offset:528
	v_add_u32_e32 v190, 0xb0, v164
	v_ashrrev_i32_e32 v191, 31, v190
	v_lshlrev_b64 v[192:193], 12, v[190:191]
	v_lshl_add_u64 v[136:137], v[136:137], 0, v[192:193]
	global_load_dwordx4 v[238:241], v[136:137], off
	global_load_dwordx4 v[242:245], v[136:137], off offset:16
	global_load_dwordx4 v[246:249], v[136:137], off offset:512
	global_load_dwordx4 v[250:253], v[136:137], off offset:528
	v_lshlrev_b64 v[136:137], 11, v[146:147]
	v_lshl_add_u64 v[136:137], s[50:51], 0, v[136:137]
	v_lshlrev_b64 v[146:147], 11, v[172:173]
	v_lshl_add_u64 v[172:173], v[136:137], 0, v[166:167]
	s_waitcnt vmcnt(15)
	v_pk_add_f32 v[136:137], v[62:63], v[140:141]
	v_pk_add_f32 v[140:141], v[60:61], v[138:139]
	s_waitcnt vmcnt(14)
	v_pk_add_f32 v[138:139], v[58:59], v[144:145]
	v_pk_add_f32 v[142:143], v[56:57], v[142:143]
	s_waitcnt vmcnt(12)
	v_pk_add_f32 v[144:145], v[54:55], v[188:189]
	v_pk_add_f32 v[186:187], v[52:53], v[186:187]
	v_pk_add_f32 v[170:171], v[50:51], v[170:171]
	v_pk_add_f32 v[168:169], v[48:49], v[168:169]
	v_cvt_pk_f16_f32 v139, v138, v139
	v_cvt_pk_f16_f32 v137, v136, v137
	v_cvt_pk_f16_f32 v138, v142, v143
	v_cvt_pk_f16_f32 v136, v140, v141
	s_waitcnt vmcnt(11)
	v_pk_add_f32 v[188:189], v[46:47], v[202:203]
	v_pk_add_f32 v[192:193], v[44:45], v[200:201]
	s_waitcnt vmcnt(10)
	v_pk_add_f32 v[200:201], v[42:43], v[206:207]
	v_pk_add_f32 v[202:203], v[40:41], v[204:205]
	v_cvt_pk_f16_f32 v143, v170, v171
	v_cvt_pk_f16_f32 v141, v144, v145
	v_cvt_pk_f16_f32 v142, v168, v169
	v_cvt_pk_f16_f32 v140, v186, v187
	global_store_dwordx4 v[172:173], v[136:139], off sc0 sc1
	global_store_dwordx4 v[172:173], v[140:143], off offset:256 sc0 sc1
	v_cvt_pk_f16_f32 v145, v200, v201
	v_lshl_add_u64 v[136:137], s[50:51], 0, v[146:147]
	v_cvt_pk_f16_f32 v143, v188, v189
	v_cvt_pk_f16_f32 v144, v202, v203
	v_cvt_pk_f16_f32 v142, v192, v193
	v_lshl_add_u64 v[140:141], v[136:137], 0, v[166:167]
	global_store_dwordx4 v[140:141], v[142:145], off sc0 sc1
	s_waitcnt vmcnt(12)
	v_pk_add_f32 v[136:137], v[38:39], v[216:217]
	s_waitcnt vmcnt(11)
	v_pk_add_f32 v[138:139], v[34:35], v[220:221]
	v_pk_add_f32 v[142:143], v[36:37], v[214:215]
	v_pk_add_f32 v[144:145], v[32:33], v[218:219]
	v_cvt_pk_f16_f32 v139, v138, v139
	v_cvt_pk_f16_f32 v137, v136, v137
	v_cvt_pk_f16_f32 v138, v144, v145
	v_cvt_pk_f16_f32 v136, v142, v143
	global_store_dwordx4 v[140:141], v[136:139], off offset:256 sc0 sc1
	v_lshlrev_b64 v[140:141], 11, v[182:183]
	s_waitcnt vmcnt(11)
	v_pk_add_f32 v[142:143], v[28:29], v[222:223]
	v_pk_add_f32 v[136:137], v[30:31], v[224:225]
	s_waitcnt vmcnt(10)
	v_pk_add_f32 v[138:139], v[26:27], v[228:229]
	v_pk_add_f32 v[144:145], v[24:25], v[226:227]
	v_lshl_add_u64 v[140:141], s[50:51], 0, v[140:141]
	v_cvt_pk_f16_f32 v139, v138, v139
	v_cvt_pk_f16_f32 v137, v136, v137
	v_cvt_pk_f16_f32 v138, v144, v145
	v_cvt_pk_f16_f32 v136, v142, v143
	v_lshl_add_u64 v[140:141], v[140:141], 0, v[166:167]
	global_store_dwordx4 v[140:141], v[136:139], off sc0 sc1
	s_waitcnt vmcnt(10)
	v_pk_add_f32 v[142:143], v[20:21], v[230:231]
	s_waitcnt vmcnt(9)
	v_pk_add_f32 v[144:145], v[16:17], v[234:235]
	v_pk_add_f32 v[136:137], v[22:23], v[232:233]
	v_pk_add_f32 v[138:139], v[18:19], v[236:237]
	v_cvt_pk_f16_f32 v137, v136, v137
	v_cvt_pk_f16_f32 v139, v138, v139
	v_cvt_pk_f16_f32 v138, v144, v145
	v_cvt_pk_f16_f32 v136, v142, v143
	global_store_dwordx4 v[140:141], v[136:139], off offset:256 sc0 sc1
	v_lshlrev_b64 v[140:141], 11, v[190:191]
	s_waitcnt vmcnt(9)
	v_pk_add_f32 v[142:143], v[12:13], v[238:239]
	v_pk_add_f32 v[136:137], v[14:15], v[240:241]
	s_waitcnt vmcnt(8)
	v_pk_add_f32 v[138:139], v[10:11], v[244:245]
	v_pk_add_f32 v[144:145], v[8:9], v[242:243]
	v_lshl_add_u64 v[140:141], s[50:51], 0, v[140:141]
	v_cvt_pk_f16_f32 v139, v138, v139
	v_cvt_pk_f16_f32 v137, v136, v137
	v_cvt_pk_f16_f32 v138, v144, v145
	v_cvt_pk_f16_f32 v136, v142, v143
	v_lshl_add_u64 v[140:141], v[140:141], 0, v[166:167]
	global_store_dwordx4 v[140:141], v[136:139], off sc0 sc1
	s_waitcnt vmcnt(8)
	v_pk_add_f32 v[142:143], v[4:5], v[246:247]
	s_waitcnt vmcnt(7)
	v_pk_add_f32 v[144:145], v[0:1], v[250:251]
	v_pk_add_f32 v[136:137], v[6:7], v[248:249]
	v_pk_add_f32 v[138:139], v[2:3], v[252:253]
	v_cvt_pk_f16_f32 v137, v136, v137
	v_cvt_pk_f16_f32 v139, v138, v139
	v_cvt_pk_f16_f32 v138, v144, v145
	v_cvt_pk_f16_f32 v136, v142, v143
	global_store_dwordx4 v[140:141], v[136:139], off offset:256 sc0 sc1
	s_cbranch_execnz .LBB0_510
;     __device__ __forceinline__ void operator()(const f32x4 (&acc)[2][2][4][2], const pg8::Unit& u, int wr, int wc, int fr, int fq) const {
;     ...
;                 for (int ai = 0; ai < 2; ++ai) {
;                     f16x8 hv[4][2];
; #pragma unroll
;                     for (int m = 0; m < 4; ++m) { const size_t off = (size_t)(row0 + ai * 128 + m * 16) * DM + col0;
; #pragma unroll
;                         for (int bj = 0; bj < 2; ++bj) hv[m][bj] = *(const f16x8*)(xh + off + bj * 128); }
;                     asm volatile("" ::: "memory");
; #pragma unroll
;                     for (int m = 0; m < 4; ++m) { const size_t off = (size_t)(row0 + ai * 128 + m * 16) * DM + col0;
; #pragma unroll
;                         for (int bj = 0; bj < 2; ++bj) { const f32x8 b8 = __builtin_convertvector(hv[m][bj], f32x8); const f32x4 a0 = acc[ai][bj][m][0], a1 = acc[ai][bj][m][1];
;                             const f32x8 xx = {b8[0] + a0[0], b8[1] + a0[1], b8[2] + a0[2], b8[3] + a0[3], b8[4] + a1[0], b8[5] + a1[1], b8[6] + a1[2], b8[7] + a1[3]};
;                             *(f16x8*)(xh + off + bj * 128) = __builtin_convertvector(xx, f16x8); } }
;                     asm volatile("" ::: "memory");
.LBB0_509:
	v_lshl_add_u64 v[168:169], s[50:51], 0, v[166:167]
	v_lshl_add_u64 v[134:135], v[168:169], 0, v[134:135]
	global_load_dwordx4 v[186:189], v[134:135], off
	global_load_dwordx4 v[200:203], v[134:135], off offset:256
	v_lshlrev_b64 v[182:183], 11, v[132:133]
	v_lshl_add_u64 v[132:133], v[168:169], 0, v[182:183]
	global_load_dwordx4 v[204:207], v[132:133], off
	global_load_dwordx4 v[144:147], v[132:133], off offset:256
	v_lshlrev_b64 v[172:173], 11, v[130:131]
	v_lshl_add_u64 v[130:131], v[168:169], 0, v[172:173]
	global_load_dwordx4 v[140:143], v[130:131], off
	global_load_dwordx4 v[136:139], v[130:131], off offset:256
	v_lshlrev_b64 v[170:171], 11, v[128:129]
	v_lshl_add_u64 v[128:129], v[168:169], 0, v[170:171]
	global_load_dwordx4 v[132:135], v[128:129], off
	s_nop 0
	global_load_dwordx4 v[128:131], v[128:129], off offset:256
	s_mov_b64 s[10:11], 0x40000
	s_waitcnt vmcnt(0)
	v_cvt_f32_f16_e32 v190, v189
	v_cvt_f32_f16_sdwa v191, v189 dst_sel:DWORD dst_unused:UNUSED_PAD src0_sel:WORD_1
	v_cvt_f32_f16_e32 v192, v188
	v_cvt_f32_f16_sdwa v193, v188 dst_sel:DWORD dst_unused:UNUSED_PAD src0_sel:WORD_1
	v_cvt_f32_f16_e32 v188, v187
	v_cvt_f32_f16_sdwa v189, v187 dst_sel:DWORD dst_unused:UNUSED_PAD src0_sel:WORD_1
	v_cvt_f32_f16_e32 v208, v186
	v_cvt_f32_f16_sdwa v209, v186 dst_sel:DWORD dst_unused:UNUSED_PAD src0_sel:WORD_1
	v_pk_add_f32 v[120:121], v[120:121], v[192:193]
	v_pk_add_f32 v[126:127], v[126:127], v[188:189]
	v_pk_add_f32 v[122:123], v[122:123], v[190:191]
	v_pk_add_f32 v[124:125], v[124:125], v[208:209]
	v_cvt_pk_f16_f32 v123, v122, v123
	v_cvt_pk_f16_f32 v122, v120, v121
	v_cvt_pk_f16_f32 v121, v126, v127
	v_cvt_pk_f16_f32 v120, v124, v125
	v_lshl_add_u64 v[124:125], v[174:175], 0, v[166:167]
	global_store_dwordx4 v[124:125], v[120:123], off sc0 sc1
	v_cvt_f32_f16_e32 v126, v201
	v_cvt_f32_f16_sdwa v127, v201 dst_sel:DWORD dst_unused:UNUSED_PAD src0_sel:WORD_1
	v_cvt_f32_f16_e32 v120, v203
	v_cvt_f32_f16_sdwa v121, v203 dst_sel:DWORD dst_unused:UNUSED_PAD src0_sel:WORD_1
	v_cvt_f32_f16_e32 v122, v202
	v_cvt_f32_f16_sdwa v123, v202 dst_sel:DWORD dst_unused:UNUSED_PAD src0_sel:WORD_1
	v_cvt_f32_f16_e32 v174, v200
	v_cvt_f32_f16_sdwa v175, v200 dst_sel:DWORD dst_unused:UNUSED_PAD src0_sel:WORD_1
	v_pk_add_f32 v[110:111], v[110:111], v[126:127]
	v_pk_add_f32 v[104:105], v[104:105], v[122:123]
	v_pk_add_f32 v[106:107], v[106:107], v[120:121]
	v_pk_add_f32 v[108:109], v[108:109], v[174:175]
	v_cvt_pk_f16_f32 v107, v106, v107
	v_cvt_pk_f16_f32 v106, v104, v105
	v_cvt_pk_f16_f32 v105, v110, v111
	v_cvt_pk_f16_f32 v104, v108, v109
	global_store_dwordx4 v[124:125], v[104:107], off offset:256 sc0 sc1
	v_cvt_f32_f16_e32 v108, v205
	v_cvt_f32_f16_sdwa v109, v205 dst_sel:DWORD dst_unused:UNUSED_PAD src0_sel:WORD_1
	v_cvt_f32_f16_e32 v104, v207
	v_cvt_f32_f16_sdwa v105, v207 dst_sel:DWORD dst_unused:UNUSED_PAD src0_sel:WORD_1
	v_cvt_f32_f16_e32 v106, v206
	v_cvt_f32_f16_sdwa v107, v206 dst_sel:DWORD dst_unused:UNUSED_PAD src0_sel:WORD_1
	v_cvt_f32_f16_e32 v110, v204
	v_cvt_f32_f16_sdwa v111, v204 dst_sel:DWORD dst_unused:UNUSED_PAD src0_sel:WORD_1
	v_pk_add_f32 v[108:109], v[118:119], v[108:109]
	v_pk_add_f32 v[104:105], v[114:115], v[104:105]
	v_pk_add_f32 v[112:113], v[112:113], v[106:107]
	v_pk_add_f32 v[110:111], v[116:117], v[110:111]
	v_cvt_pk_f16_f32 v107, v104, v105
	v_cvt_pk_f16_f32 v105, v108, v109
	v_lshl_add_u64 v[108:109], s[50:51], 0, v[182:183]
	v_cvt_pk_f16_f32 v106, v112, v113
	v_cvt_pk_f16_f32 v104, v110, v111
	v_lshl_add_u64 v[108:109], v[108:109], 0, v[166:167]
	global_store_dwordx4 v[108:109], v[104:107], off sc0 sc1
	v_cvt_f32_f16_e32 v110, v145
	v_cvt_f32_f16_sdwa v111, v145 dst_sel:DWORD dst_unused:UNUSED_PAD src0_sel:WORD_1
	v_cvt_f32_f16_e32 v104, v147
	v_cvt_f32_f16_sdwa v105, v147 dst_sel:DWORD dst_unused:UNUSED_PAD src0_sel:WORD_1
	v_cvt_f32_f16_e32 v106, v146
	v_cvt_f32_f16_sdwa v107, v146 dst_sel:DWORD dst_unused:UNUSED_PAD src0_sel:WORD_1
	v_cvt_f32_f16_e32 v112, v144
	v_cvt_f32_f16_sdwa v113, v144 dst_sel:DWORD dst_unused:UNUSED_PAD src0_sel:WORD_1
	v_pk_add_f32 v[102:103], v[102:103], v[110:111]
	v_pk_add_f32 v[96:97], v[96:97], v[106:107]
	v_pk_add_f32 v[98:99], v[98:99], v[104:105]
	v_pk_add_f32 v[100:101], v[100:101], v[112:113]
	v_cvt_pk_f16_f32 v99, v98, v99
	v_cvt_pk_f16_f32 v98, v96, v97
	v_cvt_pk_f16_f32 v97, v102, v103
	v_cvt_pk_f16_f32 v96, v100, v101
	global_store_dwordx4 v[108:109], v[96:99], off offset:256 sc0 sc1
	v_cvt_f32_f16_e32 v102, v140
	v_cvt_f32_f16_sdwa v103, v140 dst_sel:DWORD dst_unused:UNUSED_PAD src0_sel:WORD_1
	v_cvt_f32_f16_e32 v96, v143
	v_cvt_f32_f16_sdwa v97, v143 dst_sel:DWORD dst_unused:UNUSED_PAD src0_sel:WORD_1
	v_cvt_f32_f16_e32 v98, v142
	v_cvt_f32_f16_sdwa v99, v142 dst_sel:DWORD dst_unused:UNUSED_PAD src0_sel:WORD_1
	v_cvt_f32_f16_e32 v100, v141
	v_cvt_f32_f16_sdwa v101, v141 dst_sel:DWORD dst_unused:UNUSED_PAD src0_sel:WORD_1
	v_pk_add_f32 v[92:93], v[92:93], v[102:103]
	v_pk_add_f32 v[88:89], v[88:89], v[98:99]
	v_pk_add_f32 v[90:91], v[90:91], v[96:97]
	v_pk_add_f32 v[94:95], v[94:95], v[100:101]
	v_cvt_pk_f16_f32 v91, v90, v91
	v_cvt_pk_f16_f32 v90, v88, v89
	v_cvt_pk_f16_f32 v88, v92, v93
	v_lshl_add_u64 v[92:93], s[50:51], 0, v[172:173]
	v_cvt_pk_f16_f32 v89, v94, v95
	v_lshl_add_u64 v[92:93], v[92:93], 0, v[166:167]
	global_store_dwordx4 v[92:93], v[88:91], off sc0 sc1
	v_cvt_f32_f16_e32 v94, v137
	v_cvt_f32_f16_sdwa v95, v137 dst_sel:DWORD dst_unused:UNUSED_PAD src0_sel:WORD_1
	v_cvt_f32_f16_e32 v88, v139
	v_cvt_f32_f16_sdwa v89, v139 dst_sel:DWORD dst_unused:UNUSED_PAD src0_sel:WORD_1
	v_cvt_f32_f16_e32 v90, v138
;     __device__ __forceinline__ void operator()(const f32x4 (&acc)[2][2][4][2], const pg8::Unit& u, int wr, int wc, int fr, int fq) const {
;     ...
;                 for (int ai = 0; ai < 2; ++ai) {
;                     f16x8 hv[4][2];
; #pragma unroll
;                     for (int m = 0; m < 4; ++m) { const size_t off = (size_t)(row0 + ai * 128 + m * 16) * DM + col0;
; #pragma unroll
;                         for (int bj = 0; bj < 2; ++bj) hv[m][bj] = *(const f16x8*)(xh + off + bj * 128); }
;                     asm volatile("" ::: "memory");
; #pragma unroll
;                     for (int m = 0; m < 4; ++m) { const size_t off = (size_t)(row0 + ai * 128 + m * 16) * DM + col0;
; #pragma unroll
;                         for (int bj = 0; bj < 2; ++bj) { const f32x8 b8 = __builtin_convertvector(hv[m][bj], f32x8); const f32x4 a0 = acc[ai][bj][m][0], a1 = acc[ai][bj][m][1];
;                             const f32x8 xx = {b8[0] + a0[0], b8[1] + a0[1], b8[2] + a0[2], b8[3] + a0[3], b8[4] + a1[0], b8[5] + a1[1], b8[6] + a1[2], b8[7] + a1[3]};
;                             *(f16x8*)(xh + off + bj * 128) = __builtin_convertvector(xx, f16x8); } }
;                     asm volatile("" ::: "memory");
	v_cvt_f32_f16_sdwa v91, v138 dst_sel:DWORD dst_unused:UNUSED_PAD src0_sel:WORD_1
	v_cvt_f32_f16_e32 v96, v136
	v_cvt_f32_f16_sdwa v97, v136 dst_sel:DWORD dst_unused:UNUSED_PAD src0_sel:WORD_1
	v_pk_add_f32 v[86:87], v[86:87], v[94:95]
	v_pk_add_f32 v[80:81], v[80:81], v[90:91]
	v_pk_add_f32 v[82:83], v[82:83], v[88:89]
	v_pk_add_f32 v[84:85], v[84:85], v[96:97]
	v_cvt_pk_f16_f32 v83, v82, v83
	v_cvt_pk_f16_f32 v82, v80, v81
	v_cvt_pk_f16_f32 v81, v86, v87
	v_cvt_pk_f16_f32 v80, v84, v85
	global_store_dwordx4 v[92:93], v[80:83], off offset:256 sc0 sc1
	v_cvt_f32_f16_e32 v86, v132
	v_cvt_f32_f16_sdwa v87, v132 dst_sel:DWORD dst_unused:UNUSED_PAD src0_sel:WORD_1
	v_cvt_f32_f16_e32 v80, v135
	v_cvt_f32_f16_sdwa v81, v135 dst_sel:DWORD dst_unused:UNUSED_PAD src0_sel:WORD_1
	v_cvt_f32_f16_e32 v82, v134
	v_cvt_f32_f16_sdwa v83, v134 dst_sel:DWORD dst_unused:UNUSED_PAD src0_sel:WORD_1
	v_cvt_f32_f16_e32 v84, v133
	v_cvt_f32_f16_sdwa v85, v133 dst_sel:DWORD dst_unused:UNUSED_PAD src0_sel:WORD_1
	v_pk_add_f32 v[76:77], v[76:77], v[86:87]
	v_pk_add_f32 v[72:73], v[72:73], v[82:83]
	v_pk_add_f32 v[74:75], v[74:75], v[80:81]
	v_pk_add_f32 v[78:79], v[78:79], v[84:85]
	v_cvt_pk_f16_f32 v75, v74, v75
	v_cvt_pk_f16_f32 v74, v72, v73
	v_cvt_pk_f16_f32 v72, v76, v77
	v_lshl_add_u64 v[76:77], s[50:51], 0, v[170:171]
	v_cvt_pk_f16_f32 v73, v78, v79
	v_lshl_add_u64 v[76:77], v[76:77], 0, v[166:167]
	global_store_dwordx4 v[76:77], v[72:75], off sc0 sc1
	v_cvt_f32_f16_e32 v78, v129
	v_cvt_f32_f16_sdwa v79, v129 dst_sel:DWORD dst_unused:UNUSED_PAD src0_sel:WORD_1
	v_cvt_f32_f16_e32 v72, v131
	v_cvt_f32_f16_sdwa v73, v131 dst_sel:DWORD dst_unused:UNUSED_PAD src0_sel:WORD_1
	v_cvt_f32_f16_e32 v74, v130
	v_cvt_f32_f16_sdwa v75, v130 dst_sel:DWORD dst_unused:UNUSED_PAD src0_sel:WORD_1
	v_cvt_f32_f16_e32 v80, v128
	v_cvt_f32_f16_sdwa v81, v128 dst_sel:DWORD dst_unused:UNUSED_PAD src0_sel:WORD_1
	v_pk_add_f32 v[70:71], v[70:71], v[78:79]
	v_pk_add_f32 v[64:65], v[64:65], v[74:75]
	v_pk_add_f32 v[66:67], v[66:67], v[72:73]
	v_pk_add_f32 v[68:69], v[68:69], v[80:81]
	v_cvt_pk_f16_f32 v67, v66, v67
	v_cvt_pk_f16_f32 v66, v64, v65
	v_cvt_pk_f16_f32 v65, v70, v71
	v_cvt_pk_f16_f32 v64, v68, v69
	global_store_dwordx4 v[76:77], v[64:67], off offset:256 sc0 sc1
	s_nop 1
	v_lshlrev_b64 v[64:65], 11, v[164:165]
	v_lshl_add_u64 v[100:101], v[64:65], 0, s[10:11]
	v_lshl_add_u64 v[66:67], v[168:169], 0, v[100:101]
	global_load_dwordx4 v[84:87], v[66:67], off
	global_load_dwordx4 v[88:91], v[66:67], off offset:256
	s_mov_b64 s[10:11], 0x48000
	v_lshl_add_u64 v[102:103], v[64:65], 0, s[10:11]
	v_lshl_add_u64 v[66:67], v[168:169], 0, v[102:103]
	global_load_dwordx4 v[92:95], v[66:67], off
	global_load_dwordx4 v[96:99], v[66:67], off offset:256
	s_mov_b64 s[10:11], 0x50000
	v_lshl_add_u64 v[82:83], v[64:65], 0, s[10:11]
	v_lshl_add_u64 v[66:67], v[168:169], 0, v[82:83]
	global_load_dwordx4 v[76:79], v[66:67], off
	global_load_dwordx4 v[72:75], v[66:67], off offset:256
	s_mov_b64 s[10:11], 0x58000
	v_lshl_add_u64 v[80:81], v[64:65], 0, s[10:11]
	v_lshl_add_u64 v[64:65], v[168:169], 0, v[80:81]
	global_load_dwordx4 v[68:71], v[64:65], off
	s_nop 0
	global_load_dwordx4 v[64:67], v[64:65], off offset:256
	s_waitcnt vmcnt(7)
	v_cvt_f32_f16_e32 v104, v87
	v_cvt_f32_f16_sdwa v105, v87 dst_sel:DWORD dst_unused:UNUSED_PAD src0_sel:WORD_1
	v_cvt_f32_f16_e32 v106, v86
	v_cvt_f32_f16_sdwa v107, v86 dst_sel:DWORD dst_unused:UNUSED_PAD src0_sel:WORD_1
	v_cvt_f32_f16_e32 v108, v84
	v_cvt_f32_f16_sdwa v109, v84 dst_sel:DWORD dst_unused:UNUSED_PAD src0_sel:WORD_1
	v_cvt_f32_f16_e32 v86, v85
	v_cvt_f32_f16_sdwa v87, v85 dst_sel:DWORD dst_unused:UNUSED_PAD src0_sel:WORD_1
	v_pk_add_f32 v[56:57], v[56:57], v[106:107]
	v_pk_add_f32 v[60:61], v[60:61], v[108:109]
	v_pk_add_f32 v[58:59], v[58:59], v[104:105]
	v_pk_add_f32 v[62:63], v[62:63], v[86:87]
	v_cvt_pk_f16_f32 v59, v58, v59
	v_cvt_pk_f16_f32 v58, v56, v57
	v_cvt_pk_f16_f32 v56, v60, v61
	v_lshl_add_u64 v[60:61], s[50:51], 0, v[100:101]
	v_cvt_pk_f16_f32 v57, v62, v63
	v_lshl_add_u64 v[60:61], v[60:61], 0, v[166:167]
	global_store_dwordx4 v[60:61], v[56:59], off sc0 sc1
	s_waitcnt vmcnt(7)
	v_cvt_f32_f16_e32 v62, v89
	v_cvt_f32_f16_sdwa v63, v89 dst_sel:DWORD dst_unused:UNUSED_PAD src0_sel:WORD_1
	v_cvt_f32_f16_e32 v56, v91
	v_cvt_f32_f16_sdwa v57, v91 dst_sel:DWORD dst_unused:UNUSED_PAD src0_sel:WORD_1
	v_cvt_f32_f16_e32 v58, v90
	v_cvt_f32_f16_sdwa v59, v90 dst_sel:DWORD dst_unused:UNUSED_PAD src0_sel:WORD_1
	v_cvt_f32_f16_e32 v84, v88
	v_cvt_f32_f16_sdwa v85, v88 dst_sel:DWORD dst_unused:UNUSED_PAD src0_sel:WORD_1
	v_pk_add_f32 v[54:55], v[54:55], v[62:63]
	v_pk_add_f32 v[48:49], v[48:49], v[58:59]
	v_pk_add_f32 v[50:51], v[50:51], v[56:57]
	v_pk_add_f32 v[52:53], v[52:53], v[84:85]
	v_cvt_pk_f16_f32 v51, v50, v51
	v_cvt_pk_f16_f32 v50, v48, v49
	v_cvt_pk_f16_f32 v49, v54, v55
	v_cvt_pk_f16_f32 v48, v52, v53
	global_store_dwordx4 v[60:61], v[48:51], off offset:256 sc0 sc1
	s_waitcnt vmcnt(7)
;     __device__ __forceinline__ void operator()(const f32x4 (&acc)[2][2][4][2], const pg8::Unit& u, int wr, int wc, int fr, int fq) const {
;     ...
;                     for (int m = 0; m < 4; ++m) { const size_t off = (size_t)(row0 + ai * 128 + m * 16) * DM + col0;
; #pragma unroll
;                         for (int bj = 0; bj < 2; ++bj) { const f32x8 b8 = __builtin_convertvector(hv[m][bj], f32x8); const f32x4 a0 = acc[ai][bj][m][0], a1 = acc[ai][bj][m][1];
;                             const f32x8 xx = {b8[0] + a0[0], b8[1] + a0[1], b8[2] + a0[2], b8[3] + a0[3], b8[4] + a1[0], b8[5] + a1[1], b8[6] + a1[2], b8[7] + a1[3]};
;                             *(f16x8*)(xh + off + bj * 128) = __builtin_convertvector(xx, f16x8); } }
;                     asm volatile("" ::: "memory");
	v_cvt_f32_f16_e32 v54, v92
	v_cvt_f32_f16_sdwa v55, v92 dst_sel:DWORD dst_unused:UNUSED_PAD src0_sel:WORD_1
	v_cvt_f32_f16_e32 v48, v95
	v_cvt_f32_f16_sdwa v49, v95 dst_sel:DWORD dst_unused:UNUSED_PAD src0_sel:WORD_1
	v_cvt_f32_f16_e32 v50, v94
	v_cvt_f32_f16_sdwa v51, v94 dst_sel:DWORD dst_unused:UNUSED_PAD src0_sel:WORD_1
	v_cvt_f32_f16_e32 v52, v93
	v_cvt_f32_f16_sdwa v53, v93 dst_sel:DWORD dst_unused:UNUSED_PAD src0_sel:WORD_1
	v_pk_add_f32 v[44:45], v[44:45], v[54:55]
	v_pk_add_f32 v[40:41], v[40:41], v[50:51]
	v_pk_add_f32 v[42:43], v[42:43], v[48:49]
	v_pk_add_f32 v[46:47], v[46:47], v[52:53]
	v_cvt_pk_f16_f32 v43, v42, v43
	v_cvt_pk_f16_f32 v42, v40, v41
	v_cvt_pk_f16_f32 v40, v44, v45
	v_lshl_add_u64 v[44:45], s[50:51], 0, v[102:103]
	v_cvt_pk_f16_f32 v41, v46, v47
	v_lshl_add_u64 v[44:45], v[44:45], 0, v[166:167]
	global_store_dwordx4 v[44:45], v[40:43], off sc0 sc1
	s_waitcnt vmcnt(7)
	v_cvt_f32_f16_e32 v46, v97
	v_cvt_f32_f16_sdwa v47, v97 dst_sel:DWORD dst_unused:UNUSED_PAD src0_sel:WORD_1
	v_cvt_f32_f16_e32 v40, v99
	v_cvt_f32_f16_sdwa v41, v99 dst_sel:DWORD dst_unused:UNUSED_PAD src0_sel:WORD_1
	v_cvt_f32_f16_e32 v42, v98
	v_cvt_f32_f16_sdwa v43, v98 dst_sel:DWORD dst_unused:UNUSED_PAD src0_sel:WORD_1
	v_cvt_f32_f16_e32 v48, v96
	v_cvt_f32_f16_sdwa v49, v96 dst_sel:DWORD dst_unused:UNUSED_PAD src0_sel:WORD_1
	v_pk_add_f32 v[38:39], v[38:39], v[46:47]
	v_pk_add_f32 v[32:33], v[32:33], v[42:43]
	v_pk_add_f32 v[34:35], v[34:35], v[40:41]
	v_pk_add_f32 v[36:37], v[36:37], v[48:49]
	v_cvt_pk_f16_f32 v35, v34, v35
	v_cvt_pk_f16_f32 v34, v32, v33
	v_cvt_pk_f16_f32 v33, v38, v39
	v_cvt_pk_f16_f32 v32, v36, v37
	global_store_dwordx4 v[44:45], v[32:35], off offset:256 sc0 sc1
	s_waitcnt vmcnt(7)
	v_cvt_f32_f16_e32 v38, v76
	v_cvt_f32_f16_sdwa v39, v76 dst_sel:DWORD dst_unused:UNUSED_PAD src0_sel:WORD_1
	v_cvt_f32_f16_e32 v32, v79
	v_cvt_f32_f16_sdwa v33, v79 dst_sel:DWORD dst_unused:UNUSED_PAD src0_sel:WORD_1
	v_cvt_f32_f16_e32 v34, v78
	v_cvt_f32_f16_sdwa v35, v78 dst_sel:DWORD dst_unused:UNUSED_PAD src0_sel:WORD_1
	v_cvt_f32_f16_e32 v36, v77
	v_cvt_f32_f16_sdwa v37, v77 dst_sel:DWORD dst_unused:UNUSED_PAD src0_sel:WORD_1
	v_pk_add_f32 v[28:29], v[28:29], v[38:39]
	v_pk_add_f32 v[24:25], v[24:25], v[34:35]
	v_pk_add_f32 v[26:27], v[26:27], v[32:33]
	v_pk_add_f32 v[30:31], v[30:31], v[36:37]
	v_cvt_pk_f16_f32 v27, v26, v27
	v_cvt_pk_f16_f32 v26, v24, v25
	v_cvt_pk_f16_f32 v24, v28, v29
	v_lshl_add_u64 v[28:29], s[50:51], 0, v[82:83]
	v_cvt_pk_f16_f32 v25, v30, v31
	v_lshl_add_u64 v[28:29], v[28:29], 0, v[166:167]
	global_store_dwordx4 v[28:29], v[24:27], off sc0 sc1
	s_waitcnt vmcnt(7)
	v_cvt_f32_f16_e32 v30, v73
	v_cvt_f32_f16_sdwa v31, v73 dst_sel:DWORD dst_unused:UNUSED_PAD src0_sel:WORD_1
	v_cvt_f32_f16_e32 v24, v75
	v_cvt_f32_f16_sdwa v25, v75 dst_sel:DWORD dst_unused:UNUSED_PAD src0_sel:WORD_1
	v_cvt_f32_f16_e32 v26, v74
	v_cvt_f32_f16_sdwa v27, v74 dst_sel:DWORD dst_unused:UNUSED_PAD src0_sel:WORD_1
	v_cvt_f32_f16_e32 v32, v72
	v_cvt_f32_f16_sdwa v33, v72 dst_sel:DWORD dst_unused:UNUSED_PAD src0_sel:WORD_1
	v_pk_add_f32 v[22:23], v[22:23], v[30:31]
	v_pk_add_f32 v[16:17], v[16:17], v[26:27]
	v_pk_add_f32 v[18:19], v[18:19], v[24:25]
	v_pk_add_f32 v[20:21], v[20:21], v[32:33]
	v_cvt_pk_f16_f32 v19, v18, v19
	v_cvt_pk_f16_f32 v18, v16, v17
	v_cvt_pk_f16_f32 v17, v22, v23
	v_cvt_pk_f16_f32 v16, v20, v21
	global_store_dwordx4 v[28:29], v[16:19], off offset:256 sc0 sc1
	s_waitcnt vmcnt(7)
	v_cvt_f32_f16_e32 v22, v68
	v_cvt_f32_f16_sdwa v23, v68 dst_sel:DWORD dst_unused:UNUSED_PAD src0_sel:WORD_1
	v_cvt_f32_f16_e32 v16, v71
	v_cvt_f32_f16_sdwa v17, v71 dst_sel:DWORD dst_unused:UNUSED_PAD src0_sel:WORD_1
	v_cvt_f32_f16_e32 v18, v70
	v_cvt_f32_f16_sdwa v19, v70 dst_sel:DWORD dst_unused:UNUSED_PAD src0_sel:WORD_1
	v_cvt_f32_f16_e32 v20, v69
	v_cvt_f32_f16_sdwa v21, v69 dst_sel:DWORD dst_unused:UNUSED_PAD src0_sel:WORD_1
	v_pk_add_f32 v[12:13], v[12:13], v[22:23]
	v_pk_add_f32 v[8:9], v[8:9], v[18:19]
	v_pk_add_f32 v[10:11], v[10:11], v[16:17]
	v_pk_add_f32 v[14:15], v[14:15], v[20:21]
	v_cvt_pk_f16_f32 v11, v10, v11
	v_cvt_pk_f16_f32 v10, v8, v9
	v_cvt_pk_f16_f32 v8, v12, v13
	v_lshl_add_u64 v[12:13], s[50:51], 0, v[80:81]
	v_cvt_pk_f16_f32 v9, v14, v15
	v_lshl_add_u64 v[12:13], v[12:13], 0, v[166:167]
	global_store_dwordx4 v[12:13], v[8:11], off sc0 sc1
	s_waitcnt vmcnt(7)
	v_cvt_f32_f16_e32 v14, v65
	v_cvt_f32_f16_sdwa v15, v65 dst_sel:DWORD dst_unused:UNUSED_PAD src0_sel:WORD_1
	v_cvt_f32_f16_e32 v8, v67
	v_cvt_f32_f16_sdwa v9, v67 dst_sel:DWORD dst_unused:UNUSED_PAD src0_sel:WORD_1
	v_cvt_f32_f16_e32 v10, v66
	v_cvt_f32_f16_sdwa v11, v66 dst_sel:DWORD dst_unused:UNUSED_PAD src0_sel:WORD_1
	v_cvt_f32_f16_e32 v16, v64
	v_cvt_f32_f16_sdwa v17, v64 dst_sel:DWORD dst_unused:UNUSED_PAD src0_sel:WORD_1
	v_pk_add_f32 v[6:7], v[6:7], v[14:15]
	v_pk_add_f32 v[0:1], v[0:1], v[10:11]
	v_pk_add_f32 v[2:3], v[2:3], v[8:9]
	v_pk_add_f32 v[4:5], v[4:5], v[16:17]
	v_cvt_pk_f16_f32 v3, v2, v3
	v_cvt_pk_f16_f32 v2, v0, v1
	v_cvt_pk_f16_f32 v1, v6, v7
	v_cvt_pk_f16_f32 v0, v4, v5
	global_store_dwordx4 v[12:13], v[0:3], off offset:256 sc0 sc1

; __device__ __forceinline__ unsigned cvtpk(float lo, float hi) { f32x2_t v = {lo, hi}; bf16x2_t b = __builtin_convertvector(v, bf16x2_t); return __builtin_bit_cast(unsigned, b); }
; __device__ __forceinline__ void norm_phase(const float* x, const _Float16* xh, const float* g, bf16_t* h, int rows) {
;     ...
;         for (int r = 0; r < 4; ++r) { float s = 0.f;
; #pragma unroll
;             for (int j = 0; j < 4; ++j) s += (v[r][j].x * v[r][j].x + v[r][j].y * v[r][j].y) + (v[r][j].z * v[r][j].z + v[r][j].w * v[r][j].w);
;             const float rstd = 1.0f / sqrtf(wave_sum(s) * (1.0f / DM) + RMS_EPS);
;             u32x2* o8 = (u32x2*)(h + (size_t)(m0 + r) * DM) + lane;
; #pragma unroll
;             for (int j = 0; j < 4; ++j) { u32x2 w; w.x = cvtpk(v[r][j].x * rstd * gv[j].x, v[r][j].y * rstd * gv[j].y); w.y = cvtpk(v[r][j].z * rstd * gv[j].z, v[r][j].w * rstd * gv[j].w); o8[64 * j] = w; } }
.LBB0_522:
	s_waitcnt vmcnt(15)
	v_pk_mul_f32 v[104:105], v[78:79], v[78:79]
	v_pk_mul_f32 v[106:107], v[76:77], v[76:77]
	v_add_u32_e32 v80, s30, v80
	v_pk_mov_b32 v[108:109], v[106:107], v[104:105] op_sel:[1,0]
	v_mov_b32_e32 v107, v105
	v_pk_add_f32 v[104:105], v[108:109], v[106:107]
	s_waitcnt vmcnt(14)
	v_pk_mul_f32 v[106:107], v[74:75], v[74:75]
	v_pk_add_f32 v[104:105], v[104:105], v[104:105] op_sel_hi:[0,1]
	v_pk_mul_f32 v[108:109], v[72:73], v[72:73]
	s_waitcnt vmcnt(13)
	v_mul_f32_e32 v104, v68, v68
	v_pk_mov_b32 v[110:111], v[108:109], v[106:107] op_sel:[1,0]
	v_mov_b32_e32 v109, v107
	v_pk_add_f32 v[106:107], v[110:111], v[108:109]
	v_pk_fma_f32 v[108:109], v[68:69], v[68:69], v[104:105] op_sel_hi:[1,1,0]
	v_mul_f32_e32 v104, v70, v70
	v_pk_add_f32 v[106:107], v[106:107], v[106:107] op_sel_hi:[0,1]
	v_pk_fma_f32 v[110:111], v[70:71], v[70:71], v[104:105] op_sel_hi:[1,1,0]
	s_waitcnt vmcnt(12)
	v_mul_f32_e32 v108, v64, v64
	v_mul_f32_e32 v110, v65, v65
	v_mul_f32_e32 v106, v66, v66
	v_mul_f32_e32 v104, v67, v67
	v_pk_add_f32 v[108:109], v[108:109], v[110:111]
	v_pk_add_f32 v[104:105], v[106:107], v[104:105]
	s_waitcnt vmcnt(11)
	v_pk_mul_f32 v[106:107], v[62:63], v[62:63]
	v_pk_add_f32 v[104:105], v[108:109], v[104:105]
	v_pk_mul_f32 v[108:109], v[60:61], v[60:61]
	v_add_f32_e32 v81, v104, v105
	ds_bpermute_b32 v104, v98, v81
	v_lshl_add_u64 v[88:89], v[88:89], 0, s[70:71]
	s_waitcnt lgkmcnt(0)
	v_add_f32_e32 v81, v81, v104
	ds_bpermute_b32 v104, v99, v81
	s_waitcnt lgkmcnt(0)
	v_add_f32_e32 v81, v81, v104
	ds_bpermute_b32 v104, v100, v81
	s_waitcnt lgkmcnt(0)
	v_add_f32_e32 v81, v81, v104
	ds_bpermute_b32 v104, v101, v81
	s_waitcnt lgkmcnt(0)
	v_add_f32_e32 v81, v81, v104
	ds_bpermute_b32 v104, v102, v81
	s_waitcnt lgkmcnt(0)
	v_add_f32_e32 v81, v81, v104
	ds_bpermute_b32 v104, v103, v81
	s_waitcnt lgkmcnt(0)
	v_add_f32_e32 v81, v81, v104
	v_fmamk_f32 v81, v81, 0x3a800000, v195
	v_mul_f32_e32 v104, 0x4f800000, v81
	v_cmp_gt_f32_e32 vcc, s33, v81
	s_nop 1
	v_cndmask_b32_e32 v81, v81, v104, vcc
	v_sqrt_f32_e32 v110, v81
	v_lshl_add_u64 v[104:105], v[90:91], 0, v[86:87]
	v_lshl_add_u64 v[86:87], v[86:87], 0, s[68:69]
	v_add_u32_e32 v111, -1, v110
	v_add_u32_e32 v112, 1, v110
	v_fma_f32 v113, -v111, v110, v81
	v_fma_f32 v114, -v112, v110, v81
	v_cmp_ge_f32_e64 s[0:1], 0, v113
	s_nop 1
	v_cndmask_b32_e64 v110, v110, v111, s[0:1]
	v_cmp_lt_f32_e64 s[0:1], 0, v114
	s_nop 1
	v_cndmask_b32_e64 v110, v110, v112, s[0:1]
	v_mul_f32_e32 v111, 0x37800000, v110
	v_cndmask_b32_e32 v110, v110, v111, vcc
	v_cmp_class_f32_e32 vcc, v81, v197
	s_nop 1
	v_cndmask_b32_e32 v81, v110, v81, vcc
	v_div_scale_f32 v112, s[0:1], v81, v81, 1.0
	v_rcp_f32_e32 v113, v112
	v_pk_mov_b32 v[110:111], v[108:109], v[106:107] op_sel:[1,0]
	v_div_scale_f32 v106, vcc, 1.0, v81, 1.0
	v_fma_f32 v109, -v112, v113, 1.0
	v_fmac_f32_e32 v113, v109, v113
	v_mul_f32_e32 v109, v106, v113
	v_fma_f32 v114, -v112, v109, v106
	v_fmac_f32_e32 v109, v114, v113
	v_fma_f32 v106, -v112, v109, v106
	v_div_fmas_f32 v106, v106, v113, v109
	v_mov_b32_e32 v109, v107
	v_pk_add_f32 v[108:109], v[110:111], v[108:109]
	s_waitcnt vmcnt(10)
	v_pk_mul_f32 v[110:111], v[58:59], v[58:59]
	v_pk_add_f32 v[108:109], v[108:109], v[108:109] op_sel_hi:[0,1]
	v_pk_mul_f32 v[112:113], v[56:57], v[56:57]
	s_waitcnt vmcnt(9)
	v_mul_f32_e32 v108, v52, v52
	v_pk_mov_b32 v[114:115], v[112:113], v[110:111] op_sel:[1,0]
	v_mov_b32_e32 v113, v111
	v_pk_add_f32 v[110:111], v[114:115], v[112:113]
	v_pk_fma_f32 v[112:113], v[52:53], v[52:53], v[108:109] op_sel_hi:[1,1,0]
	v_mul_f32_e32 v108, v54, v54
	v_pk_add_f32 v[110:111], v[110:111], v[110:111] op_sel_hi:[0,1]
	v_pk_fma_f32 v[114:115], v[54:55], v[54:55], v[108:109] op_sel_hi:[1,1,0]
	s_waitcnt vmcnt(8)
	v_mul_f32_e32 v112, v48, v48
	v_mul_f32_e32 v114, v49, v49
	v_mul_f32_e32 v110, v50, v50
	v_mul_f32_e32 v108, v51, v51
	v_pk_add_f32 v[112:113], v[112:113], v[114:115]
	v_pk_add_f32 v[108:109], v[110:111], v[108:109]
	v_div_fixup_f32 v106, v106, v81, 1.0
	v_pk_add_f32 v[108:109], v[112:113], v[108:109]
	v_pk_mul_f32 v[76:77], v[76:77], v[106:107] op_sel_hi:[1,0]
	v_add_f32_e32 v81, v108, v109
	ds_bpermute_b32 v107, v98, v81
	s_waitcnt vmcnt(0)
	v_pk_mul_f32 v[76:77], v[12:13], v[76:77]
	s_brev_b32 s0, 32
	v_cvt_pk_bf16_f32 v76, v76, v77
	s_waitcnt lgkmcnt(0)
	v_add_f32_e32 v81, v81, v107
	v_pk_mul_f32 v[78:79], v[78:79], v[106:107] op_sel_hi:[1,0]
	ds_bpermute_b32 v107, v99, v81
	v_pk_mul_f32 v[78:79], v[14:15], v[78:79]
	s_waitcnt lgkmcnt(0)
	v_add_f32_e32 v81, v81, v107
	v_cvt_pk_bf16_f32 v77, v78, v79
	v_add_co_u32_e32 v78, vcc, s0, v104
	ds_bpermute_b32 v104, v100, v81
	s_nop 0
	v_addc_co_u32_e32 v79, vcc, 0, v105, vcc
	global_store_dwordx2 v[78:79], v[76:77], off sc0 sc1
	v_pk_mul_f32 v[72:73], v[72:73], v[106:107] op_sel_hi:[1,0]
	s_waitcnt lgkmcnt(0)
	v_add_f32_e32 v76, v81, v104
	ds_bpermute_b32 v77, v101, v76
	v_pk_mul_f32 v[74:75], v[74:75], v[106:107] op_sel_hi:[1,0]
	v_pk_mul_f32 v[72:73], v[8:9], v[72:73]
	v_pk_mul_f32 v[74:75], v[10:11], v[74:75]
	v_cvt_pk_bf16_f32 v72, v72, v73
	v_cvt_pk_bf16_f32 v73, v74, v75
	global_store_dwordx2 v[78:79], v[72:73], off offset:512 sc0 sc1
	s_waitcnt lgkmcnt(0)
	v_add_f32_e32 v72, v76, v77
	ds_bpermute_b32 v73, v102, v72
	v_pk_mul_f32 v[68:69], v[68:69], v[106:107] op_sel_hi:[1,0]
	v_pk_mul_f32 v[70:71], v[70:71], v[106:107] op_sel_hi:[1,0]
	v_pk_mul_f32 v[68:69], v[4:5], v[68:69]
	v_pk_mul_f32 v[70:71], v[6:7], v[70:71]
	s_waitcnt lgkmcnt(0)
	v_add_f32_e32 v72, v72, v73
	ds_bpermute_b32 v73, v103, v72
	v_cvt_pk_bf16_f32 v68, v68, v69
	v_cvt_pk_bf16_f32 v69, v70, v71
	global_store_dwordx2 v[78:79], v[68:69], off offset:1024 sc0 sc1
	v_pk_mul_f32 v[64:65], v[64:65], v[106:107] op_sel_hi:[1,0]
	s_waitcnt lgkmcnt(0)
; __device__ __forceinline__ unsigned cvtpk(float lo, float hi) { f32x2_t v = {lo, hi}; bf16x2_t b = __builtin_convertvector(v, bf16x2_t); return __builtin_bit_cast(unsigned, b); }
; __device__ __forceinline__ void norm_phase(const float* x, const _Float16* xh, const float* g, bf16_t* h, int rows) {
;     ...
;         for (int r = 0; r < 4; ++r) { float s = 0.f;
; #pragma unroll
;             for (int j = 0; j < 4; ++j) s += (v[r][j].x * v[r][j].x + v[r][j].y * v[r][j].y) + (v[r][j].z * v[r][j].z + v[r][j].w * v[r][j].w);
;             const float rstd = 1.0f / sqrtf(wave_sum(s) * (1.0f / DM) + RMS_EPS);
;             u32x2* o8 = (u32x2*)(h + (size_t)(m0 + r) * DM) + lane;
; #pragma unroll
;             for (int j = 0; j < 4; ++j) { u32x2 w; w.x = cvtpk(v[r][j].x * rstd * gv[j].x, v[r][j].y * rstd * gv[j].y); w.y = cvtpk(v[r][j].z * rstd * gv[j].z, v[r][j].w * rstd * gv[j].w); o8[64 * j] = w; } }
	v_add_f32_e32 v68, v72, v73
	v_fmamk_f32 v68, v68, 0x3a800000, v195
	v_mul_f32_e32 v69, 0x4f800000, v68
	v_cmp_gt_f32_e32 vcc, s33, v68
	v_pk_mul_f32 v[64:65], v[0:1], v[64:65]
	v_pk_mul_f32 v[66:67], v[66:67], v[106:107] op_sel_hi:[1,0]
	v_cndmask_b32_e32 v68, v68, v69, vcc
	v_sqrt_f32_e32 v69, v68
	v_cvt_pk_bf16_f32 v64, v64, v65
	v_pk_mul_f32 v[66:67], v[2:3], v[66:67]
	v_add_u32_e32 v65, -1, v69
	v_fma_f32 v70, -v65, v69, v68
	v_cmp_ge_f32_e64 s[0:1], 0, v70
	v_add_u32_e32 v70, 1, v69
	s_nop 0
	v_cndmask_b32_e64 v65, v69, v65, s[0:1]
	v_fma_f32 v69, -v70, v69, v68
	v_cmp_lt_f32_e64 s[0:1], 0, v69
	s_nop 1
	v_cndmask_b32_e64 v65, v65, v70, s[0:1]
	v_mul_f32_e32 v69, 0x37800000, v65
	v_cndmask_b32_e32 v65, v65, v69, vcc
	v_cmp_class_f32_e32 vcc, v68, v197
	s_nop 1
	v_cndmask_b32_e32 v72, v65, v68, vcc
	v_div_scale_f32 v68, s[0:1], v72, v72, 1.0
	v_rcp_f32_e32 v69, v68
	v_cvt_pk_bf16_f32 v65, v66, v67
	global_store_dwordx2 v[78:79], v[64:65], off offset:1536 sc0 sc1
	v_fma_f32 v64, -v68, v69, 1.0
	v_fmac_f32_e32 v69, v64, v69
	v_div_scale_f32 v64, vcc, 1.0, v72, 1.0
	v_mul_f32_e32 v65, v64, v69
	v_fma_f32 v66, -v68, v65, v64
	v_fmac_f32_e32 v65, v66, v69
	v_fma_f32 v64, -v68, v65, v64
	v_div_fmas_f32 v73, v64, v69, v65
	v_pk_mul_f32 v[64:65], v[46:47], v[46:47]
	v_pk_mul_f32 v[66:67], v[44:45], v[44:45]
	s_nop 0
	v_pk_mov_b32 v[68:69], v[66:67], v[64:65] op_sel:[1,0]
	v_mov_b32_e32 v67, v65
	v_pk_add_f32 v[64:65], v[68:69], v[66:67]
	v_pk_mul_f32 v[66:67], v[42:43], v[42:43]
	v_pk_add_f32 v[64:65], v[64:65], v[64:65] op_sel_hi:[0,1]
	v_pk_mul_f32 v[68:69], v[40:41], v[40:41]
	v_mul_f32_e32 v64, v36, v36
	v_pk_mov_b32 v[70:71], v[68:69], v[66:67] op_sel:[1,0]
	v_mov_b32_e32 v69, v67
	v_pk_add_f32 v[66:67], v[70:71], v[68:69]
	v_pk_fma_f32 v[68:69], v[36:37], v[36:37], v[64:65] op_sel_hi:[1,1,0]
	v_mul_f32_e32 v64, v38, v38
	v_pk_add_f32 v[66:67], v[66:67], v[66:67] op_sel_hi:[0,1]
	v_pk_fma_f32 v[70:71], v[38:39], v[38:39], v[64:65] op_sel_hi:[1,1,0]
	v_mul_f32_e32 v68, v32, v32
	v_mul_f32_e32 v70, v33, v33
	v_mul_f32_e32 v66, v34, v34
	v_mul_f32_e32 v64, v35, v35
	v_pk_add_f32 v[68:69], v[68:69], v[70:71]
	v_pk_add_f32 v[64:65], v[66:67], v[64:65]
	v_lshl_add_u64 v[66:67], v[84:85], 0, v[96:97]
	v_pk_add_f32 v[64:65], v[68:69], v[64:65]
	s_nop 0
	v_add_f32_e32 v65, v64, v65
	ds_bpermute_b32 v68, v98, v65
	v_div_fixup_f32 v64, v73, v72, 1.0
	v_pk_mul_f32 v[60:61], v[60:61], v[64:65] op_sel_hi:[1,0]
	s_waitcnt lgkmcnt(0)
	v_add_f32_e32 v65, v65, v68
	ds_bpermute_b32 v68, v99, v65
	v_pk_mul_f32 v[62:63], v[62:63], v[64:65] op_sel_hi:[1,0]
	v_pk_mul_f32 v[60:61], v[12:13], v[60:61]
	v_pk_mul_f32 v[62:63], v[14:15], v[62:63]
	v_cvt_pk_bf16_f32 v60, v60, v61
	v_cvt_pk_bf16_f32 v61, v62, v63
	s_waitcnt lgkmcnt(0)
	v_add_f32_e32 v62, v65, v68
	ds_bpermute_b32 v63, v100, v62
	global_store_dwordx2 v[66:67], v[60:61], off sc0 sc1
	v_pk_mul_f32 v[56:57], v[56:57], v[64:65] op_sel_hi:[1,0]
	v_pk_mul_f32 v[58:59], v[58:59], v[64:65] op_sel_hi:[1,0]
	v_pk_mul_f32 v[56:57], v[8:9], v[56:57]
	s_waitcnt lgkmcnt(0)
	v_add_f32_e32 v60, v62, v63
	ds_bpermute_b32 v61, v101, v60
	v_pk_mul_f32 v[58:59], v[10:11], v[58:59]
	v_cvt_pk_bf16_f32 v56, v56, v57
	v_cvt_pk_bf16_f32 v57, v58, v59
	global_store_dwordx2 v[66:67], v[56:57], off offset:512 sc0 sc1
	s_waitcnt lgkmcnt(0)
	v_add_f32_e32 v56, v60, v61
	ds_bpermute_b32 v57, v102, v56
	v_pk_mul_f32 v[52:53], v[52:53], v[64:65] op_sel_hi:[1,0]
	v_pk_mul_f32 v[54:55], v[54:55], v[64:65] op_sel_hi:[1,0]
	v_pk_mul_f32 v[52:53], v[4:5], v[52:53]
	v_pk_mul_f32 v[54:55], v[6:7], v[54:55]
	s_waitcnt lgkmcnt(0)
	v_add_f32_e32 v56, v56, v57
	ds_bpermute_b32 v57, v103, v56
	v_cvt_pk_bf16_f32 v52, v52, v53
	v_cvt_pk_bf16_f32 v53, v54, v55
	global_store_dwordx2 v[66:67], v[52:53], off offset:1024 sc0 sc1
	v_pk_mul_f32 v[48:49], v[48:49], v[64:65] op_sel_hi:[1,0]
	s_waitcnt lgkmcnt(0)
	v_add_f32_e32 v52, v56, v57
	v_fmamk_f32 v52, v52, 0x3a800000, v195
	v_mul_f32_e32 v53, 0x4f800000, v52
	v_cmp_gt_f32_e32 vcc, s33, v52
	v_pk_mul_f32 v[48:49], v[0:1], v[48:49]
	v_pk_mul_f32 v[50:51], v[50:51], v[64:65] op_sel_hi:[1,0]
	v_cndmask_b32_e32 v52, v52, v53, vcc
	v_sqrt_f32_e32 v53, v52
	v_cvt_pk_bf16_f32 v48, v48, v49
	v_pk_mul_f32 v[50:51], v[2:3], v[50:51]
	v_add_u32_e32 v49, -1, v53
	v_fma_f32 v54, -v49, v53, v52
	v_cmp_ge_f32_e64 s[0:1], 0, v54
	v_add_u32_e32 v54, 1, v53
	s_nop 0
	v_cndmask_b32_e64 v49, v53, v49, s[0:1]
	v_fma_f32 v53, -v54, v53, v52
	v_cmp_lt_f32_e64 s[0:1], 0, v53
	s_nop 1
	v_cndmask_b32_e64 v49, v49, v54, s[0:1]
	v_mul_f32_e32 v53, 0x37800000, v49
	v_cndmask_b32_e32 v49, v49, v53, vcc
	v_cmp_class_f32_e32 vcc, v52, v197
	s_nop 1
	v_cndmask_b32_e32 v56, v49, v52, vcc
	v_div_scale_f32 v52, s[0:1], v56, v56, 1.0
	v_rcp_f32_e32 v53, v52
	v_cvt_pk_bf16_f32 v49, v50, v51
	global_store_dwordx2 v[66:67], v[48:49], off offset:1536 sc0 sc1
	v_fma_f32 v48, -v52, v53, 1.0
	v_fmac_f32_e32 v53, v48, v53
	v_div_scale_f32 v48, vcc, 1.0, v56, 1.0
	v_mul_f32_e32 v49, v48, v53
	v_fma_f32 v50, -v52, v49, v48
	v_fmac_f32_e32 v49, v50, v53
	v_fma_f32 v48, -v52, v49, v48
	v_div_fmas_f32 v57, v48, v53, v49
	v_pk_mul_f32 v[48:49], v[30:31], v[30:31]
	v_pk_mul_f32 v[50:51], v[28:29], v[28:29]
	s_nop 0
	v_pk_mov_b32 v[52:53], v[50:51], v[48:49] op_sel:[1,0]
	v_mov_b32_e32 v51, v49
	v_pk_add_f32 v[48:49], v[52:53], v[50:51]
	v_pk_mul_f32 v[50:51], v[26:27], v[26:27]
	v_pk_add_f32 v[48:49], v[48:49], v[48:49] op_sel_hi:[0,1]
	v_pk_mul_f32 v[52:53], v[24:25], v[24:25]
	v_mul_f32_e32 v48, v20, v20
	v_pk_mov_b32 v[54:55], v[52:53], v[50:51] op_sel:[1,0]
	v_mov_b32_e32 v53, v51
	v_pk_add_f32 v[50:51], v[54:55], v[52:53]
	v_pk_fma_f32 v[52:53], v[20:21], v[20:21], v[48:49] op_sel_hi:[1,1,0]
	v_mul_f32_e32 v48, v22, v22
	v_pk_add_f32 v[50:51], v[50:51], v[50:51] op_sel_hi:[0,1]
	v_pk_fma_f32 v[54:55], v[22:23], v[22:23], v[48:49] op_sel_hi:[1,1,0]
	v_mul_f32_e32 v52, v16, v16
	v_mul_f32_e32 v54, v17, v17
	v_mul_f32_e32 v50, v18, v18
	v_mul_f32_e32 v48, v19, v19
	v_pk_add_f32 v[52:53], v[52:53], v[54:55]
	v_pk_add_f32 v[48:49], v[50:51], v[48:49]
	v_lshl_add_u64 v[50:51], v[84:85], 0, v[94:95]
	v_pk_add_f32 v[48:49], v[52:53], v[48:49]
	s_nop 0
	v_add_f32_e32 v49, v48, v49
	ds_bpermute_b32 v52, v98, v49
	v_div_fixup_f32 v48, v57, v56, 1.0
	v_pk_mul_f32 v[44:45], v[44:45], v[48:49] op_sel_hi:[1,0]
	s_waitcnt lgkmcnt(0)
; __device__ __forceinline__ unsigned cvtpk(float lo, float hi) { f32x2_t v = {lo, hi}; bf16x2_t b = __builtin_convertvector(v, bf16x2_t); return __builtin_bit_cast(unsigned, b); }
; __device__ __forceinline__ void norm_phase(const float* x, const _Float16* xh, const float* g, bf16_t* h, int rows) {
;     ...
;         for (int r = 0; r < 4; ++r) { float s = 0.f;
; #pragma unroll
;             for (int j = 0; j < 4; ++j) s += (v[r][j].x * v[r][j].x + v[r][j].y * v[r][j].y) + (v[r][j].z * v[r][j].z + v[r][j].w * v[r][j].w);
;             const float rstd = 1.0f / sqrtf(wave_sum(s) * (1.0f / DM) + RMS_EPS);
;             u32x2* o8 = (u32x2*)(h + (size_t)(m0 + r) * DM) + lane;
; #pragma unroll
;             for (int j = 0; j < 4; ++j) { u32x2 w; w.x = cvtpk(v[r][j].x * rstd * gv[j].x, v[r][j].y * rstd * gv[j].y); w.y = cvtpk(v[r][j].z * rstd * gv[j].z, v[r][j].w * rstd * gv[j].w); o8[64 * j] = w; } }
;     }
	v_add_f32_e32 v49, v49, v52
	ds_bpermute_b32 v52, v99, v49
	v_pk_mul_f32 v[46:47], v[46:47], v[48:49] op_sel_hi:[1,0]
	v_pk_mul_f32 v[44:45], v[12:13], v[44:45]
	v_pk_mul_f32 v[46:47], v[14:15], v[46:47]
	v_cvt_pk_bf16_f32 v44, v44, v45
	v_cvt_pk_bf16_f32 v45, v46, v47
	s_waitcnt lgkmcnt(0)
	v_add_f32_e32 v46, v49, v52
	ds_bpermute_b32 v47, v100, v46
	global_store_dwordx2 v[50:51], v[44:45], off sc0 sc1
	v_pk_mul_f32 v[40:41], v[40:41], v[48:49] op_sel_hi:[1,0]
	v_pk_mul_f32 v[42:43], v[42:43], v[48:49] op_sel_hi:[1,0]
	v_pk_mul_f32 v[40:41], v[8:9], v[40:41]
	s_waitcnt lgkmcnt(0)
	v_add_f32_e32 v44, v46, v47
	ds_bpermute_b32 v45, v101, v44
	v_pk_mul_f32 v[42:43], v[10:11], v[42:43]
	v_cvt_pk_bf16_f32 v40, v40, v41
	v_cvt_pk_bf16_f32 v41, v42, v43
	global_store_dwordx2 v[50:51], v[40:41], off offset:512 sc0 sc1
	s_waitcnt lgkmcnt(0)
	v_add_f32_e32 v40, v44, v45
	ds_bpermute_b32 v41, v102, v40
	v_pk_mul_f32 v[36:37], v[36:37], v[48:49] op_sel_hi:[1,0]
	v_pk_mul_f32 v[38:39], v[38:39], v[48:49] op_sel_hi:[1,0]
	v_pk_mul_f32 v[36:37], v[4:5], v[36:37]
	v_pk_mul_f32 v[38:39], v[6:7], v[38:39]
	s_waitcnt lgkmcnt(0)
	v_add_f32_e32 v40, v40, v41
	ds_bpermute_b32 v41, v103, v40
	v_cvt_pk_bf16_f32 v36, v36, v37
	v_cvt_pk_bf16_f32 v37, v38, v39
	global_store_dwordx2 v[50:51], v[36:37], off offset:1024 sc0 sc1
	v_pk_mul_f32 v[32:33], v[32:33], v[48:49] op_sel_hi:[1,0]
	s_waitcnt lgkmcnt(0)
	v_add_f32_e32 v36, v40, v41
	v_fmamk_f32 v36, v36, 0x3a800000, v195
	v_mul_f32_e32 v37, 0x4f800000, v36
	v_cmp_gt_f32_e32 vcc, s33, v36
	v_pk_mul_f32 v[32:33], v[0:1], v[32:33]
	v_pk_mul_f32 v[34:35], v[34:35], v[48:49] op_sel_hi:[1,0]
	v_cndmask_b32_e32 v36, v36, v37, vcc
	v_sqrt_f32_e32 v37, v36
	v_cvt_pk_bf16_f32 v32, v32, v33
	v_pk_mul_f32 v[34:35], v[2:3], v[34:35]
	v_add_u32_e32 v33, -1, v37
	v_fma_f32 v38, -v33, v37, v36
	v_cmp_ge_f32_e64 s[0:1], 0, v38
	v_add_u32_e32 v38, 1, v37
	s_nop 0
	v_cndmask_b32_e64 v33, v37, v33, s[0:1]
	v_fma_f32 v37, -v38, v37, v36
	v_cmp_lt_f32_e64 s[0:1], 0, v37
	s_nop 1
	v_cndmask_b32_e64 v33, v33, v38, s[0:1]
	v_mul_f32_e32 v37, 0x37800000, v33
	v_cndmask_b32_e32 v33, v33, v37, vcc
	v_cmp_class_f32_e32 vcc, v36, v197
	s_nop 1
	v_cndmask_b32_e32 v36, v33, v36, vcc
	v_div_scale_f32 v37, s[0:1], v36, v36, 1.0
	v_rcp_f32_e32 v38, v37
	v_cvt_pk_bf16_f32 v33, v34, v35
	global_store_dwordx2 v[50:51], v[32:33], off offset:1536 sc0 sc1
	v_fma_f32 v32, -v37, v38, 1.0
	v_fmac_f32_e32 v38, v32, v38
	v_div_scale_f32 v32, vcc, 1.0, v36, 1.0
	v_mul_f32_e32 v33, v32, v38
	v_fma_f32 v34, -v37, v33, v32
	v_fmac_f32_e32 v33, v34, v38
	v_fma_f32 v32, -v37, v33, v32
	v_div_fmas_f32 v32, v32, v38, v33
	v_div_fixup_f32 v32, v32, v36, 1.0
	v_pk_mul_f32 v[28:29], v[28:29], v[32:33] op_sel_hi:[1,0]
	v_pk_mul_f32 v[30:31], v[30:31], v[32:33] op_sel_hi:[1,0]
	v_pk_mul_f32 v[24:25], v[24:25], v[32:33] op_sel_hi:[1,0]
	v_pk_mul_f32 v[26:27], v[26:27], v[32:33] op_sel_hi:[1,0]
	v_pk_mul_f32 v[20:21], v[20:21], v[32:33] op_sel_hi:[1,0]
	v_pk_mul_f32 v[22:23], v[22:23], v[32:33] op_sel_hi:[1,0]
	v_pk_mul_f32 v[16:17], v[16:17], v[32:33] op_sel_hi:[1,0]
	v_pk_mul_f32 v[18:19], v[18:19], v[32:33] op_sel_hi:[1,0]
	v_pk_mul_f32 v[28:29], v[12:13], v[28:29]
	v_pk_mul_f32 v[30:31], v[14:15], v[30:31]
	v_pk_mul_f32 v[24:25], v[8:9], v[24:25]
	v_pk_mul_f32 v[26:27], v[10:11], v[26:27]
	v_pk_mul_f32 v[20:21], v[4:5], v[20:21]
	v_pk_mul_f32 v[22:23], v[6:7], v[22:23]
	v_pk_mul_f32 v[16:17], v[0:1], v[16:17]
	v_pk_mul_f32 v[18:19], v[2:3], v[18:19]
	v_cmp_le_i32_e32 vcc, s62, v80
	v_lshl_add_u64 v[34:35], v[84:85], 0, v[92:93]
	v_cvt_pk_bf16_f32 v28, v28, v29
	v_cvt_pk_bf16_f32 v29, v30, v31
	v_cvt_pk_bf16_f32 v24, v24, v25
	v_cvt_pk_bf16_f32 v25, v26, v27
	v_cvt_pk_bf16_f32 v20, v20, v21
	v_cvt_pk_bf16_f32 v21, v22, v23
	v_cvt_pk_bf16_f32 v16, v16, v17
	v_cvt_pk_bf16_f32 v17, v18, v19
	s_or_b64 s[6:7], vcc, s[6:7]
	global_store_dwordx2 v[34:35], v[28:29], off sc0 sc1
	global_store_dwordx2 v[34:35], v[24:25], off offset:512 sc0 sc1
	global_store_dwordx2 v[34:35], v[20:21], off offset:1024 sc0 sc1
	global_store_dwordx2 v[34:35], v[16:17], off offset:1536 sc0 sc1
	s_andn2_b64 exec, exec, s[6:7]
	s_cbranch_execz .LBB0_69
